# norm phases P1/P6 fully hand-pipelined incl ctx rows, mod vectors in registers, 16 consecutive rows per wave
# speedup vs baseline: 1.0232x; 1.0118x over previous
; #define PIN(i) ((const float*)(const GASP float*)karg_q(i))
; __device__ __forceinline__ int obid() { int b = blockIdx.x; asm volatile("" : "+s"(b)); return b; }
; __device__ __forceinline__ int otid() { int t = threadIdx.x; asm volatile("" : "+v"(t)); return t; }
; #define PN_LOAD(dst, rw) do { const float* s_ = (rw) < NLAT ? hlat + (size_t)(rw) * 1024 : hctx + (size_t)((rw) - NLAT) * 1024; \
;         _Pragma("unroll") for (int i = 0; i < 4; ++i) dst[i] = *(const float4*)(s_ + i * 256 + lane * 4); } while (0)
; __device__ __forceinline__ void p_norm(const float* hlat, const float* hctx, const float* g, const float* modl, int sh_off, int sc_off, bf16_t* A, int M,
;                                        const float* part, const float* cgate, float* hcout) {
;     const int tid = otid(), lane = tid & 63, wave = tid >> 6;
;     const int stride = gridDim.x * 8;
;     int row = obid() * 8 + wave;
;     float4 v[4], nv[4];
;     ...
;     if (row < M) PN_LOAD(v, row);
;     while (row < M) {
;         const int nrow = row + stride;
;         if (nrow < M) PN_LOAD(nv, nrow);
;         const int r = row < NLAT ? (row >> 11) : 16;
; __global__ void __launch_bounds__(512, 2) hybrid_fwd(Params P) {
;     ...
;         const float* hl_in = l == 0 ? PIN(0) : POUT;
;         const float* hc_in = l == 0 ? PIN(2) : hc;
;         const int Mf = last ? NLAT : MTOK;
;         p_norm(hl_in, hc_in, PIN(6) + l * 1024, modl, 0, 1024, AO, MTOK, l > 0 ? (const float*)(PWS + WS_MK) : nullptr, mod + (size_t)((l > 0 ? l - 1 : 0) * 17 + 16) * 6144 + 5 * 1024, hc);
.LBB0_406:
	s_load_dwordx2 s[6:7], s[16:17], 0x0
	s_mul_hi_u32 s5, s8, 0x66000
	s_mov_b32 s9, s55
	v_mov_b32_e32 v14, v253
	s_waitcnt lgkmcnt(0)
	v_writelane_b32 v255, s6, 41
	v_ashrrev_i32_e32 v1, 6, v14
	s_nop 0
	v_writelane_b32 v255, s7, 42
	s_mul_i32 s6, s8, 0x66000
	s_add_u32 s6, s56, s6
	s_addc_u32 s7, s57, s5
	v_writelane_b32 v255, s6, 43
	s_mov_b32 s5, s63
	s_lshl_b32 s5, s5, 3
	v_writelane_b32 v255, s7, 44
	v_writelane_b32 v255, s8, 45
	s_lshl_b32 s6, s8, 10
	s_mov_b32 s7, s55
	v_writelane_b32 v255, s9, 46
	v_writelane_b32 v255, s6, 47
	v_add_u32_e32 v50, s5, v1
	s_waitcnt vmcnt(0) lgkmcnt(0)
	v_readlane_b32 s100, v255, 45
	s_load_dwordx2 s[48:49], s[0:1], 0x30
	s_cmp_eq_u32 s100, 0
	s_cselect_b32 s101, 0, 0xe8
	s_load_dwordx2 s[46:47], s[0:1], s101
	s_load_dwordx2 s[16:17], s[0:1], 0x10
	s_mul_i32 s101, s100, 0x66000
	s_add_u32 s50, s56, s101
	s_addc_u32 s51, s57, 0
	s_sub_u32 s20, s101, 0x66000
	s_cmp_eq_u32 s100, 0
	s_cselect_b32 s20, 0, s20
	s_add_u32 s20, s20, 0x65000
	s_add_u32 s20, s56, s20
	s_addc_u32 s21, s57, 0
	s_add_u32 s98, s50, 0x1000
	s_addc_u32 s99, s51, 0
	s_lshl_b32 s101, s100, 12
	v_and_b32_e32 v240, 63, v253
	v_lshlrev_b32_e32 v241, 4, v240
	v_lshrrev_b32_e32 v148, 7, v50
	v_lshlrev_b32_e32 v146, 4, v50
	v_lshl_add_u32 v144, v146, 12, v241
	v_lshlrev_b32_e32 v146, 11, v146
	v_lshl_add_u32 v146, v240, 3, v146
	v_mul_u32_u24_e32 v148, 0x6000, v148
	v_add_u32_e32 v148, v148, v241
	s_waitcnt lgkmcnt(0)
	s_add_u32 s48, s48, s101
	s_addc_u32 s49, s49, 0
	s_cmp_eq_u32 s100, 0
	s_cselect_b32 s16, s16, s64
	s_cselect_b32 s17, s17, s65
	s_cmp_eq_u32 s100, 0
	s_cbranch_scc1 .Lnorm_P1_alt
	global_load_dwordx4 v[80:83], v144, s[46:47]
	global_load_dwordx4 v[84:87], v144, s[46:47] offset:1024
	global_load_dwordx4 v[88:91], v144, s[46:47] offset:2048
	global_load_dwordx4 v[92:95], v144, s[46:47] offset:3072
	v_add_u32_e32 v144, 0x1000, v144
	global_load_dwordx4 v[34:37], v148, s[98:99]
	global_load_dwordx4 v[38:41], v148, s[98:99] offset:1024
	global_load_dwordx4 v[42:45], v148, s[98:99] offset:2048
	global_load_dwordx4 v[46:49], v148, s[98:99] offset:3072
	global_load_dwordx4 v[224:227], v148, s[50:51]
	global_load_dwordx4 v[228:231], v148, s[50:51] offset:1024
	global_load_dwordx4 v[232:235], v148, s[50:51] offset:2048
	global_load_dwordx4 v[236:239], v148, s[50:51] offset:3072
	global_load_dwordx4 v[188:191], v241, s[48:49]
	global_load_dwordx4 v[192:195], v241, s[48:49] offset:1024
	global_load_dwordx4 v[196:199], v241, s[48:49] offset:2048
	global_load_dwordx4 v[200:203], v241, s[48:49] offset:3072
	global_load_dwordx4 v[96:99], v144, s[46:47]
	global_load_dwordx4 v[100:103], v144, s[46:47] offset:1024
	global_load_dwordx4 v[104:107], v144, s[46:47] offset:2048
	global_load_dwordx4 v[108:111], v144, s[46:47] offset:3072
	v_add_u32_e32 v144, 0x1000, v144
	global_load_dwordx4 v[112:115], v144, s[46:47]
	global_load_dwordx4 v[116:119], v144, s[46:47] offset:1024
	global_load_dwordx4 v[120:123], v144, s[46:47] offset:2048
	global_load_dwordx4 v[124:127], v144, s[46:47] offset:3072
	v_add_u32_e32 v144, 0x1000, v144
	global_load_dwordx4 v[128:131], v144, s[46:47]
	global_load_dwordx4 v[132:135], v144, s[46:47] offset:1024
	global_load_dwordx4 v[136:139], v144, s[46:47] offset:2048
	global_load_dwordx4 v[140:143], v144, s[46:47] offset:3072
	v_add_u32_e32 v144, 0x1000, v144
	global_load_dwordx4 v[156:159], v144, s[46:47]
	global_load_dwordx4 v[160:163], v144, s[46:47] offset:1024
	global_load_dwordx4 v[164:167], v144, s[46:47] offset:2048
	global_load_dwordx4 v[168:171], v144, s[46:47] offset:3072
	v_add_u32_e32 v144, 0x1000, v144
	global_load_dwordx4 v[172:175], v144, s[46:47]
	global_load_dwordx4 v[176:179], v144, s[46:47] offset:1024
	global_load_dwordx4 v[180:183], v144, s[46:47] offset:2048
	global_load_dwordx4 v[184:187], v144, s[46:47] offset:3072
	v_add_u32_e32 v144, 0x1000, v144
	s_waitcnt vmcnt(32)
	v_pk_mul_f32 v[242:243], v[80:81], v[80:81]
	v_pk_mul_f32 v[244:245], v[84:85], v[84:85]
	v_pk_mul_f32 v[246:247], v[82:83], v[82:83]
	v_pk_mul_f32 v[248:249], v[86:87], v[86:87]
	v_add_f32_e32 v204, v245, v244
	v_add_f32_e32 v205, v243, v242
	v_add_f32_e32 v204, v248, v204
	v_add_f32_e32 v205, v246, v205
	v_add_f32_e32 v204, v249, v204
	v_add_f32_e32 v205, v247, v205
	v_pk_mul_f32 v[242:243], v[88:89], v[88:89]
	v_pk_mul_f32 v[244:245], v[92:93], v[92:93]
	v_pk_mul_f32 v[246:247], v[90:91], v[90:91]
	v_pk_mul_f32 v[248:249], v[94:95], v[94:95]
	v_add_f32_e32 v206, v243, v242
	v_add_f32_e32 v207, v245, v244
	v_add_f32_e32 v206, v246, v206
	v_add_f32_e32 v207, v248, v207
	v_add_f32_e32 v206, v247, v206
	v_add_f32_e32 v207, v249, v207
	v_add_f32_e32 v204, v205, v204
	v_add_f32_e32 v204, v204, v206
	v_add_f32_e32 v204, v204, v207
	ds_swizzle_b32 v205, v204 offset:swizzle(SWAP,1)
	s_waitcnt lgkmcnt(0)
	v_add_f32_e32 v204, v204, v205
	ds_swizzle_b32 v205, v204 offset:swizzle(SWAP,2)
	s_waitcnt lgkmcnt(0)
	v_add_f32_e32 v204, v204, v205
	ds_swizzle_b32 v205, v204 offset:swizzle(SWAP,4)
	s_waitcnt lgkmcnt(0)
	v_add_f32_e32 v204, v204, v205
	ds_swizzle_b32 v205, v204 offset:swizzle(SWAP,8)
	s_waitcnt lgkmcnt(0)
	v_add_f32_e32 v204, v204, v205
	ds_swizzle_b32 v205, v204 offset:swizzle(SWAP,16)
	s_waitcnt lgkmcnt(0)
	v_add_f32_e32 v204, v204, v205
	v_mov_b32_e32 v205, v204
	s_nop 1
	v_permlane32_swap_b32_e32 v204, v205
	v_add_f32_e32 v204, v204, v205
	v_mov_b32_e32 v205, 0x358637bd
	v_fmamk_f32 v204, v204, 0x3a800000, v205
	v_rsq_f32_e32 v204, v204
	s_nop 0
	s_waitcnt vmcnt(20)
; __device__ __forceinline__ unsigned pk2(float lo, float hi) { const g_f32x2 f = {lo, hi}; return __builtin_bit_cast(unsigned, __builtin_convertvector(f, g_bf16x2)); }
; __device__ __forceinline__ void p_norm(const float* hlat, const float* hctx, const float* g, const float* modl, int sh_off, int sc_off, bf16_t* A, int M,
;                                        const float* part, const float* cgate, float* hcout) {
;     ...
;         float ss = 0.f;
; #pragma unroll
;         for (int i = 0; i < 4; ++i) {
;             if (part != nullptr && row >= NLAT) {
;                 const size_t po = (size_t)(row - NLAT) * 1024 + i * 256 + lane * 4;
;                 const float4 p0 = *(const float4*)(part + po), p1 = *(const float4*)(part + (size_t)4096 * 1024 + po), cg = *(const float4*)(cgate + i * 256 + lane * 4);
;                 v[i].x += cg.x * (p0.x + p1.x); v[i].y += cg.y * (p0.y + p1.y); v[i].z += cg.z * (p0.z + p1.z); v[i].w += cg.w * (p0.w + p1.w);
;                 *(float4*)(hcout + po) = v[i];
;             }
;             ss += v[i].x * v[i].x + v[i].y * v[i].y + v[i].z * v[i].z + v[i].w * v[i].w; }
;         ss = wave_sum(ss);
;         const float rstd = rsqrtf(ss * (1.0f / 1024.0f) + EPS);
;         const float* mr = modl + (size_t)r * 6144;
; #pragma unroll
;         for (int i = 0; i < 4; ++i) {
;             const int k = i * 256 + lane * 4;
;             const float4 gg = *(const float4*)(g + k), scv = *(const float4*)(mr + sc_off + k), shv = *(const float4*)(mr + sh_off + k);
;             const float o0 = v[i].x * rstd * gg.x * (1.0f + scv.x) + shv.x, o1 = v[i].y * rstd * gg.y * (1.0f + scv.y) + shv.y;
;             const float o2 = v[i].z * rstd * gg.z * (1.0f + scv.z) + shv.z, o3 = v[i].w * rstd * gg.w * (1.0f + scv.w) + shv.w;
;             uint2 w; w.x = pk2(o0, o1); w.y = pk2(o2, o3);
;             *(uint2*)(A + (size_t)row * 1024 + k) = w;
;         }
; #pragma unroll
;         for (int i = 0; i < 4; ++i) v[i] = nv[i];
;         row = nrow;
	v_pk_add_f32 v[34:35], v[34:35], 1.0 op_sel_hi:[1,0]
	v_pk_add_f32 v[36:37], v[36:37], 1.0 op_sel_hi:[1,0]
	v_pk_add_f32 v[38:39], v[38:39], 1.0 op_sel_hi:[1,0]
	v_pk_add_f32 v[40:41], v[40:41], 1.0 op_sel_hi:[1,0]
	v_pk_add_f32 v[42:43], v[42:43], 1.0 op_sel_hi:[1,0]
	v_pk_add_f32 v[44:45], v[44:45], 1.0 op_sel_hi:[1,0]
	v_pk_add_f32 v[46:47], v[46:47], 1.0 op_sel_hi:[1,0]
	v_pk_add_f32 v[48:49], v[48:49], 1.0 op_sel_hi:[1,0]
	v_pk_mul_f32 v[80:81], v[80:81], v[204:205] op_sel_hi:[1,0]
	v_pk_mul_f32 v[82:83], v[82:83], v[204:205] op_sel_hi:[1,0]
	v_pk_mul_f32 v[80:81], v[188:189], v[80:81]
	v_pk_mul_f32 v[82:83], v[190:191], v[82:83]
	v_pk_fma_f32 v[80:81], v[34:35], v[80:81], v[224:225]
	v_pk_fma_f32 v[82:83], v[36:37], v[82:83], v[226:227]
	v_cvt_pk_bf16_f32 v80, v80, v81
	v_cvt_pk_bf16_f32 v81, v82, v83
	global_store_dwordx2 v146, v[80:81], s[66:67]
	v_pk_mul_f32 v[84:85], v[84:85], v[204:205] op_sel_hi:[1,0]
	v_pk_mul_f32 v[86:87], v[86:87], v[204:205] op_sel_hi:[1,0]
	v_pk_mul_f32 v[84:85], v[192:193], v[84:85]
	v_pk_mul_f32 v[86:87], v[194:195], v[86:87]
	v_pk_fma_f32 v[84:85], v[38:39], v[84:85], v[228:229]
	v_pk_fma_f32 v[86:87], v[40:41], v[86:87], v[230:231]
	v_cvt_pk_bf16_f32 v84, v84, v85
	v_cvt_pk_bf16_f32 v85, v86, v87
	global_store_dwordx2 v146, v[84:85], s[66:67] offset:512
	v_pk_mul_f32 v[88:89], v[88:89], v[204:205] op_sel_hi:[1,0]
	v_pk_mul_f32 v[90:91], v[90:91], v[204:205] op_sel_hi:[1,0]
	v_pk_mul_f32 v[88:89], v[196:197], v[88:89]
	v_pk_mul_f32 v[90:91], v[198:199], v[90:91]
	v_pk_fma_f32 v[88:89], v[42:43], v[88:89], v[232:233]
	v_pk_fma_f32 v[90:91], v[44:45], v[90:91], v[234:235]
	v_cvt_pk_bf16_f32 v88, v88, v89
	v_cvt_pk_bf16_f32 v89, v90, v91
	global_store_dwordx2 v146, v[88:89], s[66:67] offset:1024
	v_pk_mul_f32 v[92:93], v[92:93], v[204:205] op_sel_hi:[1,0]
	v_pk_mul_f32 v[94:95], v[94:95], v[204:205] op_sel_hi:[1,0]
	v_pk_mul_f32 v[92:93], v[200:201], v[92:93]
	v_pk_mul_f32 v[94:95], v[202:203], v[94:95]
	v_pk_fma_f32 v[92:93], v[46:47], v[92:93], v[236:237]
	v_pk_fma_f32 v[94:95], v[48:49], v[94:95], v[238:239]
	v_cvt_pk_bf16_f32 v92, v92, v93
	v_cvt_pk_bf16_f32 v93, v94, v95
	global_store_dwordx2 v146, v[92:93], s[66:67] offset:1536
	v_add_u32_e32 v146, 0x800, v146
	global_load_dwordx4 v[80:83], v144, s[46:47]
	global_load_dwordx4 v[84:87], v144, s[46:47] offset:1024
	global_load_dwordx4 v[88:91], v144, s[46:47] offset:2048
	global_load_dwordx4 v[92:95], v144, s[46:47] offset:3072
	v_add_u32_e32 v144, 0x1000, v144
	s_waitcnt vmcnt(24)
	v_pk_mul_f32 v[242:243], v[96:97], v[96:97]
	v_pk_mul_f32 v[244:245], v[100:101], v[100:101]
	v_pk_mul_f32 v[246:247], v[98:99], v[98:99]
	v_pk_mul_f32 v[248:249], v[102:103], v[102:103]
	v_add_f32_e32 v204, v245, v244
	v_add_f32_e32 v205, v243, v242
	v_add_f32_e32 v204, v248, v204
	v_add_f32_e32 v205, v246, v205
	v_add_f32_e32 v204, v249, v204
	v_add_f32_e32 v205, v247, v205
	v_pk_mul_f32 v[242:243], v[104:105], v[104:105]
	v_pk_mul_f32 v[244:245], v[108:109], v[108:109]
	v_pk_mul_f32 v[246:247], v[106:107], v[106:107]
	v_pk_mul_f32 v[248:249], v[110:111], v[110:111]
	v_add_f32_e32 v206, v243, v242
	v_add_f32_e32 v207, v245, v244
	v_add_f32_e32 v206, v246, v206
	v_add_f32_e32 v207, v248, v207
	v_add_f32_e32 v206, v247, v206
	v_add_f32_e32 v207, v249, v207
	v_add_f32_e32 v204, v205, v204
	v_add_f32_e32 v204, v204, v206
	v_add_f32_e32 v204, v204, v207
	ds_swizzle_b32 v205, v204 offset:swizzle(SWAP,1)
	s_waitcnt lgkmcnt(0)
	v_add_f32_e32 v204, v204, v205
	ds_swizzle_b32 v205, v204 offset:swizzle(SWAP,2)
	s_waitcnt lgkmcnt(0)
	v_add_f32_e32 v204, v204, v205
	ds_swizzle_b32 v205, v204 offset:swizzle(SWAP,4)
	s_waitcnt lgkmcnt(0)
	v_add_f32_e32 v204, v204, v205
	ds_swizzle_b32 v205, v204 offset:swizzle(SWAP,8)
	s_waitcnt lgkmcnt(0)
	v_add_f32_e32 v204, v204, v205
	ds_swizzle_b32 v205, v204 offset:swizzle(SWAP,16)
	s_waitcnt lgkmcnt(0)
	v_add_f32_e32 v204, v204, v205
	v_mov_b32_e32 v205, v204
	s_nop 1
	v_permlane32_swap_b32_e32 v204, v205
	v_add_f32_e32 v204, v204, v205
	v_mov_b32_e32 v205, 0x358637bd
	v_fmamk_f32 v204, v204, 0x3a800000, v205
	v_rsq_f32_e32 v204, v204
	s_nop 0
	v_pk_mul_f32 v[96:97], v[96:97], v[204:205] op_sel_hi:[1,0]
	v_pk_mul_f32 v[98:99], v[98:99], v[204:205] op_sel_hi:[1,0]
	v_pk_mul_f32 v[96:97], v[188:189], v[96:97]
	v_pk_mul_f32 v[98:99], v[190:191], v[98:99]
	v_pk_fma_f32 v[96:97], v[34:35], v[96:97], v[224:225]
	v_pk_fma_f32 v[98:99], v[36:37], v[98:99], v[226:227]
	v_cvt_pk_bf16_f32 v96, v96, v97
	v_cvt_pk_bf16_f32 v97, v98, v99
	global_store_dwordx2 v146, v[96:97], s[66:67]
	v_pk_mul_f32 v[100:101], v[100:101], v[204:205] op_sel_hi:[1,0]
	v_pk_mul_f32 v[102:103], v[102:103], v[204:205] op_sel_hi:[1,0]
	v_pk_mul_f32 v[100:101], v[192:193], v[100:101]
	v_pk_mul_f32 v[102:103], v[194:195], v[102:103]
	v_pk_fma_f32 v[100:101], v[38:39], v[100:101], v[228:229]
	v_pk_fma_f32 v[102:103], v[40:41], v[102:103], v[230:231]
	v_cvt_pk_bf16_f32 v100, v100, v101
	v_cvt_pk_bf16_f32 v101, v102, v103
	global_store_dwordx2 v146, v[100:101], s[66:67] offset:512
	v_pk_mul_f32 v[104:105], v[104:105], v[204:205] op_sel_hi:[1,0]
	v_pk_mul_f32 v[106:107], v[106:107], v[204:205] op_sel_hi:[1,0]
	v_pk_mul_f32 v[104:105], v[196:197], v[104:105]
	v_pk_mul_f32 v[106:107], v[198:199], v[106:107]
	v_pk_fma_f32 v[104:105], v[42:43], v[104:105], v[232:233]
	v_pk_fma_f32 v[106:107], v[44:45], v[106:107], v[234:235]
	v_cvt_pk_bf16_f32 v104, v104, v105
	v_cvt_pk_bf16_f32 v105, v106, v107
	global_store_dwordx2 v146, v[104:105], s[66:67] offset:1024
	v_pk_mul_f32 v[108:109], v[108:109], v[204:205] op_sel_hi:[1,0]
	v_pk_mul_f32 v[110:111], v[110:111], v[204:205] op_sel_hi:[1,0]
	v_pk_mul_f32 v[108:109], v[200:201], v[108:109]
	v_pk_mul_f32 v[110:111], v[202:203], v[110:111]
	v_pk_fma_f32 v[108:109], v[46:47], v[108:109], v[236:237]
	v_pk_fma_f32 v[110:111], v[48:49], v[110:111], v[238:239]
	v_cvt_pk_bf16_f32 v108, v108, v109
	v_cvt_pk_bf16_f32 v109, v110, v111
	global_store_dwordx2 v146, v[108:109], s[66:67] offset:1536
	v_add_u32_e32 v146, 0x800, v146
	global_load_dwordx4 v[96:99], v144, s[46:47]
	global_load_dwordx4 v[100:103], v144, s[46:47] offset:1024
	global_load_dwordx4 v[104:107], v144, s[46:47] offset:2048
	global_load_dwordx4 v[108:111], v144, s[46:47] offset:3072
	v_add_u32_e32 v144, 0x1000, v144
	s_waitcnt vmcnt(28)
; __device__ __forceinline__ unsigned pk2(float lo, float hi) { const g_f32x2 f = {lo, hi}; return __builtin_bit_cast(unsigned, __builtin_convertvector(f, g_bf16x2)); }
; __device__ __forceinline__ void p_norm(const float* hlat, const float* hctx, const float* g, const float* modl, int sh_off, int sc_off, bf16_t* A, int M,
;                                        const float* part, const float* cgate, float* hcout) {
;     ...
;         float ss = 0.f;
; #pragma unroll
;         for (int i = 0; i < 4; ++i) {
;             if (part != nullptr && row >= NLAT) {
;                 const size_t po = (size_t)(row - NLAT) * 1024 + i * 256 + lane * 4;
;                 const float4 p0 = *(const float4*)(part + po), p1 = *(const float4*)(part + (size_t)4096 * 1024 + po), cg = *(const float4*)(cgate + i * 256 + lane * 4);
;                 v[i].x += cg.x * (p0.x + p1.x); v[i].y += cg.y * (p0.y + p1.y); v[i].z += cg.z * (p0.z + p1.z); v[i].w += cg.w * (p0.w + p1.w);
;                 *(float4*)(hcout + po) = v[i];
;             }
;             ss += v[i].x * v[i].x + v[i].y * v[i].y + v[i].z * v[i].z + v[i].w * v[i].w; }
;         ss = wave_sum(ss);
;         const float rstd = rsqrtf(ss * (1.0f / 1024.0f) + EPS);
;         const float* mr = modl + (size_t)r * 6144;
; #pragma unroll
;         for (int i = 0; i < 4; ++i) {
;             const int k = i * 256 + lane * 4;
;             const float4 gg = *(const float4*)(g + k), scv = *(const float4*)(mr + sc_off + k), shv = *(const float4*)(mr + sh_off + k);
;             const float o0 = v[i].x * rstd * gg.x * (1.0f + scv.x) + shv.x, o1 = v[i].y * rstd * gg.y * (1.0f + scv.y) + shv.y;
;             const float o2 = v[i].z * rstd * gg.z * (1.0f + scv.z) + shv.z, o3 = v[i].w * rstd * gg.w * (1.0f + scv.w) + shv.w;
;             uint2 w; w.x = pk2(o0, o1); w.y = pk2(o2, o3);
;             *(uint2*)(A + (size_t)row * 1024 + k) = w;
;         }
; #pragma unroll
;         for (int i = 0; i < 4; ++i) v[i] = nv[i];
;         row = nrow;
	v_pk_mul_f32 v[242:243], v[112:113], v[112:113]
	v_pk_mul_f32 v[244:245], v[116:117], v[116:117]
	v_pk_mul_f32 v[246:247], v[114:115], v[114:115]
	v_pk_mul_f32 v[248:249], v[118:119], v[118:119]
	v_add_f32_e32 v204, v245, v244
	v_add_f32_e32 v205, v243, v242
	v_add_f32_e32 v204, v248, v204
	v_add_f32_e32 v205, v246, v205
	v_add_f32_e32 v204, v249, v204
	v_add_f32_e32 v205, v247, v205
	v_pk_mul_f32 v[242:243], v[120:121], v[120:121]
	v_pk_mul_f32 v[244:245], v[124:125], v[124:125]
	v_pk_mul_f32 v[246:247], v[122:123], v[122:123]
	v_pk_mul_f32 v[248:249], v[126:127], v[126:127]
	v_add_f32_e32 v206, v243, v242
	v_add_f32_e32 v207, v245, v244
	v_add_f32_e32 v206, v246, v206
	v_add_f32_e32 v207, v248, v207
	v_add_f32_e32 v206, v247, v206
	v_add_f32_e32 v207, v249, v207
	v_add_f32_e32 v204, v205, v204
	v_add_f32_e32 v204, v204, v206
	v_add_f32_e32 v204, v204, v207
	ds_swizzle_b32 v205, v204 offset:swizzle(SWAP,1)
	s_waitcnt lgkmcnt(0)
	v_add_f32_e32 v204, v204, v205
	ds_swizzle_b32 v205, v204 offset:swizzle(SWAP,2)
	s_waitcnt lgkmcnt(0)
	v_add_f32_e32 v204, v204, v205
	ds_swizzle_b32 v205, v204 offset:swizzle(SWAP,4)
	s_waitcnt lgkmcnt(0)
	v_add_f32_e32 v204, v204, v205
	ds_swizzle_b32 v205, v204 offset:swizzle(SWAP,8)
	s_waitcnt lgkmcnt(0)
	v_add_f32_e32 v204, v204, v205
	ds_swizzle_b32 v205, v204 offset:swizzle(SWAP,16)
	s_waitcnt lgkmcnt(0)
	v_add_f32_e32 v204, v204, v205
	v_mov_b32_e32 v205, v204
	s_nop 1
	v_permlane32_swap_b32_e32 v204, v205
	v_add_f32_e32 v204, v204, v205
	v_mov_b32_e32 v205, 0x358637bd
	v_fmamk_f32 v204, v204, 0x3a800000, v205
	v_rsq_f32_e32 v204, v204
	s_nop 0
	v_pk_mul_f32 v[112:113], v[112:113], v[204:205] op_sel_hi:[1,0]
	v_pk_mul_f32 v[114:115], v[114:115], v[204:205] op_sel_hi:[1,0]
	v_pk_mul_f32 v[112:113], v[188:189], v[112:113]
	v_pk_mul_f32 v[114:115], v[190:191], v[114:115]
	v_pk_fma_f32 v[112:113], v[34:35], v[112:113], v[224:225]
	v_pk_fma_f32 v[114:115], v[36:37], v[114:115], v[226:227]
	v_cvt_pk_bf16_f32 v112, v112, v113
	v_cvt_pk_bf16_f32 v113, v114, v115
	global_store_dwordx2 v146, v[112:113], s[66:67]
	v_pk_mul_f32 v[116:117], v[116:117], v[204:205] op_sel_hi:[1,0]
	v_pk_mul_f32 v[118:119], v[118:119], v[204:205] op_sel_hi:[1,0]
	v_pk_mul_f32 v[116:117], v[192:193], v[116:117]
	v_pk_mul_f32 v[118:119], v[194:195], v[118:119]
	v_pk_fma_f32 v[116:117], v[38:39], v[116:117], v[228:229]
	v_pk_fma_f32 v[118:119], v[40:41], v[118:119], v[230:231]
	v_cvt_pk_bf16_f32 v116, v116, v117
	v_cvt_pk_bf16_f32 v117, v118, v119
	global_store_dwordx2 v146, v[116:117], s[66:67] offset:512
	v_pk_mul_f32 v[120:121], v[120:121], v[204:205] op_sel_hi:[1,0]
	v_pk_mul_f32 v[122:123], v[122:123], v[204:205] op_sel_hi:[1,0]
	v_pk_mul_f32 v[120:121], v[196:197], v[120:121]
	v_pk_mul_f32 v[122:123], v[198:199], v[122:123]
	v_pk_fma_f32 v[120:121], v[42:43], v[120:121], v[232:233]
	v_pk_fma_f32 v[122:123], v[44:45], v[122:123], v[234:235]
	v_cvt_pk_bf16_f32 v120, v120, v121
	v_cvt_pk_bf16_f32 v121, v122, v123
	global_store_dwordx2 v146, v[120:121], s[66:67] offset:1024
	v_pk_mul_f32 v[124:125], v[124:125], v[204:205] op_sel_hi:[1,0]
	v_pk_mul_f32 v[126:127], v[126:127], v[204:205] op_sel_hi:[1,0]
	v_pk_mul_f32 v[124:125], v[200:201], v[124:125]
	v_pk_mul_f32 v[126:127], v[202:203], v[126:127]
	v_pk_fma_f32 v[124:125], v[46:47], v[124:125], v[236:237]
	v_pk_fma_f32 v[126:127], v[48:49], v[126:127], v[238:239]
	v_cvt_pk_bf16_f32 v124, v124, v125
	v_cvt_pk_bf16_f32 v125, v126, v127
	global_store_dwordx2 v146, v[124:125], s[66:67] offset:1536
	v_add_u32_e32 v146, 0x800, v146
	global_load_dwordx4 v[112:115], v144, s[46:47]
	global_load_dwordx4 v[116:119], v144, s[46:47] offset:1024
	global_load_dwordx4 v[120:123], v144, s[46:47] offset:2048
	global_load_dwordx4 v[124:127], v144, s[46:47] offset:3072
	v_add_u32_e32 v144, 0x1000, v144
	s_waitcnt vmcnt(32)
	v_pk_mul_f32 v[242:243], v[128:129], v[128:129]
	v_pk_mul_f32 v[244:245], v[132:133], v[132:133]
	v_pk_mul_f32 v[246:247], v[130:131], v[130:131]
	v_pk_mul_f32 v[248:249], v[134:135], v[134:135]
	v_add_f32_e32 v204, v245, v244
	v_add_f32_e32 v205, v243, v242
	v_add_f32_e32 v204, v248, v204
	v_add_f32_e32 v205, v246, v205
	v_add_f32_e32 v204, v249, v204
	v_add_f32_e32 v205, v247, v205
	v_pk_mul_f32 v[242:243], v[136:137], v[136:137]
	v_pk_mul_f32 v[244:245], v[140:141], v[140:141]
	v_pk_mul_f32 v[246:247], v[138:139], v[138:139]
	v_pk_mul_f32 v[248:249], v[142:143], v[142:143]
	v_add_f32_e32 v206, v243, v242
	v_add_f32_e32 v207, v245, v244
	v_add_f32_e32 v206, v246, v206
	v_add_f32_e32 v207, v248, v207
	v_add_f32_e32 v206, v247, v206
	v_add_f32_e32 v207, v249, v207
	v_add_f32_e32 v204, v205, v204
	v_add_f32_e32 v204, v204, v206
	v_add_f32_e32 v204, v204, v207
	ds_swizzle_b32 v205, v204 offset:swizzle(SWAP,1)
	s_waitcnt lgkmcnt(0)
	v_add_f32_e32 v204, v204, v205
	ds_swizzle_b32 v205, v204 offset:swizzle(SWAP,2)
	s_waitcnt lgkmcnt(0)
	v_add_f32_e32 v204, v204, v205
	ds_swizzle_b32 v205, v204 offset:swizzle(SWAP,4)
	s_waitcnt lgkmcnt(0)
	v_add_f32_e32 v204, v204, v205
	ds_swizzle_b32 v205, v204 offset:swizzle(SWAP,8)
	s_waitcnt lgkmcnt(0)
	v_add_f32_e32 v204, v204, v205
	ds_swizzle_b32 v205, v204 offset:swizzle(SWAP,16)
	s_waitcnt lgkmcnt(0)
; __device__ __forceinline__ unsigned pk2(float lo, float hi) { const g_f32x2 f = {lo, hi}; return __builtin_bit_cast(unsigned, __builtin_convertvector(f, g_bf16x2)); }
; __device__ __forceinline__ void p_norm(const float* hlat, const float* hctx, const float* g, const float* modl, int sh_off, int sc_off, bf16_t* A, int M,
;                                        const float* part, const float* cgate, float* hcout) {
;     ...
;         float ss = 0.f;
; #pragma unroll
;         for (int i = 0; i < 4; ++i) {
;             if (part != nullptr && row >= NLAT) {
;                 const size_t po = (size_t)(row - NLAT) * 1024 + i * 256 + lane * 4;
;                 const float4 p0 = *(const float4*)(part + po), p1 = *(const float4*)(part + (size_t)4096 * 1024 + po), cg = *(const float4*)(cgate + i * 256 + lane * 4);
;                 v[i].x += cg.x * (p0.x + p1.x); v[i].y += cg.y * (p0.y + p1.y); v[i].z += cg.z * (p0.z + p1.z); v[i].w += cg.w * (p0.w + p1.w);
;                 *(float4*)(hcout + po) = v[i];
;             }
;             ss += v[i].x * v[i].x + v[i].y * v[i].y + v[i].z * v[i].z + v[i].w * v[i].w; }
;         ss = wave_sum(ss);
;         const float rstd = rsqrtf(ss * (1.0f / 1024.0f) + EPS);
;         const float* mr = modl + (size_t)r * 6144;
; #pragma unroll
;         for (int i = 0; i < 4; ++i) {
;             const int k = i * 256 + lane * 4;
;             const float4 gg = *(const float4*)(g + k), scv = *(const float4*)(mr + sc_off + k), shv = *(const float4*)(mr + sh_off + k);
;             const float o0 = v[i].x * rstd * gg.x * (1.0f + scv.x) + shv.x, o1 = v[i].y * rstd * gg.y * (1.0f + scv.y) + shv.y;
;             const float o2 = v[i].z * rstd * gg.z * (1.0f + scv.z) + shv.z, o3 = v[i].w * rstd * gg.w * (1.0f + scv.w) + shv.w;
;             uint2 w; w.x = pk2(o0, o1); w.y = pk2(o2, o3);
;             *(uint2*)(A + (size_t)row * 1024 + k) = w;
;         }
; #pragma unroll
;         for (int i = 0; i < 4; ++i) v[i] = nv[i];
;         row = nrow;
	v_add_f32_e32 v204, v204, v205
	v_mov_b32_e32 v205, v204
	s_nop 1
	v_permlane32_swap_b32_e32 v204, v205
	v_add_f32_e32 v204, v204, v205
	v_mov_b32_e32 v205, 0x358637bd
	v_fmamk_f32 v204, v204, 0x3a800000, v205
	v_rsq_f32_e32 v204, v204
	s_nop 0
	v_pk_mul_f32 v[128:129], v[128:129], v[204:205] op_sel_hi:[1,0]
	v_pk_mul_f32 v[130:131], v[130:131], v[204:205] op_sel_hi:[1,0]
	v_pk_mul_f32 v[128:129], v[188:189], v[128:129]
	v_pk_mul_f32 v[130:131], v[190:191], v[130:131]
	v_pk_fma_f32 v[128:129], v[34:35], v[128:129], v[224:225]
	v_pk_fma_f32 v[130:131], v[36:37], v[130:131], v[226:227]
	v_cvt_pk_bf16_f32 v128, v128, v129
	v_cvt_pk_bf16_f32 v129, v130, v131
	global_store_dwordx2 v146, v[128:129], s[66:67]
	v_pk_mul_f32 v[132:133], v[132:133], v[204:205] op_sel_hi:[1,0]
	v_pk_mul_f32 v[134:135], v[134:135], v[204:205] op_sel_hi:[1,0]
	v_pk_mul_f32 v[132:133], v[192:193], v[132:133]
	v_pk_mul_f32 v[134:135], v[194:195], v[134:135]
	v_pk_fma_f32 v[132:133], v[38:39], v[132:133], v[228:229]
	v_pk_fma_f32 v[134:135], v[40:41], v[134:135], v[230:231]
	v_cvt_pk_bf16_f32 v132, v132, v133
	v_cvt_pk_bf16_f32 v133, v134, v135
	global_store_dwordx2 v146, v[132:133], s[66:67] offset:512
	v_pk_mul_f32 v[136:137], v[136:137], v[204:205] op_sel_hi:[1,0]
	v_pk_mul_f32 v[138:139], v[138:139], v[204:205] op_sel_hi:[1,0]
	v_pk_mul_f32 v[136:137], v[196:197], v[136:137]
	v_pk_mul_f32 v[138:139], v[198:199], v[138:139]
	v_pk_fma_f32 v[136:137], v[42:43], v[136:137], v[232:233]
	v_pk_fma_f32 v[138:139], v[44:45], v[138:139], v[234:235]
	v_cvt_pk_bf16_f32 v136, v136, v137
	v_cvt_pk_bf16_f32 v137, v138, v139
	global_store_dwordx2 v146, v[136:137], s[66:67] offset:1024
	v_pk_mul_f32 v[140:141], v[140:141], v[204:205] op_sel_hi:[1,0]
	v_pk_mul_f32 v[142:143], v[142:143], v[204:205] op_sel_hi:[1,0]
	v_pk_mul_f32 v[140:141], v[200:201], v[140:141]
	v_pk_mul_f32 v[142:143], v[202:203], v[142:143]
	v_pk_fma_f32 v[140:141], v[46:47], v[140:141], v[236:237]
	v_pk_fma_f32 v[142:143], v[48:49], v[142:143], v[238:239]
	v_cvt_pk_bf16_f32 v140, v140, v141
	v_cvt_pk_bf16_f32 v141, v142, v143
	global_store_dwordx2 v146, v[140:141], s[66:67] offset:1536
	v_add_u32_e32 v146, 0x800, v146
	global_load_dwordx4 v[128:131], v144, s[46:47]
	global_load_dwordx4 v[132:135], v144, s[46:47] offset:1024
	global_load_dwordx4 v[136:139], v144, s[46:47] offset:2048
	global_load_dwordx4 v[140:143], v144, s[46:47] offset:3072
	v_add_u32_e32 v144, 0x1000, v144
	s_waitcnt vmcnt(36)
	v_pk_mul_f32 v[242:243], v[156:157], v[156:157]
	v_pk_mul_f32 v[244:245], v[160:161], v[160:161]
	v_pk_mul_f32 v[246:247], v[158:159], v[158:159]
	v_pk_mul_f32 v[248:249], v[162:163], v[162:163]
	v_add_f32_e32 v204, v245, v244
	v_add_f32_e32 v205, v243, v242
	v_add_f32_e32 v204, v248, v204
	v_add_f32_e32 v205, v246, v205
	v_add_f32_e32 v204, v249, v204
	v_add_f32_e32 v205, v247, v205
	v_pk_mul_f32 v[242:243], v[164:165], v[164:165]
	v_pk_mul_f32 v[244:245], v[168:169], v[168:169]
	v_pk_mul_f32 v[246:247], v[166:167], v[166:167]
	v_pk_mul_f32 v[248:249], v[170:171], v[170:171]
	v_add_f32_e32 v206, v243, v242
	v_add_f32_e32 v207, v245, v244
	v_add_f32_e32 v206, v246, v206
	v_add_f32_e32 v207, v248, v207
	v_add_f32_e32 v206, v247, v206
	v_add_f32_e32 v207, v249, v207
	v_add_f32_e32 v204, v205, v204
	v_add_f32_e32 v204, v204, v206
	v_add_f32_e32 v204, v204, v207
	ds_swizzle_b32 v205, v204 offset:swizzle(SWAP,1)
	s_waitcnt lgkmcnt(0)
	v_add_f32_e32 v204, v204, v205
	ds_swizzle_b32 v205, v204 offset:swizzle(SWAP,2)
	s_waitcnt lgkmcnt(0)
	v_add_f32_e32 v204, v204, v205
	ds_swizzle_b32 v205, v204 offset:swizzle(SWAP,4)
	s_waitcnt lgkmcnt(0)
	v_add_f32_e32 v204, v204, v205
	ds_swizzle_b32 v205, v204 offset:swizzle(SWAP,8)
	s_waitcnt lgkmcnt(0)
	v_add_f32_e32 v204, v204, v205
	ds_swizzle_b32 v205, v204 offset:swizzle(SWAP,16)
	s_waitcnt lgkmcnt(0)
	v_add_f32_e32 v204, v204, v205
	v_mov_b32_e32 v205, v204
	s_nop 1
	v_permlane32_swap_b32_e32 v204, v205
	v_add_f32_e32 v204, v204, v205
	v_mov_b32_e32 v205, 0x358637bd
	v_fmamk_f32 v204, v204, 0x3a800000, v205
	v_rsq_f32_e32 v204, v204
	s_nop 0
	v_pk_mul_f32 v[156:157], v[156:157], v[204:205] op_sel_hi:[1,0]
	v_pk_mul_f32 v[158:159], v[158:159], v[204:205] op_sel_hi:[1,0]
	v_pk_mul_f32 v[156:157], v[188:189], v[156:157]
	v_pk_mul_f32 v[158:159], v[190:191], v[158:159]
	v_pk_fma_f32 v[156:157], v[34:35], v[156:157], v[224:225]
	v_pk_fma_f32 v[158:159], v[36:37], v[158:159], v[226:227]
	v_cvt_pk_bf16_f32 v156, v156, v157
	v_cvt_pk_bf16_f32 v157, v158, v159
	global_store_dwordx2 v146, v[156:157], s[66:67]
	v_pk_mul_f32 v[160:161], v[160:161], v[204:205] op_sel_hi:[1,0]
	v_pk_mul_f32 v[162:163], v[162:163], v[204:205] op_sel_hi:[1,0]
	v_pk_mul_f32 v[160:161], v[192:193], v[160:161]
	v_pk_mul_f32 v[162:163], v[194:195], v[162:163]
	v_pk_fma_f32 v[160:161], v[38:39], v[160:161], v[228:229]
	v_pk_fma_f32 v[162:163], v[40:41], v[162:163], v[230:231]
	v_cvt_pk_bf16_f32 v160, v160, v161
	v_cvt_pk_bf16_f32 v161, v162, v163
	global_store_dwordx2 v146, v[160:161], s[66:67] offset:512
	v_pk_mul_f32 v[164:165], v[164:165], v[204:205] op_sel_hi:[1,0]
	v_pk_mul_f32 v[166:167], v[166:167], v[204:205] op_sel_hi:[1,0]
	v_pk_mul_f32 v[164:165], v[196:197], v[164:165]
	v_pk_mul_f32 v[166:167], v[198:199], v[166:167]
	v_pk_fma_f32 v[164:165], v[42:43], v[164:165], v[232:233]
	v_pk_fma_f32 v[166:167], v[44:45], v[166:167], v[234:235]
	v_cvt_pk_bf16_f32 v164, v164, v165
	v_cvt_pk_bf16_f32 v165, v166, v167
	global_store_dwordx2 v146, v[164:165], s[66:67] offset:1024
	v_pk_mul_f32 v[168:169], v[168:169], v[204:205] op_sel_hi:[1,0]
	v_pk_mul_f32 v[170:171], v[170:171], v[204:205] op_sel_hi:[1,0]
	v_pk_mul_f32 v[168:169], v[200:201], v[168:169]
	v_pk_mul_f32 v[170:171], v[202:203], v[170:171]
	v_pk_fma_f32 v[168:169], v[46:47], v[168:169], v[236:237]
	v_pk_fma_f32 v[170:171], v[48:49], v[170:171], v[238:239]
	v_cvt_pk_bf16_f32 v168, v168, v169
	v_cvt_pk_bf16_f32 v169, v170, v171
	global_store_dwordx2 v146, v[168:169], s[66:67] offset:1536
	v_add_u32_e32 v146, 0x800, v146
	global_load_dwordx4 v[156:159], v144, s[46:47]
	global_load_dwordx4 v[160:163], v144, s[46:47] offset:1024
	global_load_dwordx4 v[164:167], v144, s[46:47] offset:2048
	global_load_dwordx4 v[168:171], v144, s[46:47] offset:3072
	v_add_u32_e32 v144, 0x1000, v144
	s_waitcnt vmcnt(40)
; __device__ __forceinline__ unsigned pk2(float lo, float hi) { const g_f32x2 f = {lo, hi}; return __builtin_bit_cast(unsigned, __builtin_convertvector(f, g_bf16x2)); }
; __device__ __forceinline__ void p_norm(const float* hlat, const float* hctx, const float* g, const float* modl, int sh_off, int sc_off, bf16_t* A, int M,
;                                        const float* part, const float* cgate, float* hcout) {
;     ...
;         float ss = 0.f;
; #pragma unroll
;         for (int i = 0; i < 4; ++i) {
;             if (part != nullptr && row >= NLAT) {
;                 const size_t po = (size_t)(row - NLAT) * 1024 + i * 256 + lane * 4;
;                 const float4 p0 = *(const float4*)(part + po), p1 = *(const float4*)(part + (size_t)4096 * 1024 + po), cg = *(const float4*)(cgate + i * 256 + lane * 4);
;                 v[i].x += cg.x * (p0.x + p1.x); v[i].y += cg.y * (p0.y + p1.y); v[i].z += cg.z * (p0.z + p1.z); v[i].w += cg.w * (p0.w + p1.w);
;                 *(float4*)(hcout + po) = v[i];
;             }
;             ss += v[i].x * v[i].x + v[i].y * v[i].y + v[i].z * v[i].z + v[i].w * v[i].w; }
;         ss = wave_sum(ss);
;         const float rstd = rsqrtf(ss * (1.0f / 1024.0f) + EPS);
;         const float* mr = modl + (size_t)r * 6144;
; #pragma unroll
;         for (int i = 0; i < 4; ++i) {
;             const int k = i * 256 + lane * 4;
;             const float4 gg = *(const float4*)(g + k), scv = *(const float4*)(mr + sc_off + k), shv = *(const float4*)(mr + sh_off + k);
;             const float o0 = v[i].x * rstd * gg.x * (1.0f + scv.x) + shv.x, o1 = v[i].y * rstd * gg.y * (1.0f + scv.y) + shv.y;
;             const float o2 = v[i].z * rstd * gg.z * (1.0f + scv.z) + shv.z, o3 = v[i].w * rstd * gg.w * (1.0f + scv.w) + shv.w;
;             uint2 w; w.x = pk2(o0, o1); w.y = pk2(o2, o3);
;             *(uint2*)(A + (size_t)row * 1024 + k) = w;
;         }
; #pragma unroll
;         for (int i = 0; i < 4; ++i) v[i] = nv[i];
;         row = nrow;
	v_pk_mul_f32 v[242:243], v[172:173], v[172:173]
	v_pk_mul_f32 v[244:245], v[176:177], v[176:177]
	v_pk_mul_f32 v[246:247], v[174:175], v[174:175]
	v_pk_mul_f32 v[248:249], v[178:179], v[178:179]
	v_add_f32_e32 v204, v245, v244
	v_add_f32_e32 v205, v243, v242
	v_add_f32_e32 v204, v248, v204
	v_add_f32_e32 v205, v246, v205
	v_add_f32_e32 v204, v249, v204
	v_add_f32_e32 v205, v247, v205
	v_pk_mul_f32 v[242:243], v[180:181], v[180:181]
	v_pk_mul_f32 v[244:245], v[184:185], v[184:185]
	v_pk_mul_f32 v[246:247], v[182:183], v[182:183]
	v_pk_mul_f32 v[248:249], v[186:187], v[186:187]
	v_add_f32_e32 v206, v243, v242
	v_add_f32_e32 v207, v245, v244
	v_add_f32_e32 v206, v246, v206
	v_add_f32_e32 v207, v248, v207
	v_add_f32_e32 v206, v247, v206
	v_add_f32_e32 v207, v249, v207
	v_add_f32_e32 v204, v205, v204
	v_add_f32_e32 v204, v204, v206
	v_add_f32_e32 v204, v204, v207
	ds_swizzle_b32 v205, v204 offset:swizzle(SWAP,1)
	s_waitcnt lgkmcnt(0)
	v_add_f32_e32 v204, v204, v205
	ds_swizzle_b32 v205, v204 offset:swizzle(SWAP,2)
	s_waitcnt lgkmcnt(0)
	v_add_f32_e32 v204, v204, v205
	ds_swizzle_b32 v205, v204 offset:swizzle(SWAP,4)
	s_waitcnt lgkmcnt(0)
	v_add_f32_e32 v204, v204, v205
	ds_swizzle_b32 v205, v204 offset:swizzle(SWAP,8)
	s_waitcnt lgkmcnt(0)
	v_add_f32_e32 v204, v204, v205
	ds_swizzle_b32 v205, v204 offset:swizzle(SWAP,16)
	s_waitcnt lgkmcnt(0)
	v_add_f32_e32 v204, v204, v205
	v_mov_b32_e32 v205, v204
	s_nop 1
	v_permlane32_swap_b32_e32 v204, v205
	v_add_f32_e32 v204, v204, v205
	v_mov_b32_e32 v205, 0x358637bd
	v_fmamk_f32 v204, v204, 0x3a800000, v205
	v_rsq_f32_e32 v204, v204
	s_nop 0
	v_pk_mul_f32 v[172:173], v[172:173], v[204:205] op_sel_hi:[1,0]
	v_pk_mul_f32 v[174:175], v[174:175], v[204:205] op_sel_hi:[1,0]
	v_pk_mul_f32 v[172:173], v[188:189], v[172:173]
	v_pk_mul_f32 v[174:175], v[190:191], v[174:175]
	v_pk_fma_f32 v[172:173], v[34:35], v[172:173], v[224:225]
	v_pk_fma_f32 v[174:175], v[36:37], v[174:175], v[226:227]
	v_cvt_pk_bf16_f32 v172, v172, v173
	v_cvt_pk_bf16_f32 v173, v174, v175
	global_store_dwordx2 v146, v[172:173], s[66:67]
	v_pk_mul_f32 v[176:177], v[176:177], v[204:205] op_sel_hi:[1,0]
	v_pk_mul_f32 v[178:179], v[178:179], v[204:205] op_sel_hi:[1,0]
	v_pk_mul_f32 v[176:177], v[192:193], v[176:177]
	v_pk_mul_f32 v[178:179], v[194:195], v[178:179]
	v_pk_fma_f32 v[176:177], v[38:39], v[176:177], v[228:229]
	v_pk_fma_f32 v[178:179], v[40:41], v[178:179], v[230:231]
	v_cvt_pk_bf16_f32 v176, v176, v177
	v_cvt_pk_bf16_f32 v177, v178, v179
	global_store_dwordx2 v146, v[176:177], s[66:67] offset:512
	v_pk_mul_f32 v[180:181], v[180:181], v[204:205] op_sel_hi:[1,0]
	v_pk_mul_f32 v[182:183], v[182:183], v[204:205] op_sel_hi:[1,0]
	v_pk_mul_f32 v[180:181], v[196:197], v[180:181]
	v_pk_mul_f32 v[182:183], v[198:199], v[182:183]
	v_pk_fma_f32 v[180:181], v[42:43], v[180:181], v[232:233]
	v_pk_fma_f32 v[182:183], v[44:45], v[182:183], v[234:235]
	v_cvt_pk_bf16_f32 v180, v180, v181
	v_cvt_pk_bf16_f32 v181, v182, v183
	global_store_dwordx2 v146, v[180:181], s[66:67] offset:1024
	v_pk_mul_f32 v[184:185], v[184:185], v[204:205] op_sel_hi:[1,0]
	v_pk_mul_f32 v[186:187], v[186:187], v[204:205] op_sel_hi:[1,0]
	v_pk_mul_f32 v[184:185], v[200:201], v[184:185]
	v_pk_mul_f32 v[186:187], v[202:203], v[186:187]
	v_pk_fma_f32 v[184:185], v[46:47], v[184:185], v[236:237]
	v_pk_fma_f32 v[186:187], v[48:49], v[186:187], v[238:239]
	v_cvt_pk_bf16_f32 v184, v184, v185
	v_cvt_pk_bf16_f32 v185, v186, v187
	global_store_dwordx2 v146, v[184:185], s[66:67] offset:1536
	v_add_u32_e32 v146, 0x800, v146
	global_load_dwordx4 v[172:175], v144, s[46:47]
	global_load_dwordx4 v[176:179], v144, s[46:47] offset:1024
	global_load_dwordx4 v[180:183], v144, s[46:47] offset:2048
	global_load_dwordx4 v[184:187], v144, s[46:47] offset:3072
	v_add_u32_e32 v144, 0x1000, v144
	s_waitcnt vmcnt(40)
	v_pk_mul_f32 v[242:243], v[80:81], v[80:81]
	v_pk_mul_f32 v[244:245], v[84:85], v[84:85]
	v_pk_mul_f32 v[246:247], v[82:83], v[82:83]
	v_pk_mul_f32 v[248:249], v[86:87], v[86:87]
	v_add_f32_e32 v204, v245, v244
	v_add_f32_e32 v205, v243, v242
	v_add_f32_e32 v204, v248, v204
	v_add_f32_e32 v205, v246, v205
	v_add_f32_e32 v204, v249, v204
	v_add_f32_e32 v205, v247, v205
	v_pk_mul_f32 v[242:243], v[88:89], v[88:89]
	v_pk_mul_f32 v[244:245], v[92:93], v[92:93]
	v_pk_mul_f32 v[246:247], v[90:91], v[90:91]
	v_pk_mul_f32 v[248:249], v[94:95], v[94:95]
	v_add_f32_e32 v206, v243, v242
	v_add_f32_e32 v207, v245, v244
	v_add_f32_e32 v206, v246, v206
	v_add_f32_e32 v207, v248, v207
	v_add_f32_e32 v206, v247, v206
	v_add_f32_e32 v207, v249, v207
	v_add_f32_e32 v204, v205, v204
	v_add_f32_e32 v204, v204, v206
	v_add_f32_e32 v204, v204, v207
	ds_swizzle_b32 v205, v204 offset:swizzle(SWAP,1)
	s_waitcnt lgkmcnt(0)
	v_add_f32_e32 v204, v204, v205
	ds_swizzle_b32 v205, v204 offset:swizzle(SWAP,2)
	s_waitcnt lgkmcnt(0)
	v_add_f32_e32 v204, v204, v205
	ds_swizzle_b32 v205, v204 offset:swizzle(SWAP,4)
	s_waitcnt lgkmcnt(0)
	v_add_f32_e32 v204, v204, v205
	ds_swizzle_b32 v205, v204 offset:swizzle(SWAP,8)
	s_waitcnt lgkmcnt(0)
	v_add_f32_e32 v204, v204, v205
	ds_swizzle_b32 v205, v204 offset:swizzle(SWAP,16)
	s_waitcnt lgkmcnt(0)
; __device__ __forceinline__ unsigned pk2(float lo, float hi) { const g_f32x2 f = {lo, hi}; return __builtin_bit_cast(unsigned, __builtin_convertvector(f, g_bf16x2)); }
; __device__ __forceinline__ void p_norm(const float* hlat, const float* hctx, const float* g, const float* modl, int sh_off, int sc_off, bf16_t* A, int M,
;                                        const float* part, const float* cgate, float* hcout) {
;     ...
;         float ss = 0.f;
; #pragma unroll
;         for (int i = 0; i < 4; ++i) {
;             if (part != nullptr && row >= NLAT) {
;                 const size_t po = (size_t)(row - NLAT) * 1024 + i * 256 + lane * 4;
;                 const float4 p0 = *(const float4*)(part + po), p1 = *(const float4*)(part + (size_t)4096 * 1024 + po), cg = *(const float4*)(cgate + i * 256 + lane * 4);
;                 v[i].x += cg.x * (p0.x + p1.x); v[i].y += cg.y * (p0.y + p1.y); v[i].z += cg.z * (p0.z + p1.z); v[i].w += cg.w * (p0.w + p1.w);
;                 *(float4*)(hcout + po) = v[i];
;             }
;             ss += v[i].x * v[i].x + v[i].y * v[i].y + v[i].z * v[i].z + v[i].w * v[i].w; }
;         ss = wave_sum(ss);
;         const float rstd = rsqrtf(ss * (1.0f / 1024.0f) + EPS);
;         const float* mr = modl + (size_t)r * 6144;
; #pragma unroll
;         for (int i = 0; i < 4; ++i) {
;             const int k = i * 256 + lane * 4;
;             const float4 gg = *(const float4*)(g + k), scv = *(const float4*)(mr + sc_off + k), shv = *(const float4*)(mr + sh_off + k);
;             const float o0 = v[i].x * rstd * gg.x * (1.0f + scv.x) + shv.x, o1 = v[i].y * rstd * gg.y * (1.0f + scv.y) + shv.y;
;             const float o2 = v[i].z * rstd * gg.z * (1.0f + scv.z) + shv.z, o3 = v[i].w * rstd * gg.w * (1.0f + scv.w) + shv.w;
;             uint2 w; w.x = pk2(o0, o1); w.y = pk2(o2, o3);
;             *(uint2*)(A + (size_t)row * 1024 + k) = w;
;         }
; #pragma unroll
;         for (int i = 0; i < 4; ++i) v[i] = nv[i];
;         row = nrow;
	v_add_f32_e32 v204, v204, v205
	v_mov_b32_e32 v205, v204
	s_nop 1
	v_permlane32_swap_b32_e32 v204, v205
	v_add_f32_e32 v204, v204, v205
	v_mov_b32_e32 v205, 0x358637bd
	v_fmamk_f32 v204, v204, 0x3a800000, v205
	v_rsq_f32_e32 v204, v204
	s_nop 0
	v_pk_mul_f32 v[80:81], v[80:81], v[204:205] op_sel_hi:[1,0]
	v_pk_mul_f32 v[82:83], v[82:83], v[204:205] op_sel_hi:[1,0]
	v_pk_mul_f32 v[80:81], v[188:189], v[80:81]
	v_pk_mul_f32 v[82:83], v[190:191], v[82:83]
	v_pk_fma_f32 v[80:81], v[34:35], v[80:81], v[224:225]
	v_pk_fma_f32 v[82:83], v[36:37], v[82:83], v[226:227]
	v_cvt_pk_bf16_f32 v80, v80, v81
	v_cvt_pk_bf16_f32 v81, v82, v83
	global_store_dwordx2 v146, v[80:81], s[66:67]
	v_pk_mul_f32 v[84:85], v[84:85], v[204:205] op_sel_hi:[1,0]
	v_pk_mul_f32 v[86:87], v[86:87], v[204:205] op_sel_hi:[1,0]
	v_pk_mul_f32 v[84:85], v[192:193], v[84:85]
	v_pk_mul_f32 v[86:87], v[194:195], v[86:87]
	v_pk_fma_f32 v[84:85], v[38:39], v[84:85], v[228:229]
	v_pk_fma_f32 v[86:87], v[40:41], v[86:87], v[230:231]
	v_cvt_pk_bf16_f32 v84, v84, v85
	v_cvt_pk_bf16_f32 v85, v86, v87
	global_store_dwordx2 v146, v[84:85], s[66:67] offset:512
	v_pk_mul_f32 v[88:89], v[88:89], v[204:205] op_sel_hi:[1,0]
	v_pk_mul_f32 v[90:91], v[90:91], v[204:205] op_sel_hi:[1,0]
	v_pk_mul_f32 v[88:89], v[196:197], v[88:89]
	v_pk_mul_f32 v[90:91], v[198:199], v[90:91]
	v_pk_fma_f32 v[88:89], v[42:43], v[88:89], v[232:233]
	v_pk_fma_f32 v[90:91], v[44:45], v[90:91], v[234:235]
	v_cvt_pk_bf16_f32 v88, v88, v89
	v_cvt_pk_bf16_f32 v89, v90, v91
	global_store_dwordx2 v146, v[88:89], s[66:67] offset:1024
	v_pk_mul_f32 v[92:93], v[92:93], v[204:205] op_sel_hi:[1,0]
	v_pk_mul_f32 v[94:95], v[94:95], v[204:205] op_sel_hi:[1,0]
	v_pk_mul_f32 v[92:93], v[200:201], v[92:93]
	v_pk_mul_f32 v[94:95], v[202:203], v[94:95]
	v_pk_fma_f32 v[92:93], v[46:47], v[92:93], v[236:237]
	v_pk_fma_f32 v[94:95], v[48:49], v[94:95], v[238:239]
	v_cvt_pk_bf16_f32 v92, v92, v93
	v_cvt_pk_bf16_f32 v93, v94, v95
	global_store_dwordx2 v146, v[92:93], s[66:67] offset:1536
	v_add_u32_e32 v146, 0x800, v146
	global_load_dwordx4 v[80:83], v144, s[46:47]
	global_load_dwordx4 v[84:87], v144, s[46:47] offset:1024
	global_load_dwordx4 v[88:91], v144, s[46:47] offset:2048
	global_load_dwordx4 v[92:95], v144, s[46:47] offset:3072
	v_add_u32_e32 v144, 0x1000, v144
	s_waitcnt vmcnt(40)
	v_pk_mul_f32 v[242:243], v[96:97], v[96:97]
	v_pk_mul_f32 v[244:245], v[100:101], v[100:101]
	v_pk_mul_f32 v[246:247], v[98:99], v[98:99]
	v_pk_mul_f32 v[248:249], v[102:103], v[102:103]
	v_add_f32_e32 v204, v245, v244
	v_add_f32_e32 v205, v243, v242
	v_add_f32_e32 v204, v248, v204
	v_add_f32_e32 v205, v246, v205
	v_add_f32_e32 v204, v249, v204
	v_add_f32_e32 v205, v247, v205
	v_pk_mul_f32 v[242:243], v[104:105], v[104:105]
	v_pk_mul_f32 v[244:245], v[108:109], v[108:109]
	v_pk_mul_f32 v[246:247], v[106:107], v[106:107]
	v_pk_mul_f32 v[248:249], v[110:111], v[110:111]
	v_add_f32_e32 v206, v243, v242
	v_add_f32_e32 v207, v245, v244
	v_add_f32_e32 v206, v246, v206
	v_add_f32_e32 v207, v248, v207
	v_add_f32_e32 v206, v247, v206
	v_add_f32_e32 v207, v249, v207
	v_add_f32_e32 v204, v205, v204
	v_add_f32_e32 v204, v204, v206
	v_add_f32_e32 v204, v204, v207
	ds_swizzle_b32 v205, v204 offset:swizzle(SWAP,1)
	s_waitcnt lgkmcnt(0)
	v_add_f32_e32 v204, v204, v205
	ds_swizzle_b32 v205, v204 offset:swizzle(SWAP,2)
	s_waitcnt lgkmcnt(0)
	v_add_f32_e32 v204, v204, v205
	ds_swizzle_b32 v205, v204 offset:swizzle(SWAP,4)
	s_waitcnt lgkmcnt(0)
	v_add_f32_e32 v204, v204, v205
	ds_swizzle_b32 v205, v204 offset:swizzle(SWAP,8)
	s_waitcnt lgkmcnt(0)
	v_add_f32_e32 v204, v204, v205
	ds_swizzle_b32 v205, v204 offset:swizzle(SWAP,16)
	s_waitcnt lgkmcnt(0)
	v_add_f32_e32 v204, v204, v205
	v_mov_b32_e32 v205, v204
	s_nop 1
	v_permlane32_swap_b32_e32 v204, v205
	v_add_f32_e32 v204, v204, v205
	v_mov_b32_e32 v205, 0x358637bd
	v_fmamk_f32 v204, v204, 0x3a800000, v205
	v_rsq_f32_e32 v204, v204
	s_nop 0
	v_pk_mul_f32 v[96:97], v[96:97], v[204:205] op_sel_hi:[1,0]
	v_pk_mul_f32 v[98:99], v[98:99], v[204:205] op_sel_hi:[1,0]
	v_pk_mul_f32 v[96:97], v[188:189], v[96:97]
	v_pk_mul_f32 v[98:99], v[190:191], v[98:99]
	v_pk_fma_f32 v[96:97], v[34:35], v[96:97], v[224:225]
	v_pk_fma_f32 v[98:99], v[36:37], v[98:99], v[226:227]
	v_cvt_pk_bf16_f32 v96, v96, v97
	v_cvt_pk_bf16_f32 v97, v98, v99
	global_store_dwordx2 v146, v[96:97], s[66:67]
	v_pk_mul_f32 v[100:101], v[100:101], v[204:205] op_sel_hi:[1,0]
	v_pk_mul_f32 v[102:103], v[102:103], v[204:205] op_sel_hi:[1,0]
	v_pk_mul_f32 v[100:101], v[192:193], v[100:101]
	v_pk_mul_f32 v[102:103], v[194:195], v[102:103]
	v_pk_fma_f32 v[100:101], v[38:39], v[100:101], v[228:229]
	v_pk_fma_f32 v[102:103], v[40:41], v[102:103], v[230:231]
	v_cvt_pk_bf16_f32 v100, v100, v101
	v_cvt_pk_bf16_f32 v101, v102, v103
	global_store_dwordx2 v146, v[100:101], s[66:67] offset:512
	v_pk_mul_f32 v[104:105], v[104:105], v[204:205] op_sel_hi:[1,0]
	v_pk_mul_f32 v[106:107], v[106:107], v[204:205] op_sel_hi:[1,0]
	v_pk_mul_f32 v[104:105], v[196:197], v[104:105]
	v_pk_mul_f32 v[106:107], v[198:199], v[106:107]
	v_pk_fma_f32 v[104:105], v[42:43], v[104:105], v[232:233]
	v_pk_fma_f32 v[106:107], v[44:45], v[106:107], v[234:235]
	v_cvt_pk_bf16_f32 v104, v104, v105
	v_cvt_pk_bf16_f32 v105, v106, v107
	global_store_dwordx2 v146, v[104:105], s[66:67] offset:1024
	v_pk_mul_f32 v[108:109], v[108:109], v[204:205] op_sel_hi:[1,0]
	v_pk_mul_f32 v[110:111], v[110:111], v[204:205] op_sel_hi:[1,0]
	v_pk_mul_f32 v[108:109], v[200:201], v[108:109]
	v_pk_mul_f32 v[110:111], v[202:203], v[110:111]
	v_pk_fma_f32 v[108:109], v[46:47], v[108:109], v[236:237]
	v_pk_fma_f32 v[110:111], v[48:49], v[110:111], v[238:239]
	v_cvt_pk_bf16_f32 v108, v108, v109
	v_cvt_pk_bf16_f32 v109, v110, v111
	global_store_dwordx2 v146, v[108:109], s[66:67] offset:1536
	v_add_u32_e32 v146, 0x800, v146
	global_load_dwordx4 v[96:99], v144, s[46:47]
	global_load_dwordx4 v[100:103], v144, s[46:47] offset:1024
	global_load_dwordx4 v[104:107], v144, s[46:47] offset:2048
	global_load_dwordx4 v[108:111], v144, s[46:47] offset:3072
	v_add_u32_e32 v144, 0x1000, v144
	s_waitcnt vmcnt(40)
; __device__ __forceinline__ unsigned pk2(float lo, float hi) { const g_f32x2 f = {lo, hi}; return __builtin_bit_cast(unsigned, __builtin_convertvector(f, g_bf16x2)); }
; __device__ __forceinline__ void p_norm(const float* hlat, const float* hctx, const float* g, const float* modl, int sh_off, int sc_off, bf16_t* A, int M,
;                                        const float* part, const float* cgate, float* hcout) {
;     ...
;         float ss = 0.f;
; #pragma unroll
;         for (int i = 0; i < 4; ++i) {
;             if (part != nullptr && row >= NLAT) {
;                 const size_t po = (size_t)(row - NLAT) * 1024 + i * 256 + lane * 4;
;                 const float4 p0 = *(const float4*)(part + po), p1 = *(const float4*)(part + (size_t)4096 * 1024 + po), cg = *(const float4*)(cgate + i * 256 + lane * 4);
;                 v[i].x += cg.x * (p0.x + p1.x); v[i].y += cg.y * (p0.y + p1.y); v[i].z += cg.z * (p0.z + p1.z); v[i].w += cg.w * (p0.w + p1.w);
;                 *(float4*)(hcout + po) = v[i];
;             }
;             ss += v[i].x * v[i].x + v[i].y * v[i].y + v[i].z * v[i].z + v[i].w * v[i].w; }
;         ss = wave_sum(ss);
;         const float rstd = rsqrtf(ss * (1.0f / 1024.0f) + EPS);
;         const float* mr = modl + (size_t)r * 6144;
; #pragma unroll
;         for (int i = 0; i < 4; ++i) {
;             const int k = i * 256 + lane * 4;
;             const float4 gg = *(const float4*)(g + k), scv = *(const float4*)(mr + sc_off + k), shv = *(const float4*)(mr + sh_off + k);
;             const float o0 = v[i].x * rstd * gg.x * (1.0f + scv.x) + shv.x, o1 = v[i].y * rstd * gg.y * (1.0f + scv.y) + shv.y;
;             const float o2 = v[i].z * rstd * gg.z * (1.0f + scv.z) + shv.z, o3 = v[i].w * rstd * gg.w * (1.0f + scv.w) + shv.w;
;             uint2 w; w.x = pk2(o0, o1); w.y = pk2(o2, o3);
;             *(uint2*)(A + (size_t)row * 1024 + k) = w;
;         }
; #pragma unroll
;         for (int i = 0; i < 4; ++i) v[i] = nv[i];
;         row = nrow;
	v_pk_mul_f32 v[242:243], v[112:113], v[112:113]
	v_pk_mul_f32 v[244:245], v[116:117], v[116:117]
	v_pk_mul_f32 v[246:247], v[114:115], v[114:115]
	v_pk_mul_f32 v[248:249], v[118:119], v[118:119]
	v_add_f32_e32 v204, v245, v244
	v_add_f32_e32 v205, v243, v242
	v_add_f32_e32 v204, v248, v204
	v_add_f32_e32 v205, v246, v205
	v_add_f32_e32 v204, v249, v204
	v_add_f32_e32 v205, v247, v205
	v_pk_mul_f32 v[242:243], v[120:121], v[120:121]
	v_pk_mul_f32 v[244:245], v[124:125], v[124:125]
	v_pk_mul_f32 v[246:247], v[122:123], v[122:123]
	v_pk_mul_f32 v[248:249], v[126:127], v[126:127]
	v_add_f32_e32 v206, v243, v242
	v_add_f32_e32 v207, v245, v244
	v_add_f32_e32 v206, v246, v206
	v_add_f32_e32 v207, v248, v207
	v_add_f32_e32 v206, v247, v206
	v_add_f32_e32 v207, v249, v207
	v_add_f32_e32 v204, v205, v204
	v_add_f32_e32 v204, v204, v206
	v_add_f32_e32 v204, v204, v207
	ds_swizzle_b32 v205, v204 offset:swizzle(SWAP,1)
	s_waitcnt lgkmcnt(0)
	v_add_f32_e32 v204, v204, v205
	ds_swizzle_b32 v205, v204 offset:swizzle(SWAP,2)
	s_waitcnt lgkmcnt(0)
	v_add_f32_e32 v204, v204, v205
	ds_swizzle_b32 v205, v204 offset:swizzle(SWAP,4)
	s_waitcnt lgkmcnt(0)
	v_add_f32_e32 v204, v204, v205
	ds_swizzle_b32 v205, v204 offset:swizzle(SWAP,8)
	s_waitcnt lgkmcnt(0)
	v_add_f32_e32 v204, v204, v205
	ds_swizzle_b32 v205, v204 offset:swizzle(SWAP,16)
	s_waitcnt lgkmcnt(0)
	v_add_f32_e32 v204, v204, v205
	v_mov_b32_e32 v205, v204
	s_nop 1
	v_permlane32_swap_b32_e32 v204, v205
	v_add_f32_e32 v204, v204, v205
	v_mov_b32_e32 v205, 0x358637bd
	v_fmamk_f32 v204, v204, 0x3a800000, v205
	v_rsq_f32_e32 v204, v204
	s_nop 0
	v_pk_mul_f32 v[112:113], v[112:113], v[204:205] op_sel_hi:[1,0]
	v_pk_mul_f32 v[114:115], v[114:115], v[204:205] op_sel_hi:[1,0]
	v_pk_mul_f32 v[112:113], v[188:189], v[112:113]
	v_pk_mul_f32 v[114:115], v[190:191], v[114:115]
	v_pk_fma_f32 v[112:113], v[34:35], v[112:113], v[224:225]
	v_pk_fma_f32 v[114:115], v[36:37], v[114:115], v[226:227]
	v_cvt_pk_bf16_f32 v112, v112, v113
	v_cvt_pk_bf16_f32 v113, v114, v115
	global_store_dwordx2 v146, v[112:113], s[66:67]
	v_pk_mul_f32 v[116:117], v[116:117], v[204:205] op_sel_hi:[1,0]
	v_pk_mul_f32 v[118:119], v[118:119], v[204:205] op_sel_hi:[1,0]
	v_pk_mul_f32 v[116:117], v[192:193], v[116:117]
	v_pk_mul_f32 v[118:119], v[194:195], v[118:119]
	v_pk_fma_f32 v[116:117], v[38:39], v[116:117], v[228:229]
	v_pk_fma_f32 v[118:119], v[40:41], v[118:119], v[230:231]
	v_cvt_pk_bf16_f32 v116, v116, v117
	v_cvt_pk_bf16_f32 v117, v118, v119
	global_store_dwordx2 v146, v[116:117], s[66:67] offset:512
	v_pk_mul_f32 v[120:121], v[120:121], v[204:205] op_sel_hi:[1,0]
	v_pk_mul_f32 v[122:123], v[122:123], v[204:205] op_sel_hi:[1,0]
	v_pk_mul_f32 v[120:121], v[196:197], v[120:121]
	v_pk_mul_f32 v[122:123], v[198:199], v[122:123]
	v_pk_fma_f32 v[120:121], v[42:43], v[120:121], v[232:233]
	v_pk_fma_f32 v[122:123], v[44:45], v[122:123], v[234:235]
	v_cvt_pk_bf16_f32 v120, v120, v121
	v_cvt_pk_bf16_f32 v121, v122, v123
	global_store_dwordx2 v146, v[120:121], s[66:67] offset:1024
	v_pk_mul_f32 v[124:125], v[124:125], v[204:205] op_sel_hi:[1,0]
	v_pk_mul_f32 v[126:127], v[126:127], v[204:205] op_sel_hi:[1,0]
	v_pk_mul_f32 v[124:125], v[200:201], v[124:125]
	v_pk_mul_f32 v[126:127], v[202:203], v[126:127]
	v_pk_fma_f32 v[124:125], v[46:47], v[124:125], v[236:237]
	v_pk_fma_f32 v[126:127], v[48:49], v[126:127], v[238:239]
	v_cvt_pk_bf16_f32 v124, v124, v125
	v_cvt_pk_bf16_f32 v125, v126, v127
	global_store_dwordx2 v146, v[124:125], s[66:67] offset:1536
	v_add_u32_e32 v146, 0x800, v146
	global_load_dwordx4 v[112:115], v144, s[46:47]
	global_load_dwordx4 v[116:119], v144, s[46:47] offset:1024
	global_load_dwordx4 v[120:123], v144, s[46:47] offset:2048
	global_load_dwordx4 v[124:127], v144, s[46:47] offset:3072
	v_add_u32_e32 v144, 0x1000, v144
	s_waitcnt vmcnt(40)
	v_pk_mul_f32 v[242:243], v[128:129], v[128:129]
	v_pk_mul_f32 v[244:245], v[132:133], v[132:133]
	v_pk_mul_f32 v[246:247], v[130:131], v[130:131]
	v_pk_mul_f32 v[248:249], v[134:135], v[134:135]
	v_add_f32_e32 v204, v245, v244
	v_add_f32_e32 v205, v243, v242
	v_add_f32_e32 v204, v248, v204
	v_add_f32_e32 v205, v246, v205
	v_add_f32_e32 v204, v249, v204
	v_add_f32_e32 v205, v247, v205
	v_pk_mul_f32 v[242:243], v[136:137], v[136:137]
	v_pk_mul_f32 v[244:245], v[140:141], v[140:141]
	v_pk_mul_f32 v[246:247], v[138:139], v[138:139]
	v_pk_mul_f32 v[248:249], v[142:143], v[142:143]
	v_add_f32_e32 v206, v243, v242
	v_add_f32_e32 v207, v245, v244
	v_add_f32_e32 v206, v246, v206
	v_add_f32_e32 v207, v248, v207
	v_add_f32_e32 v206, v247, v206
	v_add_f32_e32 v207, v249, v207
	v_add_f32_e32 v204, v205, v204
	v_add_f32_e32 v204, v204, v206
	v_add_f32_e32 v204, v204, v207
	ds_swizzle_b32 v205, v204 offset:swizzle(SWAP,1)
	s_waitcnt lgkmcnt(0)
	v_add_f32_e32 v204, v204, v205
	ds_swizzle_b32 v205, v204 offset:swizzle(SWAP,2)
	s_waitcnt lgkmcnt(0)
	v_add_f32_e32 v204, v204, v205
	ds_swizzle_b32 v205, v204 offset:swizzle(SWAP,4)
	s_waitcnt lgkmcnt(0)
	v_add_f32_e32 v204, v204, v205
	ds_swizzle_b32 v205, v204 offset:swizzle(SWAP,8)
	s_waitcnt lgkmcnt(0)
	v_add_f32_e32 v204, v204, v205
	ds_swizzle_b32 v205, v204 offset:swizzle(SWAP,16)
	s_waitcnt lgkmcnt(0)
; __device__ __forceinline__ unsigned pk2(float lo, float hi) { const g_f32x2 f = {lo, hi}; return __builtin_bit_cast(unsigned, __builtin_convertvector(f, g_bf16x2)); }
; __device__ __forceinline__ void p_norm(const float* hlat, const float* hctx, const float* g, const float* modl, int sh_off, int sc_off, bf16_t* A, int M,
;                                        const float* part, const float* cgate, float* hcout) {
;     ...
;         float ss = 0.f;
; #pragma unroll
;         for (int i = 0; i < 4; ++i) {
;             if (part != nullptr && row >= NLAT) {
;                 const size_t po = (size_t)(row - NLAT) * 1024 + i * 256 + lane * 4;
;                 const float4 p0 = *(const float4*)(part + po), p1 = *(const float4*)(part + (size_t)4096 * 1024 + po), cg = *(const float4*)(cgate + i * 256 + lane * 4);
;                 v[i].x += cg.x * (p0.x + p1.x); v[i].y += cg.y * (p0.y + p1.y); v[i].z += cg.z * (p0.z + p1.z); v[i].w += cg.w * (p0.w + p1.w);
;                 *(float4*)(hcout + po) = v[i];
;             }
;             ss += v[i].x * v[i].x + v[i].y * v[i].y + v[i].z * v[i].z + v[i].w * v[i].w; }
;         ss = wave_sum(ss);
;         const float rstd = rsqrtf(ss * (1.0f / 1024.0f) + EPS);
;         const float* mr = modl + (size_t)r * 6144;
; #pragma unroll
;         for (int i = 0; i < 4; ++i) {
;             const int k = i * 256 + lane * 4;
;             const float4 gg = *(const float4*)(g + k), scv = *(const float4*)(mr + sc_off + k), shv = *(const float4*)(mr + sh_off + k);
;             const float o0 = v[i].x * rstd * gg.x * (1.0f + scv.x) + shv.x, o1 = v[i].y * rstd * gg.y * (1.0f + scv.y) + shv.y;
;             const float o2 = v[i].z * rstd * gg.z * (1.0f + scv.z) + shv.z, o3 = v[i].w * rstd * gg.w * (1.0f + scv.w) + shv.w;
;             uint2 w; w.x = pk2(o0, o1); w.y = pk2(o2, o3);
;             *(uint2*)(A + (size_t)row * 1024 + k) = w;
;         }
; #pragma unroll
;         for (int i = 0; i < 4; ++i) v[i] = nv[i];
;         row = nrow;
	v_add_f32_e32 v204, v204, v205
	v_mov_b32_e32 v205, v204
	s_nop 1
	v_permlane32_swap_b32_e32 v204, v205
	v_add_f32_e32 v204, v204, v205
	v_mov_b32_e32 v205, 0x358637bd
	v_fmamk_f32 v204, v204, 0x3a800000, v205
	v_rsq_f32_e32 v204, v204
	s_nop 0
	v_pk_mul_f32 v[128:129], v[128:129], v[204:205] op_sel_hi:[1,0]
	v_pk_mul_f32 v[130:131], v[130:131], v[204:205] op_sel_hi:[1,0]
	v_pk_mul_f32 v[128:129], v[188:189], v[128:129]
	v_pk_mul_f32 v[130:131], v[190:191], v[130:131]
	v_pk_fma_f32 v[128:129], v[34:35], v[128:129], v[224:225]
	v_pk_fma_f32 v[130:131], v[36:37], v[130:131], v[226:227]
	v_cvt_pk_bf16_f32 v128, v128, v129
	v_cvt_pk_bf16_f32 v129, v130, v131
	global_store_dwordx2 v146, v[128:129], s[66:67]
	v_pk_mul_f32 v[132:133], v[132:133], v[204:205] op_sel_hi:[1,0]
	v_pk_mul_f32 v[134:135], v[134:135], v[204:205] op_sel_hi:[1,0]
	v_pk_mul_f32 v[132:133], v[192:193], v[132:133]
	v_pk_mul_f32 v[134:135], v[194:195], v[134:135]
	v_pk_fma_f32 v[132:133], v[38:39], v[132:133], v[228:229]
	v_pk_fma_f32 v[134:135], v[40:41], v[134:135], v[230:231]
	v_cvt_pk_bf16_f32 v132, v132, v133
	v_cvt_pk_bf16_f32 v133, v134, v135
	global_store_dwordx2 v146, v[132:133], s[66:67] offset:512
	v_pk_mul_f32 v[136:137], v[136:137], v[204:205] op_sel_hi:[1,0]
	v_pk_mul_f32 v[138:139], v[138:139], v[204:205] op_sel_hi:[1,0]
	v_pk_mul_f32 v[136:137], v[196:197], v[136:137]
	v_pk_mul_f32 v[138:139], v[198:199], v[138:139]
	v_pk_fma_f32 v[136:137], v[42:43], v[136:137], v[232:233]
	v_pk_fma_f32 v[138:139], v[44:45], v[138:139], v[234:235]
	v_cvt_pk_bf16_f32 v136, v136, v137
	v_cvt_pk_bf16_f32 v137, v138, v139
	global_store_dwordx2 v146, v[136:137], s[66:67] offset:1024
	v_pk_mul_f32 v[140:141], v[140:141], v[204:205] op_sel_hi:[1,0]
	v_pk_mul_f32 v[142:143], v[142:143], v[204:205] op_sel_hi:[1,0]
	v_pk_mul_f32 v[140:141], v[200:201], v[140:141]
	v_pk_mul_f32 v[142:143], v[202:203], v[142:143]
	v_pk_fma_f32 v[140:141], v[46:47], v[140:141], v[236:237]
	v_pk_fma_f32 v[142:143], v[48:49], v[142:143], v[238:239]
	v_cvt_pk_bf16_f32 v140, v140, v141
	v_cvt_pk_bf16_f32 v141, v142, v143
	global_store_dwordx2 v146, v[140:141], s[66:67] offset:1536
	v_add_u32_e32 v146, 0x800, v146
	global_load_dwordx4 v[128:131], v144, s[46:47]
	global_load_dwordx4 v[132:135], v144, s[46:47] offset:1024
	global_load_dwordx4 v[136:139], v144, s[46:47] offset:2048
	global_load_dwordx4 v[140:143], v144, s[46:47] offset:3072
	v_add_u32_e32 v144, 0x1000, v144
	s_waitcnt vmcnt(40)
	v_pk_mul_f32 v[242:243], v[156:157], v[156:157]
	v_pk_mul_f32 v[244:245], v[160:161], v[160:161]
	v_pk_mul_f32 v[246:247], v[158:159], v[158:159]
	v_pk_mul_f32 v[248:249], v[162:163], v[162:163]
	v_add_f32_e32 v204, v245, v244
	v_add_f32_e32 v205, v243, v242
	v_add_f32_e32 v204, v248, v204
	v_add_f32_e32 v205, v246, v205
	v_add_f32_e32 v204, v249, v204
	v_add_f32_e32 v205, v247, v205
	v_pk_mul_f32 v[242:243], v[164:165], v[164:165]
	v_pk_mul_f32 v[244:245], v[168:169], v[168:169]
	v_pk_mul_f32 v[246:247], v[166:167], v[166:167]
	v_pk_mul_f32 v[248:249], v[170:171], v[170:171]
	v_add_f32_e32 v206, v243, v242
	v_add_f32_e32 v207, v245, v244
	v_add_f32_e32 v206, v246, v206
	v_add_f32_e32 v207, v248, v207
	v_add_f32_e32 v206, v247, v206
	v_add_f32_e32 v207, v249, v207
	v_add_f32_e32 v204, v205, v204
	v_add_f32_e32 v204, v204, v206
	v_add_f32_e32 v204, v204, v207
	ds_swizzle_b32 v205, v204 offset:swizzle(SWAP,1)
	s_waitcnt lgkmcnt(0)
	v_add_f32_e32 v204, v204, v205
	ds_swizzle_b32 v205, v204 offset:swizzle(SWAP,2)
	s_waitcnt lgkmcnt(0)
	v_add_f32_e32 v204, v204, v205
	ds_swizzle_b32 v205, v204 offset:swizzle(SWAP,4)
	s_waitcnt lgkmcnt(0)
	v_add_f32_e32 v204, v204, v205
	ds_swizzle_b32 v205, v204 offset:swizzle(SWAP,8)
	s_waitcnt lgkmcnt(0)
	v_add_f32_e32 v204, v204, v205
	ds_swizzle_b32 v205, v204 offset:swizzle(SWAP,16)
	s_waitcnt lgkmcnt(0)
	v_add_f32_e32 v204, v204, v205
	v_mov_b32_e32 v205, v204
	s_nop 1
	v_permlane32_swap_b32_e32 v204, v205
	v_add_f32_e32 v204, v204, v205
	v_mov_b32_e32 v205, 0x358637bd
	v_fmamk_f32 v204, v204, 0x3a800000, v205
	v_rsq_f32_e32 v204, v204
	s_nop 0
	v_pk_mul_f32 v[156:157], v[156:157], v[204:205] op_sel_hi:[1,0]
	v_pk_mul_f32 v[158:159], v[158:159], v[204:205] op_sel_hi:[1,0]
	v_pk_mul_f32 v[156:157], v[188:189], v[156:157]
	v_pk_mul_f32 v[158:159], v[190:191], v[158:159]
	v_pk_fma_f32 v[156:157], v[34:35], v[156:157], v[224:225]
	v_pk_fma_f32 v[158:159], v[36:37], v[158:159], v[226:227]
	v_cvt_pk_bf16_f32 v156, v156, v157
	v_cvt_pk_bf16_f32 v157, v158, v159
	global_store_dwordx2 v146, v[156:157], s[66:67]
	v_pk_mul_f32 v[160:161], v[160:161], v[204:205] op_sel_hi:[1,0]
	v_pk_mul_f32 v[162:163], v[162:163], v[204:205] op_sel_hi:[1,0]
	v_pk_mul_f32 v[160:161], v[192:193], v[160:161]
	v_pk_mul_f32 v[162:163], v[194:195], v[162:163]
	v_pk_fma_f32 v[160:161], v[38:39], v[160:161], v[228:229]
	v_pk_fma_f32 v[162:163], v[40:41], v[162:163], v[230:231]
	v_cvt_pk_bf16_f32 v160, v160, v161
	v_cvt_pk_bf16_f32 v161, v162, v163
	global_store_dwordx2 v146, v[160:161], s[66:67] offset:512
	v_pk_mul_f32 v[164:165], v[164:165], v[204:205] op_sel_hi:[1,0]
	v_pk_mul_f32 v[166:167], v[166:167], v[204:205] op_sel_hi:[1,0]
	v_pk_mul_f32 v[164:165], v[196:197], v[164:165]
	v_pk_mul_f32 v[166:167], v[198:199], v[166:167]
	v_pk_fma_f32 v[164:165], v[42:43], v[164:165], v[232:233]
	v_pk_fma_f32 v[166:167], v[44:45], v[166:167], v[234:235]
	v_cvt_pk_bf16_f32 v164, v164, v165
	v_cvt_pk_bf16_f32 v165, v166, v167
	global_store_dwordx2 v146, v[164:165], s[66:67] offset:1024
	v_pk_mul_f32 v[168:169], v[168:169], v[204:205] op_sel_hi:[1,0]
	v_pk_mul_f32 v[170:171], v[170:171], v[204:205] op_sel_hi:[1,0]
	v_pk_mul_f32 v[168:169], v[200:201], v[168:169]
	v_pk_mul_f32 v[170:171], v[202:203], v[170:171]
	v_pk_fma_f32 v[168:169], v[46:47], v[168:169], v[236:237]
	v_pk_fma_f32 v[170:171], v[48:49], v[170:171], v[238:239]
	v_cvt_pk_bf16_f32 v168, v168, v169
	v_cvt_pk_bf16_f32 v169, v170, v171
	global_store_dwordx2 v146, v[168:169], s[66:67] offset:1536
	v_add_u32_e32 v146, 0x800, v146
	v_lshl_add_u32 v144, v50, 13, v241
	v_mov_b32_e32 v152, v144
	v_add_u32_e32 v150, 0x1000000, v144
	global_load_dwordx4 v[156:159], v144, s[16:17]
	global_load_dwordx4 v[160:163], v144, s[16:17] offset:1024
	global_load_dwordx4 v[164:167], v144, s[16:17] offset:2048
	global_load_dwordx4 v[168:171], v144, s[16:17] offset:3072
	v_add_u32_e32 v144, 0x1000, v144
	s_waitcnt vmcnt(40)
; __device__ __forceinline__ unsigned pk2(float lo, float hi) { const g_f32x2 f = {lo, hi}; return __builtin_bit_cast(unsigned, __builtin_convertvector(f, g_bf16x2)); }
; __device__ __forceinline__ void p_norm(const float* hlat, const float* hctx, const float* g, const float* modl, int sh_off, int sc_off, bf16_t* A, int M,
;                                        const float* part, const float* cgate, float* hcout) {
;     ...
;         float ss = 0.f;
; #pragma unroll
;         for (int i = 0; i < 4; ++i) {
;             if (part != nullptr && row >= NLAT) {
;                 const size_t po = (size_t)(row - NLAT) * 1024 + i * 256 + lane * 4;
;                 const float4 p0 = *(const float4*)(part + po), p1 = *(const float4*)(part + (size_t)4096 * 1024 + po), cg = *(const float4*)(cgate + i * 256 + lane * 4);
;                 v[i].x += cg.x * (p0.x + p1.x); v[i].y += cg.y * (p0.y + p1.y); v[i].z += cg.z * (p0.z + p1.z); v[i].w += cg.w * (p0.w + p1.w);
;                 *(float4*)(hcout + po) = v[i];
;             }
;             ss += v[i].x * v[i].x + v[i].y * v[i].y + v[i].z * v[i].z + v[i].w * v[i].w; }
;         ss = wave_sum(ss);
;         const float rstd = rsqrtf(ss * (1.0f / 1024.0f) + EPS);
;         const float* mr = modl + (size_t)r * 6144;
; #pragma unroll
;         for (int i = 0; i < 4; ++i) {
;             const int k = i * 256 + lane * 4;
;             const float4 gg = *(const float4*)(g + k), scv = *(const float4*)(mr + sc_off + k), shv = *(const float4*)(mr + sh_off + k);
;             const float o0 = v[i].x * rstd * gg.x * (1.0f + scv.x) + shv.x, o1 = v[i].y * rstd * gg.y * (1.0f + scv.y) + shv.y;
;             const float o2 = v[i].z * rstd * gg.z * (1.0f + scv.z) + shv.z, o3 = v[i].w * rstd * gg.w * (1.0f + scv.w) + shv.w;
;             uint2 w; w.x = pk2(o0, o1); w.y = pk2(o2, o3);
;             *(uint2*)(A + (size_t)row * 1024 + k) = w;
;         }
	v_pk_mul_f32 v[242:243], v[172:173], v[172:173]
	v_pk_mul_f32 v[244:245], v[176:177], v[176:177]
	v_pk_mul_f32 v[246:247], v[174:175], v[174:175]
	v_pk_mul_f32 v[248:249], v[178:179], v[178:179]
	v_add_f32_e32 v204, v245, v244
	v_add_f32_e32 v205, v243, v242
	v_add_f32_e32 v204, v248, v204
	v_add_f32_e32 v205, v246, v205
	v_add_f32_e32 v204, v249, v204
	v_add_f32_e32 v205, v247, v205
	v_pk_mul_f32 v[242:243], v[180:181], v[180:181]
	v_pk_mul_f32 v[244:245], v[184:185], v[184:185]
	v_pk_mul_f32 v[246:247], v[182:183], v[182:183]
	v_pk_mul_f32 v[248:249], v[186:187], v[186:187]
	v_add_f32_e32 v206, v243, v242
	v_add_f32_e32 v207, v245, v244
	v_add_f32_e32 v206, v246, v206
	v_add_f32_e32 v207, v248, v207
	v_add_f32_e32 v206, v247, v206
	v_add_f32_e32 v207, v249, v207
	v_add_f32_e32 v204, v205, v204
	v_add_f32_e32 v204, v204, v206
	v_add_f32_e32 v204, v204, v207
	ds_swizzle_b32 v205, v204 offset:swizzle(SWAP,1)
	s_waitcnt lgkmcnt(0)
	v_add_f32_e32 v204, v204, v205
	ds_swizzle_b32 v205, v204 offset:swizzle(SWAP,2)
	s_waitcnt lgkmcnt(0)
	v_add_f32_e32 v204, v204, v205
	ds_swizzle_b32 v205, v204 offset:swizzle(SWAP,4)
	s_waitcnt lgkmcnt(0)
	v_add_f32_e32 v204, v204, v205
	ds_swizzle_b32 v205, v204 offset:swizzle(SWAP,8)
	s_waitcnt lgkmcnt(0)
	v_add_f32_e32 v204, v204, v205
	ds_swizzle_b32 v205, v204 offset:swizzle(SWAP,16)
	s_waitcnt lgkmcnt(0)
	v_add_f32_e32 v204, v204, v205
	v_mov_b32_e32 v205, v204
	s_nop 1
	v_permlane32_swap_b32_e32 v204, v205
	v_add_f32_e32 v204, v204, v205
	v_mov_b32_e32 v205, 0x358637bd
	v_fmamk_f32 v204, v204, 0x3a800000, v205
	v_rsq_f32_e32 v204, v204
	s_nop 0
	v_pk_mul_f32 v[172:173], v[172:173], v[204:205] op_sel_hi:[1,0]
	v_pk_mul_f32 v[174:175], v[174:175], v[204:205] op_sel_hi:[1,0]
	v_pk_mul_f32 v[172:173], v[188:189], v[172:173]
	v_pk_mul_f32 v[174:175], v[190:191], v[174:175]
	v_pk_fma_f32 v[172:173], v[34:35], v[172:173], v[224:225]
	v_pk_fma_f32 v[174:175], v[36:37], v[174:175], v[226:227]
	v_cvt_pk_bf16_f32 v172, v172, v173
	v_cvt_pk_bf16_f32 v173, v174, v175
	global_store_dwordx2 v146, v[172:173], s[66:67]
	v_pk_mul_f32 v[176:177], v[176:177], v[204:205] op_sel_hi:[1,0]
	v_pk_mul_f32 v[178:179], v[178:179], v[204:205] op_sel_hi:[1,0]
	v_pk_mul_f32 v[176:177], v[192:193], v[176:177]
	v_pk_mul_f32 v[178:179], v[194:195], v[178:179]
	v_pk_fma_f32 v[176:177], v[38:39], v[176:177], v[228:229]
	v_pk_fma_f32 v[178:179], v[40:41], v[178:179], v[230:231]
	v_cvt_pk_bf16_f32 v176, v176, v177
	v_cvt_pk_bf16_f32 v177, v178, v179
	global_store_dwordx2 v146, v[176:177], s[66:67] offset:512
	v_pk_mul_f32 v[180:181], v[180:181], v[204:205] op_sel_hi:[1,0]
	v_pk_mul_f32 v[182:183], v[182:183], v[204:205] op_sel_hi:[1,0]
	v_pk_mul_f32 v[180:181], v[196:197], v[180:181]
	v_pk_mul_f32 v[182:183], v[198:199], v[182:183]
	v_pk_fma_f32 v[180:181], v[42:43], v[180:181], v[232:233]
	v_pk_fma_f32 v[182:183], v[44:45], v[182:183], v[234:235]
	v_cvt_pk_bf16_f32 v180, v180, v181
	v_cvt_pk_bf16_f32 v181, v182, v183
	global_store_dwordx2 v146, v[180:181], s[66:67] offset:1024
	v_pk_mul_f32 v[184:185], v[184:185], v[204:205] op_sel_hi:[1,0]
	v_pk_mul_f32 v[186:187], v[186:187], v[204:205] op_sel_hi:[1,0]
	v_pk_mul_f32 v[184:185], v[200:201], v[184:185]
	v_pk_mul_f32 v[186:187], v[202:203], v[186:187]
	v_pk_fma_f32 v[184:185], v[46:47], v[184:185], v[236:237]
	v_pk_fma_f32 v[186:187], v[48:49], v[186:187], v[238:239]
	v_cvt_pk_bf16_f32 v184, v184, v185
	v_cvt_pk_bf16_f32 v185, v186, v187
	global_store_dwordx2 v146, v[184:185], s[66:67] offset:1536
	v_add_u32_e32 v146, 0x800, v146
	global_load_dwordx4 v[172:175], v144, s[16:17]
	global_load_dwordx4 v[176:179], v144, s[16:17] offset:1024
	global_load_dwordx4 v[180:183], v144, s[16:17] offset:2048
	global_load_dwordx4 v[184:187], v144, s[16:17] offset:3072
	v_add_u32_e32 v144, 0x1000, v144
	s_waitcnt vmcnt(40)
	v_pk_mul_f32 v[242:243], v[80:81], v[80:81]
	v_pk_mul_f32 v[244:245], v[84:85], v[84:85]
	v_pk_mul_f32 v[246:247], v[82:83], v[82:83]
	v_pk_mul_f32 v[248:249], v[86:87], v[86:87]
	v_add_f32_e32 v204, v245, v244
	v_add_f32_e32 v205, v243, v242
	v_add_f32_e32 v204, v248, v204
	v_add_f32_e32 v205, v246, v205
	v_add_f32_e32 v204, v249, v204
	v_add_f32_e32 v205, v247, v205
	v_pk_mul_f32 v[242:243], v[88:89], v[88:89]
	v_pk_mul_f32 v[244:245], v[92:93], v[92:93]
	v_pk_mul_f32 v[246:247], v[90:91], v[90:91]
	v_pk_mul_f32 v[248:249], v[94:95], v[94:95]
	v_add_f32_e32 v206, v243, v242
	v_add_f32_e32 v207, v245, v244
	v_add_f32_e32 v206, v246, v206
	v_add_f32_e32 v207, v248, v207
	v_add_f32_e32 v206, v247, v206
	v_add_f32_e32 v207, v249, v207
	v_add_f32_e32 v204, v205, v204
	v_add_f32_e32 v204, v204, v206
	v_add_f32_e32 v204, v204, v207
	ds_swizzle_b32 v205, v204 offset:swizzle(SWAP,1)
	s_waitcnt lgkmcnt(0)
	v_add_f32_e32 v204, v204, v205
	ds_swizzle_b32 v205, v204 offset:swizzle(SWAP,2)
	s_waitcnt lgkmcnt(0)
	v_add_f32_e32 v204, v204, v205
	ds_swizzle_b32 v205, v204 offset:swizzle(SWAP,4)
	s_waitcnt lgkmcnt(0)
	v_add_f32_e32 v204, v204, v205
	ds_swizzle_b32 v205, v204 offset:swizzle(SWAP,8)
	s_waitcnt lgkmcnt(0)
	v_add_f32_e32 v204, v204, v205
	ds_swizzle_b32 v205, v204 offset:swizzle(SWAP,16)
	s_waitcnt lgkmcnt(0)
; __device__ __forceinline__ unsigned pk2(float lo, float hi) { const g_f32x2 f = {lo, hi}; return __builtin_bit_cast(unsigned, __builtin_convertvector(f, g_bf16x2)); }
; __device__ __forceinline__ void p_norm(const float* hlat, const float* hctx, const float* g, const float* modl, int sh_off, int sc_off, bf16_t* A, int M,
;                                        const float* part, const float* cgate, float* hcout) {
;     ...
;         float ss = 0.f;
; #pragma unroll
;         for (int i = 0; i < 4; ++i) {
;             if (part != nullptr && row >= NLAT) {
;                 const size_t po = (size_t)(row - NLAT) * 1024 + i * 256 + lane * 4;
;                 const float4 p0 = *(const float4*)(part + po), p1 = *(const float4*)(part + (size_t)4096 * 1024 + po), cg = *(const float4*)(cgate + i * 256 + lane * 4);
;                 v[i].x += cg.x * (p0.x + p1.x); v[i].y += cg.y * (p0.y + p1.y); v[i].z += cg.z * (p0.z + p1.z); v[i].w += cg.w * (p0.w + p1.w);
;                 *(float4*)(hcout + po) = v[i];
;             }
;             ss += v[i].x * v[i].x + v[i].y * v[i].y + v[i].z * v[i].z + v[i].w * v[i].w; }
;         ss = wave_sum(ss);
;         const float rstd = rsqrtf(ss * (1.0f / 1024.0f) + EPS);
;         const float* mr = modl + (size_t)r * 6144;
; #pragma unroll
;         for (int i = 0; i < 4; ++i) {
;             const int k = i * 256 + lane * 4;
;             const float4 gg = *(const float4*)(g + k), scv = *(const float4*)(mr + sc_off + k), shv = *(const float4*)(mr + sh_off + k);
;             const float o0 = v[i].x * rstd * gg.x * (1.0f + scv.x) + shv.x, o1 = v[i].y * rstd * gg.y * (1.0f + scv.y) + shv.y;
;             const float o2 = v[i].z * rstd * gg.z * (1.0f + scv.z) + shv.z, o3 = v[i].w * rstd * gg.w * (1.0f + scv.w) + shv.w;
;             uint2 w; w.x = pk2(o0, o1); w.y = pk2(o2, o3);
;             *(uint2*)(A + (size_t)row * 1024 + k) = w;
;         }
	v_add_f32_e32 v204, v204, v205
	v_mov_b32_e32 v205, v204
	s_nop 1
	v_permlane32_swap_b32_e32 v204, v205
	v_add_f32_e32 v204, v204, v205
	v_mov_b32_e32 v205, 0x358637bd
	v_fmamk_f32 v204, v204, 0x3a800000, v205
	v_rsq_f32_e32 v204, v204
	s_nop 0
	v_pk_mul_f32 v[80:81], v[80:81], v[204:205] op_sel_hi:[1,0]
	v_pk_mul_f32 v[82:83], v[82:83], v[204:205] op_sel_hi:[1,0]
	v_pk_mul_f32 v[80:81], v[188:189], v[80:81]
	v_pk_mul_f32 v[82:83], v[190:191], v[82:83]
	v_pk_fma_f32 v[80:81], v[34:35], v[80:81], v[224:225]
	v_pk_fma_f32 v[82:83], v[36:37], v[82:83], v[226:227]
	v_cvt_pk_bf16_f32 v80, v80, v81
	v_cvt_pk_bf16_f32 v81, v82, v83
	global_store_dwordx2 v146, v[80:81], s[66:67]
	v_pk_mul_f32 v[84:85], v[84:85], v[204:205] op_sel_hi:[1,0]
	v_pk_mul_f32 v[86:87], v[86:87], v[204:205] op_sel_hi:[1,0]
	v_pk_mul_f32 v[84:85], v[192:193], v[84:85]
	v_pk_mul_f32 v[86:87], v[194:195], v[86:87]
	v_pk_fma_f32 v[84:85], v[38:39], v[84:85], v[228:229]
	v_pk_fma_f32 v[86:87], v[40:41], v[86:87], v[230:231]
	v_cvt_pk_bf16_f32 v84, v84, v85
	v_cvt_pk_bf16_f32 v85, v86, v87
	global_store_dwordx2 v146, v[84:85], s[66:67] offset:512
	v_pk_mul_f32 v[88:89], v[88:89], v[204:205] op_sel_hi:[1,0]
	v_pk_mul_f32 v[90:91], v[90:91], v[204:205] op_sel_hi:[1,0]
	v_pk_mul_f32 v[88:89], v[196:197], v[88:89]
	v_pk_mul_f32 v[90:91], v[198:199], v[90:91]
	v_pk_fma_f32 v[88:89], v[42:43], v[88:89], v[232:233]
	v_pk_fma_f32 v[90:91], v[44:45], v[90:91], v[234:235]
	v_cvt_pk_bf16_f32 v88, v88, v89
	v_cvt_pk_bf16_f32 v89, v90, v91
	global_store_dwordx2 v146, v[88:89], s[66:67] offset:1024
	v_pk_mul_f32 v[92:93], v[92:93], v[204:205] op_sel_hi:[1,0]
	v_pk_mul_f32 v[94:95], v[94:95], v[204:205] op_sel_hi:[1,0]
	v_pk_mul_f32 v[92:93], v[200:201], v[92:93]
	v_pk_mul_f32 v[94:95], v[202:203], v[94:95]
	v_pk_fma_f32 v[92:93], v[46:47], v[92:93], v[236:237]
	v_pk_fma_f32 v[94:95], v[48:49], v[94:95], v[238:239]
	v_cvt_pk_bf16_f32 v92, v92, v93
	v_cvt_pk_bf16_f32 v93, v94, v95
	global_store_dwordx2 v146, v[92:93], s[66:67] offset:1536
	v_add_u32_e32 v146, 0x800, v146
	global_load_dwordx4 v[8:11], v241, s[20:21]
	global_load_dwordx4 v[52:55], v241, s[20:21] offset:1024
	global_load_dwordx4 v[60:63], v241, s[20:21] offset:2048
	global_load_dwordx4 v[64:67], v241, s[20:21] offset:3072
	s_waitcnt vmcnt(40)
	v_pk_mul_f32 v[242:243], v[96:97], v[96:97]
	v_pk_mul_f32 v[244:245], v[100:101], v[100:101]
	v_pk_mul_f32 v[246:247], v[98:99], v[98:99]
	v_pk_mul_f32 v[248:249], v[102:103], v[102:103]
	v_add_f32_e32 v204, v245, v244
	v_add_f32_e32 v205, v243, v242
	v_add_f32_e32 v204, v248, v204
	v_add_f32_e32 v205, v246, v205
	v_add_f32_e32 v204, v249, v204
	v_add_f32_e32 v205, v247, v205
	v_pk_mul_f32 v[242:243], v[104:105], v[104:105]
	v_pk_mul_f32 v[244:245], v[108:109], v[108:109]
	v_pk_mul_f32 v[246:247], v[106:107], v[106:107]
	v_pk_mul_f32 v[248:249], v[110:111], v[110:111]
	v_add_f32_e32 v206, v243, v242
	v_add_f32_e32 v207, v245, v244
	v_add_f32_e32 v206, v246, v206
	v_add_f32_e32 v207, v248, v207
	v_add_f32_e32 v206, v247, v206
	v_add_f32_e32 v207, v249, v207
	v_add_f32_e32 v204, v205, v204
	v_add_f32_e32 v204, v204, v206
	v_add_f32_e32 v204, v204, v207
	ds_swizzle_b32 v205, v204 offset:swizzle(SWAP,1)
	s_waitcnt lgkmcnt(0)
	v_add_f32_e32 v204, v204, v205
	ds_swizzle_b32 v205, v204 offset:swizzle(SWAP,2)
	s_waitcnt lgkmcnt(0)
	v_add_f32_e32 v204, v204, v205
	ds_swizzle_b32 v205, v204 offset:swizzle(SWAP,4)
	s_waitcnt lgkmcnt(0)
	v_add_f32_e32 v204, v204, v205
	ds_swizzle_b32 v205, v204 offset:swizzle(SWAP,8)
	s_waitcnt lgkmcnt(0)
	v_add_f32_e32 v204, v204, v205
	ds_swizzle_b32 v205, v204 offset:swizzle(SWAP,16)
	s_waitcnt lgkmcnt(0)
	v_add_f32_e32 v204, v204, v205
	v_mov_b32_e32 v205, v204
	s_nop 1
	v_permlane32_swap_b32_e32 v204, v205
	v_add_f32_e32 v204, v204, v205
	v_mov_b32_e32 v205, 0x358637bd
	v_fmamk_f32 v204, v204, 0x3a800000, v205
	v_rsq_f32_e32 v204, v204
	s_nop 0
	v_pk_mul_f32 v[96:97], v[96:97], v[204:205] op_sel_hi:[1,0]
	v_pk_mul_f32 v[98:99], v[98:99], v[204:205] op_sel_hi:[1,0]
	v_pk_mul_f32 v[96:97], v[188:189], v[96:97]
	v_pk_mul_f32 v[98:99], v[190:191], v[98:99]
	v_pk_fma_f32 v[96:97], v[34:35], v[96:97], v[224:225]
	v_pk_fma_f32 v[98:99], v[36:37], v[98:99], v[226:227]
	v_cvt_pk_bf16_f32 v96, v96, v97
	v_cvt_pk_bf16_f32 v97, v98, v99
	global_store_dwordx2 v146, v[96:97], s[66:67]
	v_pk_mul_f32 v[100:101], v[100:101], v[204:205] op_sel_hi:[1,0]
	v_pk_mul_f32 v[102:103], v[102:103], v[204:205] op_sel_hi:[1,0]
	v_pk_mul_f32 v[100:101], v[192:193], v[100:101]
	v_pk_mul_f32 v[102:103], v[194:195], v[102:103]
	v_pk_fma_f32 v[100:101], v[38:39], v[100:101], v[228:229]
	v_pk_fma_f32 v[102:103], v[40:41], v[102:103], v[230:231]
	v_cvt_pk_bf16_f32 v100, v100, v101
	v_cvt_pk_bf16_f32 v101, v102, v103
	global_store_dwordx2 v146, v[100:101], s[66:67] offset:512
	v_pk_mul_f32 v[104:105], v[104:105], v[204:205] op_sel_hi:[1,0]
	v_pk_mul_f32 v[106:107], v[106:107], v[204:205] op_sel_hi:[1,0]
	v_pk_mul_f32 v[104:105], v[196:197], v[104:105]
	v_pk_mul_f32 v[106:107], v[198:199], v[106:107]
	v_pk_fma_f32 v[104:105], v[42:43], v[104:105], v[232:233]
	v_pk_fma_f32 v[106:107], v[44:45], v[106:107], v[234:235]
	v_cvt_pk_bf16_f32 v104, v104, v105
	v_cvt_pk_bf16_f32 v105, v106, v107
	global_store_dwordx2 v146, v[104:105], s[66:67] offset:1024
	v_pk_mul_f32 v[108:109], v[108:109], v[204:205] op_sel_hi:[1,0]
	v_pk_mul_f32 v[110:111], v[110:111], v[204:205] op_sel_hi:[1,0]
	v_pk_mul_f32 v[108:109], v[200:201], v[108:109]
	v_pk_mul_f32 v[110:111], v[202:203], v[110:111]
	v_pk_fma_f32 v[108:109], v[46:47], v[108:109], v[236:237]
	v_pk_fma_f32 v[110:111], v[48:49], v[110:111], v[238:239]
	v_cvt_pk_bf16_f32 v108, v108, v109
	v_cvt_pk_bf16_f32 v109, v110, v111
	global_store_dwordx2 v146, v[108:109], s[66:67] offset:1536
	v_add_u32_e32 v146, 0x800, v146
	global_load_dwordx4 v[80:83], v152, s[70:71]
	global_load_dwordx4 v[84:87], v152, s[70:71] offset:1024
	global_load_dwordx4 v[88:91], v152, s[70:71] offset:2048
	global_load_dwordx4 v[92:95], v152, s[70:71] offset:3072
	global_load_dwordx4 v[96:99], v150, s[70:71]
	global_load_dwordx4 v[100:103], v150, s[70:71] offset:1024
	global_load_dwordx4 v[104:107], v150, s[70:71] offset:2048
	global_load_dwordx4 v[108:111], v150, s[70:71] offset:3072
	s_waitcnt vmcnt(44)
; __device__ __forceinline__ unsigned pk2(float lo, float hi) { const g_f32x2 f = {lo, hi}; return __builtin_bit_cast(unsigned, __builtin_convertvector(f, g_bf16x2)); }
; __device__ __forceinline__ void p_norm(const float* hlat, const float* hctx, const float* g, const float* modl, int sh_off, int sc_off, bf16_t* A, int M,
;                                        const float* part, const float* cgate, float* hcout) {
;     ...
;         float ss = 0.f;
; #pragma unroll
;         for (int i = 0; i < 4; ++i) {
;             if (part != nullptr && row >= NLAT) {
;                 const size_t po = (size_t)(row - NLAT) * 1024 + i * 256 + lane * 4;
;                 const float4 p0 = *(const float4*)(part + po), p1 = *(const float4*)(part + (size_t)4096 * 1024 + po), cg = *(const float4*)(cgate + i * 256 + lane * 4);
;                 v[i].x += cg.x * (p0.x + p1.x); v[i].y += cg.y * (p0.y + p1.y); v[i].z += cg.z * (p0.z + p1.z); v[i].w += cg.w * (p0.w + p1.w);
;                 *(float4*)(hcout + po) = v[i];
;             }
;             ss += v[i].x * v[i].x + v[i].y * v[i].y + v[i].z * v[i].z + v[i].w * v[i].w; }
;         ss = wave_sum(ss);
;         const float rstd = rsqrtf(ss * (1.0f / 1024.0f) + EPS);
;         const float* mr = modl + (size_t)r * 6144;
; #pragma unroll
;         for (int i = 0; i < 4; ++i) {
;             const int k = i * 256 + lane * 4;
;             const float4 gg = *(const float4*)(g + k), scv = *(const float4*)(mr + sc_off + k), shv = *(const float4*)(mr + sh_off + k);
;             const float o0 = v[i].x * rstd * gg.x * (1.0f + scv.x) + shv.x, o1 = v[i].y * rstd * gg.y * (1.0f + scv.y) + shv.y;
;             const float o2 = v[i].z * rstd * gg.z * (1.0f + scv.z) + shv.z, o3 = v[i].w * rstd * gg.w * (1.0f + scv.w) + shv.w;
;             uint2 w; w.x = pk2(o0, o1); w.y = pk2(o2, o3);
;             *(uint2*)(A + (size_t)row * 1024 + k) = w;
;         }
	v_pk_mul_f32 v[242:243], v[112:113], v[112:113]
	v_pk_mul_f32 v[244:245], v[116:117], v[116:117]
	v_pk_mul_f32 v[246:247], v[114:115], v[114:115]
	v_pk_mul_f32 v[248:249], v[118:119], v[118:119]
	v_add_f32_e32 v204, v245, v244
	v_add_f32_e32 v205, v243, v242
	v_add_f32_e32 v204, v248, v204
	v_add_f32_e32 v205, v246, v205
	v_add_f32_e32 v204, v249, v204
	v_add_f32_e32 v205, v247, v205
	v_pk_mul_f32 v[242:243], v[120:121], v[120:121]
	v_pk_mul_f32 v[244:245], v[124:125], v[124:125]
	v_pk_mul_f32 v[246:247], v[122:123], v[122:123]
	v_pk_mul_f32 v[248:249], v[126:127], v[126:127]
	v_add_f32_e32 v206, v243, v242
	v_add_f32_e32 v207, v245, v244
	v_add_f32_e32 v206, v246, v206
	v_add_f32_e32 v207, v248, v207
	v_add_f32_e32 v206, v247, v206
	v_add_f32_e32 v207, v249, v207
	v_add_f32_e32 v204, v205, v204
	v_add_f32_e32 v204, v204, v206
	v_add_f32_e32 v204, v204, v207
	ds_swizzle_b32 v205, v204 offset:swizzle(SWAP,1)
	s_waitcnt lgkmcnt(0)
	v_add_f32_e32 v204, v204, v205
	ds_swizzle_b32 v205, v204 offset:swizzle(SWAP,2)
	s_waitcnt lgkmcnt(0)
	v_add_f32_e32 v204, v204, v205
	ds_swizzle_b32 v205, v204 offset:swizzle(SWAP,4)
	s_waitcnt lgkmcnt(0)
	v_add_f32_e32 v204, v204, v205
	ds_swizzle_b32 v205, v204 offset:swizzle(SWAP,8)
	s_waitcnt lgkmcnt(0)
	v_add_f32_e32 v204, v204, v205
	ds_swizzle_b32 v205, v204 offset:swizzle(SWAP,16)
	s_waitcnt lgkmcnt(0)
	v_add_f32_e32 v204, v204, v205
	v_mov_b32_e32 v205, v204
	s_nop 1
	v_permlane32_swap_b32_e32 v204, v205
	v_add_f32_e32 v204, v204, v205
	v_mov_b32_e32 v205, 0x358637bd
	v_fmamk_f32 v204, v204, 0x3a800000, v205
	v_rsq_f32_e32 v204, v204
	s_nop 0
	v_pk_mul_f32 v[112:113], v[112:113], v[204:205] op_sel_hi:[1,0]
	v_pk_mul_f32 v[114:115], v[114:115], v[204:205] op_sel_hi:[1,0]
	v_pk_mul_f32 v[112:113], v[188:189], v[112:113]
	v_pk_mul_f32 v[114:115], v[190:191], v[114:115]
	v_pk_fma_f32 v[112:113], v[34:35], v[112:113], v[224:225]
	v_pk_fma_f32 v[114:115], v[36:37], v[114:115], v[226:227]
	v_cvt_pk_bf16_f32 v112, v112, v113
	v_cvt_pk_bf16_f32 v113, v114, v115
	global_store_dwordx2 v146, v[112:113], s[66:67]
	v_pk_mul_f32 v[116:117], v[116:117], v[204:205] op_sel_hi:[1,0]
	v_pk_mul_f32 v[118:119], v[118:119], v[204:205] op_sel_hi:[1,0]
	v_pk_mul_f32 v[116:117], v[192:193], v[116:117]
	v_pk_mul_f32 v[118:119], v[194:195], v[118:119]
	v_pk_fma_f32 v[116:117], v[38:39], v[116:117], v[228:229]
	v_pk_fma_f32 v[118:119], v[40:41], v[118:119], v[230:231]
	v_cvt_pk_bf16_f32 v116, v116, v117
	v_cvt_pk_bf16_f32 v117, v118, v119
	global_store_dwordx2 v146, v[116:117], s[66:67] offset:512
	v_pk_mul_f32 v[120:121], v[120:121], v[204:205] op_sel_hi:[1,0]
	v_pk_mul_f32 v[122:123], v[122:123], v[204:205] op_sel_hi:[1,0]
	v_pk_mul_f32 v[120:121], v[196:197], v[120:121]
	v_pk_mul_f32 v[122:123], v[198:199], v[122:123]
	v_pk_fma_f32 v[120:121], v[42:43], v[120:121], v[232:233]
	v_pk_fma_f32 v[122:123], v[44:45], v[122:123], v[234:235]
	v_cvt_pk_bf16_f32 v120, v120, v121
	v_cvt_pk_bf16_f32 v121, v122, v123
	global_store_dwordx2 v146, v[120:121], s[66:67] offset:1024
	v_pk_mul_f32 v[124:125], v[124:125], v[204:205] op_sel_hi:[1,0]
	v_pk_mul_f32 v[126:127], v[126:127], v[204:205] op_sel_hi:[1,0]
	v_pk_mul_f32 v[124:125], v[200:201], v[124:125]
	v_pk_mul_f32 v[126:127], v[202:203], v[126:127]
	v_pk_fma_f32 v[124:125], v[46:47], v[124:125], v[236:237]
	v_pk_fma_f32 v[126:127], v[48:49], v[126:127], v[238:239]
	v_cvt_pk_bf16_f32 v124, v124, v125
	v_cvt_pk_bf16_f32 v125, v126, v127
	global_store_dwordx2 v146, v[124:125], s[66:67] offset:1536
	v_add_u32_e32 v146, 0x800, v146
	v_add_u32_e32 v207, 0x1000, v152
	global_load_dwordx4 v[112:115], v207, s[70:71]
	global_load_dwordx4 v[116:119], v207, s[70:71] offset:1024
	global_load_dwordx4 v[120:123], v207, s[70:71] offset:2048
	global_load_dwordx4 v[124:127], v207, s[70:71] offset:3072
	s_waitcnt vmcnt(44)
	v_pk_mul_f32 v[242:243], v[128:129], v[128:129]
	v_pk_mul_f32 v[244:245], v[132:133], v[132:133]
	v_pk_mul_f32 v[246:247], v[130:131], v[130:131]
	v_pk_mul_f32 v[248:249], v[134:135], v[134:135]
	v_add_f32_e32 v204, v245, v244
	v_add_f32_e32 v205, v243, v242
	v_add_f32_e32 v204, v248, v204
	v_add_f32_e32 v205, v246, v205
	v_add_f32_e32 v204, v249, v204
	v_add_f32_e32 v205, v247, v205
	v_pk_mul_f32 v[242:243], v[136:137], v[136:137]
	v_pk_mul_f32 v[244:245], v[140:141], v[140:141]
	v_pk_mul_f32 v[246:247], v[138:139], v[138:139]
	v_pk_mul_f32 v[248:249], v[142:143], v[142:143]
	v_add_f32_e32 v206, v243, v242
	v_add_f32_e32 v207, v245, v244
	v_add_f32_e32 v206, v246, v206
	v_add_f32_e32 v207, v248, v207
	v_add_f32_e32 v206, v247, v206
	v_add_f32_e32 v207, v249, v207
	v_add_f32_e32 v204, v205, v204
	v_add_f32_e32 v204, v204, v206
	v_add_f32_e32 v204, v204, v207
	ds_swizzle_b32 v205, v204 offset:swizzle(SWAP,1)
	s_waitcnt lgkmcnt(0)
	v_add_f32_e32 v204, v204, v205
	ds_swizzle_b32 v205, v204 offset:swizzle(SWAP,2)
	s_waitcnt lgkmcnt(0)
	v_add_f32_e32 v204, v204, v205
	ds_swizzle_b32 v205, v204 offset:swizzle(SWAP,4)
	s_waitcnt lgkmcnt(0)
	v_add_f32_e32 v204, v204, v205
	ds_swizzle_b32 v205, v204 offset:swizzle(SWAP,8)
	s_waitcnt lgkmcnt(0)
	v_add_f32_e32 v204, v204, v205
	ds_swizzle_b32 v205, v204 offset:swizzle(SWAP,16)
	s_waitcnt lgkmcnt(0)
; __device__ __forceinline__ void p_norm(const float* hlat, const float* hctx, const float* g, const float* modl, int sh_off, int sc_off, bf16_t* A, int M,
;                                        const float* part, const float* cgate, float* hcout) {
;     ...
;             if (part != nullptr && row >= NLAT) {
;                 const size_t po = (size_t)(row - NLAT) * 1024 + i * 256 + lane * 4;
;                 const float4 p0 = *(const float4*)(part + po), p1 = *(const float4*)(part + (size_t)4096 * 1024 + po), cg = *(const float4*)(cgate + i * 256 + lane * 4);
;                 v[i].x += cg.x * (p0.x + p1.x); v[i].y += cg.y * (p0.y + p1.y); v[i].z += cg.z * (p0.z + p1.z); v[i].w += cg.w * (p0.w + p1.w);
;                 *(float4*)(hcout + po) = v[i];
;             }
;             ss += v[i].x * v[i].x + v[i].y * v[i].y + v[i].z * v[i].z + v[i].w * v[i].w; }
;         ss = wave_sum(ss);
;         const float rstd = rsqrtf(ss * (1.0f / 1024.0f) + EPS);
	v_add_f32_e32 v204, v204, v205
	v_mov_b32_e32 v205, v204
	s_nop 1
	v_permlane32_swap_b32_e32 v204, v205
	v_add_f32_e32 v204, v204, v205
	v_mov_b32_e32 v205, 0x358637bd
	v_fmamk_f32 v204, v204, 0x3a800000, v205
	v_rsq_f32_e32 v204, v204
	s_nop 0
	v_pk_mul_f32 v[128:129], v[128:129], v[204:205] op_sel_hi:[1,0]
	v_pk_mul_f32 v[130:131], v[130:131], v[204:205] op_sel_hi:[1,0]
	v_pk_mul_f32 v[128:129], v[188:189], v[128:129]
	v_pk_mul_f32 v[130:131], v[190:191], v[130:131]
	v_pk_fma_f32 v[128:129], v[34:35], v[128:129], v[224:225]
	v_pk_fma_f32 v[130:131], v[36:37], v[130:131], v[226:227]
	v_cvt_pk_bf16_f32 v128, v128, v129
	v_cvt_pk_bf16_f32 v129, v130, v131
	global_store_dwordx2 v146, v[128:129], s[66:67]
	v_pk_mul_f32 v[132:133], v[132:133], v[204:205] op_sel_hi:[1,0]
	v_pk_mul_f32 v[134:135], v[134:135], v[204:205] op_sel_hi:[1,0]
	v_pk_mul_f32 v[132:133], v[192:193], v[132:133]
	v_pk_mul_f32 v[134:135], v[194:195], v[134:135]
	v_pk_fma_f32 v[132:133], v[38:39], v[132:133], v[228:229]
	v_pk_fma_f32 v[134:135], v[40:41], v[134:135], v[230:231]
	v_cvt_pk_bf16_f32 v132, v132, v133
	v_cvt_pk_bf16_f32 v133, v134, v135
	global_store_dwordx2 v146, v[132:133], s[66:67] offset:512
	v_pk_mul_f32 v[136:137], v[136:137], v[204:205] op_sel_hi:[1,0]
	v_pk_mul_f32 v[138:139], v[138:139], v[204:205] op_sel_hi:[1,0]
	v_pk_mul_f32 v[136:137], v[196:197], v[136:137]
	v_pk_mul_f32 v[138:139], v[198:199], v[138:139]
	v_pk_fma_f32 v[136:137], v[42:43], v[136:137], v[232:233]
	v_pk_fma_f32 v[138:139], v[44:45], v[138:139], v[234:235]
	v_cvt_pk_bf16_f32 v136, v136, v137
	v_cvt_pk_bf16_f32 v137, v138, v139
	global_store_dwordx2 v146, v[136:137], s[66:67] offset:1024
	v_pk_mul_f32 v[140:141], v[140:141], v[204:205] op_sel_hi:[1,0]
	v_pk_mul_f32 v[142:143], v[142:143], v[204:205] op_sel_hi:[1,0]
	v_pk_mul_f32 v[140:141], v[200:201], v[140:141]
	v_pk_mul_f32 v[142:143], v[202:203], v[142:143]
	v_pk_fma_f32 v[140:141], v[46:47], v[140:141], v[236:237]
	v_pk_fma_f32 v[142:143], v[48:49], v[142:143], v[238:239]
	v_cvt_pk_bf16_f32 v140, v140, v141
	v_cvt_pk_bf16_f32 v141, v142, v143
	global_store_dwordx2 v146, v[140:141], s[66:67] offset:1536
	v_add_u32_e32 v146, 0x800, v146
	v_add_u32_e32 v151, 0x60000, v241
	global_load_dwordx4 v[34:37], v151, s[98:99]
	global_load_dwordx4 v[38:41], v151, s[98:99] offset:1024
	global_load_dwordx4 v[42:45], v151, s[98:99] offset:2048
	global_load_dwordx4 v[46:49], v151, s[98:99] offset:3072
	global_load_dwordx4 v[224:227], v151, s[50:51]
	global_load_dwordx4 v[228:231], v151, s[50:51] offset:1024
	global_load_dwordx4 v[232:235], v151, s[50:51] offset:2048
	global_load_dwordx4 v[236:239], v151, s[50:51] offset:3072
	v_add_u32_e32 v207, 0x1000, v150
	global_load_dwordx4 v[128:131], v207, s[70:71]
	global_load_dwordx4 v[132:135], v207, s[70:71] offset:1024
	global_load_dwordx4 v[136:139], v207, s[70:71] offset:2048
	global_load_dwordx4 v[140:143], v207, s[70:71] offset:3072
	s_waitcnt vmcnt(24)
	v_pk_add_f32 v[80:81], v[80:81], v[96:97]
	v_pk_add_f32 v[82:83], v[82:83], v[98:99]
	v_pk_fma_f32 v[156:157], v[80:81], v[8:9], v[156:157]
	v_pk_fma_f32 v[158:159], v[82:83], v[10:11], v[158:159]
	global_store_dwordx4 v152, v[156:159], s[64:65]
	v_pk_add_f32 v[84:85], v[84:85], v[100:101]
	v_pk_add_f32 v[86:87], v[86:87], v[102:103]
	v_pk_fma_f32 v[160:161], v[84:85], v[52:53], v[160:161]
	v_pk_fma_f32 v[162:163], v[86:87], v[54:55], v[162:163]
	global_store_dwordx4 v152, v[160:163], s[64:65] offset:1024
	v_pk_add_f32 v[88:89], v[88:89], v[104:105]
	v_pk_add_f32 v[90:91], v[90:91], v[106:107]
	v_pk_fma_f32 v[164:165], v[88:89], v[60:61], v[164:165]
	v_pk_fma_f32 v[166:167], v[90:91], v[62:63], v[166:167]
	global_store_dwordx4 v152, v[164:167], s[64:65] offset:2048
	v_pk_add_f32 v[92:93], v[92:93], v[108:109]
	v_pk_add_f32 v[94:95], v[94:95], v[110:111]
	v_pk_fma_f32 v[168:169], v[92:93], v[64:65], v[168:169]
	v_pk_fma_f32 v[170:171], v[94:95], v[66:67], v[170:171]
	global_store_dwordx4 v152, v[168:171], s[64:65] offset:3072
	v_add_u32_e32 v152, 0x1000, v152
	v_pk_mul_f32 v[242:243], v[156:157], v[156:157]
	v_pk_mul_f32 v[244:245], v[160:161], v[160:161]
	v_pk_mul_f32 v[246:247], v[158:159], v[158:159]
	v_pk_mul_f32 v[248:249], v[162:163], v[162:163]
	v_add_f32_e32 v204, v245, v244
	v_add_f32_e32 v205, v243, v242
	v_add_f32_e32 v204, v248, v204
	v_add_f32_e32 v205, v246, v205
	v_add_f32_e32 v204, v249, v204
	v_add_f32_e32 v205, v247, v205
	v_pk_mul_f32 v[242:243], v[164:165], v[164:165]
	v_pk_mul_f32 v[244:245], v[168:169], v[168:169]
	v_pk_mul_f32 v[246:247], v[166:167], v[166:167]
	v_pk_mul_f32 v[248:249], v[170:171], v[170:171]
	v_add_f32_e32 v206, v243, v242
	v_add_f32_e32 v207, v245, v244
	v_add_f32_e32 v206, v246, v206
	v_add_f32_e32 v207, v248, v207
	v_add_f32_e32 v206, v247, v206
	v_add_f32_e32 v207, v249, v207
	v_add_f32_e32 v204, v205, v204
	v_add_f32_e32 v204, v204, v206
	v_add_f32_e32 v204, v204, v207
	ds_swizzle_b32 v205, v204 offset:swizzle(SWAP,1)
	s_waitcnt lgkmcnt(0)
	v_add_f32_e32 v204, v204, v205
	ds_swizzle_b32 v205, v204 offset:swizzle(SWAP,2)
	s_waitcnt lgkmcnt(0)
	v_add_f32_e32 v204, v204, v205
	ds_swizzle_b32 v205, v204 offset:swizzle(SWAP,4)
	s_waitcnt lgkmcnt(0)
	v_add_f32_e32 v204, v204, v205
	ds_swizzle_b32 v205, v204 offset:swizzle(SWAP,8)
	s_waitcnt lgkmcnt(0)
	v_add_f32_e32 v204, v204, v205
	ds_swizzle_b32 v205, v204 offset:swizzle(SWAP,16)
	s_waitcnt lgkmcnt(0)
	v_add_f32_e32 v204, v204, v205
	v_mov_b32_e32 v205, v204
	s_nop 1
	v_permlane32_swap_b32_e32 v204, v205
	v_add_f32_e32 v204, v204, v205
	v_mov_b32_e32 v205, 0x358637bd
	v_fmamk_f32 v204, v204, 0x3a800000, v205
	v_rsq_f32_e32 v204, v204
	s_nop 0
	s_waitcnt vmcnt(8)
; __device__ __forceinline__ unsigned pk2(float lo, float hi) { const g_f32x2 f = {lo, hi}; return __builtin_bit_cast(unsigned, __builtin_convertvector(f, g_bf16x2)); }
; __device__ __forceinline__ void p_norm(const float* hlat, const float* hctx, const float* g, const float* modl, int sh_off, int sc_off, bf16_t* A, int M,
;                                        const float* part, const float* cgate, float* hcout) {
;     ...
;             if (part != nullptr && row >= NLAT) {
;                 const size_t po = (size_t)(row - NLAT) * 1024 + i * 256 + lane * 4;
;                 const float4 p0 = *(const float4*)(part + po), p1 = *(const float4*)(part + (size_t)4096 * 1024 + po), cg = *(const float4*)(cgate + i * 256 + lane * 4);
;                 v[i].x += cg.x * (p0.x + p1.x); v[i].y += cg.y * (p0.y + p1.y); v[i].z += cg.z * (p0.z + p1.z); v[i].w += cg.w * (p0.w + p1.w);
;                 *(float4*)(hcout + po) = v[i];
;             }
;             ss += v[i].x * v[i].x + v[i].y * v[i].y + v[i].z * v[i].z + v[i].w * v[i].w; }
;         ss = wave_sum(ss);
;         const float rstd = rsqrtf(ss * (1.0f / 1024.0f) + EPS);
;         const float* mr = modl + (size_t)r * 6144;
; #pragma unroll
;         for (int i = 0; i < 4; ++i) {
;             const int k = i * 256 + lane * 4;
;             const float4 gg = *(const float4*)(g + k), scv = *(const float4*)(mr + sc_off + k), shv = *(const float4*)(mr + sh_off + k);
;             const float o0 = v[i].x * rstd * gg.x * (1.0f + scv.x) + shv.x, o1 = v[i].y * rstd * gg.y * (1.0f + scv.y) + shv.y;
;             const float o2 = v[i].z * rstd * gg.z * (1.0f + scv.z) + shv.z, o3 = v[i].w * rstd * gg.w * (1.0f + scv.w) + shv.w;
;             uint2 w; w.x = pk2(o0, o1); w.y = pk2(o2, o3);
;             *(uint2*)(A + (size_t)row * 1024 + k) = w;
;         }
	v_pk_add_f32 v[34:35], v[34:35], 1.0 op_sel_hi:[1,0]
	v_pk_add_f32 v[36:37], v[36:37], 1.0 op_sel_hi:[1,0]
	v_pk_add_f32 v[38:39], v[38:39], 1.0 op_sel_hi:[1,0]
	v_pk_add_f32 v[40:41], v[40:41], 1.0 op_sel_hi:[1,0]
	v_pk_add_f32 v[42:43], v[42:43], 1.0 op_sel_hi:[1,0]
	v_pk_add_f32 v[44:45], v[44:45], 1.0 op_sel_hi:[1,0]
	v_pk_add_f32 v[46:47], v[46:47], 1.0 op_sel_hi:[1,0]
	v_pk_add_f32 v[48:49], v[48:49], 1.0 op_sel_hi:[1,0]
	v_lshlrev_b32_e32 v146, 12, v50
	v_lshl_add_u32 v146, v240, 3, v146
	v_add_u32_e32 v146, 0x4000000, v146
	v_pk_mul_f32 v[156:157], v[156:157], v[204:205] op_sel_hi:[1,0]
	v_pk_mul_f32 v[158:159], v[158:159], v[204:205] op_sel_hi:[1,0]
	v_pk_mul_f32 v[156:157], v[188:189], v[156:157]
	v_pk_mul_f32 v[158:159], v[190:191], v[158:159]
	v_pk_fma_f32 v[156:157], v[34:35], v[156:157], v[224:225]
	v_pk_fma_f32 v[158:159], v[36:37], v[158:159], v[226:227]
	v_cvt_pk_bf16_f32 v156, v156, v157
	v_cvt_pk_bf16_f32 v157, v158, v159
	global_store_dwordx2 v146, v[156:157], s[66:67]
	v_pk_mul_f32 v[160:161], v[160:161], v[204:205] op_sel_hi:[1,0]
	v_pk_mul_f32 v[162:163], v[162:163], v[204:205] op_sel_hi:[1,0]
	v_pk_mul_f32 v[160:161], v[192:193], v[160:161]
	v_pk_mul_f32 v[162:163], v[194:195], v[162:163]
	v_pk_fma_f32 v[160:161], v[38:39], v[160:161], v[228:229]
	v_pk_fma_f32 v[162:163], v[40:41], v[162:163], v[230:231]
	v_cvt_pk_bf16_f32 v160, v160, v161
	v_cvt_pk_bf16_f32 v161, v162, v163
	global_store_dwordx2 v146, v[160:161], s[66:67] offset:512
	v_pk_mul_f32 v[164:165], v[164:165], v[204:205] op_sel_hi:[1,0]
	v_pk_mul_f32 v[166:167], v[166:167], v[204:205] op_sel_hi:[1,0]
	v_pk_mul_f32 v[164:165], v[196:197], v[164:165]
	v_pk_mul_f32 v[166:167], v[198:199], v[166:167]
	v_pk_fma_f32 v[164:165], v[42:43], v[164:165], v[232:233]
	v_pk_fma_f32 v[166:167], v[44:45], v[166:167], v[234:235]
	v_cvt_pk_bf16_f32 v164, v164, v165
	v_cvt_pk_bf16_f32 v165, v166, v167
	global_store_dwordx2 v146, v[164:165], s[66:67] offset:1024
	v_pk_mul_f32 v[168:169], v[168:169], v[204:205] op_sel_hi:[1,0]
	v_pk_mul_f32 v[170:171], v[170:171], v[204:205] op_sel_hi:[1,0]
	v_pk_mul_f32 v[168:169], v[200:201], v[168:169]
	v_pk_mul_f32 v[170:171], v[202:203], v[170:171]
	v_pk_fma_f32 v[168:169], v[46:47], v[168:169], v[236:237]
	v_pk_fma_f32 v[170:171], v[48:49], v[170:171], v[238:239]
	v_cvt_pk_bf16_f32 v168, v168, v169
	v_cvt_pk_bf16_f32 v169, v170, v171
	global_store_dwordx2 v146, v[168:169], s[66:67] offset:1536
	v_add_u32_e32 v146, 0x800, v146
	s_waitcnt vmcnt(8)
	v_pk_add_f32 v[112:113], v[112:113], v[128:129]
	v_pk_add_f32 v[114:115], v[114:115], v[130:131]
	v_pk_fma_f32 v[172:173], v[112:113], v[8:9], v[172:173]
	v_pk_fma_f32 v[174:175], v[114:115], v[10:11], v[174:175]
	global_store_dwordx4 v152, v[172:175], s[64:65]
	v_pk_add_f32 v[116:117], v[116:117], v[132:133]
	v_pk_add_f32 v[118:119], v[118:119], v[134:135]
	v_pk_fma_f32 v[176:177], v[116:117], v[52:53], v[176:177]
	v_pk_fma_f32 v[178:179], v[118:119], v[54:55], v[178:179]
	global_store_dwordx4 v152, v[176:179], s[64:65] offset:1024
	v_pk_add_f32 v[120:121], v[120:121], v[136:137]
	v_pk_add_f32 v[122:123], v[122:123], v[138:139]
	v_pk_fma_f32 v[180:181], v[120:121], v[60:61], v[180:181]
	v_pk_fma_f32 v[182:183], v[122:123], v[62:63], v[182:183]
	global_store_dwordx4 v152, v[180:183], s[64:65] offset:2048
	v_pk_add_f32 v[124:125], v[124:125], v[140:141]
	v_pk_add_f32 v[126:127], v[126:127], v[142:143]
	v_pk_fma_f32 v[184:185], v[124:125], v[64:65], v[184:185]
	v_pk_fma_f32 v[186:187], v[126:127], v[66:67], v[186:187]
	global_store_dwordx4 v152, v[184:187], s[64:65] offset:3072
	v_add_u32_e32 v152, 0x1000, v152
	v_pk_mul_f32 v[242:243], v[172:173], v[172:173]
	v_pk_mul_f32 v[244:245], v[176:177], v[176:177]
	v_pk_mul_f32 v[246:247], v[174:175], v[174:175]
	v_pk_mul_f32 v[248:249], v[178:179], v[178:179]
	v_add_f32_e32 v204, v245, v244
	v_add_f32_e32 v205, v243, v242
	v_add_f32_e32 v204, v248, v204
	v_add_f32_e32 v205, v246, v205
	v_add_f32_e32 v204, v249, v204
	v_add_f32_e32 v205, v247, v205
	v_pk_mul_f32 v[242:243], v[180:181], v[180:181]
	v_pk_mul_f32 v[244:245], v[184:185], v[184:185]
	v_pk_mul_f32 v[246:247], v[182:183], v[182:183]
	v_pk_mul_f32 v[248:249], v[186:187], v[186:187]
	v_add_f32_e32 v206, v243, v242
	v_add_f32_e32 v207, v245, v244
	v_add_f32_e32 v206, v246, v206
	v_add_f32_e32 v207, v248, v207
	v_add_f32_e32 v206, v247, v206
	v_add_f32_e32 v207, v249, v207
	v_add_f32_e32 v204, v205, v204
	v_add_f32_e32 v204, v204, v206
	v_add_f32_e32 v204, v204, v207
	ds_swizzle_b32 v205, v204 offset:swizzle(SWAP,1)
	s_waitcnt lgkmcnt(0)
	v_add_f32_e32 v204, v204, v205
	ds_swizzle_b32 v205, v204 offset:swizzle(SWAP,2)
	s_waitcnt lgkmcnt(0)
	v_add_f32_e32 v204, v204, v205
	ds_swizzle_b32 v205, v204 offset:swizzle(SWAP,4)
	s_waitcnt lgkmcnt(0)
	v_add_f32_e32 v204, v204, v205
	ds_swizzle_b32 v205, v204 offset:swizzle(SWAP,8)
	s_waitcnt lgkmcnt(0)
	v_add_f32_e32 v204, v204, v205
	ds_swizzle_b32 v205, v204 offset:swizzle(SWAP,16)
	s_waitcnt lgkmcnt(0)
; __device__ __forceinline__ unsigned pk2(float lo, float hi) { const g_f32x2 f = {lo, hi}; return __builtin_bit_cast(unsigned, __builtin_convertvector(f, g_bf16x2)); }
; #define PN_LOAD(dst, rw) do { const float* s_ = (rw) < NLAT ? hlat + (size_t)(rw) * 1024 : hctx + (size_t)((rw) - NLAT) * 1024; \
;         _Pragma("unroll") for (int i = 0; i < 4; ++i) dst[i] = *(const float4*)(s_ + i * 256 + lane * 4); } while (0)
; __device__ __forceinline__ void p_norm(const float* hlat, const float* hctx, const float* g, const float* modl, int sh_off, int sc_off, bf16_t* A, int M,
;                                        const float* part, const float* cgate, float* hcout) {
;     ...
;     if (row < M) PN_LOAD(v, row);
;     ...
;         ss = wave_sum(ss);
;         const float rstd = rsqrtf(ss * (1.0f / 1024.0f) + EPS);
;         const float* mr = modl + (size_t)r * 6144;
; #pragma unroll
;         for (int i = 0; i < 4; ++i) {
;             const int k = i * 256 + lane * 4;
;             const float4 gg = *(const float4*)(g + k), scv = *(const float4*)(mr + sc_off + k), shv = *(const float4*)(mr + sh_off + k);
;             const float o0 = v[i].x * rstd * gg.x * (1.0f + scv.x) + shv.x, o1 = v[i].y * rstd * gg.y * (1.0f + scv.y) + shv.y;
;             const float o2 = v[i].z * rstd * gg.z * (1.0f + scv.z) + shv.z, o3 = v[i].w * rstd * gg.w * (1.0f + scv.w) + shv.w;
;             uint2 w; w.x = pk2(o0, o1); w.y = pk2(o2, o3);
;             *(uint2*)(A + (size_t)row * 1024 + k) = w;
;         }
	v_add_f32_e32 v204, v204, v205
	v_mov_b32_e32 v205, v204
	s_nop 1
	v_permlane32_swap_b32_e32 v204, v205
	v_add_f32_e32 v204, v204, v205
	v_mov_b32_e32 v205, 0x358637bd
	v_fmamk_f32 v204, v204, 0x3a800000, v205
	v_rsq_f32_e32 v204, v204
	s_nop 0
	v_pk_mul_f32 v[172:173], v[172:173], v[204:205] op_sel_hi:[1,0]
	v_pk_mul_f32 v[174:175], v[174:175], v[204:205] op_sel_hi:[1,0]
	v_pk_mul_f32 v[172:173], v[188:189], v[172:173]
	v_pk_mul_f32 v[174:175], v[190:191], v[174:175]
	v_pk_fma_f32 v[172:173], v[34:35], v[172:173], v[224:225]
	v_pk_fma_f32 v[174:175], v[36:37], v[174:175], v[226:227]
	v_cvt_pk_bf16_f32 v172, v172, v173
	v_cvt_pk_bf16_f32 v173, v174, v175
	global_store_dwordx2 v146, v[172:173], s[66:67]
	v_pk_mul_f32 v[176:177], v[176:177], v[204:205] op_sel_hi:[1,0]
	v_pk_mul_f32 v[178:179], v[178:179], v[204:205] op_sel_hi:[1,0]
	v_pk_mul_f32 v[176:177], v[192:193], v[176:177]
	v_pk_mul_f32 v[178:179], v[194:195], v[178:179]
	v_pk_fma_f32 v[176:177], v[38:39], v[176:177], v[228:229]
	v_pk_fma_f32 v[178:179], v[40:41], v[178:179], v[230:231]
	v_cvt_pk_bf16_f32 v176, v176, v177
	v_cvt_pk_bf16_f32 v177, v178, v179
	global_store_dwordx2 v146, v[176:177], s[66:67] offset:512
	v_pk_mul_f32 v[180:181], v[180:181], v[204:205] op_sel_hi:[1,0]
	v_pk_mul_f32 v[182:183], v[182:183], v[204:205] op_sel_hi:[1,0]
	v_pk_mul_f32 v[180:181], v[196:197], v[180:181]
	v_pk_mul_f32 v[182:183], v[198:199], v[182:183]
	v_pk_fma_f32 v[180:181], v[42:43], v[180:181], v[232:233]
	v_pk_fma_f32 v[182:183], v[44:45], v[182:183], v[234:235]
	v_cvt_pk_bf16_f32 v180, v180, v181
	v_cvt_pk_bf16_f32 v181, v182, v183
	global_store_dwordx2 v146, v[180:181], s[66:67] offset:1024
	v_pk_mul_f32 v[184:185], v[184:185], v[204:205] op_sel_hi:[1,0]
	v_pk_mul_f32 v[186:187], v[186:187], v[204:205] op_sel_hi:[1,0]
	v_pk_mul_f32 v[184:185], v[200:201], v[184:185]
	v_pk_mul_f32 v[186:187], v[202:203], v[186:187]
	v_pk_fma_f32 v[184:185], v[46:47], v[184:185], v[236:237]
	v_pk_fma_f32 v[186:187], v[48:49], v[186:187], v[238:239]
	v_cvt_pk_bf16_f32 v184, v184, v185
	v_cvt_pk_bf16_f32 v185, v186, v187
	global_store_dwordx2 v146, v[184:185], s[66:67] offset:1536
	v_add_u32_e32 v146, 0x800, v146
	s_branch .Lnorm_P1_end
.Lnorm_P1_alt:
	global_load_dwordx4 v[80:83], v144, s[46:47]
	global_load_dwordx4 v[84:87], v144, s[46:47] offset:1024
	global_load_dwordx4 v[88:91], v144, s[46:47] offset:2048
	global_load_dwordx4 v[92:95], v144, s[46:47] offset:3072
	v_add_u32_e32 v144, 0x1000, v144
	global_load_dwordx4 v[34:37], v148, s[98:99]
	global_load_dwordx4 v[38:41], v148, s[98:99] offset:1024
	global_load_dwordx4 v[42:45], v148, s[98:99] offset:2048
	global_load_dwordx4 v[46:49], v148, s[98:99] offset:3072
	global_load_dwordx4 v[224:227], v148, s[50:51]
	global_load_dwordx4 v[228:231], v148, s[50:51] offset:1024
	global_load_dwordx4 v[232:235], v148, s[50:51] offset:2048
	global_load_dwordx4 v[236:239], v148, s[50:51] offset:3072
	global_load_dwordx4 v[188:191], v241, s[48:49]
	global_load_dwordx4 v[192:195], v241, s[48:49] offset:1024
	global_load_dwordx4 v[196:199], v241, s[48:49] offset:2048
	global_load_dwordx4 v[200:203], v241, s[48:49] offset:3072
	global_load_dwordx4 v[96:99], v144, s[46:47]
	global_load_dwordx4 v[100:103], v144, s[46:47] offset:1024
	global_load_dwordx4 v[104:107], v144, s[46:47] offset:2048
	global_load_dwordx4 v[108:111], v144, s[46:47] offset:3072
	v_add_u32_e32 v144, 0x1000, v144
	global_load_dwordx4 v[112:115], v144, s[46:47]
	global_load_dwordx4 v[116:119], v144, s[46:47] offset:1024
	global_load_dwordx4 v[120:123], v144, s[46:47] offset:2048
	global_load_dwordx4 v[124:127], v144, s[46:47] offset:3072
	v_add_u32_e32 v144, 0x1000, v144
	global_load_dwordx4 v[128:131], v144, s[46:47]
	global_load_dwordx4 v[132:135], v144, s[46:47] offset:1024
	global_load_dwordx4 v[136:139], v144, s[46:47] offset:2048
	global_load_dwordx4 v[140:143], v144, s[46:47] offset:3072
	v_add_u32_e32 v144, 0x1000, v144
	global_load_dwordx4 v[156:159], v144, s[46:47]
	global_load_dwordx4 v[160:163], v144, s[46:47] offset:1024
	global_load_dwordx4 v[164:167], v144, s[46:47] offset:2048
	global_load_dwordx4 v[168:171], v144, s[46:47] offset:3072
	v_add_u32_e32 v144, 0x1000, v144
	global_load_dwordx4 v[172:175], v144, s[46:47]
	global_load_dwordx4 v[176:179], v144, s[46:47] offset:1024
	global_load_dwordx4 v[180:183], v144, s[46:47] offset:2048
	global_load_dwordx4 v[184:187], v144, s[46:47] offset:3072
	v_add_u32_e32 v144, 0x1000, v144
	s_waitcnt vmcnt(32)
	v_pk_mul_f32 v[242:243], v[80:81], v[80:81]
	v_pk_mul_f32 v[244:245], v[84:85], v[84:85]
	v_pk_mul_f32 v[246:247], v[82:83], v[82:83]
	v_pk_mul_f32 v[248:249], v[86:87], v[86:87]
	v_add_f32_e32 v204, v245, v244
	v_add_f32_e32 v205, v243, v242
	v_add_f32_e32 v204, v248, v204
	v_add_f32_e32 v205, v246, v205
	v_add_f32_e32 v204, v249, v204
	v_add_f32_e32 v205, v247, v205
	v_pk_mul_f32 v[242:243], v[88:89], v[88:89]
	v_pk_mul_f32 v[244:245], v[92:93], v[92:93]
	v_pk_mul_f32 v[246:247], v[90:91], v[90:91]
	v_pk_mul_f32 v[248:249], v[94:95], v[94:95]
	v_add_f32_e32 v206, v243, v242
	v_add_f32_e32 v207, v245, v244
	v_add_f32_e32 v206, v246, v206
	v_add_f32_e32 v207, v248, v207
	v_add_f32_e32 v206, v247, v206
	v_add_f32_e32 v207, v249, v207
	v_add_f32_e32 v204, v205, v204
	v_add_f32_e32 v204, v204, v206
	v_add_f32_e32 v204, v204, v207
	ds_swizzle_b32 v205, v204 offset:swizzle(SWAP,1)
	s_waitcnt lgkmcnt(0)
	v_add_f32_e32 v204, v204, v205
	ds_swizzle_b32 v205, v204 offset:swizzle(SWAP,2)
	s_waitcnt lgkmcnt(0)
	v_add_f32_e32 v204, v204, v205
	ds_swizzle_b32 v205, v204 offset:swizzle(SWAP,4)
	s_waitcnt lgkmcnt(0)
; __device__ __forceinline__ unsigned pk2(float lo, float hi) { const g_f32x2 f = {lo, hi}; return __builtin_bit_cast(unsigned, __builtin_convertvector(f, g_bf16x2)); }
; __device__ __forceinline__ void p_norm(const float* hlat, const float* hctx, const float* g, const float* modl, int sh_off, int sc_off, bf16_t* A, int M,
;                                        const float* part, const float* cgate, float* hcout) {
;     ...
;         ss = wave_sum(ss);
;         const float rstd = rsqrtf(ss * (1.0f / 1024.0f) + EPS);
;         const float* mr = modl + (size_t)r * 6144;
; #pragma unroll
;         for (int i = 0; i < 4; ++i) {
;             const int k = i * 256 + lane * 4;
;             const float4 gg = *(const float4*)(g + k), scv = *(const float4*)(mr + sc_off + k), shv = *(const float4*)(mr + sh_off + k);
;             const float o0 = v[i].x * rstd * gg.x * (1.0f + scv.x) + shv.x, o1 = v[i].y * rstd * gg.y * (1.0f + scv.y) + shv.y;
;             const float o2 = v[i].z * rstd * gg.z * (1.0f + scv.z) + shv.z, o3 = v[i].w * rstd * gg.w * (1.0f + scv.w) + shv.w;
;             uint2 w; w.x = pk2(o0, o1); w.y = pk2(o2, o3);
;             *(uint2*)(A + (size_t)row * 1024 + k) = w;
;         }
	v_add_f32_e32 v204, v204, v205
	ds_swizzle_b32 v205, v204 offset:swizzle(SWAP,8)
	s_waitcnt lgkmcnt(0)
	v_add_f32_e32 v204, v204, v205
	ds_swizzle_b32 v205, v204 offset:swizzle(SWAP,16)
	s_waitcnt lgkmcnt(0)
	v_add_f32_e32 v204, v204, v205
	v_mov_b32_e32 v205, v204
	s_nop 1
	v_permlane32_swap_b32_e32 v204, v205
	v_add_f32_e32 v204, v204, v205
	v_mov_b32_e32 v205, 0x358637bd
	v_fmamk_f32 v204, v204, 0x3a800000, v205
	v_rsq_f32_e32 v204, v204
	s_nop 0
	s_waitcnt vmcnt(20)
	v_pk_add_f32 v[34:35], v[34:35], 1.0 op_sel_hi:[1,0]
	v_pk_add_f32 v[36:37], v[36:37], 1.0 op_sel_hi:[1,0]
	v_pk_add_f32 v[38:39], v[38:39], 1.0 op_sel_hi:[1,0]
	v_pk_add_f32 v[40:41], v[40:41], 1.0 op_sel_hi:[1,0]
	v_pk_add_f32 v[42:43], v[42:43], 1.0 op_sel_hi:[1,0]
	v_pk_add_f32 v[44:45], v[44:45], 1.0 op_sel_hi:[1,0]
	v_pk_add_f32 v[46:47], v[46:47], 1.0 op_sel_hi:[1,0]
	v_pk_add_f32 v[48:49], v[48:49], 1.0 op_sel_hi:[1,0]
	v_pk_mul_f32 v[80:81], v[80:81], v[204:205] op_sel_hi:[1,0]
	v_pk_mul_f32 v[82:83], v[82:83], v[204:205] op_sel_hi:[1,0]
	v_pk_mul_f32 v[80:81], v[188:189], v[80:81]
	v_pk_mul_f32 v[82:83], v[190:191], v[82:83]
	v_pk_fma_f32 v[80:81], v[34:35], v[80:81], v[224:225]
	v_pk_fma_f32 v[82:83], v[36:37], v[82:83], v[226:227]
	v_cvt_pk_bf16_f32 v80, v80, v81
	v_cvt_pk_bf16_f32 v81, v82, v83
	global_store_dwordx2 v146, v[80:81], s[66:67]
	v_pk_mul_f32 v[84:85], v[84:85], v[204:205] op_sel_hi:[1,0]
	v_pk_mul_f32 v[86:87], v[86:87], v[204:205] op_sel_hi:[1,0]
	v_pk_mul_f32 v[84:85], v[192:193], v[84:85]
	v_pk_mul_f32 v[86:87], v[194:195], v[86:87]
	v_pk_fma_f32 v[84:85], v[38:39], v[84:85], v[228:229]
	v_pk_fma_f32 v[86:87], v[40:41], v[86:87], v[230:231]
	v_cvt_pk_bf16_f32 v84, v84, v85
	v_cvt_pk_bf16_f32 v85, v86, v87
	global_store_dwordx2 v146, v[84:85], s[66:67] offset:512
	v_pk_mul_f32 v[88:89], v[88:89], v[204:205] op_sel_hi:[1,0]
	v_pk_mul_f32 v[90:91], v[90:91], v[204:205] op_sel_hi:[1,0]
	v_pk_mul_f32 v[88:89], v[196:197], v[88:89]
	v_pk_mul_f32 v[90:91], v[198:199], v[90:91]
	v_pk_fma_f32 v[88:89], v[42:43], v[88:89], v[232:233]
	v_pk_fma_f32 v[90:91], v[44:45], v[90:91], v[234:235]
	v_cvt_pk_bf16_f32 v88, v88, v89
	v_cvt_pk_bf16_f32 v89, v90, v91
	global_store_dwordx2 v146, v[88:89], s[66:67] offset:1024
	v_pk_mul_f32 v[92:93], v[92:93], v[204:205] op_sel_hi:[1,0]
	v_pk_mul_f32 v[94:95], v[94:95], v[204:205] op_sel_hi:[1,0]
	v_pk_mul_f32 v[92:93], v[200:201], v[92:93]
	v_pk_mul_f32 v[94:95], v[202:203], v[94:95]
	v_pk_fma_f32 v[92:93], v[46:47], v[92:93], v[236:237]
	v_pk_fma_f32 v[94:95], v[48:49], v[94:95], v[238:239]
	v_cvt_pk_bf16_f32 v92, v92, v93
	v_cvt_pk_bf16_f32 v93, v94, v95
	global_store_dwordx2 v146, v[92:93], s[66:67] offset:1536
	v_add_u32_e32 v146, 0x800, v146
	global_load_dwordx4 v[80:83], v144, s[46:47]
	global_load_dwordx4 v[84:87], v144, s[46:47] offset:1024
	global_load_dwordx4 v[88:91], v144, s[46:47] offset:2048
	global_load_dwordx4 v[92:95], v144, s[46:47] offset:3072
	v_add_u32_e32 v144, 0x1000, v144
	s_waitcnt vmcnt(24)
	v_pk_mul_f32 v[242:243], v[96:97], v[96:97]
	v_pk_mul_f32 v[244:245], v[100:101], v[100:101]
	v_pk_mul_f32 v[246:247], v[98:99], v[98:99]
	v_pk_mul_f32 v[248:249], v[102:103], v[102:103]
	v_add_f32_e32 v204, v245, v244
	v_add_f32_e32 v205, v243, v242
	v_add_f32_e32 v204, v248, v204
	v_add_f32_e32 v205, v246, v205
	v_add_f32_e32 v204, v249, v204
	v_add_f32_e32 v205, v247, v205
	v_pk_mul_f32 v[242:243], v[104:105], v[104:105]
	v_pk_mul_f32 v[244:245], v[108:109], v[108:109]
	v_pk_mul_f32 v[246:247], v[106:107], v[106:107]
	v_pk_mul_f32 v[248:249], v[110:111], v[110:111]
	v_add_f32_e32 v206, v243, v242
	v_add_f32_e32 v207, v245, v244
	v_add_f32_e32 v206, v246, v206
	v_add_f32_e32 v207, v248, v207
	v_add_f32_e32 v206, v247, v206
	v_add_f32_e32 v207, v249, v207
	v_add_f32_e32 v204, v205, v204
	v_add_f32_e32 v204, v204, v206
	v_add_f32_e32 v204, v204, v207
	ds_swizzle_b32 v205, v204 offset:swizzle(SWAP,1)
	s_waitcnt lgkmcnt(0)
	v_add_f32_e32 v204, v204, v205
	ds_swizzle_b32 v205, v204 offset:swizzle(SWAP,2)
	s_waitcnt lgkmcnt(0)
	v_add_f32_e32 v204, v204, v205
	ds_swizzle_b32 v205, v204 offset:swizzle(SWAP,4)
	s_waitcnt lgkmcnt(0)
	v_add_f32_e32 v204, v204, v205
	ds_swizzle_b32 v205, v204 offset:swizzle(SWAP,8)
	s_waitcnt lgkmcnt(0)
	v_add_f32_e32 v204, v204, v205
	ds_swizzle_b32 v205, v204 offset:swizzle(SWAP,16)
	s_waitcnt lgkmcnt(0)
	v_add_f32_e32 v204, v204, v205
	v_mov_b32_e32 v205, v204
	s_nop 1
	v_permlane32_swap_b32_e32 v204, v205
	v_add_f32_e32 v204, v204, v205
	v_mov_b32_e32 v205, 0x358637bd
	v_fmamk_f32 v204, v204, 0x3a800000, v205
	v_rsq_f32_e32 v204, v204
	s_nop 0
	v_pk_mul_f32 v[96:97], v[96:97], v[204:205] op_sel_hi:[1,0]
	v_pk_mul_f32 v[98:99], v[98:99], v[204:205] op_sel_hi:[1,0]
	v_pk_mul_f32 v[96:97], v[188:189], v[96:97]
	v_pk_mul_f32 v[98:99], v[190:191], v[98:99]
	v_pk_fma_f32 v[96:97], v[34:35], v[96:97], v[224:225]
	v_pk_fma_f32 v[98:99], v[36:37], v[98:99], v[226:227]
	v_cvt_pk_bf16_f32 v96, v96, v97
	v_cvt_pk_bf16_f32 v97, v98, v99
	global_store_dwordx2 v146, v[96:97], s[66:67]
	v_pk_mul_f32 v[100:101], v[100:101], v[204:205] op_sel_hi:[1,0]
	v_pk_mul_f32 v[102:103], v[102:103], v[204:205] op_sel_hi:[1,0]
	v_pk_mul_f32 v[100:101], v[192:193], v[100:101]
	v_pk_mul_f32 v[102:103], v[194:195], v[102:103]
	v_pk_fma_f32 v[100:101], v[38:39], v[100:101], v[228:229]
	v_pk_fma_f32 v[102:103], v[40:41], v[102:103], v[230:231]
	v_cvt_pk_bf16_f32 v100, v100, v101
	v_cvt_pk_bf16_f32 v101, v102, v103
	global_store_dwordx2 v146, v[100:101], s[66:67] offset:512
	v_pk_mul_f32 v[104:105], v[104:105], v[204:205] op_sel_hi:[1,0]
	v_pk_mul_f32 v[106:107], v[106:107], v[204:205] op_sel_hi:[1,0]
	v_pk_mul_f32 v[104:105], v[196:197], v[104:105]
	v_pk_mul_f32 v[106:107], v[198:199], v[106:107]
	v_pk_fma_f32 v[104:105], v[42:43], v[104:105], v[232:233]
	v_pk_fma_f32 v[106:107], v[44:45], v[106:107], v[234:235]
	v_cvt_pk_bf16_f32 v104, v104, v105
	v_cvt_pk_bf16_f32 v105, v106, v107
	global_store_dwordx2 v146, v[104:105], s[66:67] offset:1024
	v_pk_mul_f32 v[108:109], v[108:109], v[204:205] op_sel_hi:[1,0]
	v_pk_mul_f32 v[110:111], v[110:111], v[204:205] op_sel_hi:[1,0]
	v_pk_mul_f32 v[108:109], v[200:201], v[108:109]
	v_pk_mul_f32 v[110:111], v[202:203], v[110:111]
	v_pk_fma_f32 v[108:109], v[46:47], v[108:109], v[236:237]
	v_pk_fma_f32 v[110:111], v[48:49], v[110:111], v[238:239]
	v_cvt_pk_bf16_f32 v108, v108, v109
	v_cvt_pk_bf16_f32 v109, v110, v111
	global_store_dwordx2 v146, v[108:109], s[66:67] offset:1536
	v_add_u32_e32 v146, 0x800, v146
	global_load_dwordx4 v[96:99], v144, s[46:47]
	global_load_dwordx4 v[100:103], v144, s[46:47] offset:1024
	global_load_dwordx4 v[104:107], v144, s[46:47] offset:2048
	global_load_dwordx4 v[108:111], v144, s[46:47] offset:3072
	v_add_u32_e32 v144, 0x1000, v144
	s_waitcnt vmcnt(28)
; __device__ __forceinline__ unsigned pk2(float lo, float hi) { const g_f32x2 f = {lo, hi}; return __builtin_bit_cast(unsigned, __builtin_convertvector(f, g_bf16x2)); }
; __device__ __forceinline__ void p_norm(const float* hlat, const float* hctx, const float* g, const float* modl, int sh_off, int sc_off, bf16_t* A, int M,
;                                        const float* part, const float* cgate, float* hcout) {
;     ...
;         ss = wave_sum(ss);
;         const float rstd = rsqrtf(ss * (1.0f / 1024.0f) + EPS);
;         const float* mr = modl + (size_t)r * 6144;
; #pragma unroll
;         for (int i = 0; i < 4; ++i) {
;             const int k = i * 256 + lane * 4;
;             const float4 gg = *(const float4*)(g + k), scv = *(const float4*)(mr + sc_off + k), shv = *(const float4*)(mr + sh_off + k);
;             const float o0 = v[i].x * rstd * gg.x * (1.0f + scv.x) + shv.x, o1 = v[i].y * rstd * gg.y * (1.0f + scv.y) + shv.y;
;             const float o2 = v[i].z * rstd * gg.z * (1.0f + scv.z) + shv.z, o3 = v[i].w * rstd * gg.w * (1.0f + scv.w) + shv.w;
;             uint2 w; w.x = pk2(o0, o1); w.y = pk2(o2, o3);
;             *(uint2*)(A + (size_t)row * 1024 + k) = w;
;         }
	v_pk_mul_f32 v[242:243], v[112:113], v[112:113]
	v_pk_mul_f32 v[244:245], v[116:117], v[116:117]
	v_pk_mul_f32 v[246:247], v[114:115], v[114:115]
	v_pk_mul_f32 v[248:249], v[118:119], v[118:119]
	v_add_f32_e32 v204, v245, v244
	v_add_f32_e32 v205, v243, v242
	v_add_f32_e32 v204, v248, v204
	v_add_f32_e32 v205, v246, v205
	v_add_f32_e32 v204, v249, v204
	v_add_f32_e32 v205, v247, v205
	v_pk_mul_f32 v[242:243], v[120:121], v[120:121]
	v_pk_mul_f32 v[244:245], v[124:125], v[124:125]
	v_pk_mul_f32 v[246:247], v[122:123], v[122:123]
	v_pk_mul_f32 v[248:249], v[126:127], v[126:127]
	v_add_f32_e32 v206, v243, v242
	v_add_f32_e32 v207, v245, v244
	v_add_f32_e32 v206, v246, v206
	v_add_f32_e32 v207, v248, v207
	v_add_f32_e32 v206, v247, v206
	v_add_f32_e32 v207, v249, v207
	v_add_f32_e32 v204, v205, v204
	v_add_f32_e32 v204, v204, v206
	v_add_f32_e32 v204, v204, v207
	ds_swizzle_b32 v205, v204 offset:swizzle(SWAP,1)
	s_waitcnt lgkmcnt(0)
	v_add_f32_e32 v204, v204, v205
	ds_swizzle_b32 v205, v204 offset:swizzle(SWAP,2)
	s_waitcnt lgkmcnt(0)
	v_add_f32_e32 v204, v204, v205
	ds_swizzle_b32 v205, v204 offset:swizzle(SWAP,4)
	s_waitcnt lgkmcnt(0)
	v_add_f32_e32 v204, v204, v205
	ds_swizzle_b32 v205, v204 offset:swizzle(SWAP,8)
	s_waitcnt lgkmcnt(0)
	v_add_f32_e32 v204, v204, v205
	ds_swizzle_b32 v205, v204 offset:swizzle(SWAP,16)
	s_waitcnt lgkmcnt(0)
	v_add_f32_e32 v204, v204, v205
	v_mov_b32_e32 v205, v204
	s_nop 1
	v_permlane32_swap_b32_e32 v204, v205
	v_add_f32_e32 v204, v204, v205
	v_mov_b32_e32 v205, 0x358637bd
	v_fmamk_f32 v204, v204, 0x3a800000, v205
	v_rsq_f32_e32 v204, v204
	s_nop 0
	v_pk_mul_f32 v[112:113], v[112:113], v[204:205] op_sel_hi:[1,0]
	v_pk_mul_f32 v[114:115], v[114:115], v[204:205] op_sel_hi:[1,0]
	v_pk_mul_f32 v[112:113], v[188:189], v[112:113]
	v_pk_mul_f32 v[114:115], v[190:191], v[114:115]
	v_pk_fma_f32 v[112:113], v[34:35], v[112:113], v[224:225]
	v_pk_fma_f32 v[114:115], v[36:37], v[114:115], v[226:227]
	v_cvt_pk_bf16_f32 v112, v112, v113
	v_cvt_pk_bf16_f32 v113, v114, v115
	global_store_dwordx2 v146, v[112:113], s[66:67]
	v_pk_mul_f32 v[116:117], v[116:117], v[204:205] op_sel_hi:[1,0]
	v_pk_mul_f32 v[118:119], v[118:119], v[204:205] op_sel_hi:[1,0]
	v_pk_mul_f32 v[116:117], v[192:193], v[116:117]
	v_pk_mul_f32 v[118:119], v[194:195], v[118:119]
	v_pk_fma_f32 v[116:117], v[38:39], v[116:117], v[228:229]
	v_pk_fma_f32 v[118:119], v[40:41], v[118:119], v[230:231]
	v_cvt_pk_bf16_f32 v116, v116, v117
	v_cvt_pk_bf16_f32 v117, v118, v119
	global_store_dwordx2 v146, v[116:117], s[66:67] offset:512
	v_pk_mul_f32 v[120:121], v[120:121], v[204:205] op_sel_hi:[1,0]
	v_pk_mul_f32 v[122:123], v[122:123], v[204:205] op_sel_hi:[1,0]
	v_pk_mul_f32 v[120:121], v[196:197], v[120:121]
	v_pk_mul_f32 v[122:123], v[198:199], v[122:123]
	v_pk_fma_f32 v[120:121], v[42:43], v[120:121], v[232:233]
	v_pk_fma_f32 v[122:123], v[44:45], v[122:123], v[234:235]
	v_cvt_pk_bf16_f32 v120, v120, v121
	v_cvt_pk_bf16_f32 v121, v122, v123
	global_store_dwordx2 v146, v[120:121], s[66:67] offset:1024
	v_pk_mul_f32 v[124:125], v[124:125], v[204:205] op_sel_hi:[1,0]
	v_pk_mul_f32 v[126:127], v[126:127], v[204:205] op_sel_hi:[1,0]
	v_pk_mul_f32 v[124:125], v[200:201], v[124:125]
	v_pk_mul_f32 v[126:127], v[202:203], v[126:127]
	v_pk_fma_f32 v[124:125], v[46:47], v[124:125], v[236:237]
	v_pk_fma_f32 v[126:127], v[48:49], v[126:127], v[238:239]
	v_cvt_pk_bf16_f32 v124, v124, v125
	v_cvt_pk_bf16_f32 v125, v126, v127
	global_store_dwordx2 v146, v[124:125], s[66:67] offset:1536
	v_add_u32_e32 v146, 0x800, v146
	global_load_dwordx4 v[112:115], v144, s[46:47]
	global_load_dwordx4 v[116:119], v144, s[46:47] offset:1024
	global_load_dwordx4 v[120:123], v144, s[46:47] offset:2048
	global_load_dwordx4 v[124:127], v144, s[46:47] offset:3072
	v_add_u32_e32 v144, 0x1000, v144
	s_waitcnt vmcnt(32)
	v_pk_mul_f32 v[242:243], v[128:129], v[128:129]
	v_pk_mul_f32 v[244:245], v[132:133], v[132:133]
	v_pk_mul_f32 v[246:247], v[130:131], v[130:131]
	v_pk_mul_f32 v[248:249], v[134:135], v[134:135]
	v_add_f32_e32 v204, v245, v244
	v_add_f32_e32 v205, v243, v242
	v_add_f32_e32 v204, v248, v204
	v_add_f32_e32 v205, v246, v205
	v_add_f32_e32 v204, v249, v204
	v_add_f32_e32 v205, v247, v205
	v_pk_mul_f32 v[242:243], v[136:137], v[136:137]
	v_pk_mul_f32 v[244:245], v[140:141], v[140:141]
	v_pk_mul_f32 v[246:247], v[138:139], v[138:139]
	v_pk_mul_f32 v[248:249], v[142:143], v[142:143]
	v_add_f32_e32 v206, v243, v242
	v_add_f32_e32 v207, v245, v244
	v_add_f32_e32 v206, v246, v206
	v_add_f32_e32 v207, v248, v207
	v_add_f32_e32 v206, v247, v206
	v_add_f32_e32 v207, v249, v207
	v_add_f32_e32 v204, v205, v204
	v_add_f32_e32 v204, v204, v206
	v_add_f32_e32 v204, v204, v207
	ds_swizzle_b32 v205, v204 offset:swizzle(SWAP,1)
	s_waitcnt lgkmcnt(0)
	v_add_f32_e32 v204, v204, v205
	ds_swizzle_b32 v205, v204 offset:swizzle(SWAP,2)
	s_waitcnt lgkmcnt(0)
	v_add_f32_e32 v204, v204, v205
	ds_swizzle_b32 v205, v204 offset:swizzle(SWAP,4)
	s_waitcnt lgkmcnt(0)
	v_add_f32_e32 v204, v204, v205
	ds_swizzle_b32 v205, v204 offset:swizzle(SWAP,8)
	s_waitcnt lgkmcnt(0)
	v_add_f32_e32 v204, v204, v205
	ds_swizzle_b32 v205, v204 offset:swizzle(SWAP,16)
	s_waitcnt lgkmcnt(0)
; __device__ __forceinline__ unsigned pk2(float lo, float hi) { const g_f32x2 f = {lo, hi}; return __builtin_bit_cast(unsigned, __builtin_convertvector(f, g_bf16x2)); }
; __device__ __forceinline__ void p_norm(const float* hlat, const float* hctx, const float* g, const float* modl, int sh_off, int sc_off, bf16_t* A, int M,
;                                        const float* part, const float* cgate, float* hcout) {
;     ...
;         ss = wave_sum(ss);
;         const float rstd = rsqrtf(ss * (1.0f / 1024.0f) + EPS);
;         const float* mr = modl + (size_t)r * 6144;
; #pragma unroll
;         for (int i = 0; i < 4; ++i) {
;             const int k = i * 256 + lane * 4;
;             const float4 gg = *(const float4*)(g + k), scv = *(const float4*)(mr + sc_off + k), shv = *(const float4*)(mr + sh_off + k);
;             const float o0 = v[i].x * rstd * gg.x * (1.0f + scv.x) + shv.x, o1 = v[i].y * rstd * gg.y * (1.0f + scv.y) + shv.y;
;             const float o2 = v[i].z * rstd * gg.z * (1.0f + scv.z) + shv.z, o3 = v[i].w * rstd * gg.w * (1.0f + scv.w) + shv.w;
;             uint2 w; w.x = pk2(o0, o1); w.y = pk2(o2, o3);
;             *(uint2*)(A + (size_t)row * 1024 + k) = w;
;         }
	v_add_f32_e32 v204, v204, v205
	v_mov_b32_e32 v205, v204
	s_nop 1
	v_permlane32_swap_b32_e32 v204, v205
	v_add_f32_e32 v204, v204, v205
	v_mov_b32_e32 v205, 0x358637bd
	v_fmamk_f32 v204, v204, 0x3a800000, v205
	v_rsq_f32_e32 v204, v204
	s_nop 0
	v_pk_mul_f32 v[128:129], v[128:129], v[204:205] op_sel_hi:[1,0]
	v_pk_mul_f32 v[130:131], v[130:131], v[204:205] op_sel_hi:[1,0]
	v_pk_mul_f32 v[128:129], v[188:189], v[128:129]
	v_pk_mul_f32 v[130:131], v[190:191], v[130:131]
	v_pk_fma_f32 v[128:129], v[34:35], v[128:129], v[224:225]
	v_pk_fma_f32 v[130:131], v[36:37], v[130:131], v[226:227]
	v_cvt_pk_bf16_f32 v128, v128, v129
	v_cvt_pk_bf16_f32 v129, v130, v131
	global_store_dwordx2 v146, v[128:129], s[66:67]
	v_pk_mul_f32 v[132:133], v[132:133], v[204:205] op_sel_hi:[1,0]
	v_pk_mul_f32 v[134:135], v[134:135], v[204:205] op_sel_hi:[1,0]
	v_pk_mul_f32 v[132:133], v[192:193], v[132:133]
	v_pk_mul_f32 v[134:135], v[194:195], v[134:135]
	v_pk_fma_f32 v[132:133], v[38:39], v[132:133], v[228:229]
	v_pk_fma_f32 v[134:135], v[40:41], v[134:135], v[230:231]
	v_cvt_pk_bf16_f32 v132, v132, v133
	v_cvt_pk_bf16_f32 v133, v134, v135
	global_store_dwordx2 v146, v[132:133], s[66:67] offset:512
	v_pk_mul_f32 v[136:137], v[136:137], v[204:205] op_sel_hi:[1,0]
	v_pk_mul_f32 v[138:139], v[138:139], v[204:205] op_sel_hi:[1,0]
	v_pk_mul_f32 v[136:137], v[196:197], v[136:137]
	v_pk_mul_f32 v[138:139], v[198:199], v[138:139]
	v_pk_fma_f32 v[136:137], v[42:43], v[136:137], v[232:233]
	v_pk_fma_f32 v[138:139], v[44:45], v[138:139], v[234:235]
	v_cvt_pk_bf16_f32 v136, v136, v137
	v_cvt_pk_bf16_f32 v137, v138, v139
	global_store_dwordx2 v146, v[136:137], s[66:67] offset:1024
	v_pk_mul_f32 v[140:141], v[140:141], v[204:205] op_sel_hi:[1,0]
	v_pk_mul_f32 v[142:143], v[142:143], v[204:205] op_sel_hi:[1,0]
	v_pk_mul_f32 v[140:141], v[200:201], v[140:141]
	v_pk_mul_f32 v[142:143], v[202:203], v[142:143]
	v_pk_fma_f32 v[140:141], v[46:47], v[140:141], v[236:237]
	v_pk_fma_f32 v[142:143], v[48:49], v[142:143], v[238:239]
	v_cvt_pk_bf16_f32 v140, v140, v141
	v_cvt_pk_bf16_f32 v141, v142, v143
	global_store_dwordx2 v146, v[140:141], s[66:67] offset:1536
	v_add_u32_e32 v146, 0x800, v146
	global_load_dwordx4 v[128:131], v144, s[46:47]
	global_load_dwordx4 v[132:135], v144, s[46:47] offset:1024
	global_load_dwordx4 v[136:139], v144, s[46:47] offset:2048
	global_load_dwordx4 v[140:143], v144, s[46:47] offset:3072
	v_add_u32_e32 v144, 0x1000, v144
	s_waitcnt vmcnt(36)
	v_pk_mul_f32 v[242:243], v[156:157], v[156:157]
	v_pk_mul_f32 v[244:245], v[160:161], v[160:161]
	v_pk_mul_f32 v[246:247], v[158:159], v[158:159]
	v_pk_mul_f32 v[248:249], v[162:163], v[162:163]
	v_add_f32_e32 v204, v245, v244
	v_add_f32_e32 v205, v243, v242
	v_add_f32_e32 v204, v248, v204
	v_add_f32_e32 v205, v246, v205
	v_add_f32_e32 v204, v249, v204
	v_add_f32_e32 v205, v247, v205
	v_pk_mul_f32 v[242:243], v[164:165], v[164:165]
	v_pk_mul_f32 v[244:245], v[168:169], v[168:169]
	v_pk_mul_f32 v[246:247], v[166:167], v[166:167]
	v_pk_mul_f32 v[248:249], v[170:171], v[170:171]
	v_add_f32_e32 v206, v243, v242
	v_add_f32_e32 v207, v245, v244
	v_add_f32_e32 v206, v246, v206
	v_add_f32_e32 v207, v248, v207
	v_add_f32_e32 v206, v247, v206
	v_add_f32_e32 v207, v249, v207
	v_add_f32_e32 v204, v205, v204
	v_add_f32_e32 v204, v204, v206
	v_add_f32_e32 v204, v204, v207
	ds_swizzle_b32 v205, v204 offset:swizzle(SWAP,1)
	s_waitcnt lgkmcnt(0)
	v_add_f32_e32 v204, v204, v205
	ds_swizzle_b32 v205, v204 offset:swizzle(SWAP,2)
	s_waitcnt lgkmcnt(0)
	v_add_f32_e32 v204, v204, v205
	ds_swizzle_b32 v205, v204 offset:swizzle(SWAP,4)
	s_waitcnt lgkmcnt(0)
	v_add_f32_e32 v204, v204, v205
	ds_swizzle_b32 v205, v204 offset:swizzle(SWAP,8)
	s_waitcnt lgkmcnt(0)
	v_add_f32_e32 v204, v204, v205
	ds_swizzle_b32 v205, v204 offset:swizzle(SWAP,16)
	s_waitcnt lgkmcnt(0)
	v_add_f32_e32 v204, v204, v205
	v_mov_b32_e32 v205, v204
	s_nop 1
	v_permlane32_swap_b32_e32 v204, v205
	v_add_f32_e32 v204, v204, v205
	v_mov_b32_e32 v205, 0x358637bd
	v_fmamk_f32 v204, v204, 0x3a800000, v205
	v_rsq_f32_e32 v204, v204
	s_nop 0
	v_pk_mul_f32 v[156:157], v[156:157], v[204:205] op_sel_hi:[1,0]
	v_pk_mul_f32 v[158:159], v[158:159], v[204:205] op_sel_hi:[1,0]
	v_pk_mul_f32 v[156:157], v[188:189], v[156:157]
	v_pk_mul_f32 v[158:159], v[190:191], v[158:159]
	v_pk_fma_f32 v[156:157], v[34:35], v[156:157], v[224:225]
	v_pk_fma_f32 v[158:159], v[36:37], v[158:159], v[226:227]
	v_cvt_pk_bf16_f32 v156, v156, v157
	v_cvt_pk_bf16_f32 v157, v158, v159
	global_store_dwordx2 v146, v[156:157], s[66:67]
	v_pk_mul_f32 v[160:161], v[160:161], v[204:205] op_sel_hi:[1,0]
	v_pk_mul_f32 v[162:163], v[162:163], v[204:205] op_sel_hi:[1,0]
	v_pk_mul_f32 v[160:161], v[192:193], v[160:161]
	v_pk_mul_f32 v[162:163], v[194:195], v[162:163]
	v_pk_fma_f32 v[160:161], v[38:39], v[160:161], v[228:229]
	v_pk_fma_f32 v[162:163], v[40:41], v[162:163], v[230:231]
	v_cvt_pk_bf16_f32 v160, v160, v161
	v_cvt_pk_bf16_f32 v161, v162, v163
	global_store_dwordx2 v146, v[160:161], s[66:67] offset:512
	v_pk_mul_f32 v[164:165], v[164:165], v[204:205] op_sel_hi:[1,0]
	v_pk_mul_f32 v[166:167], v[166:167], v[204:205] op_sel_hi:[1,0]
	v_pk_mul_f32 v[164:165], v[196:197], v[164:165]
	v_pk_mul_f32 v[166:167], v[198:199], v[166:167]
	v_pk_fma_f32 v[164:165], v[42:43], v[164:165], v[232:233]
	v_pk_fma_f32 v[166:167], v[44:45], v[166:167], v[234:235]
	v_cvt_pk_bf16_f32 v164, v164, v165
	v_cvt_pk_bf16_f32 v165, v166, v167
	global_store_dwordx2 v146, v[164:165], s[66:67] offset:1024
	v_pk_mul_f32 v[168:169], v[168:169], v[204:205] op_sel_hi:[1,0]
	v_pk_mul_f32 v[170:171], v[170:171], v[204:205] op_sel_hi:[1,0]
	v_pk_mul_f32 v[168:169], v[200:201], v[168:169]
	v_pk_mul_f32 v[170:171], v[202:203], v[170:171]
	v_pk_fma_f32 v[168:169], v[46:47], v[168:169], v[236:237]
	v_pk_fma_f32 v[170:171], v[48:49], v[170:171], v[238:239]
	v_cvt_pk_bf16_f32 v168, v168, v169
	v_cvt_pk_bf16_f32 v169, v170, v171
	global_store_dwordx2 v146, v[168:169], s[66:67] offset:1536
	v_add_u32_e32 v146, 0x800, v146
	global_load_dwordx4 v[156:159], v144, s[46:47]
	global_load_dwordx4 v[160:163], v144, s[46:47] offset:1024
	global_load_dwordx4 v[164:167], v144, s[46:47] offset:2048
	global_load_dwordx4 v[168:171], v144, s[46:47] offset:3072
	v_add_u32_e32 v144, 0x1000, v144
	s_waitcnt vmcnt(40)
; __device__ __forceinline__ unsigned pk2(float lo, float hi) { const g_f32x2 f = {lo, hi}; return __builtin_bit_cast(unsigned, __builtin_convertvector(f, g_bf16x2)); }
; __device__ __forceinline__ void p_norm(const float* hlat, const float* hctx, const float* g, const float* modl, int sh_off, int sc_off, bf16_t* A, int M,
;                                        const float* part, const float* cgate, float* hcout) {
;     ...
;         ss = wave_sum(ss);
;         const float rstd = rsqrtf(ss * (1.0f / 1024.0f) + EPS);
;         const float* mr = modl + (size_t)r * 6144;
; #pragma unroll
;         for (int i = 0; i < 4; ++i) {
;             const int k = i * 256 + lane * 4;
;             const float4 gg = *(const float4*)(g + k), scv = *(const float4*)(mr + sc_off + k), shv = *(const float4*)(mr + sh_off + k);
;             const float o0 = v[i].x * rstd * gg.x * (1.0f + scv.x) + shv.x, o1 = v[i].y * rstd * gg.y * (1.0f + scv.y) + shv.y;
;             const float o2 = v[i].z * rstd * gg.z * (1.0f + scv.z) + shv.z, o3 = v[i].w * rstd * gg.w * (1.0f + scv.w) + shv.w;
;             uint2 w; w.x = pk2(o0, o1); w.y = pk2(o2, o3);
;             *(uint2*)(A + (size_t)row * 1024 + k) = w;
;         }
	v_pk_mul_f32 v[242:243], v[172:173], v[172:173]
	v_pk_mul_f32 v[244:245], v[176:177], v[176:177]
	v_pk_mul_f32 v[246:247], v[174:175], v[174:175]
	v_pk_mul_f32 v[248:249], v[178:179], v[178:179]
	v_add_f32_e32 v204, v245, v244
	v_add_f32_e32 v205, v243, v242
	v_add_f32_e32 v204, v248, v204
	v_add_f32_e32 v205, v246, v205
	v_add_f32_e32 v204, v249, v204
	v_add_f32_e32 v205, v247, v205
	v_pk_mul_f32 v[242:243], v[180:181], v[180:181]
	v_pk_mul_f32 v[244:245], v[184:185], v[184:185]
	v_pk_mul_f32 v[246:247], v[182:183], v[182:183]
	v_pk_mul_f32 v[248:249], v[186:187], v[186:187]
	v_add_f32_e32 v206, v243, v242
	v_add_f32_e32 v207, v245, v244
	v_add_f32_e32 v206, v246, v206
	v_add_f32_e32 v207, v248, v207
	v_add_f32_e32 v206, v247, v206
	v_add_f32_e32 v207, v249, v207
	v_add_f32_e32 v204, v205, v204
	v_add_f32_e32 v204, v204, v206
	v_add_f32_e32 v204, v204, v207
	ds_swizzle_b32 v205, v204 offset:swizzle(SWAP,1)
	s_waitcnt lgkmcnt(0)
	v_add_f32_e32 v204, v204, v205
	ds_swizzle_b32 v205, v204 offset:swizzle(SWAP,2)
	s_waitcnt lgkmcnt(0)
	v_add_f32_e32 v204, v204, v205
	ds_swizzle_b32 v205, v204 offset:swizzle(SWAP,4)
	s_waitcnt lgkmcnt(0)
	v_add_f32_e32 v204, v204, v205
	ds_swizzle_b32 v205, v204 offset:swizzle(SWAP,8)
	s_waitcnt lgkmcnt(0)
	v_add_f32_e32 v204, v204, v205
	ds_swizzle_b32 v205, v204 offset:swizzle(SWAP,16)
	s_waitcnt lgkmcnt(0)
	v_add_f32_e32 v204, v204, v205
	v_mov_b32_e32 v205, v204
	s_nop 1
	v_permlane32_swap_b32_e32 v204, v205
	v_add_f32_e32 v204, v204, v205
	v_mov_b32_e32 v205, 0x358637bd
	v_fmamk_f32 v204, v204, 0x3a800000, v205
	v_rsq_f32_e32 v204, v204
	s_nop 0
	v_pk_mul_f32 v[172:173], v[172:173], v[204:205] op_sel_hi:[1,0]
	v_pk_mul_f32 v[174:175], v[174:175], v[204:205] op_sel_hi:[1,0]
	v_pk_mul_f32 v[172:173], v[188:189], v[172:173]
	v_pk_mul_f32 v[174:175], v[190:191], v[174:175]
	v_pk_fma_f32 v[172:173], v[34:35], v[172:173], v[224:225]
	v_pk_fma_f32 v[174:175], v[36:37], v[174:175], v[226:227]
	v_cvt_pk_bf16_f32 v172, v172, v173
	v_cvt_pk_bf16_f32 v173, v174, v175
	global_store_dwordx2 v146, v[172:173], s[66:67]
	v_pk_mul_f32 v[176:177], v[176:177], v[204:205] op_sel_hi:[1,0]
	v_pk_mul_f32 v[178:179], v[178:179], v[204:205] op_sel_hi:[1,0]
	v_pk_mul_f32 v[176:177], v[192:193], v[176:177]
	v_pk_mul_f32 v[178:179], v[194:195], v[178:179]
	v_pk_fma_f32 v[176:177], v[38:39], v[176:177], v[228:229]
	v_pk_fma_f32 v[178:179], v[40:41], v[178:179], v[230:231]
	v_cvt_pk_bf16_f32 v176, v176, v177
	v_cvt_pk_bf16_f32 v177, v178, v179
	global_store_dwordx2 v146, v[176:177], s[66:67] offset:512
	v_pk_mul_f32 v[180:181], v[180:181], v[204:205] op_sel_hi:[1,0]
	v_pk_mul_f32 v[182:183], v[182:183], v[204:205] op_sel_hi:[1,0]
	v_pk_mul_f32 v[180:181], v[196:197], v[180:181]
	v_pk_mul_f32 v[182:183], v[198:199], v[182:183]
	v_pk_fma_f32 v[180:181], v[42:43], v[180:181], v[232:233]
	v_pk_fma_f32 v[182:183], v[44:45], v[182:183], v[234:235]
	v_cvt_pk_bf16_f32 v180, v180, v181
	v_cvt_pk_bf16_f32 v181, v182, v183
	global_store_dwordx2 v146, v[180:181], s[66:67] offset:1024
	v_pk_mul_f32 v[184:185], v[184:185], v[204:205] op_sel_hi:[1,0]
	v_pk_mul_f32 v[186:187], v[186:187], v[204:205] op_sel_hi:[1,0]
	v_pk_mul_f32 v[184:185], v[200:201], v[184:185]
	v_pk_mul_f32 v[186:187], v[202:203], v[186:187]
	v_pk_fma_f32 v[184:185], v[46:47], v[184:185], v[236:237]
	v_pk_fma_f32 v[186:187], v[48:49], v[186:187], v[238:239]
	v_cvt_pk_bf16_f32 v184, v184, v185
	v_cvt_pk_bf16_f32 v185, v186, v187
	global_store_dwordx2 v146, v[184:185], s[66:67] offset:1536
	v_add_u32_e32 v146, 0x800, v146
	global_load_dwordx4 v[172:175], v144, s[46:47]
	global_load_dwordx4 v[176:179], v144, s[46:47] offset:1024
	global_load_dwordx4 v[180:183], v144, s[46:47] offset:2048
	global_load_dwordx4 v[184:187], v144, s[46:47] offset:3072
	v_add_u32_e32 v144, 0x1000, v144
	s_waitcnt vmcnt(40)
	v_pk_mul_f32 v[242:243], v[80:81], v[80:81]
	v_pk_mul_f32 v[244:245], v[84:85], v[84:85]
	v_pk_mul_f32 v[246:247], v[82:83], v[82:83]
	v_pk_mul_f32 v[248:249], v[86:87], v[86:87]
	v_add_f32_e32 v204, v245, v244
	v_add_f32_e32 v205, v243, v242
	v_add_f32_e32 v204, v248, v204
	v_add_f32_e32 v205, v246, v205
	v_add_f32_e32 v204, v249, v204
	v_add_f32_e32 v205, v247, v205
	v_pk_mul_f32 v[242:243], v[88:89], v[88:89]
	v_pk_mul_f32 v[244:245], v[92:93], v[92:93]
	v_pk_mul_f32 v[246:247], v[90:91], v[90:91]
	v_pk_mul_f32 v[248:249], v[94:95], v[94:95]
	v_add_f32_e32 v206, v243, v242
	v_add_f32_e32 v207, v245, v244
	v_add_f32_e32 v206, v246, v206
	v_add_f32_e32 v207, v248, v207
	v_add_f32_e32 v206, v247, v206
	v_add_f32_e32 v207, v249, v207
	v_add_f32_e32 v204, v205, v204
	v_add_f32_e32 v204, v204, v206
	v_add_f32_e32 v204, v204, v207
	ds_swizzle_b32 v205, v204 offset:swizzle(SWAP,1)
	s_waitcnt lgkmcnt(0)
	v_add_f32_e32 v204, v204, v205
	ds_swizzle_b32 v205, v204 offset:swizzle(SWAP,2)
	s_waitcnt lgkmcnt(0)
	v_add_f32_e32 v204, v204, v205
	ds_swizzle_b32 v205, v204 offset:swizzle(SWAP,4)
	s_waitcnt lgkmcnt(0)
	v_add_f32_e32 v204, v204, v205
	ds_swizzle_b32 v205, v204 offset:swizzle(SWAP,8)
	s_waitcnt lgkmcnt(0)
	v_add_f32_e32 v204, v204, v205
	ds_swizzle_b32 v205, v204 offset:swizzle(SWAP,16)
	s_waitcnt lgkmcnt(0)
; __device__ __forceinline__ unsigned pk2(float lo, float hi) { const g_f32x2 f = {lo, hi}; return __builtin_bit_cast(unsigned, __builtin_convertvector(f, g_bf16x2)); }
; __device__ __forceinline__ void p_norm(const float* hlat, const float* hctx, const float* g, const float* modl, int sh_off, int sc_off, bf16_t* A, int M,
;                                        const float* part, const float* cgate, float* hcout) {
;     ...
;         ss = wave_sum(ss);
;         const float rstd = rsqrtf(ss * (1.0f / 1024.0f) + EPS);
;         const float* mr = modl + (size_t)r * 6144;
; #pragma unroll
;         for (int i = 0; i < 4; ++i) {
;             const int k = i * 256 + lane * 4;
;             const float4 gg = *(const float4*)(g + k), scv = *(const float4*)(mr + sc_off + k), shv = *(const float4*)(mr + sh_off + k);
;             const float o0 = v[i].x * rstd * gg.x * (1.0f + scv.x) + shv.x, o1 = v[i].y * rstd * gg.y * (1.0f + scv.y) + shv.y;
;             const float o2 = v[i].z * rstd * gg.z * (1.0f + scv.z) + shv.z, o3 = v[i].w * rstd * gg.w * (1.0f + scv.w) + shv.w;
;             uint2 w; w.x = pk2(o0, o1); w.y = pk2(o2, o3);
;             *(uint2*)(A + (size_t)row * 1024 + k) = w;
;         }
	v_add_f32_e32 v204, v204, v205
	v_mov_b32_e32 v205, v204
	s_nop 1
	v_permlane32_swap_b32_e32 v204, v205
	v_add_f32_e32 v204, v204, v205
	v_mov_b32_e32 v205, 0x358637bd
	v_fmamk_f32 v204, v204, 0x3a800000, v205
	v_rsq_f32_e32 v204, v204
	s_nop 0
	v_pk_mul_f32 v[80:81], v[80:81], v[204:205] op_sel_hi:[1,0]
	v_pk_mul_f32 v[82:83], v[82:83], v[204:205] op_sel_hi:[1,0]
	v_pk_mul_f32 v[80:81], v[188:189], v[80:81]
	v_pk_mul_f32 v[82:83], v[190:191], v[82:83]
	v_pk_fma_f32 v[80:81], v[34:35], v[80:81], v[224:225]
	v_pk_fma_f32 v[82:83], v[36:37], v[82:83], v[226:227]
	v_cvt_pk_bf16_f32 v80, v80, v81
	v_cvt_pk_bf16_f32 v81, v82, v83
	global_store_dwordx2 v146, v[80:81], s[66:67]
	v_pk_mul_f32 v[84:85], v[84:85], v[204:205] op_sel_hi:[1,0]
	v_pk_mul_f32 v[86:87], v[86:87], v[204:205] op_sel_hi:[1,0]
	v_pk_mul_f32 v[84:85], v[192:193], v[84:85]
	v_pk_mul_f32 v[86:87], v[194:195], v[86:87]
	v_pk_fma_f32 v[84:85], v[38:39], v[84:85], v[228:229]
	v_pk_fma_f32 v[86:87], v[40:41], v[86:87], v[230:231]
	v_cvt_pk_bf16_f32 v84, v84, v85
	v_cvt_pk_bf16_f32 v85, v86, v87
	global_store_dwordx2 v146, v[84:85], s[66:67] offset:512
	v_pk_mul_f32 v[88:89], v[88:89], v[204:205] op_sel_hi:[1,0]
	v_pk_mul_f32 v[90:91], v[90:91], v[204:205] op_sel_hi:[1,0]
	v_pk_mul_f32 v[88:89], v[196:197], v[88:89]
	v_pk_mul_f32 v[90:91], v[198:199], v[90:91]
	v_pk_fma_f32 v[88:89], v[42:43], v[88:89], v[232:233]
	v_pk_fma_f32 v[90:91], v[44:45], v[90:91], v[234:235]
	v_cvt_pk_bf16_f32 v88, v88, v89
	v_cvt_pk_bf16_f32 v89, v90, v91
	global_store_dwordx2 v146, v[88:89], s[66:67] offset:1024
	v_pk_mul_f32 v[92:93], v[92:93], v[204:205] op_sel_hi:[1,0]
	v_pk_mul_f32 v[94:95], v[94:95], v[204:205] op_sel_hi:[1,0]
	v_pk_mul_f32 v[92:93], v[200:201], v[92:93]
	v_pk_mul_f32 v[94:95], v[202:203], v[94:95]
	v_pk_fma_f32 v[92:93], v[46:47], v[92:93], v[236:237]
	v_pk_fma_f32 v[94:95], v[48:49], v[94:95], v[238:239]
	v_cvt_pk_bf16_f32 v92, v92, v93
	v_cvt_pk_bf16_f32 v93, v94, v95
	global_store_dwordx2 v146, v[92:93], s[66:67] offset:1536
	v_add_u32_e32 v146, 0x800, v146
	global_load_dwordx4 v[80:83], v144, s[46:47]
	global_load_dwordx4 v[84:87], v144, s[46:47] offset:1024
	global_load_dwordx4 v[88:91], v144, s[46:47] offset:2048
	global_load_dwordx4 v[92:95], v144, s[46:47] offset:3072
	v_add_u32_e32 v144, 0x1000, v144
	s_waitcnt vmcnt(40)
	v_pk_mul_f32 v[242:243], v[96:97], v[96:97]
	v_pk_mul_f32 v[244:245], v[100:101], v[100:101]
	v_pk_mul_f32 v[246:247], v[98:99], v[98:99]
	v_pk_mul_f32 v[248:249], v[102:103], v[102:103]
	v_add_f32_e32 v204, v245, v244
	v_add_f32_e32 v205, v243, v242
	v_add_f32_e32 v204, v248, v204
	v_add_f32_e32 v205, v246, v205
	v_add_f32_e32 v204, v249, v204
	v_add_f32_e32 v205, v247, v205
	v_pk_mul_f32 v[242:243], v[104:105], v[104:105]
	v_pk_mul_f32 v[244:245], v[108:109], v[108:109]
	v_pk_mul_f32 v[246:247], v[106:107], v[106:107]
	v_pk_mul_f32 v[248:249], v[110:111], v[110:111]
	v_add_f32_e32 v206, v243, v242
	v_add_f32_e32 v207, v245, v244
	v_add_f32_e32 v206, v246, v206
	v_add_f32_e32 v207, v248, v207
	v_add_f32_e32 v206, v247, v206
	v_add_f32_e32 v207, v249, v207
	v_add_f32_e32 v204, v205, v204
	v_add_f32_e32 v204, v204, v206
	v_add_f32_e32 v204, v204, v207
	ds_swizzle_b32 v205, v204 offset:swizzle(SWAP,1)
	s_waitcnt lgkmcnt(0)
	v_add_f32_e32 v204, v204, v205
	ds_swizzle_b32 v205, v204 offset:swizzle(SWAP,2)
	s_waitcnt lgkmcnt(0)
	v_add_f32_e32 v204, v204, v205
	ds_swizzle_b32 v205, v204 offset:swizzle(SWAP,4)
	s_waitcnt lgkmcnt(0)
	v_add_f32_e32 v204, v204, v205
	ds_swizzle_b32 v205, v204 offset:swizzle(SWAP,8)
	s_waitcnt lgkmcnt(0)
	v_add_f32_e32 v204, v204, v205
	ds_swizzle_b32 v205, v204 offset:swizzle(SWAP,16)
	s_waitcnt lgkmcnt(0)
	v_add_f32_e32 v204, v204, v205
	v_mov_b32_e32 v205, v204
	s_nop 1
	v_permlane32_swap_b32_e32 v204, v205
	v_add_f32_e32 v204, v204, v205
	v_mov_b32_e32 v205, 0x358637bd
	v_fmamk_f32 v204, v204, 0x3a800000, v205
	v_rsq_f32_e32 v204, v204
	s_nop 0
	v_pk_mul_f32 v[96:97], v[96:97], v[204:205] op_sel_hi:[1,0]
	v_pk_mul_f32 v[98:99], v[98:99], v[204:205] op_sel_hi:[1,0]
	v_pk_mul_f32 v[96:97], v[188:189], v[96:97]
	v_pk_mul_f32 v[98:99], v[190:191], v[98:99]
	v_pk_fma_f32 v[96:97], v[34:35], v[96:97], v[224:225]
	v_pk_fma_f32 v[98:99], v[36:37], v[98:99], v[226:227]
	v_cvt_pk_bf16_f32 v96, v96, v97
	v_cvt_pk_bf16_f32 v97, v98, v99
	global_store_dwordx2 v146, v[96:97], s[66:67]
	v_pk_mul_f32 v[100:101], v[100:101], v[204:205] op_sel_hi:[1,0]
	v_pk_mul_f32 v[102:103], v[102:103], v[204:205] op_sel_hi:[1,0]
	v_pk_mul_f32 v[100:101], v[192:193], v[100:101]
	v_pk_mul_f32 v[102:103], v[194:195], v[102:103]
	v_pk_fma_f32 v[100:101], v[38:39], v[100:101], v[228:229]
	v_pk_fma_f32 v[102:103], v[40:41], v[102:103], v[230:231]
	v_cvt_pk_bf16_f32 v100, v100, v101
	v_cvt_pk_bf16_f32 v101, v102, v103
	global_store_dwordx2 v146, v[100:101], s[66:67] offset:512
	v_pk_mul_f32 v[104:105], v[104:105], v[204:205] op_sel_hi:[1,0]
	v_pk_mul_f32 v[106:107], v[106:107], v[204:205] op_sel_hi:[1,0]
	v_pk_mul_f32 v[104:105], v[196:197], v[104:105]
	v_pk_mul_f32 v[106:107], v[198:199], v[106:107]
	v_pk_fma_f32 v[104:105], v[42:43], v[104:105], v[232:233]
	v_pk_fma_f32 v[106:107], v[44:45], v[106:107], v[234:235]
	v_cvt_pk_bf16_f32 v104, v104, v105
	v_cvt_pk_bf16_f32 v105, v106, v107
	global_store_dwordx2 v146, v[104:105], s[66:67] offset:1024
	v_pk_mul_f32 v[108:109], v[108:109], v[204:205] op_sel_hi:[1,0]
	v_pk_mul_f32 v[110:111], v[110:111], v[204:205] op_sel_hi:[1,0]
	v_pk_mul_f32 v[108:109], v[200:201], v[108:109]
	v_pk_mul_f32 v[110:111], v[202:203], v[110:111]
	v_pk_fma_f32 v[108:109], v[46:47], v[108:109], v[236:237]
	v_pk_fma_f32 v[110:111], v[48:49], v[110:111], v[238:239]
	v_cvt_pk_bf16_f32 v108, v108, v109
	v_cvt_pk_bf16_f32 v109, v110, v111
	global_store_dwordx2 v146, v[108:109], s[66:67] offset:1536
	v_add_u32_e32 v146, 0x800, v146
	global_load_dwordx4 v[96:99], v144, s[46:47]
	global_load_dwordx4 v[100:103], v144, s[46:47] offset:1024
	global_load_dwordx4 v[104:107], v144, s[46:47] offset:2048
	global_load_dwordx4 v[108:111], v144, s[46:47] offset:3072
	v_add_u32_e32 v144, 0x1000, v144
	s_waitcnt vmcnt(40)
; __device__ __forceinline__ unsigned pk2(float lo, float hi) { const g_f32x2 f = {lo, hi}; return __builtin_bit_cast(unsigned, __builtin_convertvector(f, g_bf16x2)); }
; __device__ __forceinline__ void p_norm(const float* hlat, const float* hctx, const float* g, const float* modl, int sh_off, int sc_off, bf16_t* A, int M,
;                                        const float* part, const float* cgate, float* hcout) {
;     ...
;         ss = wave_sum(ss);
;         const float rstd = rsqrtf(ss * (1.0f / 1024.0f) + EPS);
;         const float* mr = modl + (size_t)r * 6144;
; #pragma unroll
;         for (int i = 0; i < 4; ++i) {
;             const int k = i * 256 + lane * 4;
;             const float4 gg = *(const float4*)(g + k), scv = *(const float4*)(mr + sc_off + k), shv = *(const float4*)(mr + sh_off + k);
;             const float o0 = v[i].x * rstd * gg.x * (1.0f + scv.x) + shv.x, o1 = v[i].y * rstd * gg.y * (1.0f + scv.y) + shv.y;
;             const float o2 = v[i].z * rstd * gg.z * (1.0f + scv.z) + shv.z, o3 = v[i].w * rstd * gg.w * (1.0f + scv.w) + shv.w;
;             uint2 w; w.x = pk2(o0, o1); w.y = pk2(o2, o3);
;             *(uint2*)(A + (size_t)row * 1024 + k) = w;
;         }
	v_pk_mul_f32 v[242:243], v[112:113], v[112:113]
	v_pk_mul_f32 v[244:245], v[116:117], v[116:117]
	v_pk_mul_f32 v[246:247], v[114:115], v[114:115]
	v_pk_mul_f32 v[248:249], v[118:119], v[118:119]
	v_add_f32_e32 v204, v245, v244
	v_add_f32_e32 v205, v243, v242
	v_add_f32_e32 v204, v248, v204
	v_add_f32_e32 v205, v246, v205
	v_add_f32_e32 v204, v249, v204
	v_add_f32_e32 v205, v247, v205
	v_pk_mul_f32 v[242:243], v[120:121], v[120:121]
	v_pk_mul_f32 v[244:245], v[124:125], v[124:125]
	v_pk_mul_f32 v[246:247], v[122:123], v[122:123]
	v_pk_mul_f32 v[248:249], v[126:127], v[126:127]
	v_add_f32_e32 v206, v243, v242
	v_add_f32_e32 v207, v245, v244
	v_add_f32_e32 v206, v246, v206
	v_add_f32_e32 v207, v248, v207
	v_add_f32_e32 v206, v247, v206
	v_add_f32_e32 v207, v249, v207
	v_add_f32_e32 v204, v205, v204
	v_add_f32_e32 v204, v204, v206
	v_add_f32_e32 v204, v204, v207
	ds_swizzle_b32 v205, v204 offset:swizzle(SWAP,1)
	s_waitcnt lgkmcnt(0)
	v_add_f32_e32 v204, v204, v205
	ds_swizzle_b32 v205, v204 offset:swizzle(SWAP,2)
	s_waitcnt lgkmcnt(0)
	v_add_f32_e32 v204, v204, v205
	ds_swizzle_b32 v205, v204 offset:swizzle(SWAP,4)
	s_waitcnt lgkmcnt(0)
	v_add_f32_e32 v204, v204, v205
	ds_swizzle_b32 v205, v204 offset:swizzle(SWAP,8)
	s_waitcnt lgkmcnt(0)
	v_add_f32_e32 v204, v204, v205
	ds_swizzle_b32 v205, v204 offset:swizzle(SWAP,16)
	s_waitcnt lgkmcnt(0)
	v_add_f32_e32 v204, v204, v205
	v_mov_b32_e32 v205, v204
	s_nop 1
	v_permlane32_swap_b32_e32 v204, v205
	v_add_f32_e32 v204, v204, v205
	v_mov_b32_e32 v205, 0x358637bd
	v_fmamk_f32 v204, v204, 0x3a800000, v205
	v_rsq_f32_e32 v204, v204
	s_nop 0
	v_pk_mul_f32 v[112:113], v[112:113], v[204:205] op_sel_hi:[1,0]
	v_pk_mul_f32 v[114:115], v[114:115], v[204:205] op_sel_hi:[1,0]
	v_pk_mul_f32 v[112:113], v[188:189], v[112:113]
	v_pk_mul_f32 v[114:115], v[190:191], v[114:115]
	v_pk_fma_f32 v[112:113], v[34:35], v[112:113], v[224:225]
	v_pk_fma_f32 v[114:115], v[36:37], v[114:115], v[226:227]
	v_cvt_pk_bf16_f32 v112, v112, v113
	v_cvt_pk_bf16_f32 v113, v114, v115
	global_store_dwordx2 v146, v[112:113], s[66:67]
	v_pk_mul_f32 v[116:117], v[116:117], v[204:205] op_sel_hi:[1,0]
	v_pk_mul_f32 v[118:119], v[118:119], v[204:205] op_sel_hi:[1,0]
	v_pk_mul_f32 v[116:117], v[192:193], v[116:117]
	v_pk_mul_f32 v[118:119], v[194:195], v[118:119]
	v_pk_fma_f32 v[116:117], v[38:39], v[116:117], v[228:229]
	v_pk_fma_f32 v[118:119], v[40:41], v[118:119], v[230:231]
	v_cvt_pk_bf16_f32 v116, v116, v117
	v_cvt_pk_bf16_f32 v117, v118, v119
	global_store_dwordx2 v146, v[116:117], s[66:67] offset:512
	v_pk_mul_f32 v[120:121], v[120:121], v[204:205] op_sel_hi:[1,0]
	v_pk_mul_f32 v[122:123], v[122:123], v[204:205] op_sel_hi:[1,0]
	v_pk_mul_f32 v[120:121], v[196:197], v[120:121]
	v_pk_mul_f32 v[122:123], v[198:199], v[122:123]
	v_pk_fma_f32 v[120:121], v[42:43], v[120:121], v[232:233]
	v_pk_fma_f32 v[122:123], v[44:45], v[122:123], v[234:235]
	v_cvt_pk_bf16_f32 v120, v120, v121
	v_cvt_pk_bf16_f32 v121, v122, v123
	global_store_dwordx2 v146, v[120:121], s[66:67] offset:1024
	v_pk_mul_f32 v[124:125], v[124:125], v[204:205] op_sel_hi:[1,0]
	v_pk_mul_f32 v[126:127], v[126:127], v[204:205] op_sel_hi:[1,0]
	v_pk_mul_f32 v[124:125], v[200:201], v[124:125]
	v_pk_mul_f32 v[126:127], v[202:203], v[126:127]
	v_pk_fma_f32 v[124:125], v[46:47], v[124:125], v[236:237]
	v_pk_fma_f32 v[126:127], v[48:49], v[126:127], v[238:239]
	v_cvt_pk_bf16_f32 v124, v124, v125
	v_cvt_pk_bf16_f32 v125, v126, v127
	global_store_dwordx2 v146, v[124:125], s[66:67] offset:1536
	v_add_u32_e32 v146, 0x800, v146
	global_load_dwordx4 v[112:115], v144, s[46:47]
	global_load_dwordx4 v[116:119], v144, s[46:47] offset:1024
	global_load_dwordx4 v[120:123], v144, s[46:47] offset:2048
	global_load_dwordx4 v[124:127], v144, s[46:47] offset:3072
	v_add_u32_e32 v144, 0x1000, v144
	s_waitcnt vmcnt(40)
	v_pk_mul_f32 v[242:243], v[128:129], v[128:129]
	v_pk_mul_f32 v[244:245], v[132:133], v[132:133]
	v_pk_mul_f32 v[246:247], v[130:131], v[130:131]
	v_pk_mul_f32 v[248:249], v[134:135], v[134:135]
	v_add_f32_e32 v204, v245, v244
	v_add_f32_e32 v205, v243, v242
	v_add_f32_e32 v204, v248, v204
	v_add_f32_e32 v205, v246, v205
	v_add_f32_e32 v204, v249, v204
	v_add_f32_e32 v205, v247, v205
	v_pk_mul_f32 v[242:243], v[136:137], v[136:137]
	v_pk_mul_f32 v[244:245], v[140:141], v[140:141]
	v_pk_mul_f32 v[246:247], v[138:139], v[138:139]
	v_pk_mul_f32 v[248:249], v[142:143], v[142:143]
	v_add_f32_e32 v206, v243, v242
	v_add_f32_e32 v207, v245, v244
	v_add_f32_e32 v206, v246, v206
	v_add_f32_e32 v207, v248, v207
	v_add_f32_e32 v206, v247, v206
	v_add_f32_e32 v207, v249, v207
	v_add_f32_e32 v204, v205, v204
	v_add_f32_e32 v204, v204, v206
	v_add_f32_e32 v204, v204, v207
	ds_swizzle_b32 v205, v204 offset:swizzle(SWAP,1)
	s_waitcnt lgkmcnt(0)
	v_add_f32_e32 v204, v204, v205
	ds_swizzle_b32 v205, v204 offset:swizzle(SWAP,2)
	s_waitcnt lgkmcnt(0)
	v_add_f32_e32 v204, v204, v205
	ds_swizzle_b32 v205, v204 offset:swizzle(SWAP,4)
	s_waitcnt lgkmcnt(0)
	v_add_f32_e32 v204, v204, v205
	ds_swizzle_b32 v205, v204 offset:swizzle(SWAP,8)
	s_waitcnt lgkmcnt(0)
	v_add_f32_e32 v204, v204, v205
	ds_swizzle_b32 v205, v204 offset:swizzle(SWAP,16)
	s_waitcnt lgkmcnt(0)
; __device__ __forceinline__ unsigned pk2(float lo, float hi) { const g_f32x2 f = {lo, hi}; return __builtin_bit_cast(unsigned, __builtin_convertvector(f, g_bf16x2)); }
; __device__ __forceinline__ void p_norm(const float* hlat, const float* hctx, const float* g, const float* modl, int sh_off, int sc_off, bf16_t* A, int M,
;                                        const float* part, const float* cgate, float* hcout) {
;     ...
;         ss = wave_sum(ss);
;         const float rstd = rsqrtf(ss * (1.0f / 1024.0f) + EPS);
;         const float* mr = modl + (size_t)r * 6144;
; #pragma unroll
;         for (int i = 0; i < 4; ++i) {
;             const int k = i * 256 + lane * 4;
;             const float4 gg = *(const float4*)(g + k), scv = *(const float4*)(mr + sc_off + k), shv = *(const float4*)(mr + sh_off + k);
;             const float o0 = v[i].x * rstd * gg.x * (1.0f + scv.x) + shv.x, o1 = v[i].y * rstd * gg.y * (1.0f + scv.y) + shv.y;
;             const float o2 = v[i].z * rstd * gg.z * (1.0f + scv.z) + shv.z, o3 = v[i].w * rstd * gg.w * (1.0f + scv.w) + shv.w;
;             uint2 w; w.x = pk2(o0, o1); w.y = pk2(o2, o3);
;             *(uint2*)(A + (size_t)row * 1024 + k) = w;
;         }
	v_add_f32_e32 v204, v204, v205
	v_mov_b32_e32 v205, v204
	s_nop 1
	v_permlane32_swap_b32_e32 v204, v205
	v_add_f32_e32 v204, v204, v205
	v_mov_b32_e32 v205, 0x358637bd
	v_fmamk_f32 v204, v204, 0x3a800000, v205
	v_rsq_f32_e32 v204, v204
	s_nop 0
	v_pk_mul_f32 v[128:129], v[128:129], v[204:205] op_sel_hi:[1,0]
	v_pk_mul_f32 v[130:131], v[130:131], v[204:205] op_sel_hi:[1,0]
	v_pk_mul_f32 v[128:129], v[188:189], v[128:129]
	v_pk_mul_f32 v[130:131], v[190:191], v[130:131]
	v_pk_fma_f32 v[128:129], v[34:35], v[128:129], v[224:225]
	v_pk_fma_f32 v[130:131], v[36:37], v[130:131], v[226:227]
	v_cvt_pk_bf16_f32 v128, v128, v129
	v_cvt_pk_bf16_f32 v129, v130, v131
	global_store_dwordx2 v146, v[128:129], s[66:67]
	v_pk_mul_f32 v[132:133], v[132:133], v[204:205] op_sel_hi:[1,0]
	v_pk_mul_f32 v[134:135], v[134:135], v[204:205] op_sel_hi:[1,0]
	v_pk_mul_f32 v[132:133], v[192:193], v[132:133]
	v_pk_mul_f32 v[134:135], v[194:195], v[134:135]
	v_pk_fma_f32 v[132:133], v[38:39], v[132:133], v[228:229]
	v_pk_fma_f32 v[134:135], v[40:41], v[134:135], v[230:231]
	v_cvt_pk_bf16_f32 v132, v132, v133
	v_cvt_pk_bf16_f32 v133, v134, v135
	global_store_dwordx2 v146, v[132:133], s[66:67] offset:512
	v_pk_mul_f32 v[136:137], v[136:137], v[204:205] op_sel_hi:[1,0]
	v_pk_mul_f32 v[138:139], v[138:139], v[204:205] op_sel_hi:[1,0]
	v_pk_mul_f32 v[136:137], v[196:197], v[136:137]
	v_pk_mul_f32 v[138:139], v[198:199], v[138:139]
	v_pk_fma_f32 v[136:137], v[42:43], v[136:137], v[232:233]
	v_pk_fma_f32 v[138:139], v[44:45], v[138:139], v[234:235]
	v_cvt_pk_bf16_f32 v136, v136, v137
	v_cvt_pk_bf16_f32 v137, v138, v139
	global_store_dwordx2 v146, v[136:137], s[66:67] offset:1024
	v_pk_mul_f32 v[140:141], v[140:141], v[204:205] op_sel_hi:[1,0]
	v_pk_mul_f32 v[142:143], v[142:143], v[204:205] op_sel_hi:[1,0]
	v_pk_mul_f32 v[140:141], v[200:201], v[140:141]
	v_pk_mul_f32 v[142:143], v[202:203], v[142:143]
	v_pk_fma_f32 v[140:141], v[46:47], v[140:141], v[236:237]
	v_pk_fma_f32 v[142:143], v[48:49], v[142:143], v[238:239]
	v_cvt_pk_bf16_f32 v140, v140, v141
	v_cvt_pk_bf16_f32 v141, v142, v143
	global_store_dwordx2 v146, v[140:141], s[66:67] offset:1536
	v_add_u32_e32 v146, 0x800, v146
	global_load_dwordx4 v[128:131], v144, s[46:47]
	global_load_dwordx4 v[132:135], v144, s[46:47] offset:1024
	global_load_dwordx4 v[136:139], v144, s[46:47] offset:2048
	global_load_dwordx4 v[140:143], v144, s[46:47] offset:3072
	v_add_u32_e32 v144, 0x1000, v144
	s_waitcnt vmcnt(40)
	v_pk_mul_f32 v[242:243], v[156:157], v[156:157]
	v_pk_mul_f32 v[244:245], v[160:161], v[160:161]
	v_pk_mul_f32 v[246:247], v[158:159], v[158:159]
	v_pk_mul_f32 v[248:249], v[162:163], v[162:163]
	v_add_f32_e32 v204, v245, v244
	v_add_f32_e32 v205, v243, v242
	v_add_f32_e32 v204, v248, v204
	v_add_f32_e32 v205, v246, v205
	v_add_f32_e32 v204, v249, v204
	v_add_f32_e32 v205, v247, v205
	v_pk_mul_f32 v[242:243], v[164:165], v[164:165]
	v_pk_mul_f32 v[244:245], v[168:169], v[168:169]
	v_pk_mul_f32 v[246:247], v[166:167], v[166:167]
	v_pk_mul_f32 v[248:249], v[170:171], v[170:171]
	v_add_f32_e32 v206, v243, v242
	v_add_f32_e32 v207, v245, v244
	v_add_f32_e32 v206, v246, v206
	v_add_f32_e32 v207, v248, v207
	v_add_f32_e32 v206, v247, v206
	v_add_f32_e32 v207, v249, v207
	v_add_f32_e32 v204, v205, v204
	v_add_f32_e32 v204, v204, v206
	v_add_f32_e32 v204, v204, v207
	ds_swizzle_b32 v205, v204 offset:swizzle(SWAP,1)
	s_waitcnt lgkmcnt(0)
	v_add_f32_e32 v204, v204, v205
	ds_swizzle_b32 v205, v204 offset:swizzle(SWAP,2)
	s_waitcnt lgkmcnt(0)
	v_add_f32_e32 v204, v204, v205
	ds_swizzle_b32 v205, v204 offset:swizzle(SWAP,4)
	s_waitcnt lgkmcnt(0)
	v_add_f32_e32 v204, v204, v205
	ds_swizzle_b32 v205, v204 offset:swizzle(SWAP,8)
	s_waitcnt lgkmcnt(0)
	v_add_f32_e32 v204, v204, v205
	ds_swizzle_b32 v205, v204 offset:swizzle(SWAP,16)
	s_waitcnt lgkmcnt(0)
	v_add_f32_e32 v204, v204, v205
	v_mov_b32_e32 v205, v204
	s_nop 1
	v_permlane32_swap_b32_e32 v204, v205
	v_add_f32_e32 v204, v204, v205
	v_mov_b32_e32 v205, 0x358637bd
	v_fmamk_f32 v204, v204, 0x3a800000, v205
	v_rsq_f32_e32 v204, v204
	s_nop 0
	v_pk_mul_f32 v[156:157], v[156:157], v[204:205] op_sel_hi:[1,0]
	v_pk_mul_f32 v[158:159], v[158:159], v[204:205] op_sel_hi:[1,0]
	v_pk_mul_f32 v[156:157], v[188:189], v[156:157]
	v_pk_mul_f32 v[158:159], v[190:191], v[158:159]
	v_pk_fma_f32 v[156:157], v[34:35], v[156:157], v[224:225]
	v_pk_fma_f32 v[158:159], v[36:37], v[158:159], v[226:227]
	v_cvt_pk_bf16_f32 v156, v156, v157
	v_cvt_pk_bf16_f32 v157, v158, v159
	global_store_dwordx2 v146, v[156:157], s[66:67]
	v_pk_mul_f32 v[160:161], v[160:161], v[204:205] op_sel_hi:[1,0]
	v_pk_mul_f32 v[162:163], v[162:163], v[204:205] op_sel_hi:[1,0]
	v_pk_mul_f32 v[160:161], v[192:193], v[160:161]
	v_pk_mul_f32 v[162:163], v[194:195], v[162:163]
	v_pk_fma_f32 v[160:161], v[38:39], v[160:161], v[228:229]
	v_pk_fma_f32 v[162:163], v[40:41], v[162:163], v[230:231]
	v_cvt_pk_bf16_f32 v160, v160, v161
	v_cvt_pk_bf16_f32 v161, v162, v163
	global_store_dwordx2 v146, v[160:161], s[66:67] offset:512
	v_pk_mul_f32 v[164:165], v[164:165], v[204:205] op_sel_hi:[1,0]
	v_pk_mul_f32 v[166:167], v[166:167], v[204:205] op_sel_hi:[1,0]
	v_pk_mul_f32 v[164:165], v[196:197], v[164:165]
	v_pk_mul_f32 v[166:167], v[198:199], v[166:167]
	v_pk_fma_f32 v[164:165], v[42:43], v[164:165], v[232:233]
	v_pk_fma_f32 v[166:167], v[44:45], v[166:167], v[234:235]
	v_cvt_pk_bf16_f32 v164, v164, v165
	v_cvt_pk_bf16_f32 v165, v166, v167
	global_store_dwordx2 v146, v[164:165], s[66:67] offset:1024
	v_pk_mul_f32 v[168:169], v[168:169], v[204:205] op_sel_hi:[1,0]
	v_pk_mul_f32 v[170:171], v[170:171], v[204:205] op_sel_hi:[1,0]
	v_pk_mul_f32 v[168:169], v[200:201], v[168:169]
	v_pk_mul_f32 v[170:171], v[202:203], v[170:171]
	v_pk_fma_f32 v[168:169], v[46:47], v[168:169], v[236:237]
	v_pk_fma_f32 v[170:171], v[48:49], v[170:171], v[238:239]
	v_cvt_pk_bf16_f32 v168, v168, v169
	v_cvt_pk_bf16_f32 v169, v170, v171
	global_store_dwordx2 v146, v[168:169], s[66:67] offset:1536
	v_add_u32_e32 v146, 0x800, v146
	v_lshl_add_u32 v144, v50, 13, v241
	v_mov_b32_e32 v152, v144
	v_add_u32_e32 v150, 0x1000000, v144
	global_load_dwordx4 v[156:159], v144, s[16:17]
	global_load_dwordx4 v[160:163], v144, s[16:17] offset:1024
	global_load_dwordx4 v[164:167], v144, s[16:17] offset:2048
	global_load_dwordx4 v[168:171], v144, s[16:17] offset:3072
	v_add_u32_e32 v144, 0x1000, v144
	s_waitcnt vmcnt(40)
; __device__ __forceinline__ unsigned pk2(float lo, float hi) { const g_f32x2 f = {lo, hi}; return __builtin_bit_cast(unsigned, __builtin_convertvector(f, g_bf16x2)); }
; __device__ __forceinline__ void p_norm(const float* hlat, const float* hctx, const float* g, const float* modl, int sh_off, int sc_off, bf16_t* A, int M,
;                                        const float* part, const float* cgate, float* hcout) {
;     ...
;         ss = wave_sum(ss);
;         const float rstd = rsqrtf(ss * (1.0f / 1024.0f) + EPS);
;         const float* mr = modl + (size_t)r * 6144;
; #pragma unroll
;         for (int i = 0; i < 4; ++i) {
;             const int k = i * 256 + lane * 4;
;             const float4 gg = *(const float4*)(g + k), scv = *(const float4*)(mr + sc_off + k), shv = *(const float4*)(mr + sh_off + k);
;             const float o0 = v[i].x * rstd * gg.x * (1.0f + scv.x) + shv.x, o1 = v[i].y * rstd * gg.y * (1.0f + scv.y) + shv.y;
;             const float o2 = v[i].z * rstd * gg.z * (1.0f + scv.z) + shv.z, o3 = v[i].w * rstd * gg.w * (1.0f + scv.w) + shv.w;
;             uint2 w; w.x = pk2(o0, o1); w.y = pk2(o2, o3);
;             *(uint2*)(A + (size_t)row * 1024 + k) = w;
;         }
	v_pk_mul_f32 v[242:243], v[172:173], v[172:173]
	v_pk_mul_f32 v[244:245], v[176:177], v[176:177]
	v_pk_mul_f32 v[246:247], v[174:175], v[174:175]
	v_pk_mul_f32 v[248:249], v[178:179], v[178:179]
	v_add_f32_e32 v204, v245, v244
	v_add_f32_e32 v205, v243, v242
	v_add_f32_e32 v204, v248, v204
	v_add_f32_e32 v205, v246, v205
	v_add_f32_e32 v204, v249, v204
	v_add_f32_e32 v205, v247, v205
	v_pk_mul_f32 v[242:243], v[180:181], v[180:181]
	v_pk_mul_f32 v[244:245], v[184:185], v[184:185]
	v_pk_mul_f32 v[246:247], v[182:183], v[182:183]
	v_pk_mul_f32 v[248:249], v[186:187], v[186:187]
	v_add_f32_e32 v206, v243, v242
	v_add_f32_e32 v207, v245, v244
	v_add_f32_e32 v206, v246, v206
	v_add_f32_e32 v207, v248, v207
	v_add_f32_e32 v206, v247, v206
	v_add_f32_e32 v207, v249, v207
	v_add_f32_e32 v204, v205, v204
	v_add_f32_e32 v204, v204, v206
	v_add_f32_e32 v204, v204, v207
	ds_swizzle_b32 v205, v204 offset:swizzle(SWAP,1)
	s_waitcnt lgkmcnt(0)
	v_add_f32_e32 v204, v204, v205
	ds_swizzle_b32 v205, v204 offset:swizzle(SWAP,2)
	s_waitcnt lgkmcnt(0)
	v_add_f32_e32 v204, v204, v205
	ds_swizzle_b32 v205, v204 offset:swizzle(SWAP,4)
	s_waitcnt lgkmcnt(0)
	v_add_f32_e32 v204, v204, v205
	ds_swizzle_b32 v205, v204 offset:swizzle(SWAP,8)
	s_waitcnt lgkmcnt(0)
	v_add_f32_e32 v204, v204, v205
	ds_swizzle_b32 v205, v204 offset:swizzle(SWAP,16)
	s_waitcnt lgkmcnt(0)
	v_add_f32_e32 v204, v204, v205
	v_mov_b32_e32 v205, v204
	s_nop 1
	v_permlane32_swap_b32_e32 v204, v205
	v_add_f32_e32 v204, v204, v205
	v_mov_b32_e32 v205, 0x358637bd
	v_fmamk_f32 v204, v204, 0x3a800000, v205
	v_rsq_f32_e32 v204, v204
	s_nop 0
	v_pk_mul_f32 v[172:173], v[172:173], v[204:205] op_sel_hi:[1,0]
	v_pk_mul_f32 v[174:175], v[174:175], v[204:205] op_sel_hi:[1,0]
	v_pk_mul_f32 v[172:173], v[188:189], v[172:173]
	v_pk_mul_f32 v[174:175], v[190:191], v[174:175]
	v_pk_fma_f32 v[172:173], v[34:35], v[172:173], v[224:225]
	v_pk_fma_f32 v[174:175], v[36:37], v[174:175], v[226:227]
	v_cvt_pk_bf16_f32 v172, v172, v173
	v_cvt_pk_bf16_f32 v173, v174, v175
	global_store_dwordx2 v146, v[172:173], s[66:67]
	v_pk_mul_f32 v[176:177], v[176:177], v[204:205] op_sel_hi:[1,0]
	v_pk_mul_f32 v[178:179], v[178:179], v[204:205] op_sel_hi:[1,0]
	v_pk_mul_f32 v[176:177], v[192:193], v[176:177]
	v_pk_mul_f32 v[178:179], v[194:195], v[178:179]
	v_pk_fma_f32 v[176:177], v[38:39], v[176:177], v[228:229]
	v_pk_fma_f32 v[178:179], v[40:41], v[178:179], v[230:231]
	v_cvt_pk_bf16_f32 v176, v176, v177
	v_cvt_pk_bf16_f32 v177, v178, v179
	global_store_dwordx2 v146, v[176:177], s[66:67] offset:512
	v_pk_mul_f32 v[180:181], v[180:181], v[204:205] op_sel_hi:[1,0]
	v_pk_mul_f32 v[182:183], v[182:183], v[204:205] op_sel_hi:[1,0]
	v_pk_mul_f32 v[180:181], v[196:197], v[180:181]
	v_pk_mul_f32 v[182:183], v[198:199], v[182:183]
	v_pk_fma_f32 v[180:181], v[42:43], v[180:181], v[232:233]
	v_pk_fma_f32 v[182:183], v[44:45], v[182:183], v[234:235]
	v_cvt_pk_bf16_f32 v180, v180, v181
	v_cvt_pk_bf16_f32 v181, v182, v183
	global_store_dwordx2 v146, v[180:181], s[66:67] offset:1024
	v_pk_mul_f32 v[184:185], v[184:185], v[204:205] op_sel_hi:[1,0]
	v_pk_mul_f32 v[186:187], v[186:187], v[204:205] op_sel_hi:[1,0]
	v_pk_mul_f32 v[184:185], v[200:201], v[184:185]
	v_pk_mul_f32 v[186:187], v[202:203], v[186:187]
	v_pk_fma_f32 v[184:185], v[46:47], v[184:185], v[236:237]
	v_pk_fma_f32 v[186:187], v[48:49], v[186:187], v[238:239]
	v_cvt_pk_bf16_f32 v184, v184, v185
	v_cvt_pk_bf16_f32 v185, v186, v187
	global_store_dwordx2 v146, v[184:185], s[66:67] offset:1536
	v_add_u32_e32 v146, 0x800, v146
	global_load_dwordx4 v[172:175], v144, s[16:17]
	global_load_dwordx4 v[176:179], v144, s[16:17] offset:1024
	global_load_dwordx4 v[180:183], v144, s[16:17] offset:2048
	global_load_dwordx4 v[184:187], v144, s[16:17] offset:3072
	v_add_u32_e32 v144, 0x1000, v144
	s_waitcnt vmcnt(40)
	v_pk_mul_f32 v[242:243], v[80:81], v[80:81]
	v_pk_mul_f32 v[244:245], v[84:85], v[84:85]
	v_pk_mul_f32 v[246:247], v[82:83], v[82:83]
	v_pk_mul_f32 v[248:249], v[86:87], v[86:87]
	v_add_f32_e32 v204, v245, v244
	v_add_f32_e32 v205, v243, v242
	v_add_f32_e32 v204, v248, v204
	v_add_f32_e32 v205, v246, v205
	v_add_f32_e32 v204, v249, v204
	v_add_f32_e32 v205, v247, v205
	v_pk_mul_f32 v[242:243], v[88:89], v[88:89]
	v_pk_mul_f32 v[244:245], v[92:93], v[92:93]
	v_pk_mul_f32 v[246:247], v[90:91], v[90:91]
	v_pk_mul_f32 v[248:249], v[94:95], v[94:95]
	v_add_f32_e32 v206, v243, v242
	v_add_f32_e32 v207, v245, v244
	v_add_f32_e32 v206, v246, v206
	v_add_f32_e32 v207, v248, v207
	v_add_f32_e32 v206, v247, v206
	v_add_f32_e32 v207, v249, v207
	v_add_f32_e32 v204, v205, v204
	v_add_f32_e32 v204, v204, v206
	v_add_f32_e32 v204, v204, v207
	ds_swizzle_b32 v205, v204 offset:swizzle(SWAP,1)
	s_waitcnt lgkmcnt(0)
	v_add_f32_e32 v204, v204, v205
	ds_swizzle_b32 v205, v204 offset:swizzle(SWAP,2)
	s_waitcnt lgkmcnt(0)
	v_add_f32_e32 v204, v204, v205
	ds_swizzle_b32 v205, v204 offset:swizzle(SWAP,4)
	s_waitcnt lgkmcnt(0)
	v_add_f32_e32 v204, v204, v205
	ds_swizzle_b32 v205, v204 offset:swizzle(SWAP,8)
	s_waitcnt lgkmcnt(0)
	v_add_f32_e32 v204, v204, v205
	ds_swizzle_b32 v205, v204 offset:swizzle(SWAP,16)
	s_waitcnt lgkmcnt(0)
; __device__ __forceinline__ unsigned pk2(float lo, float hi) { const g_f32x2 f = {lo, hi}; return __builtin_bit_cast(unsigned, __builtin_convertvector(f, g_bf16x2)); }
; __device__ __forceinline__ void p_norm(const float* hlat, const float* hctx, const float* g, const float* modl, int sh_off, int sc_off, bf16_t* A, int M,
;                                        const float* part, const float* cgate, float* hcout) {
;     ...
;         ss = wave_sum(ss);
;         const float rstd = rsqrtf(ss * (1.0f / 1024.0f) + EPS);
;         const float* mr = modl + (size_t)r * 6144;
; #pragma unroll
;         for (int i = 0; i < 4; ++i) {
;             const int k = i * 256 + lane * 4;
;             const float4 gg = *(const float4*)(g + k), scv = *(const float4*)(mr + sc_off + k), shv = *(const float4*)(mr + sh_off + k);
;             const float o0 = v[i].x * rstd * gg.x * (1.0f + scv.x) + shv.x, o1 = v[i].y * rstd * gg.y * (1.0f + scv.y) + shv.y;
;             const float o2 = v[i].z * rstd * gg.z * (1.0f + scv.z) + shv.z, o3 = v[i].w * rstd * gg.w * (1.0f + scv.w) + shv.w;
;             uint2 w; w.x = pk2(o0, o1); w.y = pk2(o2, o3);
;             *(uint2*)(A + (size_t)row * 1024 + k) = w;
;         }
	v_add_f32_e32 v204, v204, v205
	v_mov_b32_e32 v205, v204
	s_nop 1
	v_permlane32_swap_b32_e32 v204, v205
	v_add_f32_e32 v204, v204, v205
	v_mov_b32_e32 v205, 0x358637bd
	v_fmamk_f32 v204, v204, 0x3a800000, v205
	v_rsq_f32_e32 v204, v204
	s_nop 0
	v_pk_mul_f32 v[80:81], v[80:81], v[204:205] op_sel_hi:[1,0]
	v_pk_mul_f32 v[82:83], v[82:83], v[204:205] op_sel_hi:[1,0]
	v_pk_mul_f32 v[80:81], v[188:189], v[80:81]
	v_pk_mul_f32 v[82:83], v[190:191], v[82:83]
	v_pk_fma_f32 v[80:81], v[34:35], v[80:81], v[224:225]
	v_pk_fma_f32 v[82:83], v[36:37], v[82:83], v[226:227]
	v_cvt_pk_bf16_f32 v80, v80, v81
	v_cvt_pk_bf16_f32 v81, v82, v83
	global_store_dwordx2 v146, v[80:81], s[66:67]
	v_pk_mul_f32 v[84:85], v[84:85], v[204:205] op_sel_hi:[1,0]
	v_pk_mul_f32 v[86:87], v[86:87], v[204:205] op_sel_hi:[1,0]
	v_pk_mul_f32 v[84:85], v[192:193], v[84:85]
	v_pk_mul_f32 v[86:87], v[194:195], v[86:87]
	v_pk_fma_f32 v[84:85], v[38:39], v[84:85], v[228:229]
	v_pk_fma_f32 v[86:87], v[40:41], v[86:87], v[230:231]
	v_cvt_pk_bf16_f32 v84, v84, v85
	v_cvt_pk_bf16_f32 v85, v86, v87
	global_store_dwordx2 v146, v[84:85], s[66:67] offset:512
	v_pk_mul_f32 v[88:89], v[88:89], v[204:205] op_sel_hi:[1,0]
	v_pk_mul_f32 v[90:91], v[90:91], v[204:205] op_sel_hi:[1,0]
	v_pk_mul_f32 v[88:89], v[196:197], v[88:89]
	v_pk_mul_f32 v[90:91], v[198:199], v[90:91]
	v_pk_fma_f32 v[88:89], v[42:43], v[88:89], v[232:233]
	v_pk_fma_f32 v[90:91], v[44:45], v[90:91], v[234:235]
	v_cvt_pk_bf16_f32 v88, v88, v89
	v_cvt_pk_bf16_f32 v89, v90, v91
	global_store_dwordx2 v146, v[88:89], s[66:67] offset:1024
	v_pk_mul_f32 v[92:93], v[92:93], v[204:205] op_sel_hi:[1,0]
	v_pk_mul_f32 v[94:95], v[94:95], v[204:205] op_sel_hi:[1,0]
	v_pk_mul_f32 v[92:93], v[200:201], v[92:93]
	v_pk_mul_f32 v[94:95], v[202:203], v[94:95]
	v_pk_fma_f32 v[92:93], v[46:47], v[92:93], v[236:237]
	v_pk_fma_f32 v[94:95], v[48:49], v[94:95], v[238:239]
	v_cvt_pk_bf16_f32 v92, v92, v93
	v_cvt_pk_bf16_f32 v93, v94, v95
	global_store_dwordx2 v146, v[92:93], s[66:67] offset:1536
	v_add_u32_e32 v146, 0x800, v146
	s_waitcnt vmcnt(36)
	v_pk_mul_f32 v[242:243], v[96:97], v[96:97]
	v_pk_mul_f32 v[244:245], v[100:101], v[100:101]
	v_pk_mul_f32 v[246:247], v[98:99], v[98:99]
	v_pk_mul_f32 v[248:249], v[102:103], v[102:103]
	v_add_f32_e32 v204, v245, v244
	v_add_f32_e32 v205, v243, v242
	v_add_f32_e32 v204, v248, v204
	v_add_f32_e32 v205, v246, v205
	v_add_f32_e32 v204, v249, v204
	v_add_f32_e32 v205, v247, v205
	v_pk_mul_f32 v[242:243], v[104:105], v[104:105]
	v_pk_mul_f32 v[244:245], v[108:109], v[108:109]
	v_pk_mul_f32 v[246:247], v[106:107], v[106:107]
	v_pk_mul_f32 v[248:249], v[110:111], v[110:111]
	v_add_f32_e32 v206, v243, v242
	v_add_f32_e32 v207, v245, v244
	v_add_f32_e32 v206, v246, v206
	v_add_f32_e32 v207, v248, v207
	v_add_f32_e32 v206, v247, v206
	v_add_f32_e32 v207, v249, v207
	v_add_f32_e32 v204, v205, v204
	v_add_f32_e32 v204, v204, v206
	v_add_f32_e32 v204, v204, v207
	ds_swizzle_b32 v205, v204 offset:swizzle(SWAP,1)
	s_waitcnt lgkmcnt(0)
	v_add_f32_e32 v204, v204, v205
	ds_swizzle_b32 v205, v204 offset:swizzle(SWAP,2)
	s_waitcnt lgkmcnt(0)
	v_add_f32_e32 v204, v204, v205
	ds_swizzle_b32 v205, v204 offset:swizzle(SWAP,4)
	s_waitcnt lgkmcnt(0)
	v_add_f32_e32 v204, v204, v205
	ds_swizzle_b32 v205, v204 offset:swizzle(SWAP,8)
	s_waitcnt lgkmcnt(0)
	v_add_f32_e32 v204, v204, v205
	ds_swizzle_b32 v205, v204 offset:swizzle(SWAP,16)
	s_waitcnt lgkmcnt(0)
	v_add_f32_e32 v204, v204, v205
	v_mov_b32_e32 v205, v204
	s_nop 1
	v_permlane32_swap_b32_e32 v204, v205
	v_add_f32_e32 v204, v204, v205
	v_mov_b32_e32 v205, 0x358637bd
	v_fmamk_f32 v204, v204, 0x3a800000, v205
	v_rsq_f32_e32 v204, v204
	s_nop 0
	v_pk_mul_f32 v[96:97], v[96:97], v[204:205] op_sel_hi:[1,0]
	v_pk_mul_f32 v[98:99], v[98:99], v[204:205] op_sel_hi:[1,0]
	v_pk_mul_f32 v[96:97], v[188:189], v[96:97]
	v_pk_mul_f32 v[98:99], v[190:191], v[98:99]
	v_pk_fma_f32 v[96:97], v[34:35], v[96:97], v[224:225]
	v_pk_fma_f32 v[98:99], v[36:37], v[98:99], v[226:227]
	v_cvt_pk_bf16_f32 v96, v96, v97
	v_cvt_pk_bf16_f32 v97, v98, v99
	global_store_dwordx2 v146, v[96:97], s[66:67]
	v_pk_mul_f32 v[100:101], v[100:101], v[204:205] op_sel_hi:[1,0]
	v_pk_mul_f32 v[102:103], v[102:103], v[204:205] op_sel_hi:[1,0]
	v_pk_mul_f32 v[100:101], v[192:193], v[100:101]
	v_pk_mul_f32 v[102:103], v[194:195], v[102:103]
	v_pk_fma_f32 v[100:101], v[38:39], v[100:101], v[228:229]
	v_pk_fma_f32 v[102:103], v[40:41], v[102:103], v[230:231]
	v_cvt_pk_bf16_f32 v100, v100, v101
	v_cvt_pk_bf16_f32 v101, v102, v103
	global_store_dwordx2 v146, v[100:101], s[66:67] offset:512
	v_pk_mul_f32 v[104:105], v[104:105], v[204:205] op_sel_hi:[1,0]
	v_pk_mul_f32 v[106:107], v[106:107], v[204:205] op_sel_hi:[1,0]
	v_pk_mul_f32 v[104:105], v[196:197], v[104:105]
	v_pk_mul_f32 v[106:107], v[198:199], v[106:107]
	v_pk_fma_f32 v[104:105], v[42:43], v[104:105], v[232:233]
	v_pk_fma_f32 v[106:107], v[44:45], v[106:107], v[234:235]
	v_cvt_pk_bf16_f32 v104, v104, v105
	v_cvt_pk_bf16_f32 v105, v106, v107
	global_store_dwordx2 v146, v[104:105], s[66:67] offset:1024
	v_pk_mul_f32 v[108:109], v[108:109], v[204:205] op_sel_hi:[1,0]
	v_pk_mul_f32 v[110:111], v[110:111], v[204:205] op_sel_hi:[1,0]
	v_pk_mul_f32 v[108:109], v[200:201], v[108:109]
	v_pk_mul_f32 v[110:111], v[202:203], v[110:111]
	v_pk_fma_f32 v[108:109], v[46:47], v[108:109], v[236:237]
	v_pk_fma_f32 v[110:111], v[48:49], v[110:111], v[238:239]
	v_cvt_pk_bf16_f32 v108, v108, v109
	v_cvt_pk_bf16_f32 v109, v110, v111
	global_store_dwordx2 v146, v[108:109], s[66:67] offset:1536
	v_add_u32_e32 v146, 0x800, v146
	s_waitcnt vmcnt(32)
; __device__ __forceinline__ unsigned pk2(float lo, float hi) { const g_f32x2 f = {lo, hi}; return __builtin_bit_cast(unsigned, __builtin_convertvector(f, g_bf16x2)); }
; __device__ __forceinline__ void p_norm(const float* hlat, const float* hctx, const float* g, const float* modl, int sh_off, int sc_off, bf16_t* A, int M,
;                                        const float* part, const float* cgate, float* hcout) {
;     ...
;         ss = wave_sum(ss);
;         const float rstd = rsqrtf(ss * (1.0f / 1024.0f) + EPS);
;         const float* mr = modl + (size_t)r * 6144;
; #pragma unroll
;         for (int i = 0; i < 4; ++i) {
;             const int k = i * 256 + lane * 4;
;             const float4 gg = *(const float4*)(g + k), scv = *(const float4*)(mr + sc_off + k), shv = *(const float4*)(mr + sh_off + k);
;             const float o0 = v[i].x * rstd * gg.x * (1.0f + scv.x) + shv.x, o1 = v[i].y * rstd * gg.y * (1.0f + scv.y) + shv.y;
;             const float o2 = v[i].z * rstd * gg.z * (1.0f + scv.z) + shv.z, o3 = v[i].w * rstd * gg.w * (1.0f + scv.w) + shv.w;
;             uint2 w; w.x = pk2(o0, o1); w.y = pk2(o2, o3);
;             *(uint2*)(A + (size_t)row * 1024 + k) = w;
;         }
	v_pk_mul_f32 v[242:243], v[112:113], v[112:113]
	v_pk_mul_f32 v[244:245], v[116:117], v[116:117]
	v_pk_mul_f32 v[246:247], v[114:115], v[114:115]
	v_pk_mul_f32 v[248:249], v[118:119], v[118:119]
	v_add_f32_e32 v204, v245, v244
	v_add_f32_e32 v205, v243, v242
	v_add_f32_e32 v204, v248, v204
	v_add_f32_e32 v205, v246, v205
	v_add_f32_e32 v204, v249, v204
	v_add_f32_e32 v205, v247, v205
	v_pk_mul_f32 v[242:243], v[120:121], v[120:121]
	v_pk_mul_f32 v[244:245], v[124:125], v[124:125]
	v_pk_mul_f32 v[246:247], v[122:123], v[122:123]
	v_pk_mul_f32 v[248:249], v[126:127], v[126:127]
	v_add_f32_e32 v206, v243, v242
	v_add_f32_e32 v207, v245, v244
	v_add_f32_e32 v206, v246, v206
	v_add_f32_e32 v207, v248, v207
	v_add_f32_e32 v206, v247, v206
	v_add_f32_e32 v207, v249, v207
	v_add_f32_e32 v204, v205, v204
	v_add_f32_e32 v204, v204, v206
	v_add_f32_e32 v204, v204, v207
	ds_swizzle_b32 v205, v204 offset:swizzle(SWAP,1)
	s_waitcnt lgkmcnt(0)
	v_add_f32_e32 v204, v204, v205
	ds_swizzle_b32 v205, v204 offset:swizzle(SWAP,2)
	s_waitcnt lgkmcnt(0)
	v_add_f32_e32 v204, v204, v205
	ds_swizzle_b32 v205, v204 offset:swizzle(SWAP,4)
	s_waitcnt lgkmcnt(0)
	v_add_f32_e32 v204, v204, v205
	ds_swizzle_b32 v205, v204 offset:swizzle(SWAP,8)
	s_waitcnt lgkmcnt(0)
	v_add_f32_e32 v204, v204, v205
	ds_swizzle_b32 v205, v204 offset:swizzle(SWAP,16)
	s_waitcnt lgkmcnt(0)
	v_add_f32_e32 v204, v204, v205
	v_mov_b32_e32 v205, v204
	s_nop 1
	v_permlane32_swap_b32_e32 v204, v205
	v_add_f32_e32 v204, v204, v205
	v_mov_b32_e32 v205, 0x358637bd
	v_fmamk_f32 v204, v204, 0x3a800000, v205
	v_rsq_f32_e32 v204, v204
	s_nop 0
	v_pk_mul_f32 v[112:113], v[112:113], v[204:205] op_sel_hi:[1,0]
	v_pk_mul_f32 v[114:115], v[114:115], v[204:205] op_sel_hi:[1,0]
	v_pk_mul_f32 v[112:113], v[188:189], v[112:113]
	v_pk_mul_f32 v[114:115], v[190:191], v[114:115]
	v_pk_fma_f32 v[112:113], v[34:35], v[112:113], v[224:225]
	v_pk_fma_f32 v[114:115], v[36:37], v[114:115], v[226:227]
	v_cvt_pk_bf16_f32 v112, v112, v113
	v_cvt_pk_bf16_f32 v113, v114, v115
	global_store_dwordx2 v146, v[112:113], s[66:67]
	v_pk_mul_f32 v[116:117], v[116:117], v[204:205] op_sel_hi:[1,0]
	v_pk_mul_f32 v[118:119], v[118:119], v[204:205] op_sel_hi:[1,0]
	v_pk_mul_f32 v[116:117], v[192:193], v[116:117]
	v_pk_mul_f32 v[118:119], v[194:195], v[118:119]
	v_pk_fma_f32 v[116:117], v[38:39], v[116:117], v[228:229]
	v_pk_fma_f32 v[118:119], v[40:41], v[118:119], v[230:231]
	v_cvt_pk_bf16_f32 v116, v116, v117
	v_cvt_pk_bf16_f32 v117, v118, v119
	global_store_dwordx2 v146, v[116:117], s[66:67] offset:512
	v_pk_mul_f32 v[120:121], v[120:121], v[204:205] op_sel_hi:[1,0]
	v_pk_mul_f32 v[122:123], v[122:123], v[204:205] op_sel_hi:[1,0]
	v_pk_mul_f32 v[120:121], v[196:197], v[120:121]
	v_pk_mul_f32 v[122:123], v[198:199], v[122:123]
	v_pk_fma_f32 v[120:121], v[42:43], v[120:121], v[232:233]
	v_pk_fma_f32 v[122:123], v[44:45], v[122:123], v[234:235]
	v_cvt_pk_bf16_f32 v120, v120, v121
	v_cvt_pk_bf16_f32 v121, v122, v123
	global_store_dwordx2 v146, v[120:121], s[66:67] offset:1024
	v_pk_mul_f32 v[124:125], v[124:125], v[204:205] op_sel_hi:[1,0]
	v_pk_mul_f32 v[126:127], v[126:127], v[204:205] op_sel_hi:[1,0]
	v_pk_mul_f32 v[124:125], v[200:201], v[124:125]
	v_pk_mul_f32 v[126:127], v[202:203], v[126:127]
	v_pk_fma_f32 v[124:125], v[46:47], v[124:125], v[236:237]
	v_pk_fma_f32 v[126:127], v[48:49], v[126:127], v[238:239]
	v_cvt_pk_bf16_f32 v124, v124, v125
	v_cvt_pk_bf16_f32 v125, v126, v127
	global_store_dwordx2 v146, v[124:125], s[66:67] offset:1536
	v_add_u32_e32 v146, 0x800, v146
	s_waitcnt vmcnt(28)
	v_pk_mul_f32 v[242:243], v[128:129], v[128:129]
	v_pk_mul_f32 v[244:245], v[132:133], v[132:133]
	v_pk_mul_f32 v[246:247], v[130:131], v[130:131]
	v_pk_mul_f32 v[248:249], v[134:135], v[134:135]
	v_add_f32_e32 v204, v245, v244
	v_add_f32_e32 v205, v243, v242
	v_add_f32_e32 v204, v248, v204
	v_add_f32_e32 v205, v246, v205
	v_add_f32_e32 v204, v249, v204
	v_add_f32_e32 v205, v247, v205
	v_pk_mul_f32 v[242:243], v[136:137], v[136:137]
	v_pk_mul_f32 v[244:245], v[140:141], v[140:141]
	v_pk_mul_f32 v[246:247], v[138:139], v[138:139]
	v_pk_mul_f32 v[248:249], v[142:143], v[142:143]
	v_add_f32_e32 v206, v243, v242
	v_add_f32_e32 v207, v245, v244
	v_add_f32_e32 v206, v246, v206
	v_add_f32_e32 v207, v248, v207
	v_add_f32_e32 v206, v247, v206
	v_add_f32_e32 v207, v249, v207
	v_add_f32_e32 v204, v205, v204
	v_add_f32_e32 v204, v204, v206
	v_add_f32_e32 v204, v204, v207
	ds_swizzle_b32 v205, v204 offset:swizzle(SWAP,1)
	s_waitcnt lgkmcnt(0)
	v_add_f32_e32 v204, v204, v205
	ds_swizzle_b32 v205, v204 offset:swizzle(SWAP,2)
	s_waitcnt lgkmcnt(0)
	v_add_f32_e32 v204, v204, v205
	ds_swizzle_b32 v205, v204 offset:swizzle(SWAP,4)
	s_waitcnt lgkmcnt(0)
	v_add_f32_e32 v204, v204, v205
	ds_swizzle_b32 v205, v204 offset:swizzle(SWAP,8)
	s_waitcnt lgkmcnt(0)
	v_add_f32_e32 v204, v204, v205
	ds_swizzle_b32 v205, v204 offset:swizzle(SWAP,16)
	s_waitcnt lgkmcnt(0)
; __device__ __forceinline__ unsigned pk2(float lo, float hi) { const g_f32x2 f = {lo, hi}; return __builtin_bit_cast(unsigned, __builtin_convertvector(f, g_bf16x2)); }
; #define PN_LOAD(dst, rw) do { const float* s_ = (rw) < NLAT ? hlat + (size_t)(rw) * 1024 : hctx + (size_t)((rw) - NLAT) * 1024; \
;         _Pragma("unroll") for (int i = 0; i < 4; ++i) dst[i] = *(const float4*)(s_ + i * 256 + lane * 4); } while (0)
; __device__ __forceinline__ void p_norm(const float* hlat, const float* hctx, const float* g, const float* modl, int sh_off, int sc_off, bf16_t* A, int M,
;                                        const float* part, const float* cgate, float* hcout) {
;     ...
;     if (row < M) PN_LOAD(v, row);
;     ...
;         ss = wave_sum(ss);
;         const float rstd = rsqrtf(ss * (1.0f / 1024.0f) + EPS);
;         const float* mr = modl + (size_t)r * 6144;
; #pragma unroll
;         for (int i = 0; i < 4; ++i) {
;             const int k = i * 256 + lane * 4;
;             const float4 gg = *(const float4*)(g + k), scv = *(const float4*)(mr + sc_off + k), shv = *(const float4*)(mr + sh_off + k);
;             const float o0 = v[i].x * rstd * gg.x * (1.0f + scv.x) + shv.x, o1 = v[i].y * rstd * gg.y * (1.0f + scv.y) + shv.y;
;             const float o2 = v[i].z * rstd * gg.z * (1.0f + scv.z) + shv.z, o3 = v[i].w * rstd * gg.w * (1.0f + scv.w) + shv.w;
;             uint2 w; w.x = pk2(o0, o1); w.y = pk2(o2, o3);
;             *(uint2*)(A + (size_t)row * 1024 + k) = w;
;         }
	v_add_f32_e32 v204, v204, v205
	v_mov_b32_e32 v205, v204
	s_nop 1
	v_permlane32_swap_b32_e32 v204, v205
	v_add_f32_e32 v204, v204, v205
	v_mov_b32_e32 v205, 0x358637bd
	v_fmamk_f32 v204, v204, 0x3a800000, v205
	v_rsq_f32_e32 v204, v204
	s_nop 0
	v_pk_mul_f32 v[128:129], v[128:129], v[204:205] op_sel_hi:[1,0]
	v_pk_mul_f32 v[130:131], v[130:131], v[204:205] op_sel_hi:[1,0]
	v_pk_mul_f32 v[128:129], v[188:189], v[128:129]
	v_pk_mul_f32 v[130:131], v[190:191], v[130:131]
	v_pk_fma_f32 v[128:129], v[34:35], v[128:129], v[224:225]
	v_pk_fma_f32 v[130:131], v[36:37], v[130:131], v[226:227]
	v_cvt_pk_bf16_f32 v128, v128, v129
	v_cvt_pk_bf16_f32 v129, v130, v131
	global_store_dwordx2 v146, v[128:129], s[66:67]
	v_pk_mul_f32 v[132:133], v[132:133], v[204:205] op_sel_hi:[1,0]
	v_pk_mul_f32 v[134:135], v[134:135], v[204:205] op_sel_hi:[1,0]
	v_pk_mul_f32 v[132:133], v[192:193], v[132:133]
	v_pk_mul_f32 v[134:135], v[194:195], v[134:135]
	v_pk_fma_f32 v[132:133], v[38:39], v[132:133], v[228:229]
	v_pk_fma_f32 v[134:135], v[40:41], v[134:135], v[230:231]
	v_cvt_pk_bf16_f32 v132, v132, v133
	v_cvt_pk_bf16_f32 v133, v134, v135
	global_store_dwordx2 v146, v[132:133], s[66:67] offset:512
	v_pk_mul_f32 v[136:137], v[136:137], v[204:205] op_sel_hi:[1,0]
	v_pk_mul_f32 v[138:139], v[138:139], v[204:205] op_sel_hi:[1,0]
	v_pk_mul_f32 v[136:137], v[196:197], v[136:137]
	v_pk_mul_f32 v[138:139], v[198:199], v[138:139]
	v_pk_fma_f32 v[136:137], v[42:43], v[136:137], v[232:233]
	v_pk_fma_f32 v[138:139], v[44:45], v[138:139], v[234:235]
	v_cvt_pk_bf16_f32 v136, v136, v137
	v_cvt_pk_bf16_f32 v137, v138, v139
	global_store_dwordx2 v146, v[136:137], s[66:67] offset:1024
	v_pk_mul_f32 v[140:141], v[140:141], v[204:205] op_sel_hi:[1,0]
	v_pk_mul_f32 v[142:143], v[142:143], v[204:205] op_sel_hi:[1,0]
	v_pk_mul_f32 v[140:141], v[200:201], v[140:141]
	v_pk_mul_f32 v[142:143], v[202:203], v[142:143]
	v_pk_fma_f32 v[140:141], v[46:47], v[140:141], v[236:237]
	v_pk_fma_f32 v[142:143], v[48:49], v[142:143], v[238:239]
	v_cvt_pk_bf16_f32 v140, v140, v141
	v_cvt_pk_bf16_f32 v141, v142, v143
	global_store_dwordx2 v146, v[140:141], s[66:67] offset:1536
	v_add_u32_e32 v146, 0x800, v146
	v_add_u32_e32 v151, 0x60000, v241
	global_load_dwordx4 v[34:37], v151, s[98:99]
	global_load_dwordx4 v[38:41], v151, s[98:99] offset:1024
	global_load_dwordx4 v[42:45], v151, s[98:99] offset:2048
	global_load_dwordx4 v[46:49], v151, s[98:99] offset:3072
	global_load_dwordx4 v[224:227], v151, s[50:51]
	global_load_dwordx4 v[228:231], v151, s[50:51] offset:1024
	global_load_dwordx4 v[232:235], v151, s[50:51] offset:2048
	global_load_dwordx4 v[236:239], v151, s[50:51] offset:3072
	s_waitcnt vmcnt(32)
	v_pk_mul_f32 v[242:243], v[156:157], v[156:157]
	v_pk_mul_f32 v[244:245], v[160:161], v[160:161]
	v_pk_mul_f32 v[246:247], v[158:159], v[158:159]
	v_pk_mul_f32 v[248:249], v[162:163], v[162:163]
	v_add_f32_e32 v204, v245, v244
	v_add_f32_e32 v205, v243, v242
	v_add_f32_e32 v204, v248, v204
	v_add_f32_e32 v205, v246, v205
	v_add_f32_e32 v204, v249, v204
	v_add_f32_e32 v205, v247, v205
	v_pk_mul_f32 v[242:243], v[164:165], v[164:165]
	v_pk_mul_f32 v[244:245], v[168:169], v[168:169]
	v_pk_mul_f32 v[246:247], v[166:167], v[166:167]
	v_pk_mul_f32 v[248:249], v[170:171], v[170:171]
	v_add_f32_e32 v206, v243, v242
	v_add_f32_e32 v207, v245, v244
	v_add_f32_e32 v206, v246, v206
	v_add_f32_e32 v207, v248, v207
	v_add_f32_e32 v206, v247, v206
	v_add_f32_e32 v207, v249, v207
	v_add_f32_e32 v204, v205, v204
	v_add_f32_e32 v204, v204, v206
	v_add_f32_e32 v204, v204, v207
	ds_swizzle_b32 v205, v204 offset:swizzle(SWAP,1)
	s_waitcnt lgkmcnt(0)
	v_add_f32_e32 v204, v204, v205
	ds_swizzle_b32 v205, v204 offset:swizzle(SWAP,2)
	s_waitcnt lgkmcnt(0)
	v_add_f32_e32 v204, v204, v205
	ds_swizzle_b32 v205, v204 offset:swizzle(SWAP,4)
	s_waitcnt lgkmcnt(0)
	v_add_f32_e32 v204, v204, v205
	ds_swizzle_b32 v205, v204 offset:swizzle(SWAP,8)
	s_waitcnt lgkmcnt(0)
	v_add_f32_e32 v204, v204, v205
	ds_swizzle_b32 v205, v204 offset:swizzle(SWAP,16)
	s_waitcnt lgkmcnt(0)
	v_add_f32_e32 v204, v204, v205
	v_mov_b32_e32 v205, v204
	s_nop 1
	v_permlane32_swap_b32_e32 v204, v205
	v_add_f32_e32 v204, v204, v205
	v_mov_b32_e32 v205, 0x358637bd
	v_fmamk_f32 v204, v204, 0x3a800000, v205
	v_rsq_f32_e32 v204, v204
	s_nop 0
	s_waitcnt vmcnt(0)
; __device__ __forceinline__ unsigned pk2(float lo, float hi) { const g_f32x2 f = {lo, hi}; return __builtin_bit_cast(unsigned, __builtin_convertvector(f, g_bf16x2)); }
; __device__ __forceinline__ void p_norm(const float* hlat, const float* hctx, const float* g, const float* modl, int sh_off, int sc_off, bf16_t* A, int M,
;                                        const float* part, const float* cgate, float* hcout) {
;     ...
;         ss = wave_sum(ss);
;         const float rstd = rsqrtf(ss * (1.0f / 1024.0f) + EPS);
;         const float* mr = modl + (size_t)r * 6144;
; #pragma unroll
;         for (int i = 0; i < 4; ++i) {
;             const int k = i * 256 + lane * 4;
;             const float4 gg = *(const float4*)(g + k), scv = *(const float4*)(mr + sc_off + k), shv = *(const float4*)(mr + sh_off + k);
;             const float o0 = v[i].x * rstd * gg.x * (1.0f + scv.x) + shv.x, o1 = v[i].y * rstd * gg.y * (1.0f + scv.y) + shv.y;
;             const float o2 = v[i].z * rstd * gg.z * (1.0f + scv.z) + shv.z, o3 = v[i].w * rstd * gg.w * (1.0f + scv.w) + shv.w;
;             uint2 w; w.x = pk2(o0, o1); w.y = pk2(o2, o3);
;             *(uint2*)(A + (size_t)row * 1024 + k) = w;
;         }
	v_pk_add_f32 v[34:35], v[34:35], 1.0 op_sel_hi:[1,0]
	v_pk_add_f32 v[36:37], v[36:37], 1.0 op_sel_hi:[1,0]
	v_pk_add_f32 v[38:39], v[38:39], 1.0 op_sel_hi:[1,0]
	v_pk_add_f32 v[40:41], v[40:41], 1.0 op_sel_hi:[1,0]
	v_pk_add_f32 v[42:43], v[42:43], 1.0 op_sel_hi:[1,0]
	v_pk_add_f32 v[44:45], v[44:45], 1.0 op_sel_hi:[1,0]
	v_pk_add_f32 v[46:47], v[46:47], 1.0 op_sel_hi:[1,0]
	v_pk_add_f32 v[48:49], v[48:49], 1.0 op_sel_hi:[1,0]
	v_lshlrev_b32_e32 v146, 12, v50
	v_lshl_add_u32 v146, v240, 3, v146
	v_add_u32_e32 v146, 0x4000000, v146
	v_pk_mul_f32 v[156:157], v[156:157], v[204:205] op_sel_hi:[1,0]
	v_pk_mul_f32 v[158:159], v[158:159], v[204:205] op_sel_hi:[1,0]
	v_pk_mul_f32 v[156:157], v[188:189], v[156:157]
	v_pk_mul_f32 v[158:159], v[190:191], v[158:159]
	v_pk_fma_f32 v[156:157], v[34:35], v[156:157], v[224:225]
	v_pk_fma_f32 v[158:159], v[36:37], v[158:159], v[226:227]
	v_cvt_pk_bf16_f32 v156, v156, v157
	v_cvt_pk_bf16_f32 v157, v158, v159
	global_store_dwordx2 v146, v[156:157], s[66:67]
	v_pk_mul_f32 v[160:161], v[160:161], v[204:205] op_sel_hi:[1,0]
	v_pk_mul_f32 v[162:163], v[162:163], v[204:205] op_sel_hi:[1,0]
	v_pk_mul_f32 v[160:161], v[192:193], v[160:161]
	v_pk_mul_f32 v[162:163], v[194:195], v[162:163]
	v_pk_fma_f32 v[160:161], v[38:39], v[160:161], v[228:229]
	v_pk_fma_f32 v[162:163], v[40:41], v[162:163], v[230:231]
	v_cvt_pk_bf16_f32 v160, v160, v161
	v_cvt_pk_bf16_f32 v161, v162, v163
	global_store_dwordx2 v146, v[160:161], s[66:67] offset:512
	v_pk_mul_f32 v[164:165], v[164:165], v[204:205] op_sel_hi:[1,0]
	v_pk_mul_f32 v[166:167], v[166:167], v[204:205] op_sel_hi:[1,0]
	v_pk_mul_f32 v[164:165], v[196:197], v[164:165]
	v_pk_mul_f32 v[166:167], v[198:199], v[166:167]
	v_pk_fma_f32 v[164:165], v[42:43], v[164:165], v[232:233]
	v_pk_fma_f32 v[166:167], v[44:45], v[166:167], v[234:235]
	v_cvt_pk_bf16_f32 v164, v164, v165
	v_cvt_pk_bf16_f32 v165, v166, v167
	global_store_dwordx2 v146, v[164:165], s[66:67] offset:1024
	v_pk_mul_f32 v[168:169], v[168:169], v[204:205] op_sel_hi:[1,0]
	v_pk_mul_f32 v[170:171], v[170:171], v[204:205] op_sel_hi:[1,0]
	v_pk_mul_f32 v[168:169], v[200:201], v[168:169]
	v_pk_mul_f32 v[170:171], v[202:203], v[170:171]
	v_pk_fma_f32 v[168:169], v[46:47], v[168:169], v[236:237]
	v_pk_fma_f32 v[170:171], v[48:49], v[170:171], v[238:239]
	v_cvt_pk_bf16_f32 v168, v168, v169
	v_cvt_pk_bf16_f32 v169, v170, v171
	global_store_dwordx2 v146, v[168:169], s[66:67] offset:1536
	v_add_u32_e32 v146, 0x800, v146
	v_pk_mul_f32 v[242:243], v[172:173], v[172:173]
	v_pk_mul_f32 v[244:245], v[176:177], v[176:177]
	v_pk_mul_f32 v[246:247], v[174:175], v[174:175]
	v_pk_mul_f32 v[248:249], v[178:179], v[178:179]
	v_add_f32_e32 v204, v245, v244
	v_add_f32_e32 v205, v243, v242
	v_add_f32_e32 v204, v248, v204
	v_add_f32_e32 v205, v246, v205
	v_add_f32_e32 v204, v249, v204
	v_add_f32_e32 v205, v247, v205
	v_pk_mul_f32 v[242:243], v[180:181], v[180:181]
	v_pk_mul_f32 v[244:245], v[184:185], v[184:185]
	v_pk_mul_f32 v[246:247], v[182:183], v[182:183]
	v_pk_mul_f32 v[248:249], v[186:187], v[186:187]
	v_add_f32_e32 v206, v243, v242
	v_add_f32_e32 v207, v245, v244
	v_add_f32_e32 v206, v246, v206
	v_add_f32_e32 v207, v248, v207
	v_add_f32_e32 v206, v247, v206
	v_add_f32_e32 v207, v249, v207
	v_add_f32_e32 v204, v205, v204
	v_add_f32_e32 v204, v204, v206
	v_add_f32_e32 v204, v204, v207
	ds_swizzle_b32 v205, v204 offset:swizzle(SWAP,1)
	s_waitcnt lgkmcnt(0)
	v_add_f32_e32 v204, v204, v205
	ds_swizzle_b32 v205, v204 offset:swizzle(SWAP,2)
	s_waitcnt lgkmcnt(0)
	v_add_f32_e32 v204, v204, v205
	ds_swizzle_b32 v205, v204 offset:swizzle(SWAP,4)
	s_waitcnt lgkmcnt(0)
	v_add_f32_e32 v204, v204, v205
	ds_swizzle_b32 v205, v204 offset:swizzle(SWAP,8)
	s_waitcnt lgkmcnt(0)
	v_add_f32_e32 v204, v204, v205
	ds_swizzle_b32 v205, v204 offset:swizzle(SWAP,16)
	s_waitcnt lgkmcnt(0)
	v_add_f32_e32 v204, v204, v205
	v_mov_b32_e32 v205, v204
	s_nop 1
	v_permlane32_swap_b32_e32 v204, v205
	v_add_f32_e32 v204, v204, v205
	v_mov_b32_e32 v205, 0x358637bd
	v_fmamk_f32 v204, v204, 0x3a800000, v205
	v_rsq_f32_e32 v204, v204
	s_nop 0
	v_pk_mul_f32 v[172:173], v[172:173], v[204:205] op_sel_hi:[1,0]
	v_pk_mul_f32 v[174:175], v[174:175], v[204:205] op_sel_hi:[1,0]
	v_pk_mul_f32 v[172:173], v[188:189], v[172:173]
	v_pk_mul_f32 v[174:175], v[190:191], v[174:175]
	v_pk_fma_f32 v[172:173], v[34:35], v[172:173], v[224:225]
	v_pk_fma_f32 v[174:175], v[36:37], v[174:175], v[226:227]
	v_cvt_pk_bf16_f32 v172, v172, v173
	v_cvt_pk_bf16_f32 v173, v174, v175
	global_store_dwordx2 v146, v[172:173], s[66:67]
	v_pk_mul_f32 v[176:177], v[176:177], v[204:205] op_sel_hi:[1,0]
	v_pk_mul_f32 v[178:179], v[178:179], v[204:205] op_sel_hi:[1,0]
	v_pk_mul_f32 v[176:177], v[192:193], v[176:177]
	v_pk_mul_f32 v[178:179], v[194:195], v[178:179]
	v_pk_fma_f32 v[176:177], v[38:39], v[176:177], v[228:229]
	v_pk_fma_f32 v[178:179], v[40:41], v[178:179], v[230:231]
	v_cvt_pk_bf16_f32 v176, v176, v177
	v_cvt_pk_bf16_f32 v177, v178, v179
	global_store_dwordx2 v146, v[176:177], s[66:67] offset:512
	v_pk_mul_f32 v[180:181], v[180:181], v[204:205] op_sel_hi:[1,0]
	v_pk_mul_f32 v[182:183], v[182:183], v[204:205] op_sel_hi:[1,0]
	v_pk_mul_f32 v[180:181], v[196:197], v[180:181]
	v_pk_mul_f32 v[182:183], v[198:199], v[182:183]
	v_pk_fma_f32 v[180:181], v[42:43], v[180:181], v[232:233]
	v_pk_fma_f32 v[182:183], v[44:45], v[182:183], v[234:235]
	v_cvt_pk_bf16_f32 v180, v180, v181
	v_cvt_pk_bf16_f32 v181, v182, v183
	global_store_dwordx2 v146, v[180:181], s[66:67] offset:1024
	v_pk_mul_f32 v[184:185], v[184:185], v[204:205] op_sel_hi:[1,0]
	v_pk_mul_f32 v[186:187], v[186:187], v[204:205] op_sel_hi:[1,0]
	v_pk_mul_f32 v[184:185], v[200:201], v[184:185]
	v_pk_mul_f32 v[186:187], v[202:203], v[186:187]
	v_pk_fma_f32 v[184:185], v[46:47], v[184:185], v[236:237]
	v_pk_fma_f32 v[186:187], v[48:49], v[186:187], v[238:239]
	v_cvt_pk_bf16_f32 v184, v184, v185
	v_cvt_pk_bf16_f32 v185, v186, v187
	global_store_dwordx2 v146, v[184:185], s[66:67] offset:1536
	v_add_u32_e32 v146, 0x800, v146
; #define PN_LOAD(dst, rw) do { const float* s_ = (rw) < NLAT ? hlat + (size_t)(rw) * 1024 : hctx + (size_t)((rw) - NLAT) * 1024; \
;         _Pragma("unroll") for (int i = 0; i < 4; ++i) dst[i] = *(const float4*)(s_ + i * 256 + lane * 4); } while (0)
; __device__ __forceinline__ void p_norm(const float* hlat, const float* hctx, const float* g, const float* modl, int sh_off, int sc_off, bf16_t* A, int M,
;                                        const float* part, const float* cgate, float* hcout) {
;     ...
;     while (row < M) {
;         const int nrow = row + stride;
;         if (nrow < M) PN_LOAD(nv, nrow);
;         const int r = row < NLAT ? (row >> 11) : 16;
;         float ss = 0.f;
; #pragma unroll
;         for (int i = 0; i < 4; ++i) {
;             if (part != nullptr && row >= NLAT) {
;                 const size_t po = (size_t)(row - NLAT) * 1024 + i * 256 + lane * 4;
;                 const float4 p0 = *(const float4*)(part + po), p1 = *(const float4*)(part + (size_t)4096 * 1024 + po), cg = *(const float4*)(cgate + i * 256 + lane * 4);
;                 v[i].x += cg.x * (p0.x + p1.x); v[i].y += cg.y * (p0.y + p1.y); v[i].z += cg.z * (p0.z + p1.z); v[i].w += cg.w * (p0.w + p1.w);
;                 *(float4*)(hcout + po) = v[i];
.Lnorm_P1_end:
	v_add_u32_e32 v50, 0x10000, v50
	v_cmp_gt_i32_e32 vcc, s10, v50
	v_writelane_b32 v255, s7, 48
	s_and_saveexec_b64 s[16:17], vcc
	s_cbranch_execz .LBB0_419
	s_mov_b32 s6, 0x8000
	v_cmp_gt_i32_e32 vcc, s6, v50
	v_readlane_b32 s6, v255, 39
	v_readlane_b32 s8, v255, 41
	v_readlane_b32 s7, v255, 40
	v_readlane_b32 s9, v255, 42
	v_add_u32_e32 v2, 0xffff8000, v50
	v_ashrrev_i32_e32 v51, 31, v50
	v_mov_b32_e32 v4, s7
	v_mov_b32_e32 v5, s9
	v_cndmask_b32_e32 v3, 0, v51, vcc
	v_cndmask_b32_e32 v2, v2, v50, vcc
	v_cndmask_b32_e32 v5, v4, v5, vcc
	v_mov_b32_e32 v4, s6
	v_mov_b32_e32 v6, s8
	v_cndmask_b32_e32 v4, v4, v6, vcc
	v_lshlrev_b64 v[2:3], 12, v[2:3]
	v_lshl_add_u64 v[2:3], v[4:5], 0, v[2:3]
	v_lshlrev_b32_e32 v4, 2, v14
	v_and_b32_e32 v34, 0xfc, v4
	v_lshlrev_b32_e32 v16, 2, v34
	v_mov_b32_e32 v17, v0
	v_lshl_add_u64 v[2:3], v[2:3], 0, v[16:17]
	global_load_dwordx4 v[18:21], v[2:3], off
	global_load_dwordx4 v[10:13], v[2:3], off offset:1024
	global_load_dwordx4 v[6:9], v[2:3], off offset:2048
	s_nop 0
	global_load_dwordx4 v[2:5], v[2:3], off offset:3072
	v_readlane_b32 s6, v255, 45
	s_load_dwordx2 s[8:9], s[0:1], 0x30
	v_readlane_b32 s7, v255, 46
	v_sub_u32_e64 v15, s6, 1 clamp
	s_mov_b32 s6, 0x19800
	v_mul_lo_u32 v22, v15, s6
	v_readlane_b32 s6, v255, 47
	v_readlane_b32 s7, v255, 48
	s_lshl_b64 s[6:7], s[6:7], 2
	s_waitcnt lgkmcnt(0)
	s_add_u32 s6, s8, s6
	v_mov_b32_e32 v23, v0
	s_addc_u32 s7, s9, s7
	v_lshlrev_b64 v[22:23], 2, v[22:23]
	s_cmp_lg_u64 s[2:3], 0
	v_lshl_add_u64 v[22:23], s[56:57], 0, v[22:23]
	s_cselect_b64 s[24:25], -1, 0
	s_add_u32 s26, s2, 0x1000000
	s_addc_u32 s27, s3, 0
	v_lshl_add_u64 v[22:23], v[22:23], 0, v[16:17]
	s_mov_b64 s[8:9], 0x65000
	v_lshlrev_b64 v[26:27], 11, v[50:51]
	v_and_b32_e32 v14, 63, v14
	s_add_i32 s5, s5, s72
	v_lshl_add_u64 v[36:37], v[22:23], 0, s[8:9]
	v_lshl_add_u64 v[38:39], s[6:7], 0, v[16:17]
	v_or_b32_e32 v16, 0x100, v34
	v_or_b32_e32 v22, 0x200, v34
	v_or_b32_e32 v24, 0x300, v34
	v_lshl_or_b32 v26, v14, 3, v26
	v_add_u32_e32 v42, s5, v1
	s_mov_b64 s[20:21], 0
	v_lshl_add_u64 v[40:41], s[66:67], 0, v[26:27]
	v_ashrrev_i32_e32 v43, 31, v42
	v_lshlrev_b32_e32 v44, 2, v16
	v_lshlrev_b32_e32 v46, 2, v22
	v_lshlrev_b32_e32 v48, 2, v24
	s_branch .LBB0_409

; __global__ void __launch_bounds__(512, 2) hybrid_fwd(Params P) {
;     ...
;     for (int l = 0; l < DEPTH; ++l) {
;         const bool last = (l == DEPTH - 1);
.Lhop_402:
	s_branch .LBB0_402

; #define PIN(i) ((const float*)(const GASP float*)karg_q(i))
; __device__ __forceinline__ int obid() { int b = blockIdx.x; asm volatile("" : "+s"(b)); return b; }
; __device__ __forceinline__ int otid() { int t = threadIdx.x; asm volatile("" : "+v"(t)); return t; }
; #define PN_LOAD(dst, rw) do { const float* s_ = (rw) < NLAT ? hlat + (size_t)(rw) * 1024 : hctx + (size_t)((rw) - NLAT) * 1024; \
;         _Pragma("unroll") for (int i = 0; i < 4; ++i) dst[i] = *(const float4*)(s_ + i * 256 + lane * 4); } while (0)
; __device__ __forceinline__ void p_norm(const float* hlat, const float* hctx, const float* g, const float* modl, int sh_off, int sc_off, bf16_t* A, int M,
;                                        const float* part, const float* cgate, float* hcout) {
;     const int tid = otid(), lane = tid & 63, wave = tid >> 6;
;     const int stride = gridDim.x * 8;
;     int row = obid() * 8 + wave;
;     float4 v[4], nv[4];
;     ...
;     if (row < M) PN_LOAD(v, row);
; __global__ void __launch_bounds__(512, 2) hybrid_fwd(Params P) {
;     ...
;         p_norm(POUT, hc_in, PIN(7) + l * 1024, modl, 3 * 1024, 4 * 1024, AO, Mf, last ? nullptr : (const float*)(PWS + WS_MK), modl + 16 * 6144 + 2 * 1024, hc);
.LBB0_1037:
	s_or_b64 exec, exec, s[2:3]
	s_and_b64 s[2:3], s[18:19], exec
	s_mov_b32 s2, 0x8000
	s_cselect_b32 s7, s2, 0x9000
	v_mov_b32_e32 v6, v253
	s_mov_b32 s2, s63
	s_waitcnt lgkmcnt(0)
	s_barrier
	s_lshl_b32 s5, s2, 3
	v_ashrrev_i32_e32 v1, 6, v6
	v_add_u32_e32 v50, s5, v1
	s_waitcnt vmcnt(0) lgkmcnt(0)
	v_readlane_b32 s100, v255, 45
	s_load_dwordx2 s[48:49], s[0:1], 0x38
	s_movk_i32 s101, 0xe8
	s_load_dwordx2 s[46:47], s[0:1], s101
	s_load_dwordx2 s[16:17], s[0:1], 0x10
	s_mul_i32 s101, s100, 0x66000
	s_add_u32 s50, s56, s101
	s_addc_u32 s51, s57, 0
	s_add_u32 s20, s101, 0x62000
	s_add_u32 s20, s56, s20
	s_addc_u32 s21, s57, 0
	s_add_u32 s98, s50, 0x4000
	s_addc_u32 s99, s51, 0
	s_add_u32 s50, s50, 0x3000
	s_addc_u32 s51, s51, 0
	s_lshl_b32 s101, s100, 12
	v_and_b32_e32 v240, 63, v253
	v_lshlrev_b32_e32 v241, 4, v240
	v_lshrrev_b32_e32 v148, 7, v50
	v_lshlrev_b32_e32 v146, 4, v50
	v_lshl_add_u32 v144, v146, 12, v241
	v_lshlrev_b32_e32 v146, 11, v146
	v_lshl_add_u32 v146, v240, 3, v146
	v_mul_u32_u24_e32 v148, 0x6000, v148
	v_add_u32_e32 v148, v148, v241
	s_waitcnt lgkmcnt(0)
	s_add_u32 s48, s48, s101
	s_addc_u32 s49, s49, 0
	s_cmp_eq_u32 s100, 0
	s_cselect_b32 s16, s16, s64
	s_cselect_b32 s17, s17, s65
	s_cmp_eq_u32 s100, 3
	s_cbranch_scc1 .Lnorm_P6_alt
	global_load_dwordx4 v[80:83], v144, s[46:47]
	global_load_dwordx4 v[84:87], v144, s[46:47] offset:1024
	global_load_dwordx4 v[88:91], v144, s[46:47] offset:2048
	global_load_dwordx4 v[92:95], v144, s[46:47] offset:3072
	v_add_u32_e32 v144, 0x1000, v144
	global_load_dwordx4 v[34:37], v148, s[98:99]
	global_load_dwordx4 v[38:41], v148, s[98:99] offset:1024
	global_load_dwordx4 v[42:45], v148, s[98:99] offset:2048
	global_load_dwordx4 v[46:49], v148, s[98:99] offset:3072
	global_load_dwordx4 v[224:227], v148, s[50:51]
	global_load_dwordx4 v[228:231], v148, s[50:51] offset:1024
	global_load_dwordx4 v[232:235], v148, s[50:51] offset:2048
	global_load_dwordx4 v[236:239], v148, s[50:51] offset:3072
	global_load_dwordx4 v[188:191], v241, s[48:49]
	global_load_dwordx4 v[192:195], v241, s[48:49] offset:1024
	global_load_dwordx4 v[196:199], v241, s[48:49] offset:2048
	global_load_dwordx4 v[200:203], v241, s[48:49] offset:3072
	global_load_dwordx4 v[96:99], v144, s[46:47]
	global_load_dwordx4 v[100:103], v144, s[46:47] offset:1024
	global_load_dwordx4 v[104:107], v144, s[46:47] offset:2048
	global_load_dwordx4 v[108:111], v144, s[46:47] offset:3072
	v_add_u32_e32 v144, 0x1000, v144
	global_load_dwordx4 v[112:115], v144, s[46:47]
	global_load_dwordx4 v[116:119], v144, s[46:47] offset:1024
	global_load_dwordx4 v[120:123], v144, s[46:47] offset:2048
	global_load_dwordx4 v[124:127], v144, s[46:47] offset:3072
	v_add_u32_e32 v144, 0x1000, v144
	global_load_dwordx4 v[128:131], v144, s[46:47]
	global_load_dwordx4 v[132:135], v144, s[46:47] offset:1024
	global_load_dwordx4 v[136:139], v144, s[46:47] offset:2048
	global_load_dwordx4 v[140:143], v144, s[46:47] offset:3072
	v_add_u32_e32 v144, 0x1000, v144
	global_load_dwordx4 v[156:159], v144, s[46:47]
	global_load_dwordx4 v[160:163], v144, s[46:47] offset:1024
	global_load_dwordx4 v[164:167], v144, s[46:47] offset:2048
	global_load_dwordx4 v[168:171], v144, s[46:47] offset:3072
	v_add_u32_e32 v144, 0x1000, v144
	global_load_dwordx4 v[172:175], v144, s[46:47]
	global_load_dwordx4 v[176:179], v144, s[46:47] offset:1024
	global_load_dwordx4 v[180:183], v144, s[46:47] offset:2048
	global_load_dwordx4 v[184:187], v144, s[46:47] offset:3072
	v_add_u32_e32 v144, 0x1000, v144
	s_waitcnt vmcnt(32)
	v_pk_mul_f32 v[242:243], v[80:81], v[80:81]
	v_pk_mul_f32 v[244:245], v[84:85], v[84:85]
	v_pk_mul_f32 v[246:247], v[82:83], v[82:83]
	v_pk_mul_f32 v[248:249], v[86:87], v[86:87]
	v_add_f32_e32 v204, v245, v244
	v_add_f32_e32 v205, v243, v242
	v_add_f32_e32 v204, v248, v204
	v_add_f32_e32 v205, v246, v205
	v_add_f32_e32 v204, v249, v204
	v_add_f32_e32 v205, v247, v205
	v_pk_mul_f32 v[242:243], v[88:89], v[88:89]
	v_pk_mul_f32 v[244:245], v[92:93], v[92:93]
	v_pk_mul_f32 v[246:247], v[90:91], v[90:91]
	v_pk_mul_f32 v[248:249], v[94:95], v[94:95]
	v_add_f32_e32 v206, v243, v242
	v_add_f32_e32 v207, v245, v244
	v_add_f32_e32 v206, v246, v206
	v_add_f32_e32 v207, v248, v207
	v_add_f32_e32 v206, v247, v206
	v_add_f32_e32 v207, v249, v207
	v_add_f32_e32 v204, v205, v204
	v_add_f32_e32 v204, v204, v206
	v_add_f32_e32 v204, v204, v207
	ds_swizzle_b32 v205, v204 offset:swizzle(SWAP,1)
	s_waitcnt lgkmcnt(0)
	v_add_f32_e32 v204, v204, v205
	ds_swizzle_b32 v205, v204 offset:swizzle(SWAP,2)
	s_waitcnt lgkmcnt(0)
	v_add_f32_e32 v204, v204, v205
	ds_swizzle_b32 v205, v204 offset:swizzle(SWAP,4)
	s_waitcnt lgkmcnt(0)
	v_add_f32_e32 v204, v204, v205
	ds_swizzle_b32 v205, v204 offset:swizzle(SWAP,8)
	s_waitcnt lgkmcnt(0)
	v_add_f32_e32 v204, v204, v205
	ds_swizzle_b32 v205, v204 offset:swizzle(SWAP,16)
	s_waitcnt lgkmcnt(0)
	v_add_f32_e32 v204, v204, v205
	v_mov_b32_e32 v205, v204
	s_nop 1
	v_permlane32_swap_b32_e32 v204, v205
	v_add_f32_e32 v204, v204, v205
	v_mov_b32_e32 v205, 0x358637bd
	v_fmamk_f32 v204, v204, 0x3a800000, v205
	v_rsq_f32_e32 v204, v204
	s_nop 0
	s_waitcnt vmcnt(20)
; __device__ __forceinline__ unsigned pk2(float lo, float hi) { const g_f32x2 f = {lo, hi}; return __builtin_bit_cast(unsigned, __builtin_convertvector(f, g_bf16x2)); }
; __device__ __forceinline__ void p_norm(const float* hlat, const float* hctx, const float* g, const float* modl, int sh_off, int sc_off, bf16_t* A, int M,
;                                        const float* part, const float* cgate, float* hcout) {
;     ...
;         ss = wave_sum(ss);
;         const float rstd = rsqrtf(ss * (1.0f / 1024.0f) + EPS);
;         const float* mr = modl + (size_t)r * 6144;
; #pragma unroll
;         for (int i = 0; i < 4; ++i) {
;             const int k = i * 256 + lane * 4;
;             const float4 gg = *(const float4*)(g + k), scv = *(const float4*)(mr + sc_off + k), shv = *(const float4*)(mr + sh_off + k);
;             const float o0 = v[i].x * rstd * gg.x * (1.0f + scv.x) + shv.x, o1 = v[i].y * rstd * gg.y * (1.0f + scv.y) + shv.y;
;             const float o2 = v[i].z * rstd * gg.z * (1.0f + scv.z) + shv.z, o3 = v[i].w * rstd * gg.w * (1.0f + scv.w) + shv.w;
;             uint2 w; w.x = pk2(o0, o1); w.y = pk2(o2, o3);
;             *(uint2*)(A + (size_t)row * 1024 + k) = w;
;         }
	v_pk_add_f32 v[34:35], v[34:35], 1.0 op_sel_hi:[1,0]
	v_pk_add_f32 v[36:37], v[36:37], 1.0 op_sel_hi:[1,0]
	v_pk_add_f32 v[38:39], v[38:39], 1.0 op_sel_hi:[1,0]
	v_pk_add_f32 v[40:41], v[40:41], 1.0 op_sel_hi:[1,0]
	v_pk_add_f32 v[42:43], v[42:43], 1.0 op_sel_hi:[1,0]
	v_pk_add_f32 v[44:45], v[44:45], 1.0 op_sel_hi:[1,0]
	v_pk_add_f32 v[46:47], v[46:47], 1.0 op_sel_hi:[1,0]
	v_pk_add_f32 v[48:49], v[48:49], 1.0 op_sel_hi:[1,0]
	v_pk_mul_f32 v[80:81], v[80:81], v[204:205] op_sel_hi:[1,0]
	v_pk_mul_f32 v[82:83], v[82:83], v[204:205] op_sel_hi:[1,0]
	v_pk_mul_f32 v[80:81], v[188:189], v[80:81]
	v_pk_mul_f32 v[82:83], v[190:191], v[82:83]
	v_pk_fma_f32 v[80:81], v[34:35], v[80:81], v[224:225]
	v_pk_fma_f32 v[82:83], v[36:37], v[82:83], v[226:227]
	v_cvt_pk_bf16_f32 v80, v80, v81
	v_cvt_pk_bf16_f32 v81, v82, v83
	global_store_dwordx2 v146, v[80:81], s[66:67]
	v_pk_mul_f32 v[84:85], v[84:85], v[204:205] op_sel_hi:[1,0]
	v_pk_mul_f32 v[86:87], v[86:87], v[204:205] op_sel_hi:[1,0]
	v_pk_mul_f32 v[84:85], v[192:193], v[84:85]
	v_pk_mul_f32 v[86:87], v[194:195], v[86:87]
	v_pk_fma_f32 v[84:85], v[38:39], v[84:85], v[228:229]
	v_pk_fma_f32 v[86:87], v[40:41], v[86:87], v[230:231]
	v_cvt_pk_bf16_f32 v84, v84, v85
	v_cvt_pk_bf16_f32 v85, v86, v87
	global_store_dwordx2 v146, v[84:85], s[66:67] offset:512
	v_pk_mul_f32 v[88:89], v[88:89], v[204:205] op_sel_hi:[1,0]
	v_pk_mul_f32 v[90:91], v[90:91], v[204:205] op_sel_hi:[1,0]
	v_pk_mul_f32 v[88:89], v[196:197], v[88:89]
	v_pk_mul_f32 v[90:91], v[198:199], v[90:91]
	v_pk_fma_f32 v[88:89], v[42:43], v[88:89], v[232:233]
	v_pk_fma_f32 v[90:91], v[44:45], v[90:91], v[234:235]
	v_cvt_pk_bf16_f32 v88, v88, v89
	v_cvt_pk_bf16_f32 v89, v90, v91
	global_store_dwordx2 v146, v[88:89], s[66:67] offset:1024
	v_pk_mul_f32 v[92:93], v[92:93], v[204:205] op_sel_hi:[1,0]
	v_pk_mul_f32 v[94:95], v[94:95], v[204:205] op_sel_hi:[1,0]
	v_pk_mul_f32 v[92:93], v[200:201], v[92:93]
	v_pk_mul_f32 v[94:95], v[202:203], v[94:95]
	v_pk_fma_f32 v[92:93], v[46:47], v[92:93], v[236:237]
	v_pk_fma_f32 v[94:95], v[48:49], v[94:95], v[238:239]
	v_cvt_pk_bf16_f32 v92, v92, v93
	v_cvt_pk_bf16_f32 v93, v94, v95
	global_store_dwordx2 v146, v[92:93], s[66:67] offset:1536
	v_add_u32_e32 v146, 0x800, v146
	global_load_dwordx4 v[80:83], v144, s[46:47]
	global_load_dwordx4 v[84:87], v144, s[46:47] offset:1024
	global_load_dwordx4 v[88:91], v144, s[46:47] offset:2048
	global_load_dwordx4 v[92:95], v144, s[46:47] offset:3072
	v_add_u32_e32 v144, 0x1000, v144
	s_waitcnt vmcnt(24)
	v_pk_mul_f32 v[242:243], v[96:97], v[96:97]
	v_pk_mul_f32 v[244:245], v[100:101], v[100:101]
	v_pk_mul_f32 v[246:247], v[98:99], v[98:99]
	v_pk_mul_f32 v[248:249], v[102:103], v[102:103]
	v_add_f32_e32 v204, v245, v244
	v_add_f32_e32 v205, v243, v242
	v_add_f32_e32 v204, v248, v204
	v_add_f32_e32 v205, v246, v205
	v_add_f32_e32 v204, v249, v204
	v_add_f32_e32 v205, v247, v205
	v_pk_mul_f32 v[242:243], v[104:105], v[104:105]
	v_pk_mul_f32 v[244:245], v[108:109], v[108:109]
	v_pk_mul_f32 v[246:247], v[106:107], v[106:107]
	v_pk_mul_f32 v[248:249], v[110:111], v[110:111]
	v_add_f32_e32 v206, v243, v242
	v_add_f32_e32 v207, v245, v244
	v_add_f32_e32 v206, v246, v206
	v_add_f32_e32 v207, v248, v207
	v_add_f32_e32 v206, v247, v206
	v_add_f32_e32 v207, v249, v207
	v_add_f32_e32 v204, v205, v204
	v_add_f32_e32 v204, v204, v206
	v_add_f32_e32 v204, v204, v207
	ds_swizzle_b32 v205, v204 offset:swizzle(SWAP,1)
	s_waitcnt lgkmcnt(0)
	v_add_f32_e32 v204, v204, v205
	ds_swizzle_b32 v205, v204 offset:swizzle(SWAP,2)
	s_waitcnt lgkmcnt(0)
	v_add_f32_e32 v204, v204, v205
	ds_swizzle_b32 v205, v204 offset:swizzle(SWAP,4)
	s_waitcnt lgkmcnt(0)
	v_add_f32_e32 v204, v204, v205
	ds_swizzle_b32 v205, v204 offset:swizzle(SWAP,8)
	s_waitcnt lgkmcnt(0)
	v_add_f32_e32 v204, v204, v205
	ds_swizzle_b32 v205, v204 offset:swizzle(SWAP,16)
	s_waitcnt lgkmcnt(0)
	v_add_f32_e32 v204, v204, v205
	v_mov_b32_e32 v205, v204
	s_nop 1
	v_permlane32_swap_b32_e32 v204, v205
	v_add_f32_e32 v204, v204, v205
	v_mov_b32_e32 v205, 0x358637bd
	v_fmamk_f32 v204, v204, 0x3a800000, v205
	v_rsq_f32_e32 v204, v204
	s_nop 0
	v_pk_mul_f32 v[96:97], v[96:97], v[204:205] op_sel_hi:[1,0]
	v_pk_mul_f32 v[98:99], v[98:99], v[204:205] op_sel_hi:[1,0]
	v_pk_mul_f32 v[96:97], v[188:189], v[96:97]
	v_pk_mul_f32 v[98:99], v[190:191], v[98:99]
	v_pk_fma_f32 v[96:97], v[34:35], v[96:97], v[224:225]
	v_pk_fma_f32 v[98:99], v[36:37], v[98:99], v[226:227]
	v_cvt_pk_bf16_f32 v96, v96, v97
	v_cvt_pk_bf16_f32 v97, v98, v99
	global_store_dwordx2 v146, v[96:97], s[66:67]
	v_pk_mul_f32 v[100:101], v[100:101], v[204:205] op_sel_hi:[1,0]
	v_pk_mul_f32 v[102:103], v[102:103], v[204:205] op_sel_hi:[1,0]
	v_pk_mul_f32 v[100:101], v[192:193], v[100:101]
	v_pk_mul_f32 v[102:103], v[194:195], v[102:103]
	v_pk_fma_f32 v[100:101], v[38:39], v[100:101], v[228:229]
	v_pk_fma_f32 v[102:103], v[40:41], v[102:103], v[230:231]
	v_cvt_pk_bf16_f32 v100, v100, v101
	v_cvt_pk_bf16_f32 v101, v102, v103
	global_store_dwordx2 v146, v[100:101], s[66:67] offset:512
	v_pk_mul_f32 v[104:105], v[104:105], v[204:205] op_sel_hi:[1,0]
	v_pk_mul_f32 v[106:107], v[106:107], v[204:205] op_sel_hi:[1,0]
	v_pk_mul_f32 v[104:105], v[196:197], v[104:105]
	v_pk_mul_f32 v[106:107], v[198:199], v[106:107]
	v_pk_fma_f32 v[104:105], v[42:43], v[104:105], v[232:233]
	v_pk_fma_f32 v[106:107], v[44:45], v[106:107], v[234:235]
	v_cvt_pk_bf16_f32 v104, v104, v105
	v_cvt_pk_bf16_f32 v105, v106, v107
	global_store_dwordx2 v146, v[104:105], s[66:67] offset:1024
	v_pk_mul_f32 v[108:109], v[108:109], v[204:205] op_sel_hi:[1,0]
	v_pk_mul_f32 v[110:111], v[110:111], v[204:205] op_sel_hi:[1,0]
	v_pk_mul_f32 v[108:109], v[200:201], v[108:109]
	v_pk_mul_f32 v[110:111], v[202:203], v[110:111]
	v_pk_fma_f32 v[108:109], v[46:47], v[108:109], v[236:237]
	v_pk_fma_f32 v[110:111], v[48:49], v[110:111], v[238:239]
	v_cvt_pk_bf16_f32 v108, v108, v109
	v_cvt_pk_bf16_f32 v109, v110, v111
	global_store_dwordx2 v146, v[108:109], s[66:67] offset:1536
	v_add_u32_e32 v146, 0x800, v146
	global_load_dwordx4 v[96:99], v144, s[46:47]
	global_load_dwordx4 v[100:103], v144, s[46:47] offset:1024
	global_load_dwordx4 v[104:107], v144, s[46:47] offset:2048
	global_load_dwordx4 v[108:111], v144, s[46:47] offset:3072
	v_add_u32_e32 v144, 0x1000, v144
	s_waitcnt vmcnt(28)
; __device__ __forceinline__ unsigned pk2(float lo, float hi) { const g_f32x2 f = {lo, hi}; return __builtin_bit_cast(unsigned, __builtin_convertvector(f, g_bf16x2)); }
; __device__ __forceinline__ void p_norm(const float* hlat, const float* hctx, const float* g, const float* modl, int sh_off, int sc_off, bf16_t* A, int M,
;                                        const float* part, const float* cgate, float* hcout) {
;     ...
;         ss = wave_sum(ss);
;         const float rstd = rsqrtf(ss * (1.0f / 1024.0f) + EPS);
;         const float* mr = modl + (size_t)r * 6144;
; #pragma unroll
;         for (int i = 0; i < 4; ++i) {
;             const int k = i * 256 + lane * 4;
;             const float4 gg = *(const float4*)(g + k), scv = *(const float4*)(mr + sc_off + k), shv = *(const float4*)(mr + sh_off + k);
;             const float o0 = v[i].x * rstd * gg.x * (1.0f + scv.x) + shv.x, o1 = v[i].y * rstd * gg.y * (1.0f + scv.y) + shv.y;
;             const float o2 = v[i].z * rstd * gg.z * (1.0f + scv.z) + shv.z, o3 = v[i].w * rstd * gg.w * (1.0f + scv.w) + shv.w;
;             uint2 w; w.x = pk2(o0, o1); w.y = pk2(o2, o3);
;             *(uint2*)(A + (size_t)row * 1024 + k) = w;
;         }
	v_pk_mul_f32 v[242:243], v[112:113], v[112:113]
	v_pk_mul_f32 v[244:245], v[116:117], v[116:117]
	v_pk_mul_f32 v[246:247], v[114:115], v[114:115]
	v_pk_mul_f32 v[248:249], v[118:119], v[118:119]
	v_add_f32_e32 v204, v245, v244
	v_add_f32_e32 v205, v243, v242
	v_add_f32_e32 v204, v248, v204
	v_add_f32_e32 v205, v246, v205
	v_add_f32_e32 v204, v249, v204
	v_add_f32_e32 v205, v247, v205
	v_pk_mul_f32 v[242:243], v[120:121], v[120:121]
	v_pk_mul_f32 v[244:245], v[124:125], v[124:125]
	v_pk_mul_f32 v[246:247], v[122:123], v[122:123]
	v_pk_mul_f32 v[248:249], v[126:127], v[126:127]
	v_add_f32_e32 v206, v243, v242
	v_add_f32_e32 v207, v245, v244
	v_add_f32_e32 v206, v246, v206
	v_add_f32_e32 v207, v248, v207
	v_add_f32_e32 v206, v247, v206
	v_add_f32_e32 v207, v249, v207
	v_add_f32_e32 v204, v205, v204
	v_add_f32_e32 v204, v204, v206
	v_add_f32_e32 v204, v204, v207
	ds_swizzle_b32 v205, v204 offset:swizzle(SWAP,1)
	s_waitcnt lgkmcnt(0)
	v_add_f32_e32 v204, v204, v205
	ds_swizzle_b32 v205, v204 offset:swizzle(SWAP,2)
	s_waitcnt lgkmcnt(0)
	v_add_f32_e32 v204, v204, v205
	ds_swizzle_b32 v205, v204 offset:swizzle(SWAP,4)
	s_waitcnt lgkmcnt(0)
	v_add_f32_e32 v204, v204, v205
	ds_swizzle_b32 v205, v204 offset:swizzle(SWAP,8)
	s_waitcnt lgkmcnt(0)
	v_add_f32_e32 v204, v204, v205
	ds_swizzle_b32 v205, v204 offset:swizzle(SWAP,16)
	s_waitcnt lgkmcnt(0)
	v_add_f32_e32 v204, v204, v205
	v_mov_b32_e32 v205, v204
	s_nop 1
	v_permlane32_swap_b32_e32 v204, v205
	v_add_f32_e32 v204, v204, v205
	v_mov_b32_e32 v205, 0x358637bd
	v_fmamk_f32 v204, v204, 0x3a800000, v205
	v_rsq_f32_e32 v204, v204
	s_nop 0
	v_pk_mul_f32 v[112:113], v[112:113], v[204:205] op_sel_hi:[1,0]
	v_pk_mul_f32 v[114:115], v[114:115], v[204:205] op_sel_hi:[1,0]
	v_pk_mul_f32 v[112:113], v[188:189], v[112:113]
	v_pk_mul_f32 v[114:115], v[190:191], v[114:115]
	v_pk_fma_f32 v[112:113], v[34:35], v[112:113], v[224:225]
	v_pk_fma_f32 v[114:115], v[36:37], v[114:115], v[226:227]
	v_cvt_pk_bf16_f32 v112, v112, v113
	v_cvt_pk_bf16_f32 v113, v114, v115
	global_store_dwordx2 v146, v[112:113], s[66:67]
	v_pk_mul_f32 v[116:117], v[116:117], v[204:205] op_sel_hi:[1,0]
	v_pk_mul_f32 v[118:119], v[118:119], v[204:205] op_sel_hi:[1,0]
	v_pk_mul_f32 v[116:117], v[192:193], v[116:117]
	v_pk_mul_f32 v[118:119], v[194:195], v[118:119]
	v_pk_fma_f32 v[116:117], v[38:39], v[116:117], v[228:229]
	v_pk_fma_f32 v[118:119], v[40:41], v[118:119], v[230:231]
	v_cvt_pk_bf16_f32 v116, v116, v117
	v_cvt_pk_bf16_f32 v117, v118, v119
	global_store_dwordx2 v146, v[116:117], s[66:67] offset:512
	v_pk_mul_f32 v[120:121], v[120:121], v[204:205] op_sel_hi:[1,0]
	v_pk_mul_f32 v[122:123], v[122:123], v[204:205] op_sel_hi:[1,0]
	v_pk_mul_f32 v[120:121], v[196:197], v[120:121]
	v_pk_mul_f32 v[122:123], v[198:199], v[122:123]
	v_pk_fma_f32 v[120:121], v[42:43], v[120:121], v[232:233]
	v_pk_fma_f32 v[122:123], v[44:45], v[122:123], v[234:235]
	v_cvt_pk_bf16_f32 v120, v120, v121
	v_cvt_pk_bf16_f32 v121, v122, v123
	global_store_dwordx2 v146, v[120:121], s[66:67] offset:1024
	v_pk_mul_f32 v[124:125], v[124:125], v[204:205] op_sel_hi:[1,0]
	v_pk_mul_f32 v[126:127], v[126:127], v[204:205] op_sel_hi:[1,0]
	v_pk_mul_f32 v[124:125], v[200:201], v[124:125]
	v_pk_mul_f32 v[126:127], v[202:203], v[126:127]
	v_pk_fma_f32 v[124:125], v[46:47], v[124:125], v[236:237]
	v_pk_fma_f32 v[126:127], v[48:49], v[126:127], v[238:239]
	v_cvt_pk_bf16_f32 v124, v124, v125
	v_cvt_pk_bf16_f32 v125, v126, v127
	global_store_dwordx2 v146, v[124:125], s[66:67] offset:1536
	v_add_u32_e32 v146, 0x800, v146
	global_load_dwordx4 v[112:115], v144, s[46:47]
	global_load_dwordx4 v[116:119], v144, s[46:47] offset:1024
	global_load_dwordx4 v[120:123], v144, s[46:47] offset:2048
	global_load_dwordx4 v[124:127], v144, s[46:47] offset:3072
	v_add_u32_e32 v144, 0x1000, v144
	s_waitcnt vmcnt(32)
	v_pk_mul_f32 v[242:243], v[128:129], v[128:129]
	v_pk_mul_f32 v[244:245], v[132:133], v[132:133]
	v_pk_mul_f32 v[246:247], v[130:131], v[130:131]
	v_pk_mul_f32 v[248:249], v[134:135], v[134:135]
	v_add_f32_e32 v204, v245, v244
	v_add_f32_e32 v205, v243, v242
	v_add_f32_e32 v204, v248, v204
	v_add_f32_e32 v205, v246, v205
	v_add_f32_e32 v204, v249, v204
	v_add_f32_e32 v205, v247, v205
	v_pk_mul_f32 v[242:243], v[136:137], v[136:137]
	v_pk_mul_f32 v[244:245], v[140:141], v[140:141]
	v_pk_mul_f32 v[246:247], v[138:139], v[138:139]
	v_pk_mul_f32 v[248:249], v[142:143], v[142:143]
	v_add_f32_e32 v206, v243, v242
	v_add_f32_e32 v207, v245, v244
	v_add_f32_e32 v206, v246, v206
	v_add_f32_e32 v207, v248, v207
	v_add_f32_e32 v206, v247, v206
	v_add_f32_e32 v207, v249, v207
	v_add_f32_e32 v204, v205, v204
	v_add_f32_e32 v204, v204, v206
	v_add_f32_e32 v204, v204, v207
	ds_swizzle_b32 v205, v204 offset:swizzle(SWAP,1)
	s_waitcnt lgkmcnt(0)
	v_add_f32_e32 v204, v204, v205
	ds_swizzle_b32 v205, v204 offset:swizzle(SWAP,2)
	s_waitcnt lgkmcnt(0)
	v_add_f32_e32 v204, v204, v205
	ds_swizzle_b32 v205, v204 offset:swizzle(SWAP,4)
	s_waitcnt lgkmcnt(0)
	v_add_f32_e32 v204, v204, v205
	ds_swizzle_b32 v205, v204 offset:swizzle(SWAP,8)
	s_waitcnt lgkmcnt(0)
	v_add_f32_e32 v204, v204, v205
	ds_swizzle_b32 v205, v204 offset:swizzle(SWAP,16)
	s_waitcnt lgkmcnt(0)
; __device__ __forceinline__ unsigned pk2(float lo, float hi) { const g_f32x2 f = {lo, hi}; return __builtin_bit_cast(unsigned, __builtin_convertvector(f, g_bf16x2)); }
; __device__ __forceinline__ void p_norm(const float* hlat, const float* hctx, const float* g, const float* modl, int sh_off, int sc_off, bf16_t* A, int M,
;                                        const float* part, const float* cgate, float* hcout) {
;     ...
;         float ss = 0.f;
; #pragma unroll
;         for (int i = 0; i < 4; ++i) {
;             if (part != nullptr && row >= NLAT) {
;                 const size_t po = (size_t)(row - NLAT) * 1024 + i * 256 + lane * 4;
;                 const float4 p0 = *(const float4*)(part + po), p1 = *(const float4*)(part + (size_t)4096 * 1024 + po), cg = *(const float4*)(cgate + i * 256 + lane * 4);
;                 v[i].x += cg.x * (p0.x + p1.x); v[i].y += cg.y * (p0.y + p1.y); v[i].z += cg.z * (p0.z + p1.z); v[i].w += cg.w * (p0.w + p1.w);
;                 *(float4*)(hcout + po) = v[i];
;             }
;             ss += v[i].x * v[i].x + v[i].y * v[i].y + v[i].z * v[i].z + v[i].w * v[i].w; }
;         ss = wave_sum(ss);
;         const float rstd = rsqrtf(ss * (1.0f / 1024.0f) + EPS);
;         const float* mr = modl + (size_t)r * 6144;
; #pragma unroll
;         for (int i = 0; i < 4; ++i) {
;             const int k = i * 256 + lane * 4;
;             const float4 gg = *(const float4*)(g + k), scv = *(const float4*)(mr + sc_off + k), shv = *(const float4*)(mr + sh_off + k);
;             const float o0 = v[i].x * rstd * gg.x * (1.0f + scv.x) + shv.x, o1 = v[i].y * rstd * gg.y * (1.0f + scv.y) + shv.y;
;             const float o2 = v[i].z * rstd * gg.z * (1.0f + scv.z) + shv.z, o3 = v[i].w * rstd * gg.w * (1.0f + scv.w) + shv.w;
;             uint2 w; w.x = pk2(o0, o1); w.y = pk2(o2, o3);
;             *(uint2*)(A + (size_t)row * 1024 + k) = w;
;         }
	v_add_f32_e32 v204, v204, v205
	v_mov_b32_e32 v205, v204
	s_nop 1
	v_permlane32_swap_b32_e32 v204, v205
	v_add_f32_e32 v204, v204, v205
	v_mov_b32_e32 v205, 0x358637bd
	v_fmamk_f32 v204, v204, 0x3a800000, v205
	v_rsq_f32_e32 v204, v204
	s_nop 0
	v_pk_mul_f32 v[128:129], v[128:129], v[204:205] op_sel_hi:[1,0]
	v_pk_mul_f32 v[130:131], v[130:131], v[204:205] op_sel_hi:[1,0]
	v_pk_mul_f32 v[128:129], v[188:189], v[128:129]
	v_pk_mul_f32 v[130:131], v[190:191], v[130:131]
	v_pk_fma_f32 v[128:129], v[34:35], v[128:129], v[224:225]
	v_pk_fma_f32 v[130:131], v[36:37], v[130:131], v[226:227]
	v_cvt_pk_bf16_f32 v128, v128, v129
	v_cvt_pk_bf16_f32 v129, v130, v131
	global_store_dwordx2 v146, v[128:129], s[66:67]
	v_pk_mul_f32 v[132:133], v[132:133], v[204:205] op_sel_hi:[1,0]
	v_pk_mul_f32 v[134:135], v[134:135], v[204:205] op_sel_hi:[1,0]
	v_pk_mul_f32 v[132:133], v[192:193], v[132:133]
	v_pk_mul_f32 v[134:135], v[194:195], v[134:135]
	v_pk_fma_f32 v[132:133], v[38:39], v[132:133], v[228:229]
	v_pk_fma_f32 v[134:135], v[40:41], v[134:135], v[230:231]
	v_cvt_pk_bf16_f32 v132, v132, v133
	v_cvt_pk_bf16_f32 v133, v134, v135
	global_store_dwordx2 v146, v[132:133], s[66:67] offset:512
	v_pk_mul_f32 v[136:137], v[136:137], v[204:205] op_sel_hi:[1,0]
	v_pk_mul_f32 v[138:139], v[138:139], v[204:205] op_sel_hi:[1,0]
	v_pk_mul_f32 v[136:137], v[196:197], v[136:137]
	v_pk_mul_f32 v[138:139], v[198:199], v[138:139]
	v_pk_fma_f32 v[136:137], v[42:43], v[136:137], v[232:233]
	v_pk_fma_f32 v[138:139], v[44:45], v[138:139], v[234:235]
	v_cvt_pk_bf16_f32 v136, v136, v137
	v_cvt_pk_bf16_f32 v137, v138, v139
	global_store_dwordx2 v146, v[136:137], s[66:67] offset:1024
	v_pk_mul_f32 v[140:141], v[140:141], v[204:205] op_sel_hi:[1,0]
	v_pk_mul_f32 v[142:143], v[142:143], v[204:205] op_sel_hi:[1,0]
	v_pk_mul_f32 v[140:141], v[200:201], v[140:141]
	v_pk_mul_f32 v[142:143], v[202:203], v[142:143]
	v_pk_fma_f32 v[140:141], v[46:47], v[140:141], v[236:237]
	v_pk_fma_f32 v[142:143], v[48:49], v[142:143], v[238:239]
	v_cvt_pk_bf16_f32 v140, v140, v141
	v_cvt_pk_bf16_f32 v141, v142, v143
	global_store_dwordx2 v146, v[140:141], s[66:67] offset:1536
	v_add_u32_e32 v146, 0x800, v146
	global_load_dwordx4 v[128:131], v144, s[46:47]
	global_load_dwordx4 v[132:135], v144, s[46:47] offset:1024
	global_load_dwordx4 v[136:139], v144, s[46:47] offset:2048
	global_load_dwordx4 v[140:143], v144, s[46:47] offset:3072
	v_add_u32_e32 v144, 0x1000, v144
	s_waitcnt vmcnt(36)
	v_pk_mul_f32 v[242:243], v[156:157], v[156:157]
	v_pk_mul_f32 v[244:245], v[160:161], v[160:161]
	v_pk_mul_f32 v[246:247], v[158:159], v[158:159]
	v_pk_mul_f32 v[248:249], v[162:163], v[162:163]
	v_add_f32_e32 v204, v245, v244
	v_add_f32_e32 v205, v243, v242
	v_add_f32_e32 v204, v248, v204
	v_add_f32_e32 v205, v246, v205
	v_add_f32_e32 v204, v249, v204
	v_add_f32_e32 v205, v247, v205
	v_pk_mul_f32 v[242:243], v[164:165], v[164:165]
	v_pk_mul_f32 v[244:245], v[168:169], v[168:169]
	v_pk_mul_f32 v[246:247], v[166:167], v[166:167]
	v_pk_mul_f32 v[248:249], v[170:171], v[170:171]
	v_add_f32_e32 v206, v243, v242
	v_add_f32_e32 v207, v245, v244
	v_add_f32_e32 v206, v246, v206
	v_add_f32_e32 v207, v248, v207
	v_add_f32_e32 v206, v247, v206
	v_add_f32_e32 v207, v249, v207
	v_add_f32_e32 v204, v205, v204
	v_add_f32_e32 v204, v204, v206
	v_add_f32_e32 v204, v204, v207
	ds_swizzle_b32 v205, v204 offset:swizzle(SWAP,1)
	s_waitcnt lgkmcnt(0)
	v_add_f32_e32 v204, v204, v205
	ds_swizzle_b32 v205, v204 offset:swizzle(SWAP,2)
	s_waitcnt lgkmcnt(0)
	v_add_f32_e32 v204, v204, v205
	ds_swizzle_b32 v205, v204 offset:swizzle(SWAP,4)
	s_waitcnt lgkmcnt(0)
	v_add_f32_e32 v204, v204, v205
	ds_swizzle_b32 v205, v204 offset:swizzle(SWAP,8)
	s_waitcnt lgkmcnt(0)
	v_add_f32_e32 v204, v204, v205
	ds_swizzle_b32 v205, v204 offset:swizzle(SWAP,16)
	s_waitcnt lgkmcnt(0)
	v_add_f32_e32 v204, v204, v205
	v_mov_b32_e32 v205, v204
	s_nop 1
	v_permlane32_swap_b32_e32 v204, v205
	v_add_f32_e32 v204, v204, v205
	v_mov_b32_e32 v205, 0x358637bd
	v_fmamk_f32 v204, v204, 0x3a800000, v205
	v_rsq_f32_e32 v204, v204
	s_nop 0
	v_pk_mul_f32 v[156:157], v[156:157], v[204:205] op_sel_hi:[1,0]
	v_pk_mul_f32 v[158:159], v[158:159], v[204:205] op_sel_hi:[1,0]
	v_pk_mul_f32 v[156:157], v[188:189], v[156:157]
	v_pk_mul_f32 v[158:159], v[190:191], v[158:159]
	v_pk_fma_f32 v[156:157], v[34:35], v[156:157], v[224:225]
	v_pk_fma_f32 v[158:159], v[36:37], v[158:159], v[226:227]
	v_cvt_pk_bf16_f32 v156, v156, v157
	v_cvt_pk_bf16_f32 v157, v158, v159
	global_store_dwordx2 v146, v[156:157], s[66:67]
	v_pk_mul_f32 v[160:161], v[160:161], v[204:205] op_sel_hi:[1,0]
	v_pk_mul_f32 v[162:163], v[162:163], v[204:205] op_sel_hi:[1,0]
	v_pk_mul_f32 v[160:161], v[192:193], v[160:161]
	v_pk_mul_f32 v[162:163], v[194:195], v[162:163]
	v_pk_fma_f32 v[160:161], v[38:39], v[160:161], v[228:229]
	v_pk_fma_f32 v[162:163], v[40:41], v[162:163], v[230:231]
	v_cvt_pk_bf16_f32 v160, v160, v161
	v_cvt_pk_bf16_f32 v161, v162, v163
	global_store_dwordx2 v146, v[160:161], s[66:67] offset:512
	v_pk_mul_f32 v[164:165], v[164:165], v[204:205] op_sel_hi:[1,0]
	v_pk_mul_f32 v[166:167], v[166:167], v[204:205] op_sel_hi:[1,0]
	v_pk_mul_f32 v[164:165], v[196:197], v[164:165]
	v_pk_mul_f32 v[166:167], v[198:199], v[166:167]
	v_pk_fma_f32 v[164:165], v[42:43], v[164:165], v[232:233]
	v_pk_fma_f32 v[166:167], v[44:45], v[166:167], v[234:235]
	v_cvt_pk_bf16_f32 v164, v164, v165
	v_cvt_pk_bf16_f32 v165, v166, v167
	global_store_dwordx2 v146, v[164:165], s[66:67] offset:1024
	v_pk_mul_f32 v[168:169], v[168:169], v[204:205] op_sel_hi:[1,0]
	v_pk_mul_f32 v[170:171], v[170:171], v[204:205] op_sel_hi:[1,0]
	v_pk_mul_f32 v[168:169], v[200:201], v[168:169]
	v_pk_mul_f32 v[170:171], v[202:203], v[170:171]
	v_pk_fma_f32 v[168:169], v[46:47], v[168:169], v[236:237]
	v_pk_fma_f32 v[170:171], v[48:49], v[170:171], v[238:239]
	v_cvt_pk_bf16_f32 v168, v168, v169
	v_cvt_pk_bf16_f32 v169, v170, v171
	global_store_dwordx2 v146, v[168:169], s[66:67] offset:1536
	v_add_u32_e32 v146, 0x800, v146
	global_load_dwordx4 v[156:159], v144, s[46:47]
	global_load_dwordx4 v[160:163], v144, s[46:47] offset:1024
	global_load_dwordx4 v[164:167], v144, s[46:47] offset:2048
	global_load_dwordx4 v[168:171], v144, s[46:47] offset:3072
	v_add_u32_e32 v144, 0x1000, v144
	s_waitcnt vmcnt(40)
; __device__ __forceinline__ unsigned pk2(float lo, float hi) { const g_f32x2 f = {lo, hi}; return __builtin_bit_cast(unsigned, __builtin_convertvector(f, g_bf16x2)); }
; __device__ __forceinline__ void p_norm(const float* hlat, const float* hctx, const float* g, const float* modl, int sh_off, int sc_off, bf16_t* A, int M,
;                                        const float* part, const float* cgate, float* hcout) {
;     ...
;             ss += v[i].x * v[i].x + v[i].y * v[i].y + v[i].z * v[i].z + v[i].w * v[i].w; }
;         ss = wave_sum(ss);
;         const float rstd = rsqrtf(ss * (1.0f / 1024.0f) + EPS);
;         const float* mr = modl + (size_t)r * 6144;
; #pragma unroll
;         for (int i = 0; i < 4; ++i) {
;             const int k = i * 256 + lane * 4;
;             const float4 gg = *(const float4*)(g + k), scv = *(const float4*)(mr + sc_off + k), shv = *(const float4*)(mr + sh_off + k);
;             const float o0 = v[i].x * rstd * gg.x * (1.0f + scv.x) + shv.x, o1 = v[i].y * rstd * gg.y * (1.0f + scv.y) + shv.y;
;             const float o2 = v[i].z * rstd * gg.z * (1.0f + scv.z) + shv.z, o3 = v[i].w * rstd * gg.w * (1.0f + scv.w) + shv.w;
;             uint2 w; w.x = pk2(o0, o1); w.y = pk2(o2, o3);
;             *(uint2*)(A + (size_t)row * 1024 + k) = w;
;         }
	v_pk_mul_f32 v[242:243], v[172:173], v[172:173]
	v_pk_mul_f32 v[244:245], v[176:177], v[176:177]
	v_pk_mul_f32 v[246:247], v[174:175], v[174:175]
	v_pk_mul_f32 v[248:249], v[178:179], v[178:179]
	v_add_f32_e32 v204, v245, v244
	v_add_f32_e32 v205, v243, v242
	v_add_f32_e32 v204, v248, v204
	v_add_f32_e32 v205, v246, v205
	v_add_f32_e32 v204, v249, v204
	v_add_f32_e32 v205, v247, v205
	v_pk_mul_f32 v[242:243], v[180:181], v[180:181]
	v_pk_mul_f32 v[244:245], v[184:185], v[184:185]
	v_pk_mul_f32 v[246:247], v[182:183], v[182:183]
	v_pk_mul_f32 v[248:249], v[186:187], v[186:187]
	v_add_f32_e32 v206, v243, v242
	v_add_f32_e32 v207, v245, v244
	v_add_f32_e32 v206, v246, v206
	v_add_f32_e32 v207, v248, v207
	v_add_f32_e32 v206, v247, v206
	v_add_f32_e32 v207, v249, v207
	v_add_f32_e32 v204, v205, v204
	v_add_f32_e32 v204, v204, v206
	v_add_f32_e32 v204, v204, v207
	ds_swizzle_b32 v205, v204 offset:swizzle(SWAP,1)
	s_waitcnt lgkmcnt(0)
	v_add_f32_e32 v204, v204, v205
	ds_swizzle_b32 v205, v204 offset:swizzle(SWAP,2)
	s_waitcnt lgkmcnt(0)
	v_add_f32_e32 v204, v204, v205
	ds_swizzle_b32 v205, v204 offset:swizzle(SWAP,4)
	s_waitcnt lgkmcnt(0)
	v_add_f32_e32 v204, v204, v205
	ds_swizzle_b32 v205, v204 offset:swizzle(SWAP,8)
	s_waitcnt lgkmcnt(0)
	v_add_f32_e32 v204, v204, v205
	ds_swizzle_b32 v205, v204 offset:swizzle(SWAP,16)
	s_waitcnt lgkmcnt(0)
	v_add_f32_e32 v204, v204, v205
	v_mov_b32_e32 v205, v204
	s_nop 1
	v_permlane32_swap_b32_e32 v204, v205
	v_add_f32_e32 v204, v204, v205
	v_mov_b32_e32 v205, 0x358637bd
	v_fmamk_f32 v204, v204, 0x3a800000, v205
	v_rsq_f32_e32 v204, v204
	s_nop 0
	v_pk_mul_f32 v[172:173], v[172:173], v[204:205] op_sel_hi:[1,0]
	v_pk_mul_f32 v[174:175], v[174:175], v[204:205] op_sel_hi:[1,0]
	v_pk_mul_f32 v[172:173], v[188:189], v[172:173]
	v_pk_mul_f32 v[174:175], v[190:191], v[174:175]
	v_pk_fma_f32 v[172:173], v[34:35], v[172:173], v[224:225]
	v_pk_fma_f32 v[174:175], v[36:37], v[174:175], v[226:227]
	v_cvt_pk_bf16_f32 v172, v172, v173
	v_cvt_pk_bf16_f32 v173, v174, v175
	global_store_dwordx2 v146, v[172:173], s[66:67]
	v_pk_mul_f32 v[176:177], v[176:177], v[204:205] op_sel_hi:[1,0]
	v_pk_mul_f32 v[178:179], v[178:179], v[204:205] op_sel_hi:[1,0]
	v_pk_mul_f32 v[176:177], v[192:193], v[176:177]
	v_pk_mul_f32 v[178:179], v[194:195], v[178:179]
	v_pk_fma_f32 v[176:177], v[38:39], v[176:177], v[228:229]
	v_pk_fma_f32 v[178:179], v[40:41], v[178:179], v[230:231]
	v_cvt_pk_bf16_f32 v176, v176, v177
	v_cvt_pk_bf16_f32 v177, v178, v179
	global_store_dwordx2 v146, v[176:177], s[66:67] offset:512
	v_pk_mul_f32 v[180:181], v[180:181], v[204:205] op_sel_hi:[1,0]
	v_pk_mul_f32 v[182:183], v[182:183], v[204:205] op_sel_hi:[1,0]
	v_pk_mul_f32 v[180:181], v[196:197], v[180:181]
	v_pk_mul_f32 v[182:183], v[198:199], v[182:183]
	v_pk_fma_f32 v[180:181], v[42:43], v[180:181], v[232:233]
	v_pk_fma_f32 v[182:183], v[44:45], v[182:183], v[234:235]
	v_cvt_pk_bf16_f32 v180, v180, v181
	v_cvt_pk_bf16_f32 v181, v182, v183
	global_store_dwordx2 v146, v[180:181], s[66:67] offset:1024
	v_pk_mul_f32 v[184:185], v[184:185], v[204:205] op_sel_hi:[1,0]
	v_pk_mul_f32 v[186:187], v[186:187], v[204:205] op_sel_hi:[1,0]
	v_pk_mul_f32 v[184:185], v[200:201], v[184:185]
	v_pk_mul_f32 v[186:187], v[202:203], v[186:187]
	v_pk_fma_f32 v[184:185], v[46:47], v[184:185], v[236:237]
	v_pk_fma_f32 v[186:187], v[48:49], v[186:187], v[238:239]
	v_cvt_pk_bf16_f32 v184, v184, v185
	v_cvt_pk_bf16_f32 v185, v186, v187
	global_store_dwordx2 v146, v[184:185], s[66:67] offset:1536
	v_add_u32_e32 v146, 0x800, v146
	global_load_dwordx4 v[172:175], v144, s[46:47]
	global_load_dwordx4 v[176:179], v144, s[46:47] offset:1024
	global_load_dwordx4 v[180:183], v144, s[46:47] offset:2048
	global_load_dwordx4 v[184:187], v144, s[46:47] offset:3072
	v_add_u32_e32 v144, 0x1000, v144
	s_waitcnt vmcnt(40)
	v_pk_mul_f32 v[242:243], v[80:81], v[80:81]
	v_pk_mul_f32 v[244:245], v[84:85], v[84:85]
	v_pk_mul_f32 v[246:247], v[82:83], v[82:83]
	v_pk_mul_f32 v[248:249], v[86:87], v[86:87]
	v_add_f32_e32 v204, v245, v244
	v_add_f32_e32 v205, v243, v242
	v_add_f32_e32 v204, v248, v204
	v_add_f32_e32 v205, v246, v205
	v_add_f32_e32 v204, v249, v204
	v_add_f32_e32 v205, v247, v205
	v_pk_mul_f32 v[242:243], v[88:89], v[88:89]
	v_pk_mul_f32 v[244:245], v[92:93], v[92:93]
	v_pk_mul_f32 v[246:247], v[90:91], v[90:91]
	v_pk_mul_f32 v[248:249], v[94:95], v[94:95]
	v_add_f32_e32 v206, v243, v242
	v_add_f32_e32 v207, v245, v244
	v_add_f32_e32 v206, v246, v206
	v_add_f32_e32 v207, v248, v207
	v_add_f32_e32 v206, v247, v206
	v_add_f32_e32 v207, v249, v207
	v_add_f32_e32 v204, v205, v204
	v_add_f32_e32 v204, v204, v206
	v_add_f32_e32 v204, v204, v207
	ds_swizzle_b32 v205, v204 offset:swizzle(SWAP,1)
	s_waitcnt lgkmcnt(0)
	v_add_f32_e32 v204, v204, v205
	ds_swizzle_b32 v205, v204 offset:swizzle(SWAP,2)
	s_waitcnt lgkmcnt(0)
	v_add_f32_e32 v204, v204, v205
	ds_swizzle_b32 v205, v204 offset:swizzle(SWAP,4)
	s_waitcnt lgkmcnt(0)
	v_add_f32_e32 v204, v204, v205
	ds_swizzle_b32 v205, v204 offset:swizzle(SWAP,8)
	s_waitcnt lgkmcnt(0)
	v_add_f32_e32 v204, v204, v205
	ds_swizzle_b32 v205, v204 offset:swizzle(SWAP,16)
	s_waitcnt lgkmcnt(0)
; __device__ __forceinline__ unsigned pk2(float lo, float hi) { const g_f32x2 f = {lo, hi}; return __builtin_bit_cast(unsigned, __builtin_convertvector(f, g_bf16x2)); }
; __device__ __forceinline__ void p_norm(const float* hlat, const float* hctx, const float* g, const float* modl, int sh_off, int sc_off, bf16_t* A, int M,
;                                        const float* part, const float* cgate, float* hcout) {
;     ...
;             ss += v[i].x * v[i].x + v[i].y * v[i].y + v[i].z * v[i].z + v[i].w * v[i].w; }
;         ss = wave_sum(ss);
;         const float rstd = rsqrtf(ss * (1.0f / 1024.0f) + EPS);
;         const float* mr = modl + (size_t)r * 6144;
; #pragma unroll
;         for (int i = 0; i < 4; ++i) {
;             const int k = i * 256 + lane * 4;
;             const float4 gg = *(const float4*)(g + k), scv = *(const float4*)(mr + sc_off + k), shv = *(const float4*)(mr + sh_off + k);
;             const float o0 = v[i].x * rstd * gg.x * (1.0f + scv.x) + shv.x, o1 = v[i].y * rstd * gg.y * (1.0f + scv.y) + shv.y;
;             const float o2 = v[i].z * rstd * gg.z * (1.0f + scv.z) + shv.z, o3 = v[i].w * rstd * gg.w * (1.0f + scv.w) + shv.w;
;             uint2 w; w.x = pk2(o0, o1); w.y = pk2(o2, o3);
;             *(uint2*)(A + (size_t)row * 1024 + k) = w;
;         }
	v_add_f32_e32 v204, v204, v205
	v_mov_b32_e32 v205, v204
	s_nop 1
	v_permlane32_swap_b32_e32 v204, v205
	v_add_f32_e32 v204, v204, v205
	v_mov_b32_e32 v205, 0x358637bd
	v_fmamk_f32 v204, v204, 0x3a800000, v205
	v_rsq_f32_e32 v204, v204
	s_nop 0
	v_pk_mul_f32 v[80:81], v[80:81], v[204:205] op_sel_hi:[1,0]
	v_pk_mul_f32 v[82:83], v[82:83], v[204:205] op_sel_hi:[1,0]
	v_pk_mul_f32 v[80:81], v[188:189], v[80:81]
	v_pk_mul_f32 v[82:83], v[190:191], v[82:83]
	v_pk_fma_f32 v[80:81], v[34:35], v[80:81], v[224:225]
	v_pk_fma_f32 v[82:83], v[36:37], v[82:83], v[226:227]
	v_cvt_pk_bf16_f32 v80, v80, v81
	v_cvt_pk_bf16_f32 v81, v82, v83
	global_store_dwordx2 v146, v[80:81], s[66:67]
	v_pk_mul_f32 v[84:85], v[84:85], v[204:205] op_sel_hi:[1,0]
	v_pk_mul_f32 v[86:87], v[86:87], v[204:205] op_sel_hi:[1,0]
	v_pk_mul_f32 v[84:85], v[192:193], v[84:85]
	v_pk_mul_f32 v[86:87], v[194:195], v[86:87]
	v_pk_fma_f32 v[84:85], v[38:39], v[84:85], v[228:229]
	v_pk_fma_f32 v[86:87], v[40:41], v[86:87], v[230:231]
	v_cvt_pk_bf16_f32 v84, v84, v85
	v_cvt_pk_bf16_f32 v85, v86, v87
	global_store_dwordx2 v146, v[84:85], s[66:67] offset:512
	v_pk_mul_f32 v[88:89], v[88:89], v[204:205] op_sel_hi:[1,0]
	v_pk_mul_f32 v[90:91], v[90:91], v[204:205] op_sel_hi:[1,0]
	v_pk_mul_f32 v[88:89], v[196:197], v[88:89]
	v_pk_mul_f32 v[90:91], v[198:199], v[90:91]
	v_pk_fma_f32 v[88:89], v[42:43], v[88:89], v[232:233]
	v_pk_fma_f32 v[90:91], v[44:45], v[90:91], v[234:235]
	v_cvt_pk_bf16_f32 v88, v88, v89
	v_cvt_pk_bf16_f32 v89, v90, v91
	global_store_dwordx2 v146, v[88:89], s[66:67] offset:1024
	v_pk_mul_f32 v[92:93], v[92:93], v[204:205] op_sel_hi:[1,0]
	v_pk_mul_f32 v[94:95], v[94:95], v[204:205] op_sel_hi:[1,0]
	v_pk_mul_f32 v[92:93], v[200:201], v[92:93]
	v_pk_mul_f32 v[94:95], v[202:203], v[94:95]
	v_pk_fma_f32 v[92:93], v[46:47], v[92:93], v[236:237]
	v_pk_fma_f32 v[94:95], v[48:49], v[94:95], v[238:239]
	v_cvt_pk_bf16_f32 v92, v92, v93
	v_cvt_pk_bf16_f32 v93, v94, v95
	global_store_dwordx2 v146, v[92:93], s[66:67] offset:1536
	v_add_u32_e32 v146, 0x800, v146
	global_load_dwordx4 v[80:83], v144, s[46:47]
	global_load_dwordx4 v[84:87], v144, s[46:47] offset:1024
	global_load_dwordx4 v[88:91], v144, s[46:47] offset:2048
	global_load_dwordx4 v[92:95], v144, s[46:47] offset:3072
	v_add_u32_e32 v144, 0x1000, v144
	s_waitcnt vmcnt(40)
	v_pk_mul_f32 v[242:243], v[96:97], v[96:97]
	v_pk_mul_f32 v[244:245], v[100:101], v[100:101]
	v_pk_mul_f32 v[246:247], v[98:99], v[98:99]
	v_pk_mul_f32 v[248:249], v[102:103], v[102:103]
	v_add_f32_e32 v204, v245, v244
	v_add_f32_e32 v205, v243, v242
	v_add_f32_e32 v204, v248, v204
	v_add_f32_e32 v205, v246, v205
	v_add_f32_e32 v204, v249, v204
	v_add_f32_e32 v205, v247, v205
	v_pk_mul_f32 v[242:243], v[104:105], v[104:105]
	v_pk_mul_f32 v[244:245], v[108:109], v[108:109]
	v_pk_mul_f32 v[246:247], v[106:107], v[106:107]
	v_pk_mul_f32 v[248:249], v[110:111], v[110:111]
	v_add_f32_e32 v206, v243, v242
	v_add_f32_e32 v207, v245, v244
	v_add_f32_e32 v206, v246, v206
	v_add_f32_e32 v207, v248, v207
	v_add_f32_e32 v206, v247, v206
	v_add_f32_e32 v207, v249, v207
	v_add_f32_e32 v204, v205, v204
	v_add_f32_e32 v204, v204, v206
	v_add_f32_e32 v204, v204, v207
	ds_swizzle_b32 v205, v204 offset:swizzle(SWAP,1)
	s_waitcnt lgkmcnt(0)
	v_add_f32_e32 v204, v204, v205
	ds_swizzle_b32 v205, v204 offset:swizzle(SWAP,2)
	s_waitcnt lgkmcnt(0)
	v_add_f32_e32 v204, v204, v205
	ds_swizzle_b32 v205, v204 offset:swizzle(SWAP,4)
	s_waitcnt lgkmcnt(0)
	v_add_f32_e32 v204, v204, v205
	ds_swizzle_b32 v205, v204 offset:swizzle(SWAP,8)
	s_waitcnt lgkmcnt(0)
	v_add_f32_e32 v204, v204, v205
	ds_swizzle_b32 v205, v204 offset:swizzle(SWAP,16)
	s_waitcnt lgkmcnt(0)
	v_add_f32_e32 v204, v204, v205
	v_mov_b32_e32 v205, v204
	s_nop 1
	v_permlane32_swap_b32_e32 v204, v205
	v_add_f32_e32 v204, v204, v205
	v_mov_b32_e32 v205, 0x358637bd
	v_fmamk_f32 v204, v204, 0x3a800000, v205
	v_rsq_f32_e32 v204, v204
	s_nop 0
	v_pk_mul_f32 v[96:97], v[96:97], v[204:205] op_sel_hi:[1,0]
	v_pk_mul_f32 v[98:99], v[98:99], v[204:205] op_sel_hi:[1,0]
	v_pk_mul_f32 v[96:97], v[188:189], v[96:97]
	v_pk_mul_f32 v[98:99], v[190:191], v[98:99]
	v_pk_fma_f32 v[96:97], v[34:35], v[96:97], v[224:225]
	v_pk_fma_f32 v[98:99], v[36:37], v[98:99], v[226:227]
	v_cvt_pk_bf16_f32 v96, v96, v97
	v_cvt_pk_bf16_f32 v97, v98, v99
	global_store_dwordx2 v146, v[96:97], s[66:67]
	v_pk_mul_f32 v[100:101], v[100:101], v[204:205] op_sel_hi:[1,0]
	v_pk_mul_f32 v[102:103], v[102:103], v[204:205] op_sel_hi:[1,0]
	v_pk_mul_f32 v[100:101], v[192:193], v[100:101]
	v_pk_mul_f32 v[102:103], v[194:195], v[102:103]
	v_pk_fma_f32 v[100:101], v[38:39], v[100:101], v[228:229]
	v_pk_fma_f32 v[102:103], v[40:41], v[102:103], v[230:231]
	v_cvt_pk_bf16_f32 v100, v100, v101
	v_cvt_pk_bf16_f32 v101, v102, v103
	global_store_dwordx2 v146, v[100:101], s[66:67] offset:512
	v_pk_mul_f32 v[104:105], v[104:105], v[204:205] op_sel_hi:[1,0]
	v_pk_mul_f32 v[106:107], v[106:107], v[204:205] op_sel_hi:[1,0]
	v_pk_mul_f32 v[104:105], v[196:197], v[104:105]
	v_pk_mul_f32 v[106:107], v[198:199], v[106:107]
	v_pk_fma_f32 v[104:105], v[42:43], v[104:105], v[232:233]
	v_pk_fma_f32 v[106:107], v[44:45], v[106:107], v[234:235]
	v_cvt_pk_bf16_f32 v104, v104, v105
	v_cvt_pk_bf16_f32 v105, v106, v107
	global_store_dwordx2 v146, v[104:105], s[66:67] offset:1024
	v_pk_mul_f32 v[108:109], v[108:109], v[204:205] op_sel_hi:[1,0]
	v_pk_mul_f32 v[110:111], v[110:111], v[204:205] op_sel_hi:[1,0]
	v_pk_mul_f32 v[108:109], v[200:201], v[108:109]
	v_pk_mul_f32 v[110:111], v[202:203], v[110:111]
	v_pk_fma_f32 v[108:109], v[46:47], v[108:109], v[236:237]
	v_pk_fma_f32 v[110:111], v[48:49], v[110:111], v[238:239]
	v_cvt_pk_bf16_f32 v108, v108, v109
	v_cvt_pk_bf16_f32 v109, v110, v111
	global_store_dwordx2 v146, v[108:109], s[66:67] offset:1536
	v_add_u32_e32 v146, 0x800, v146
	global_load_dwordx4 v[96:99], v144, s[46:47]
	global_load_dwordx4 v[100:103], v144, s[46:47] offset:1024
	global_load_dwordx4 v[104:107], v144, s[46:47] offset:2048
	global_load_dwordx4 v[108:111], v144, s[46:47] offset:3072
	v_add_u32_e32 v144, 0x1000, v144
	s_waitcnt vmcnt(40)
; __device__ __forceinline__ unsigned pk2(float lo, float hi) { const g_f32x2 f = {lo, hi}; return __builtin_bit_cast(unsigned, __builtin_convertvector(f, g_bf16x2)); }
; __device__ __forceinline__ void p_norm(const float* hlat, const float* hctx, const float* g, const float* modl, int sh_off, int sc_off, bf16_t* A, int M,
;                                        const float* part, const float* cgate, float* hcout) {
;     ...
;             ss += v[i].x * v[i].x + v[i].y * v[i].y + v[i].z * v[i].z + v[i].w * v[i].w; }
;         ss = wave_sum(ss);
;         const float rstd = rsqrtf(ss * (1.0f / 1024.0f) + EPS);
;         const float* mr = modl + (size_t)r * 6144;
; #pragma unroll
;         for (int i = 0; i < 4; ++i) {
;             const int k = i * 256 + lane * 4;
;             const float4 gg = *(const float4*)(g + k), scv = *(const float4*)(mr + sc_off + k), shv = *(const float4*)(mr + sh_off + k);
;             const float o0 = v[i].x * rstd * gg.x * (1.0f + scv.x) + shv.x, o1 = v[i].y * rstd * gg.y * (1.0f + scv.y) + shv.y;
;             const float o2 = v[i].z * rstd * gg.z * (1.0f + scv.z) + shv.z, o3 = v[i].w * rstd * gg.w * (1.0f + scv.w) + shv.w;
;             uint2 w; w.x = pk2(o0, o1); w.y = pk2(o2, o3);
;             *(uint2*)(A + (size_t)row * 1024 + k) = w;
;         }
	v_pk_mul_f32 v[242:243], v[112:113], v[112:113]
	v_pk_mul_f32 v[244:245], v[116:117], v[116:117]
	v_pk_mul_f32 v[246:247], v[114:115], v[114:115]
	v_pk_mul_f32 v[248:249], v[118:119], v[118:119]
	v_add_f32_e32 v204, v245, v244
	v_add_f32_e32 v205, v243, v242
	v_add_f32_e32 v204, v248, v204
	v_add_f32_e32 v205, v246, v205
	v_add_f32_e32 v204, v249, v204
	v_add_f32_e32 v205, v247, v205
	v_pk_mul_f32 v[242:243], v[120:121], v[120:121]
	v_pk_mul_f32 v[244:245], v[124:125], v[124:125]
	v_pk_mul_f32 v[246:247], v[122:123], v[122:123]
	v_pk_mul_f32 v[248:249], v[126:127], v[126:127]
	v_add_f32_e32 v206, v243, v242
	v_add_f32_e32 v207, v245, v244
	v_add_f32_e32 v206, v246, v206
	v_add_f32_e32 v207, v248, v207
	v_add_f32_e32 v206, v247, v206
	v_add_f32_e32 v207, v249, v207
	v_add_f32_e32 v204, v205, v204
	v_add_f32_e32 v204, v204, v206
	v_add_f32_e32 v204, v204, v207
	ds_swizzle_b32 v205, v204 offset:swizzle(SWAP,1)
	s_waitcnt lgkmcnt(0)
	v_add_f32_e32 v204, v204, v205
	ds_swizzle_b32 v205, v204 offset:swizzle(SWAP,2)
	s_waitcnt lgkmcnt(0)
	v_add_f32_e32 v204, v204, v205
	ds_swizzle_b32 v205, v204 offset:swizzle(SWAP,4)
	s_waitcnt lgkmcnt(0)
	v_add_f32_e32 v204, v204, v205
	ds_swizzle_b32 v205, v204 offset:swizzle(SWAP,8)
	s_waitcnt lgkmcnt(0)
	v_add_f32_e32 v204, v204, v205
	ds_swizzle_b32 v205, v204 offset:swizzle(SWAP,16)
	s_waitcnt lgkmcnt(0)
	v_add_f32_e32 v204, v204, v205
	v_mov_b32_e32 v205, v204
	s_nop 1
	v_permlane32_swap_b32_e32 v204, v205
	v_add_f32_e32 v204, v204, v205
	v_mov_b32_e32 v205, 0x358637bd
	v_fmamk_f32 v204, v204, 0x3a800000, v205
	v_rsq_f32_e32 v204, v204
	s_nop 0
	v_pk_mul_f32 v[112:113], v[112:113], v[204:205] op_sel_hi:[1,0]
	v_pk_mul_f32 v[114:115], v[114:115], v[204:205] op_sel_hi:[1,0]
	v_pk_mul_f32 v[112:113], v[188:189], v[112:113]
	v_pk_mul_f32 v[114:115], v[190:191], v[114:115]
	v_pk_fma_f32 v[112:113], v[34:35], v[112:113], v[224:225]
	v_pk_fma_f32 v[114:115], v[36:37], v[114:115], v[226:227]
	v_cvt_pk_bf16_f32 v112, v112, v113
	v_cvt_pk_bf16_f32 v113, v114, v115
	global_store_dwordx2 v146, v[112:113], s[66:67]
	v_pk_mul_f32 v[116:117], v[116:117], v[204:205] op_sel_hi:[1,0]
	v_pk_mul_f32 v[118:119], v[118:119], v[204:205] op_sel_hi:[1,0]
	v_pk_mul_f32 v[116:117], v[192:193], v[116:117]
	v_pk_mul_f32 v[118:119], v[194:195], v[118:119]
	v_pk_fma_f32 v[116:117], v[38:39], v[116:117], v[228:229]
	v_pk_fma_f32 v[118:119], v[40:41], v[118:119], v[230:231]
	v_cvt_pk_bf16_f32 v116, v116, v117
	v_cvt_pk_bf16_f32 v117, v118, v119
	global_store_dwordx2 v146, v[116:117], s[66:67] offset:512
	v_pk_mul_f32 v[120:121], v[120:121], v[204:205] op_sel_hi:[1,0]
	v_pk_mul_f32 v[122:123], v[122:123], v[204:205] op_sel_hi:[1,0]
	v_pk_mul_f32 v[120:121], v[196:197], v[120:121]
	v_pk_mul_f32 v[122:123], v[198:199], v[122:123]
	v_pk_fma_f32 v[120:121], v[42:43], v[120:121], v[232:233]
	v_pk_fma_f32 v[122:123], v[44:45], v[122:123], v[234:235]
	v_cvt_pk_bf16_f32 v120, v120, v121
	v_cvt_pk_bf16_f32 v121, v122, v123
	global_store_dwordx2 v146, v[120:121], s[66:67] offset:1024
	v_pk_mul_f32 v[124:125], v[124:125], v[204:205] op_sel_hi:[1,0]
	v_pk_mul_f32 v[126:127], v[126:127], v[204:205] op_sel_hi:[1,0]
	v_pk_mul_f32 v[124:125], v[200:201], v[124:125]
	v_pk_mul_f32 v[126:127], v[202:203], v[126:127]
	v_pk_fma_f32 v[124:125], v[46:47], v[124:125], v[236:237]
	v_pk_fma_f32 v[126:127], v[48:49], v[126:127], v[238:239]
	v_cvt_pk_bf16_f32 v124, v124, v125
	v_cvt_pk_bf16_f32 v125, v126, v127
	global_store_dwordx2 v146, v[124:125], s[66:67] offset:1536
	v_add_u32_e32 v146, 0x800, v146
	global_load_dwordx4 v[112:115], v144, s[46:47]
	global_load_dwordx4 v[116:119], v144, s[46:47] offset:1024
	global_load_dwordx4 v[120:123], v144, s[46:47] offset:2048
	global_load_dwordx4 v[124:127], v144, s[46:47] offset:3072
	v_add_u32_e32 v144, 0x1000, v144
	s_waitcnt vmcnt(40)
	v_pk_mul_f32 v[242:243], v[128:129], v[128:129]
	v_pk_mul_f32 v[244:245], v[132:133], v[132:133]
	v_pk_mul_f32 v[246:247], v[130:131], v[130:131]
	v_pk_mul_f32 v[248:249], v[134:135], v[134:135]
	v_add_f32_e32 v204, v245, v244
	v_add_f32_e32 v205, v243, v242
	v_add_f32_e32 v204, v248, v204
	v_add_f32_e32 v205, v246, v205
	v_add_f32_e32 v204, v249, v204
	v_add_f32_e32 v205, v247, v205
	v_pk_mul_f32 v[242:243], v[136:137], v[136:137]
	v_pk_mul_f32 v[244:245], v[140:141], v[140:141]
	v_pk_mul_f32 v[246:247], v[138:139], v[138:139]
	v_pk_mul_f32 v[248:249], v[142:143], v[142:143]
	v_add_f32_e32 v206, v243, v242
	v_add_f32_e32 v207, v245, v244
	v_add_f32_e32 v206, v246, v206
	v_add_f32_e32 v207, v248, v207
	v_add_f32_e32 v206, v247, v206
	v_add_f32_e32 v207, v249, v207
	v_add_f32_e32 v204, v205, v204
	v_add_f32_e32 v204, v204, v206
	v_add_f32_e32 v204, v204, v207
	ds_swizzle_b32 v205, v204 offset:swizzle(SWAP,1)
	s_waitcnt lgkmcnt(0)
	v_add_f32_e32 v204, v204, v205
	ds_swizzle_b32 v205, v204 offset:swizzle(SWAP,2)
	s_waitcnt lgkmcnt(0)
	v_add_f32_e32 v204, v204, v205
	ds_swizzle_b32 v205, v204 offset:swizzle(SWAP,4)
	s_waitcnt lgkmcnt(0)
	v_add_f32_e32 v204, v204, v205
	ds_swizzle_b32 v205, v204 offset:swizzle(SWAP,8)
	s_waitcnt lgkmcnt(0)
	v_add_f32_e32 v204, v204, v205
	ds_swizzle_b32 v205, v204 offset:swizzle(SWAP,16)
	s_waitcnt lgkmcnt(0)
; __device__ __forceinline__ unsigned pk2(float lo, float hi) { const g_f32x2 f = {lo, hi}; return __builtin_bit_cast(unsigned, __builtin_convertvector(f, g_bf16x2)); }
; #define PN_LOAD(dst, rw) do { const float* s_ = (rw) < NLAT ? hlat + (size_t)(rw) * 1024 : hctx + (size_t)((rw) - NLAT) * 1024; \
;         _Pragma("unroll") for (int i = 0; i < 4; ++i) dst[i] = *(const float4*)(s_ + i * 256 + lane * 4); } while (0)
; __device__ __forceinline__ void p_norm(const float* hlat, const float* hctx, const float* g, const float* modl, int sh_off, int sc_off, bf16_t* A, int M,
;                                        const float* part, const float* cgate, float* hcout) {
;     ...
;     if (row < M) PN_LOAD(v, row);
;     while (row < M) {
;         const int nrow = row + stride;
;         if (nrow < M) PN_LOAD(nv, nrow);
;     ...
;             ss += v[i].x * v[i].x + v[i].y * v[i].y + v[i].z * v[i].z + v[i].w * v[i].w; }
;         ss = wave_sum(ss);
;         const float rstd = rsqrtf(ss * (1.0f / 1024.0f) + EPS);
;         const float* mr = modl + (size_t)r * 6144;
; #pragma unroll
;         for (int i = 0; i < 4; ++i) {
;             const int k = i * 256 + lane * 4;
;             const float4 gg = *(const float4*)(g + k), scv = *(const float4*)(mr + sc_off + k), shv = *(const float4*)(mr + sh_off + k);
;             const float o0 = v[i].x * rstd * gg.x * (1.0f + scv.x) + shv.x, o1 = v[i].y * rstd * gg.y * (1.0f + scv.y) + shv.y;
;             const float o2 = v[i].z * rstd * gg.z * (1.0f + scv.z) + shv.z, o3 = v[i].w * rstd * gg.w * (1.0f + scv.w) + shv.w;
;             uint2 w; w.x = pk2(o0, o1); w.y = pk2(o2, o3);
;             *(uint2*)(A + (size_t)row * 1024 + k) = w;
;         }
	v_add_f32_e32 v204, v204, v205
	v_mov_b32_e32 v205, v204
	s_nop 1
	v_permlane32_swap_b32_e32 v204, v205
	v_add_f32_e32 v204, v204, v205
	v_mov_b32_e32 v205, 0x358637bd
	v_fmamk_f32 v204, v204, 0x3a800000, v205
	v_rsq_f32_e32 v204, v204
	s_nop 0
	v_pk_mul_f32 v[128:129], v[128:129], v[204:205] op_sel_hi:[1,0]
	v_pk_mul_f32 v[130:131], v[130:131], v[204:205] op_sel_hi:[1,0]
	v_pk_mul_f32 v[128:129], v[188:189], v[128:129]
	v_pk_mul_f32 v[130:131], v[190:191], v[130:131]
	v_pk_fma_f32 v[128:129], v[34:35], v[128:129], v[224:225]
	v_pk_fma_f32 v[130:131], v[36:37], v[130:131], v[226:227]
	v_cvt_pk_bf16_f32 v128, v128, v129
	v_cvt_pk_bf16_f32 v129, v130, v131
	global_store_dwordx2 v146, v[128:129], s[66:67]
	v_pk_mul_f32 v[132:133], v[132:133], v[204:205] op_sel_hi:[1,0]
	v_pk_mul_f32 v[134:135], v[134:135], v[204:205] op_sel_hi:[1,0]
	v_pk_mul_f32 v[132:133], v[192:193], v[132:133]
	v_pk_mul_f32 v[134:135], v[194:195], v[134:135]
	v_pk_fma_f32 v[132:133], v[38:39], v[132:133], v[228:229]
	v_pk_fma_f32 v[134:135], v[40:41], v[134:135], v[230:231]
	v_cvt_pk_bf16_f32 v132, v132, v133
	v_cvt_pk_bf16_f32 v133, v134, v135
	global_store_dwordx2 v146, v[132:133], s[66:67] offset:512
	v_pk_mul_f32 v[136:137], v[136:137], v[204:205] op_sel_hi:[1,0]
	v_pk_mul_f32 v[138:139], v[138:139], v[204:205] op_sel_hi:[1,0]
	v_pk_mul_f32 v[136:137], v[196:197], v[136:137]
	v_pk_mul_f32 v[138:139], v[198:199], v[138:139]
	v_pk_fma_f32 v[136:137], v[42:43], v[136:137], v[232:233]
	v_pk_fma_f32 v[138:139], v[44:45], v[138:139], v[234:235]
	v_cvt_pk_bf16_f32 v136, v136, v137
	v_cvt_pk_bf16_f32 v137, v138, v139
	global_store_dwordx2 v146, v[136:137], s[66:67] offset:1024
	v_pk_mul_f32 v[140:141], v[140:141], v[204:205] op_sel_hi:[1,0]
	v_pk_mul_f32 v[142:143], v[142:143], v[204:205] op_sel_hi:[1,0]
	v_pk_mul_f32 v[140:141], v[200:201], v[140:141]
	v_pk_mul_f32 v[142:143], v[202:203], v[142:143]
	v_pk_fma_f32 v[140:141], v[46:47], v[140:141], v[236:237]
	v_pk_fma_f32 v[142:143], v[48:49], v[142:143], v[238:239]
	v_cvt_pk_bf16_f32 v140, v140, v141
	v_cvt_pk_bf16_f32 v141, v142, v143
	global_store_dwordx2 v146, v[140:141], s[66:67] offset:1536
	v_add_u32_e32 v146, 0x800, v146
	global_load_dwordx4 v[128:131], v144, s[46:47]
	global_load_dwordx4 v[132:135], v144, s[46:47] offset:1024
	global_load_dwordx4 v[136:139], v144, s[46:47] offset:2048
	global_load_dwordx4 v[140:143], v144, s[46:47] offset:3072
	v_add_u32_e32 v144, 0x1000, v144
	s_waitcnt vmcnt(40)
	v_pk_mul_f32 v[242:243], v[156:157], v[156:157]
	v_pk_mul_f32 v[244:245], v[160:161], v[160:161]
	v_pk_mul_f32 v[246:247], v[158:159], v[158:159]
	v_pk_mul_f32 v[248:249], v[162:163], v[162:163]
	v_add_f32_e32 v204, v245, v244
	v_add_f32_e32 v205, v243, v242
	v_add_f32_e32 v204, v248, v204
	v_add_f32_e32 v205, v246, v205
	v_add_f32_e32 v204, v249, v204
	v_add_f32_e32 v205, v247, v205
	v_pk_mul_f32 v[242:243], v[164:165], v[164:165]
	v_pk_mul_f32 v[244:245], v[168:169], v[168:169]
	v_pk_mul_f32 v[246:247], v[166:167], v[166:167]
	v_pk_mul_f32 v[248:249], v[170:171], v[170:171]
	v_add_f32_e32 v206, v243, v242
	v_add_f32_e32 v207, v245, v244
	v_add_f32_e32 v206, v246, v206
	v_add_f32_e32 v207, v248, v207
	v_add_f32_e32 v206, v247, v206
	v_add_f32_e32 v207, v249, v207
	v_add_f32_e32 v204, v205, v204
	v_add_f32_e32 v204, v204, v206
	v_add_f32_e32 v204, v204, v207
	ds_swizzle_b32 v205, v204 offset:swizzle(SWAP,1)
	s_waitcnt lgkmcnt(0)
	v_add_f32_e32 v204, v204, v205
	ds_swizzle_b32 v205, v204 offset:swizzle(SWAP,2)
	s_waitcnt lgkmcnt(0)
	v_add_f32_e32 v204, v204, v205
	ds_swizzle_b32 v205, v204 offset:swizzle(SWAP,4)
	s_waitcnt lgkmcnt(0)
	v_add_f32_e32 v204, v204, v205
	ds_swizzle_b32 v205, v204 offset:swizzle(SWAP,8)
	s_waitcnt lgkmcnt(0)
	v_add_f32_e32 v204, v204, v205
	ds_swizzle_b32 v205, v204 offset:swizzle(SWAP,16)
	s_waitcnt lgkmcnt(0)
	v_add_f32_e32 v204, v204, v205
	v_mov_b32_e32 v205, v204
	s_nop 1
	v_permlane32_swap_b32_e32 v204, v205
	v_add_f32_e32 v204, v204, v205
	v_mov_b32_e32 v205, 0x358637bd
	v_fmamk_f32 v204, v204, 0x3a800000, v205
	v_rsq_f32_e32 v204, v204
	s_nop 0
	v_pk_mul_f32 v[156:157], v[156:157], v[204:205] op_sel_hi:[1,0]
	v_pk_mul_f32 v[158:159], v[158:159], v[204:205] op_sel_hi:[1,0]
	v_pk_mul_f32 v[156:157], v[188:189], v[156:157]
	v_pk_mul_f32 v[158:159], v[190:191], v[158:159]
	v_pk_fma_f32 v[156:157], v[34:35], v[156:157], v[224:225]
	v_pk_fma_f32 v[158:159], v[36:37], v[158:159], v[226:227]
	v_cvt_pk_bf16_f32 v156, v156, v157
	v_cvt_pk_bf16_f32 v157, v158, v159
	global_store_dwordx2 v146, v[156:157], s[66:67]
	v_pk_mul_f32 v[160:161], v[160:161], v[204:205] op_sel_hi:[1,0]
	v_pk_mul_f32 v[162:163], v[162:163], v[204:205] op_sel_hi:[1,0]
	v_pk_mul_f32 v[160:161], v[192:193], v[160:161]
	v_pk_mul_f32 v[162:163], v[194:195], v[162:163]
	v_pk_fma_f32 v[160:161], v[38:39], v[160:161], v[228:229]
	v_pk_fma_f32 v[162:163], v[40:41], v[162:163], v[230:231]
	v_cvt_pk_bf16_f32 v160, v160, v161
	v_cvt_pk_bf16_f32 v161, v162, v163
	global_store_dwordx2 v146, v[160:161], s[66:67] offset:512
	v_pk_mul_f32 v[164:165], v[164:165], v[204:205] op_sel_hi:[1,0]
	v_pk_mul_f32 v[166:167], v[166:167], v[204:205] op_sel_hi:[1,0]
	v_pk_mul_f32 v[164:165], v[196:197], v[164:165]
	v_pk_mul_f32 v[166:167], v[198:199], v[166:167]
	v_pk_fma_f32 v[164:165], v[42:43], v[164:165], v[232:233]
	v_pk_fma_f32 v[166:167], v[44:45], v[166:167], v[234:235]
	v_cvt_pk_bf16_f32 v164, v164, v165
	v_cvt_pk_bf16_f32 v165, v166, v167
	global_store_dwordx2 v146, v[164:165], s[66:67] offset:1024
	v_pk_mul_f32 v[168:169], v[168:169], v[204:205] op_sel_hi:[1,0]
	v_pk_mul_f32 v[170:171], v[170:171], v[204:205] op_sel_hi:[1,0]
	v_pk_mul_f32 v[168:169], v[200:201], v[168:169]
	v_pk_mul_f32 v[170:171], v[202:203], v[170:171]
	v_pk_fma_f32 v[168:169], v[46:47], v[168:169], v[236:237]
	v_pk_fma_f32 v[170:171], v[48:49], v[170:171], v[238:239]
	v_cvt_pk_bf16_f32 v168, v168, v169
	v_cvt_pk_bf16_f32 v169, v170, v171
	global_store_dwordx2 v146, v[168:169], s[66:67] offset:1536
	v_add_u32_e32 v146, 0x800, v146
	v_lshl_add_u32 v144, v50, 13, v241
	v_mov_b32_e32 v152, v144
	v_add_u32_e32 v150, 0x1000000, v144
	global_load_dwordx4 v[156:159], v144, s[16:17]
	global_load_dwordx4 v[160:163], v144, s[16:17] offset:1024
	global_load_dwordx4 v[164:167], v144, s[16:17] offset:2048
	global_load_dwordx4 v[168:171], v144, s[16:17] offset:3072
	v_add_u32_e32 v144, 0x1000, v144
	s_waitcnt vmcnt(40)
; __device__ __forceinline__ unsigned pk2(float lo, float hi) { const g_f32x2 f = {lo, hi}; return __builtin_bit_cast(unsigned, __builtin_convertvector(f, g_bf16x2)); }
; #define PN_LOAD(dst, rw) do { const float* s_ = (rw) < NLAT ? hlat + (size_t)(rw) * 1024 : hctx + (size_t)((rw) - NLAT) * 1024; \
;         _Pragma("unroll") for (int i = 0; i < 4; ++i) dst[i] = *(const float4*)(s_ + i * 256 + lane * 4); } while (0)
; __device__ __forceinline__ void p_norm(const float* hlat, const float* hctx, const float* g, const float* modl, int sh_off, int sc_off, bf16_t* A, int M,
;                                        const float* part, const float* cgate, float* hcout) {
;     ...
;     if (row < M) PN_LOAD(v, row);
;     while (row < M) {
;         const int nrow = row + stride;
;         if (nrow < M) PN_LOAD(nv, nrow);
;     ...
;             ss += v[i].x * v[i].x + v[i].y * v[i].y + v[i].z * v[i].z + v[i].w * v[i].w; }
;         ss = wave_sum(ss);
;         const float rstd = rsqrtf(ss * (1.0f / 1024.0f) + EPS);
;         const float* mr = modl + (size_t)r * 6144;
; #pragma unroll
;         for (int i = 0; i < 4; ++i) {
;             const int k = i * 256 + lane * 4;
;             const float4 gg = *(const float4*)(g + k), scv = *(const float4*)(mr + sc_off + k), shv = *(const float4*)(mr + sh_off + k);
;             const float o0 = v[i].x * rstd * gg.x * (1.0f + scv.x) + shv.x, o1 = v[i].y * rstd * gg.y * (1.0f + scv.y) + shv.y;
;             const float o2 = v[i].z * rstd * gg.z * (1.0f + scv.z) + shv.z, o3 = v[i].w * rstd * gg.w * (1.0f + scv.w) + shv.w;
;             uint2 w; w.x = pk2(o0, o1); w.y = pk2(o2, o3);
;             *(uint2*)(A + (size_t)row * 1024 + k) = w;
;         }
	v_pk_mul_f32 v[242:243], v[172:173], v[172:173]
	v_pk_mul_f32 v[244:245], v[176:177], v[176:177]
	v_pk_mul_f32 v[246:247], v[174:175], v[174:175]
	v_pk_mul_f32 v[248:249], v[178:179], v[178:179]
	v_add_f32_e32 v204, v245, v244
	v_add_f32_e32 v205, v243, v242
	v_add_f32_e32 v204, v248, v204
	v_add_f32_e32 v205, v246, v205
	v_add_f32_e32 v204, v249, v204
	v_add_f32_e32 v205, v247, v205
	v_pk_mul_f32 v[242:243], v[180:181], v[180:181]
	v_pk_mul_f32 v[244:245], v[184:185], v[184:185]
	v_pk_mul_f32 v[246:247], v[182:183], v[182:183]
	v_pk_mul_f32 v[248:249], v[186:187], v[186:187]
	v_add_f32_e32 v206, v243, v242
	v_add_f32_e32 v207, v245, v244
	v_add_f32_e32 v206, v246, v206
	v_add_f32_e32 v207, v248, v207
	v_add_f32_e32 v206, v247, v206
	v_add_f32_e32 v207, v249, v207
	v_add_f32_e32 v204, v205, v204
	v_add_f32_e32 v204, v204, v206
	v_add_f32_e32 v204, v204, v207
	ds_swizzle_b32 v205, v204 offset:swizzle(SWAP,1)
	s_waitcnt lgkmcnt(0)
	v_add_f32_e32 v204, v204, v205
	ds_swizzle_b32 v205, v204 offset:swizzle(SWAP,2)
	s_waitcnt lgkmcnt(0)
	v_add_f32_e32 v204, v204, v205
	ds_swizzle_b32 v205, v204 offset:swizzle(SWAP,4)
	s_waitcnt lgkmcnt(0)
	v_add_f32_e32 v204, v204, v205
	ds_swizzle_b32 v205, v204 offset:swizzle(SWAP,8)
	s_waitcnt lgkmcnt(0)
	v_add_f32_e32 v204, v204, v205
	ds_swizzle_b32 v205, v204 offset:swizzle(SWAP,16)
	s_waitcnt lgkmcnt(0)
	v_add_f32_e32 v204, v204, v205
	v_mov_b32_e32 v205, v204
	s_nop 1
	v_permlane32_swap_b32_e32 v204, v205
	v_add_f32_e32 v204, v204, v205
	v_mov_b32_e32 v205, 0x358637bd
	v_fmamk_f32 v204, v204, 0x3a800000, v205
	v_rsq_f32_e32 v204, v204
	s_nop 0
	v_pk_mul_f32 v[172:173], v[172:173], v[204:205] op_sel_hi:[1,0]
	v_pk_mul_f32 v[174:175], v[174:175], v[204:205] op_sel_hi:[1,0]
	v_pk_mul_f32 v[172:173], v[188:189], v[172:173]
	v_pk_mul_f32 v[174:175], v[190:191], v[174:175]
	v_pk_fma_f32 v[172:173], v[34:35], v[172:173], v[224:225]
	v_pk_fma_f32 v[174:175], v[36:37], v[174:175], v[226:227]
	v_cvt_pk_bf16_f32 v172, v172, v173
	v_cvt_pk_bf16_f32 v173, v174, v175
	global_store_dwordx2 v146, v[172:173], s[66:67]
	v_pk_mul_f32 v[176:177], v[176:177], v[204:205] op_sel_hi:[1,0]
	v_pk_mul_f32 v[178:179], v[178:179], v[204:205] op_sel_hi:[1,0]
	v_pk_mul_f32 v[176:177], v[192:193], v[176:177]
	v_pk_mul_f32 v[178:179], v[194:195], v[178:179]
	v_pk_fma_f32 v[176:177], v[38:39], v[176:177], v[228:229]
	v_pk_fma_f32 v[178:179], v[40:41], v[178:179], v[230:231]
	v_cvt_pk_bf16_f32 v176, v176, v177
	v_cvt_pk_bf16_f32 v177, v178, v179
	global_store_dwordx2 v146, v[176:177], s[66:67] offset:512
	v_pk_mul_f32 v[180:181], v[180:181], v[204:205] op_sel_hi:[1,0]
	v_pk_mul_f32 v[182:183], v[182:183], v[204:205] op_sel_hi:[1,0]
	v_pk_mul_f32 v[180:181], v[196:197], v[180:181]
	v_pk_mul_f32 v[182:183], v[198:199], v[182:183]
	v_pk_fma_f32 v[180:181], v[42:43], v[180:181], v[232:233]
	v_pk_fma_f32 v[182:183], v[44:45], v[182:183], v[234:235]
	v_cvt_pk_bf16_f32 v180, v180, v181
	v_cvt_pk_bf16_f32 v181, v182, v183
	global_store_dwordx2 v146, v[180:181], s[66:67] offset:1024
	v_pk_mul_f32 v[184:185], v[184:185], v[204:205] op_sel_hi:[1,0]
	v_pk_mul_f32 v[186:187], v[186:187], v[204:205] op_sel_hi:[1,0]
	v_pk_mul_f32 v[184:185], v[200:201], v[184:185]
	v_pk_mul_f32 v[186:187], v[202:203], v[186:187]
	v_pk_fma_f32 v[184:185], v[46:47], v[184:185], v[236:237]
	v_pk_fma_f32 v[186:187], v[48:49], v[186:187], v[238:239]
	v_cvt_pk_bf16_f32 v184, v184, v185
	v_cvt_pk_bf16_f32 v185, v186, v187
	global_store_dwordx2 v146, v[184:185], s[66:67] offset:1536
	v_add_u32_e32 v146, 0x800, v146
	global_load_dwordx4 v[172:175], v144, s[16:17]
	global_load_dwordx4 v[176:179], v144, s[16:17] offset:1024
	global_load_dwordx4 v[180:183], v144, s[16:17] offset:2048
	global_load_dwordx4 v[184:187], v144, s[16:17] offset:3072
	v_add_u32_e32 v144, 0x1000, v144
	s_waitcnt vmcnt(40)
	v_pk_mul_f32 v[242:243], v[80:81], v[80:81]
	v_pk_mul_f32 v[244:245], v[84:85], v[84:85]
	v_pk_mul_f32 v[246:247], v[82:83], v[82:83]
	v_pk_mul_f32 v[248:249], v[86:87], v[86:87]
	v_add_f32_e32 v204, v245, v244
	v_add_f32_e32 v205, v243, v242
	v_add_f32_e32 v204, v248, v204
	v_add_f32_e32 v205, v246, v205
	v_add_f32_e32 v204, v249, v204
	v_add_f32_e32 v205, v247, v205
	v_pk_mul_f32 v[242:243], v[88:89], v[88:89]
	v_pk_mul_f32 v[244:245], v[92:93], v[92:93]
	v_pk_mul_f32 v[246:247], v[90:91], v[90:91]
	v_pk_mul_f32 v[248:249], v[94:95], v[94:95]
	v_add_f32_e32 v206, v243, v242
	v_add_f32_e32 v207, v245, v244
	v_add_f32_e32 v206, v246, v206
	v_add_f32_e32 v207, v248, v207
	v_add_f32_e32 v206, v247, v206
	v_add_f32_e32 v207, v249, v207
	v_add_f32_e32 v204, v205, v204
	v_add_f32_e32 v204, v204, v206
	v_add_f32_e32 v204, v204, v207
	ds_swizzle_b32 v205, v204 offset:swizzle(SWAP,1)
	s_waitcnt lgkmcnt(0)
	v_add_f32_e32 v204, v204, v205
	ds_swizzle_b32 v205, v204 offset:swizzle(SWAP,2)
	s_waitcnt lgkmcnt(0)
	v_add_f32_e32 v204, v204, v205
	ds_swizzle_b32 v205, v204 offset:swizzle(SWAP,4)
	s_waitcnt lgkmcnt(0)
	v_add_f32_e32 v204, v204, v205
	ds_swizzle_b32 v205, v204 offset:swizzle(SWAP,8)
	s_waitcnt lgkmcnt(0)
	v_add_f32_e32 v204, v204, v205
	ds_swizzle_b32 v205, v204 offset:swizzle(SWAP,16)
	s_waitcnt lgkmcnt(0)
; __device__ __forceinline__ unsigned pk2(float lo, float hi) { const g_f32x2 f = {lo, hi}; return __builtin_bit_cast(unsigned, __builtin_convertvector(f, g_bf16x2)); }
; __device__ __forceinline__ void p_norm(const float* hlat, const float* hctx, const float* g, const float* modl, int sh_off, int sc_off, bf16_t* A, int M,
;                                        const float* part, const float* cgate, float* hcout) {
;     ...
;             if (part != nullptr && row >= NLAT) {
;                 const size_t po = (size_t)(row - NLAT) * 1024 + i * 256 + lane * 4;
;                 const float4 p0 = *(const float4*)(part + po), p1 = *(const float4*)(part + (size_t)4096 * 1024 + po), cg = *(const float4*)(cgate + i * 256 + lane * 4);
;     ...
;             ss += v[i].x * v[i].x + v[i].y * v[i].y + v[i].z * v[i].z + v[i].w * v[i].w; }
;         ss = wave_sum(ss);
;         const float rstd = rsqrtf(ss * (1.0f / 1024.0f) + EPS);
;         const float* mr = modl + (size_t)r * 6144;
; #pragma unroll
;         for (int i = 0; i < 4; ++i) {
;             const int k = i * 256 + lane * 4;
;             const float4 gg = *(const float4*)(g + k), scv = *(const float4*)(mr + sc_off + k), shv = *(const float4*)(mr + sh_off + k);
;             const float o0 = v[i].x * rstd * gg.x * (1.0f + scv.x) + shv.x, o1 = v[i].y * rstd * gg.y * (1.0f + scv.y) + shv.y;
;             const float o2 = v[i].z * rstd * gg.z * (1.0f + scv.z) + shv.z, o3 = v[i].w * rstd * gg.w * (1.0f + scv.w) + shv.w;
;             uint2 w; w.x = pk2(o0, o1); w.y = pk2(o2, o3);
;             *(uint2*)(A + (size_t)row * 1024 + k) = w;
;         }
	v_add_f32_e32 v204, v204, v205
	v_mov_b32_e32 v205, v204
	s_nop 1
	v_permlane32_swap_b32_e32 v204, v205
	v_add_f32_e32 v204, v204, v205
	v_mov_b32_e32 v205, 0x358637bd
	v_fmamk_f32 v204, v204, 0x3a800000, v205
	v_rsq_f32_e32 v204, v204
	s_nop 0
	v_pk_mul_f32 v[80:81], v[80:81], v[204:205] op_sel_hi:[1,0]
	v_pk_mul_f32 v[82:83], v[82:83], v[204:205] op_sel_hi:[1,0]
	v_pk_mul_f32 v[80:81], v[188:189], v[80:81]
	v_pk_mul_f32 v[82:83], v[190:191], v[82:83]
	v_pk_fma_f32 v[80:81], v[34:35], v[80:81], v[224:225]
	v_pk_fma_f32 v[82:83], v[36:37], v[82:83], v[226:227]
	v_cvt_pk_bf16_f32 v80, v80, v81
	v_cvt_pk_bf16_f32 v81, v82, v83
	global_store_dwordx2 v146, v[80:81], s[66:67]
	v_pk_mul_f32 v[84:85], v[84:85], v[204:205] op_sel_hi:[1,0]
	v_pk_mul_f32 v[86:87], v[86:87], v[204:205] op_sel_hi:[1,0]
	v_pk_mul_f32 v[84:85], v[192:193], v[84:85]
	v_pk_mul_f32 v[86:87], v[194:195], v[86:87]
	v_pk_fma_f32 v[84:85], v[38:39], v[84:85], v[228:229]
	v_pk_fma_f32 v[86:87], v[40:41], v[86:87], v[230:231]
	v_cvt_pk_bf16_f32 v84, v84, v85
	v_cvt_pk_bf16_f32 v85, v86, v87
	global_store_dwordx2 v146, v[84:85], s[66:67] offset:512
	v_pk_mul_f32 v[88:89], v[88:89], v[204:205] op_sel_hi:[1,0]
	v_pk_mul_f32 v[90:91], v[90:91], v[204:205] op_sel_hi:[1,0]
	v_pk_mul_f32 v[88:89], v[196:197], v[88:89]
	v_pk_mul_f32 v[90:91], v[198:199], v[90:91]
	v_pk_fma_f32 v[88:89], v[42:43], v[88:89], v[232:233]
	v_pk_fma_f32 v[90:91], v[44:45], v[90:91], v[234:235]
	v_cvt_pk_bf16_f32 v88, v88, v89
	v_cvt_pk_bf16_f32 v89, v90, v91
	global_store_dwordx2 v146, v[88:89], s[66:67] offset:1024
	v_pk_mul_f32 v[92:93], v[92:93], v[204:205] op_sel_hi:[1,0]
	v_pk_mul_f32 v[94:95], v[94:95], v[204:205] op_sel_hi:[1,0]
	v_pk_mul_f32 v[92:93], v[200:201], v[92:93]
	v_pk_mul_f32 v[94:95], v[202:203], v[94:95]
	v_pk_fma_f32 v[92:93], v[46:47], v[92:93], v[236:237]
	v_pk_fma_f32 v[94:95], v[48:49], v[94:95], v[238:239]
	v_cvt_pk_bf16_f32 v92, v92, v93
	v_cvt_pk_bf16_f32 v93, v94, v95
	global_store_dwordx2 v146, v[92:93], s[66:67] offset:1536
	v_add_u32_e32 v146, 0x800, v146
	global_load_dwordx4 v[8:11], v241, s[20:21]
	global_load_dwordx4 v[52:55], v241, s[20:21] offset:1024
	global_load_dwordx4 v[60:63], v241, s[20:21] offset:2048
	global_load_dwordx4 v[64:67], v241, s[20:21] offset:3072
	s_waitcnt vmcnt(40)
	v_pk_mul_f32 v[242:243], v[96:97], v[96:97]
	v_pk_mul_f32 v[244:245], v[100:101], v[100:101]
	v_pk_mul_f32 v[246:247], v[98:99], v[98:99]
	v_pk_mul_f32 v[248:249], v[102:103], v[102:103]
	v_add_f32_e32 v204, v245, v244
	v_add_f32_e32 v205, v243, v242
	v_add_f32_e32 v204, v248, v204
	v_add_f32_e32 v205, v246, v205
	v_add_f32_e32 v204, v249, v204
	v_add_f32_e32 v205, v247, v205
	v_pk_mul_f32 v[242:243], v[104:105], v[104:105]
	v_pk_mul_f32 v[244:245], v[108:109], v[108:109]
	v_pk_mul_f32 v[246:247], v[106:107], v[106:107]
	v_pk_mul_f32 v[248:249], v[110:111], v[110:111]
	v_add_f32_e32 v206, v243, v242
	v_add_f32_e32 v207, v245, v244
	v_add_f32_e32 v206, v246, v206
	v_add_f32_e32 v207, v248, v207
	v_add_f32_e32 v206, v247, v206
	v_add_f32_e32 v207, v249, v207
	v_add_f32_e32 v204, v205, v204
	v_add_f32_e32 v204, v204, v206
	v_add_f32_e32 v204, v204, v207
	ds_swizzle_b32 v205, v204 offset:swizzle(SWAP,1)
	s_waitcnt lgkmcnt(0)
	v_add_f32_e32 v204, v204, v205
	ds_swizzle_b32 v205, v204 offset:swizzle(SWAP,2)
	s_waitcnt lgkmcnt(0)
	v_add_f32_e32 v204, v204, v205
	ds_swizzle_b32 v205, v204 offset:swizzle(SWAP,4)
	s_waitcnt lgkmcnt(0)
	v_add_f32_e32 v204, v204, v205
	ds_swizzle_b32 v205, v204 offset:swizzle(SWAP,8)
	s_waitcnt lgkmcnt(0)
	v_add_f32_e32 v204, v204, v205
	ds_swizzle_b32 v205, v204 offset:swizzle(SWAP,16)
	s_waitcnt lgkmcnt(0)
	v_add_f32_e32 v204, v204, v205
	v_mov_b32_e32 v205, v204
	s_nop 1
	v_permlane32_swap_b32_e32 v204, v205
	v_add_f32_e32 v204, v204, v205
	v_mov_b32_e32 v205, 0x358637bd
	v_fmamk_f32 v204, v204, 0x3a800000, v205
	v_rsq_f32_e32 v204, v204
	s_nop 0
	v_pk_mul_f32 v[96:97], v[96:97], v[204:205] op_sel_hi:[1,0]
	v_pk_mul_f32 v[98:99], v[98:99], v[204:205] op_sel_hi:[1,0]
	v_pk_mul_f32 v[96:97], v[188:189], v[96:97]
	v_pk_mul_f32 v[98:99], v[190:191], v[98:99]
	v_pk_fma_f32 v[96:97], v[34:35], v[96:97], v[224:225]
	v_pk_fma_f32 v[98:99], v[36:37], v[98:99], v[226:227]
	v_cvt_pk_bf16_f32 v96, v96, v97
	v_cvt_pk_bf16_f32 v97, v98, v99
	global_store_dwordx2 v146, v[96:97], s[66:67]
	v_pk_mul_f32 v[100:101], v[100:101], v[204:205] op_sel_hi:[1,0]
	v_pk_mul_f32 v[102:103], v[102:103], v[204:205] op_sel_hi:[1,0]
	v_pk_mul_f32 v[100:101], v[192:193], v[100:101]
	v_pk_mul_f32 v[102:103], v[194:195], v[102:103]
	v_pk_fma_f32 v[100:101], v[38:39], v[100:101], v[228:229]
	v_pk_fma_f32 v[102:103], v[40:41], v[102:103], v[230:231]
	v_cvt_pk_bf16_f32 v100, v100, v101
	v_cvt_pk_bf16_f32 v101, v102, v103
	global_store_dwordx2 v146, v[100:101], s[66:67] offset:512
	v_pk_mul_f32 v[104:105], v[104:105], v[204:205] op_sel_hi:[1,0]
	v_pk_mul_f32 v[106:107], v[106:107], v[204:205] op_sel_hi:[1,0]
	v_pk_mul_f32 v[104:105], v[196:197], v[104:105]
	v_pk_mul_f32 v[106:107], v[198:199], v[106:107]
	v_pk_fma_f32 v[104:105], v[42:43], v[104:105], v[232:233]
	v_pk_fma_f32 v[106:107], v[44:45], v[106:107], v[234:235]
	v_cvt_pk_bf16_f32 v104, v104, v105
	v_cvt_pk_bf16_f32 v105, v106, v107
	global_store_dwordx2 v146, v[104:105], s[66:67] offset:1024
	v_pk_mul_f32 v[108:109], v[108:109], v[204:205] op_sel_hi:[1,0]
	v_pk_mul_f32 v[110:111], v[110:111], v[204:205] op_sel_hi:[1,0]
	v_pk_mul_f32 v[108:109], v[200:201], v[108:109]
	v_pk_mul_f32 v[110:111], v[202:203], v[110:111]
	v_pk_fma_f32 v[108:109], v[46:47], v[108:109], v[236:237]
	v_pk_fma_f32 v[110:111], v[48:49], v[110:111], v[238:239]
	v_cvt_pk_bf16_f32 v108, v108, v109
	v_cvt_pk_bf16_f32 v109, v110, v111
	global_store_dwordx2 v146, v[108:109], s[66:67] offset:1536
	v_add_u32_e32 v146, 0x800, v146
	global_load_dwordx4 v[80:83], v152, s[70:71]
	global_load_dwordx4 v[84:87], v152, s[70:71] offset:1024
	global_load_dwordx4 v[88:91], v152, s[70:71] offset:2048
	global_load_dwordx4 v[92:95], v152, s[70:71] offset:3072
	global_load_dwordx4 v[96:99], v150, s[70:71]
	global_load_dwordx4 v[100:103], v150, s[70:71] offset:1024
	global_load_dwordx4 v[104:107], v150, s[70:71] offset:2048
	global_load_dwordx4 v[108:111], v150, s[70:71] offset:3072
	s_waitcnt vmcnt(44)
; __device__ __forceinline__ unsigned pk2(float lo, float hi) { const g_f32x2 f = {lo, hi}; return __builtin_bit_cast(unsigned, __builtin_convertvector(f, g_bf16x2)); }
; __device__ __forceinline__ void p_norm(const float* hlat, const float* hctx, const float* g, const float* modl, int sh_off, int sc_off, bf16_t* A, int M,
;                                        const float* part, const float* cgate, float* hcout) {
;     ...
;             if (part != nullptr && row >= NLAT) {
;                 const size_t po = (size_t)(row - NLAT) * 1024 + i * 256 + lane * 4;
;                 const float4 p0 = *(const float4*)(part + po), p1 = *(const float4*)(part + (size_t)4096 * 1024 + po), cg = *(const float4*)(cgate + i * 256 + lane * 4);
;     ...
;             ss += v[i].x * v[i].x + v[i].y * v[i].y + v[i].z * v[i].z + v[i].w * v[i].w; }
;         ss = wave_sum(ss);
;         const float rstd = rsqrtf(ss * (1.0f / 1024.0f) + EPS);
;         const float* mr = modl + (size_t)r * 6144;
; #pragma unroll
;         for (int i = 0; i < 4; ++i) {
;             const int k = i * 256 + lane * 4;
;             const float4 gg = *(const float4*)(g + k), scv = *(const float4*)(mr + sc_off + k), shv = *(const float4*)(mr + sh_off + k);
;             const float o0 = v[i].x * rstd * gg.x * (1.0f + scv.x) + shv.x, o1 = v[i].y * rstd * gg.y * (1.0f + scv.y) + shv.y;
;             const float o2 = v[i].z * rstd * gg.z * (1.0f + scv.z) + shv.z, o3 = v[i].w * rstd * gg.w * (1.0f + scv.w) + shv.w;
;             uint2 w; w.x = pk2(o0, o1); w.y = pk2(o2, o3);
;             *(uint2*)(A + (size_t)row * 1024 + k) = w;
;         }
	v_pk_mul_f32 v[242:243], v[112:113], v[112:113]
	v_pk_mul_f32 v[244:245], v[116:117], v[116:117]
	v_pk_mul_f32 v[246:247], v[114:115], v[114:115]
	v_pk_mul_f32 v[248:249], v[118:119], v[118:119]
	v_add_f32_e32 v204, v245, v244
	v_add_f32_e32 v205, v243, v242
	v_add_f32_e32 v204, v248, v204
	v_add_f32_e32 v205, v246, v205
	v_add_f32_e32 v204, v249, v204
	v_add_f32_e32 v205, v247, v205
	v_pk_mul_f32 v[242:243], v[120:121], v[120:121]
	v_pk_mul_f32 v[244:245], v[124:125], v[124:125]
	v_pk_mul_f32 v[246:247], v[122:123], v[122:123]
	v_pk_mul_f32 v[248:249], v[126:127], v[126:127]
	v_add_f32_e32 v206, v243, v242
	v_add_f32_e32 v207, v245, v244
	v_add_f32_e32 v206, v246, v206
	v_add_f32_e32 v207, v248, v207
	v_add_f32_e32 v206, v247, v206
	v_add_f32_e32 v207, v249, v207
	v_add_f32_e32 v204, v205, v204
	v_add_f32_e32 v204, v204, v206
	v_add_f32_e32 v204, v204, v207
	ds_swizzle_b32 v205, v204 offset:swizzle(SWAP,1)
	s_waitcnt lgkmcnt(0)
	v_add_f32_e32 v204, v204, v205
	ds_swizzle_b32 v205, v204 offset:swizzle(SWAP,2)
	s_waitcnt lgkmcnt(0)
	v_add_f32_e32 v204, v204, v205
	ds_swizzle_b32 v205, v204 offset:swizzle(SWAP,4)
	s_waitcnt lgkmcnt(0)
	v_add_f32_e32 v204, v204, v205
	ds_swizzle_b32 v205, v204 offset:swizzle(SWAP,8)
	s_waitcnt lgkmcnt(0)
	v_add_f32_e32 v204, v204, v205
	ds_swizzle_b32 v205, v204 offset:swizzle(SWAP,16)
	s_waitcnt lgkmcnt(0)
	v_add_f32_e32 v204, v204, v205
	v_mov_b32_e32 v205, v204
	s_nop 1
	v_permlane32_swap_b32_e32 v204, v205
	v_add_f32_e32 v204, v204, v205
	v_mov_b32_e32 v205, 0x358637bd
	v_fmamk_f32 v204, v204, 0x3a800000, v205
	v_rsq_f32_e32 v204, v204
	s_nop 0
	v_pk_mul_f32 v[112:113], v[112:113], v[204:205] op_sel_hi:[1,0]
	v_pk_mul_f32 v[114:115], v[114:115], v[204:205] op_sel_hi:[1,0]
	v_pk_mul_f32 v[112:113], v[188:189], v[112:113]
	v_pk_mul_f32 v[114:115], v[190:191], v[114:115]
	v_pk_fma_f32 v[112:113], v[34:35], v[112:113], v[224:225]
	v_pk_fma_f32 v[114:115], v[36:37], v[114:115], v[226:227]
	v_cvt_pk_bf16_f32 v112, v112, v113
	v_cvt_pk_bf16_f32 v113, v114, v115
	global_store_dwordx2 v146, v[112:113], s[66:67]
	v_pk_mul_f32 v[116:117], v[116:117], v[204:205] op_sel_hi:[1,0]
	v_pk_mul_f32 v[118:119], v[118:119], v[204:205] op_sel_hi:[1,0]
	v_pk_mul_f32 v[116:117], v[192:193], v[116:117]
	v_pk_mul_f32 v[118:119], v[194:195], v[118:119]
	v_pk_fma_f32 v[116:117], v[38:39], v[116:117], v[228:229]
	v_pk_fma_f32 v[118:119], v[40:41], v[118:119], v[230:231]
	v_cvt_pk_bf16_f32 v116, v116, v117
	v_cvt_pk_bf16_f32 v117, v118, v119
	global_store_dwordx2 v146, v[116:117], s[66:67] offset:512
	v_pk_mul_f32 v[120:121], v[120:121], v[204:205] op_sel_hi:[1,0]
	v_pk_mul_f32 v[122:123], v[122:123], v[204:205] op_sel_hi:[1,0]
	v_pk_mul_f32 v[120:121], v[196:197], v[120:121]
	v_pk_mul_f32 v[122:123], v[198:199], v[122:123]
	v_pk_fma_f32 v[120:121], v[42:43], v[120:121], v[232:233]
	v_pk_fma_f32 v[122:123], v[44:45], v[122:123], v[234:235]
	v_cvt_pk_bf16_f32 v120, v120, v121
	v_cvt_pk_bf16_f32 v121, v122, v123
	global_store_dwordx2 v146, v[120:121], s[66:67] offset:1024
	v_pk_mul_f32 v[124:125], v[124:125], v[204:205] op_sel_hi:[1,0]
	v_pk_mul_f32 v[126:127], v[126:127], v[204:205] op_sel_hi:[1,0]
	v_pk_mul_f32 v[124:125], v[200:201], v[124:125]
	v_pk_mul_f32 v[126:127], v[202:203], v[126:127]
	v_pk_fma_f32 v[124:125], v[46:47], v[124:125], v[236:237]
	v_pk_fma_f32 v[126:127], v[48:49], v[126:127], v[238:239]
	v_cvt_pk_bf16_f32 v124, v124, v125
	v_cvt_pk_bf16_f32 v125, v126, v127
	global_store_dwordx2 v146, v[124:125], s[66:67] offset:1536
	v_add_u32_e32 v146, 0x800, v146
	v_add_u32_e32 v207, 0x1000, v152
	global_load_dwordx4 v[112:115], v207, s[70:71]
	global_load_dwordx4 v[116:119], v207, s[70:71] offset:1024
	global_load_dwordx4 v[120:123], v207, s[70:71] offset:2048
	global_load_dwordx4 v[124:127], v207, s[70:71] offset:3072
	s_waitcnt vmcnt(44)
	v_pk_mul_f32 v[242:243], v[128:129], v[128:129]
	v_pk_mul_f32 v[244:245], v[132:133], v[132:133]
	v_pk_mul_f32 v[246:247], v[130:131], v[130:131]
	v_pk_mul_f32 v[248:249], v[134:135], v[134:135]
	v_add_f32_e32 v204, v245, v244
	v_add_f32_e32 v205, v243, v242
	v_add_f32_e32 v204, v248, v204
	v_add_f32_e32 v205, v246, v205
	v_add_f32_e32 v204, v249, v204
	v_add_f32_e32 v205, v247, v205
	v_pk_mul_f32 v[242:243], v[136:137], v[136:137]
	v_pk_mul_f32 v[244:245], v[140:141], v[140:141]
	v_pk_mul_f32 v[246:247], v[138:139], v[138:139]
	v_pk_mul_f32 v[248:249], v[142:143], v[142:143]
	v_add_f32_e32 v206, v243, v242
	v_add_f32_e32 v207, v245, v244
	v_add_f32_e32 v206, v246, v206
	v_add_f32_e32 v207, v248, v207
	v_add_f32_e32 v206, v247, v206
	v_add_f32_e32 v207, v249, v207
	v_add_f32_e32 v204, v205, v204
	v_add_f32_e32 v204, v204, v206
	v_add_f32_e32 v204, v204, v207
	ds_swizzle_b32 v205, v204 offset:swizzle(SWAP,1)
	s_waitcnt lgkmcnt(0)
	v_add_f32_e32 v204, v204, v205
	ds_swizzle_b32 v205, v204 offset:swizzle(SWAP,2)
	s_waitcnt lgkmcnt(0)
	v_add_f32_e32 v204, v204, v205
	ds_swizzle_b32 v205, v204 offset:swizzle(SWAP,4)
	s_waitcnt lgkmcnt(0)
	v_add_f32_e32 v204, v204, v205
	ds_swizzle_b32 v205, v204 offset:swizzle(SWAP,8)
	s_waitcnt lgkmcnt(0)
	v_add_f32_e32 v204, v204, v205
	ds_swizzle_b32 v205, v204 offset:swizzle(SWAP,16)
	s_waitcnt lgkmcnt(0)
; __device__ __forceinline__ unsigned pk2(float lo, float hi) { const g_f32x2 f = {lo, hi}; return __builtin_bit_cast(unsigned, __builtin_convertvector(f, g_bf16x2)); }
; __device__ __forceinline__ void p_norm(const float* hlat, const float* hctx, const float* g, const float* modl, int sh_off, int sc_off, bf16_t* A, int M,
;                                        const float* part, const float* cgate, float* hcout) {
;     ...
;             if (part != nullptr && row >= NLAT) {
;                 const size_t po = (size_t)(row - NLAT) * 1024 + i * 256 + lane * 4;
;                 const float4 p0 = *(const float4*)(part + po), p1 = *(const float4*)(part + (size_t)4096 * 1024 + po), cg = *(const float4*)(cgate + i * 256 + lane * 4);
;                 v[i].x += cg.x * (p0.x + p1.x); v[i].y += cg.y * (p0.y + p1.y); v[i].z += cg.z * (p0.z + p1.z); v[i].w += cg.w * (p0.w + p1.w);
;                 *(float4*)(hcout + po) = v[i];
;             }
;             ss += v[i].x * v[i].x + v[i].y * v[i].y + v[i].z * v[i].z + v[i].w * v[i].w; }
;         ss = wave_sum(ss);
;         const float rstd = rsqrtf(ss * (1.0f / 1024.0f) + EPS);
;         const float* mr = modl + (size_t)r * 6144;
; #pragma unroll
;         for (int i = 0; i < 4; ++i) {
;             const int k = i * 256 + lane * 4;
;             const float4 gg = *(const float4*)(g + k), scv = *(const float4*)(mr + sc_off + k), shv = *(const float4*)(mr + sh_off + k);
;             const float o0 = v[i].x * rstd * gg.x * (1.0f + scv.x) + shv.x, o1 = v[i].y * rstd * gg.y * (1.0f + scv.y) + shv.y;
;             const float o2 = v[i].z * rstd * gg.z * (1.0f + scv.z) + shv.z, o3 = v[i].w * rstd * gg.w * (1.0f + scv.w) + shv.w;
;             uint2 w; w.x = pk2(o0, o1); w.y = pk2(o2, o3);
;             *(uint2*)(A + (size_t)row * 1024 + k) = w;
;         }
	v_add_f32_e32 v204, v204, v205
	v_mov_b32_e32 v205, v204
	s_nop 1
	v_permlane32_swap_b32_e32 v204, v205
	v_add_f32_e32 v204, v204, v205
	v_mov_b32_e32 v205, 0x358637bd
	v_fmamk_f32 v204, v204, 0x3a800000, v205
	v_rsq_f32_e32 v204, v204
	s_nop 0
	v_pk_mul_f32 v[128:129], v[128:129], v[204:205] op_sel_hi:[1,0]
	v_pk_mul_f32 v[130:131], v[130:131], v[204:205] op_sel_hi:[1,0]
	v_pk_mul_f32 v[128:129], v[188:189], v[128:129]
	v_pk_mul_f32 v[130:131], v[190:191], v[130:131]
	v_pk_fma_f32 v[128:129], v[34:35], v[128:129], v[224:225]
	v_pk_fma_f32 v[130:131], v[36:37], v[130:131], v[226:227]
	v_cvt_pk_bf16_f32 v128, v128, v129
	v_cvt_pk_bf16_f32 v129, v130, v131
	global_store_dwordx2 v146, v[128:129], s[66:67]
	v_pk_mul_f32 v[132:133], v[132:133], v[204:205] op_sel_hi:[1,0]
	v_pk_mul_f32 v[134:135], v[134:135], v[204:205] op_sel_hi:[1,0]
	v_pk_mul_f32 v[132:133], v[192:193], v[132:133]
	v_pk_mul_f32 v[134:135], v[194:195], v[134:135]
	v_pk_fma_f32 v[132:133], v[38:39], v[132:133], v[228:229]
	v_pk_fma_f32 v[134:135], v[40:41], v[134:135], v[230:231]
	v_cvt_pk_bf16_f32 v132, v132, v133
	v_cvt_pk_bf16_f32 v133, v134, v135
	global_store_dwordx2 v146, v[132:133], s[66:67] offset:512
	v_pk_mul_f32 v[136:137], v[136:137], v[204:205] op_sel_hi:[1,0]
	v_pk_mul_f32 v[138:139], v[138:139], v[204:205] op_sel_hi:[1,0]
	v_pk_mul_f32 v[136:137], v[196:197], v[136:137]
	v_pk_mul_f32 v[138:139], v[198:199], v[138:139]
	v_pk_fma_f32 v[136:137], v[42:43], v[136:137], v[232:233]
	v_pk_fma_f32 v[138:139], v[44:45], v[138:139], v[234:235]
	v_cvt_pk_bf16_f32 v136, v136, v137
	v_cvt_pk_bf16_f32 v137, v138, v139
	global_store_dwordx2 v146, v[136:137], s[66:67] offset:1024
	v_pk_mul_f32 v[140:141], v[140:141], v[204:205] op_sel_hi:[1,0]
	v_pk_mul_f32 v[142:143], v[142:143], v[204:205] op_sel_hi:[1,0]
	v_pk_mul_f32 v[140:141], v[200:201], v[140:141]
	v_pk_mul_f32 v[142:143], v[202:203], v[142:143]
	v_pk_fma_f32 v[140:141], v[46:47], v[140:141], v[236:237]
	v_pk_fma_f32 v[142:143], v[48:49], v[142:143], v[238:239]
	v_cvt_pk_bf16_f32 v140, v140, v141
	v_cvt_pk_bf16_f32 v141, v142, v143
	global_store_dwordx2 v146, v[140:141], s[66:67] offset:1536
	v_add_u32_e32 v146, 0x800, v146
	v_add_u32_e32 v151, 0x60000, v241
	global_load_dwordx4 v[34:37], v151, s[98:99]
	global_load_dwordx4 v[38:41], v151, s[98:99] offset:1024
	global_load_dwordx4 v[42:45], v151, s[98:99] offset:2048
	global_load_dwordx4 v[46:49], v151, s[98:99] offset:3072
	global_load_dwordx4 v[224:227], v151, s[50:51]
	global_load_dwordx4 v[228:231], v151, s[50:51] offset:1024
	global_load_dwordx4 v[232:235], v151, s[50:51] offset:2048
	global_load_dwordx4 v[236:239], v151, s[50:51] offset:3072
	v_add_u32_e32 v207, 0x1000, v150
	global_load_dwordx4 v[128:131], v207, s[70:71]
	global_load_dwordx4 v[132:135], v207, s[70:71] offset:1024
	global_load_dwordx4 v[136:139], v207, s[70:71] offset:2048
	global_load_dwordx4 v[140:143], v207, s[70:71] offset:3072
	s_waitcnt vmcnt(24)
	v_pk_add_f32 v[80:81], v[80:81], v[96:97]
	v_pk_add_f32 v[82:83], v[82:83], v[98:99]
	v_pk_fma_f32 v[156:157], v[80:81], v[8:9], v[156:157]
	v_pk_fma_f32 v[158:159], v[82:83], v[10:11], v[158:159]
	global_store_dwordx4 v152, v[156:159], s[64:65]
	v_pk_add_f32 v[84:85], v[84:85], v[100:101]
	v_pk_add_f32 v[86:87], v[86:87], v[102:103]
	v_pk_fma_f32 v[160:161], v[84:85], v[52:53], v[160:161]
	v_pk_fma_f32 v[162:163], v[86:87], v[54:55], v[162:163]
	global_store_dwordx4 v152, v[160:163], s[64:65] offset:1024
	v_pk_add_f32 v[88:89], v[88:89], v[104:105]
	v_pk_add_f32 v[90:91], v[90:91], v[106:107]
	v_pk_fma_f32 v[164:165], v[88:89], v[60:61], v[164:165]
	v_pk_fma_f32 v[166:167], v[90:91], v[62:63], v[166:167]
	global_store_dwordx4 v152, v[164:167], s[64:65] offset:2048
	v_pk_add_f32 v[92:93], v[92:93], v[108:109]
	v_pk_add_f32 v[94:95], v[94:95], v[110:111]
	v_pk_fma_f32 v[168:169], v[92:93], v[64:65], v[168:169]
	v_pk_fma_f32 v[170:171], v[94:95], v[66:67], v[170:171]
	global_store_dwordx4 v152, v[168:171], s[64:65] offset:3072
	v_add_u32_e32 v152, 0x1000, v152
	v_pk_mul_f32 v[242:243], v[156:157], v[156:157]
	v_pk_mul_f32 v[244:245], v[160:161], v[160:161]
	v_pk_mul_f32 v[246:247], v[158:159], v[158:159]
	v_pk_mul_f32 v[248:249], v[162:163], v[162:163]
	v_add_f32_e32 v204, v245, v244
	v_add_f32_e32 v205, v243, v242
	v_add_f32_e32 v204, v248, v204
	v_add_f32_e32 v205, v246, v205
	v_add_f32_e32 v204, v249, v204
	v_add_f32_e32 v205, v247, v205
	v_pk_mul_f32 v[242:243], v[164:165], v[164:165]
	v_pk_mul_f32 v[244:245], v[168:169], v[168:169]
	v_pk_mul_f32 v[246:247], v[166:167], v[166:167]
	v_pk_mul_f32 v[248:249], v[170:171], v[170:171]
	v_add_f32_e32 v206, v243, v242
	v_add_f32_e32 v207, v245, v244
	v_add_f32_e32 v206, v246, v206
	v_add_f32_e32 v207, v248, v207
	v_add_f32_e32 v206, v247, v206
	v_add_f32_e32 v207, v249, v207
	v_add_f32_e32 v204, v205, v204
	v_add_f32_e32 v204, v204, v206
	v_add_f32_e32 v204, v204, v207
	ds_swizzle_b32 v205, v204 offset:swizzle(SWAP,1)
	s_waitcnt lgkmcnt(0)
	v_add_f32_e32 v204, v204, v205
	ds_swizzle_b32 v205, v204 offset:swizzle(SWAP,2)
	s_waitcnt lgkmcnt(0)
	v_add_f32_e32 v204, v204, v205
	ds_swizzle_b32 v205, v204 offset:swizzle(SWAP,4)
	s_waitcnt lgkmcnt(0)
	v_add_f32_e32 v204, v204, v205
	ds_swizzle_b32 v205, v204 offset:swizzle(SWAP,8)
	s_waitcnt lgkmcnt(0)
	v_add_f32_e32 v204, v204, v205
	ds_swizzle_b32 v205, v204 offset:swizzle(SWAP,16)
	s_waitcnt lgkmcnt(0)
	v_add_f32_e32 v204, v204, v205
	v_mov_b32_e32 v205, v204
	s_nop 1
	v_permlane32_swap_b32_e32 v204, v205
	v_add_f32_e32 v204, v204, v205
	v_mov_b32_e32 v205, 0x358637bd
	v_fmamk_f32 v204, v204, 0x3a800000, v205
	v_rsq_f32_e32 v204, v204
	s_nop 0
	s_waitcnt vmcnt(8)
; __device__ __forceinline__ unsigned pk2(float lo, float hi) { const g_f32x2 f = {lo, hi}; return __builtin_bit_cast(unsigned, __builtin_convertvector(f, g_bf16x2)); }
; __device__ __forceinline__ void p_norm(const float* hlat, const float* hctx, const float* g, const float* modl, int sh_off, int sc_off, bf16_t* A, int M,
;                                        const float* part, const float* cgate, float* hcout) {
;     ...
;             if (part != nullptr && row >= NLAT) {
;                 const size_t po = (size_t)(row - NLAT) * 1024 + i * 256 + lane * 4;
;                 const float4 p0 = *(const float4*)(part + po), p1 = *(const float4*)(part + (size_t)4096 * 1024 + po), cg = *(const float4*)(cgate + i * 256 + lane * 4);
;                 v[i].x += cg.x * (p0.x + p1.x); v[i].y += cg.y * (p0.y + p1.y); v[i].z += cg.z * (p0.z + p1.z); v[i].w += cg.w * (p0.w + p1.w);
;                 *(float4*)(hcout + po) = v[i];
;             }
;             ss += v[i].x * v[i].x + v[i].y * v[i].y + v[i].z * v[i].z + v[i].w * v[i].w; }
;     ...
;         for (int i = 0; i < 4; ++i) {
;             const int k = i * 256 + lane * 4;
;             const float4 gg = *(const float4*)(g + k), scv = *(const float4*)(mr + sc_off + k), shv = *(const float4*)(mr + sh_off + k);
;             const float o0 = v[i].x * rstd * gg.x * (1.0f + scv.x) + shv.x, o1 = v[i].y * rstd * gg.y * (1.0f + scv.y) + shv.y;
;             const float o2 = v[i].z * rstd * gg.z * (1.0f + scv.z) + shv.z, o3 = v[i].w * rstd * gg.w * (1.0f + scv.w) + shv.w;
;             uint2 w; w.x = pk2(o0, o1); w.y = pk2(o2, o3);
;             *(uint2*)(A + (size_t)row * 1024 + k) = w;
;         }
	v_pk_add_f32 v[34:35], v[34:35], 1.0 op_sel_hi:[1,0]
	v_pk_add_f32 v[36:37], v[36:37], 1.0 op_sel_hi:[1,0]
	v_pk_add_f32 v[38:39], v[38:39], 1.0 op_sel_hi:[1,0]
	v_pk_add_f32 v[40:41], v[40:41], 1.0 op_sel_hi:[1,0]
	v_pk_add_f32 v[42:43], v[42:43], 1.0 op_sel_hi:[1,0]
	v_pk_add_f32 v[44:45], v[44:45], 1.0 op_sel_hi:[1,0]
	v_pk_add_f32 v[46:47], v[46:47], 1.0 op_sel_hi:[1,0]
	v_pk_add_f32 v[48:49], v[48:49], 1.0 op_sel_hi:[1,0]
	v_lshlrev_b32_e32 v146, 12, v50
	v_lshl_add_u32 v146, v240, 3, v146
	v_add_u32_e32 v146, 0x4000000, v146
	v_pk_mul_f32 v[156:157], v[156:157], v[204:205] op_sel_hi:[1,0]
	v_pk_mul_f32 v[158:159], v[158:159], v[204:205] op_sel_hi:[1,0]
	v_pk_mul_f32 v[156:157], v[188:189], v[156:157]
	v_pk_mul_f32 v[158:159], v[190:191], v[158:159]
	v_pk_fma_f32 v[156:157], v[34:35], v[156:157], v[224:225]
	v_pk_fma_f32 v[158:159], v[36:37], v[158:159], v[226:227]
	v_cvt_pk_bf16_f32 v156, v156, v157
	v_cvt_pk_bf16_f32 v157, v158, v159
	global_store_dwordx2 v146, v[156:157], s[66:67]
	v_pk_mul_f32 v[160:161], v[160:161], v[204:205] op_sel_hi:[1,0]
	v_pk_mul_f32 v[162:163], v[162:163], v[204:205] op_sel_hi:[1,0]
	v_pk_mul_f32 v[160:161], v[192:193], v[160:161]
	v_pk_mul_f32 v[162:163], v[194:195], v[162:163]
	v_pk_fma_f32 v[160:161], v[38:39], v[160:161], v[228:229]
	v_pk_fma_f32 v[162:163], v[40:41], v[162:163], v[230:231]
	v_cvt_pk_bf16_f32 v160, v160, v161
	v_cvt_pk_bf16_f32 v161, v162, v163
	global_store_dwordx2 v146, v[160:161], s[66:67] offset:512
	v_pk_mul_f32 v[164:165], v[164:165], v[204:205] op_sel_hi:[1,0]
	v_pk_mul_f32 v[166:167], v[166:167], v[204:205] op_sel_hi:[1,0]
	v_pk_mul_f32 v[164:165], v[196:197], v[164:165]
	v_pk_mul_f32 v[166:167], v[198:199], v[166:167]
	v_pk_fma_f32 v[164:165], v[42:43], v[164:165], v[232:233]
	v_pk_fma_f32 v[166:167], v[44:45], v[166:167], v[234:235]
	v_cvt_pk_bf16_f32 v164, v164, v165
	v_cvt_pk_bf16_f32 v165, v166, v167
	global_store_dwordx2 v146, v[164:165], s[66:67] offset:1024
	v_pk_mul_f32 v[168:169], v[168:169], v[204:205] op_sel_hi:[1,0]
	v_pk_mul_f32 v[170:171], v[170:171], v[204:205] op_sel_hi:[1,0]
	v_pk_mul_f32 v[168:169], v[200:201], v[168:169]
	v_pk_mul_f32 v[170:171], v[202:203], v[170:171]
	v_pk_fma_f32 v[168:169], v[46:47], v[168:169], v[236:237]
	v_pk_fma_f32 v[170:171], v[48:49], v[170:171], v[238:239]
	v_cvt_pk_bf16_f32 v168, v168, v169
	v_cvt_pk_bf16_f32 v169, v170, v171
	global_store_dwordx2 v146, v[168:169], s[66:67] offset:1536
	v_add_u32_e32 v146, 0x800, v146
	s_waitcnt vmcnt(8)
	v_pk_add_f32 v[112:113], v[112:113], v[128:129]
	v_pk_add_f32 v[114:115], v[114:115], v[130:131]
	v_pk_fma_f32 v[172:173], v[112:113], v[8:9], v[172:173]
	v_pk_fma_f32 v[174:175], v[114:115], v[10:11], v[174:175]
	global_store_dwordx4 v152, v[172:175], s[64:65]
	v_pk_add_f32 v[116:117], v[116:117], v[132:133]
	v_pk_add_f32 v[118:119], v[118:119], v[134:135]
	v_pk_fma_f32 v[176:177], v[116:117], v[52:53], v[176:177]
	v_pk_fma_f32 v[178:179], v[118:119], v[54:55], v[178:179]
	global_store_dwordx4 v152, v[176:179], s[64:65] offset:1024
	v_pk_add_f32 v[120:121], v[120:121], v[136:137]
	v_pk_add_f32 v[122:123], v[122:123], v[138:139]
	v_pk_fma_f32 v[180:181], v[120:121], v[60:61], v[180:181]
	v_pk_fma_f32 v[182:183], v[122:123], v[62:63], v[182:183]
	global_store_dwordx4 v152, v[180:183], s[64:65] offset:2048
	v_pk_add_f32 v[124:125], v[124:125], v[140:141]
	v_pk_add_f32 v[126:127], v[126:127], v[142:143]
	v_pk_fma_f32 v[184:185], v[124:125], v[64:65], v[184:185]
	v_pk_fma_f32 v[186:187], v[126:127], v[66:67], v[186:187]
	global_store_dwordx4 v152, v[184:187], s[64:65] offset:3072
	v_add_u32_e32 v152, 0x1000, v152
	v_pk_mul_f32 v[242:243], v[172:173], v[172:173]
	v_pk_mul_f32 v[244:245], v[176:177], v[176:177]
	v_pk_mul_f32 v[246:247], v[174:175], v[174:175]
	v_pk_mul_f32 v[248:249], v[178:179], v[178:179]
	v_add_f32_e32 v204, v245, v244
	v_add_f32_e32 v205, v243, v242
	v_add_f32_e32 v204, v248, v204
	v_add_f32_e32 v205, v246, v205
	v_add_f32_e32 v204, v249, v204
	v_add_f32_e32 v205, v247, v205
	v_pk_mul_f32 v[242:243], v[180:181], v[180:181]
	v_pk_mul_f32 v[244:245], v[184:185], v[184:185]
	v_pk_mul_f32 v[246:247], v[182:183], v[182:183]
	v_pk_mul_f32 v[248:249], v[186:187], v[186:187]
	v_add_f32_e32 v206, v243, v242
	v_add_f32_e32 v207, v245, v244
	v_add_f32_e32 v206, v246, v206
	v_add_f32_e32 v207, v248, v207
	v_add_f32_e32 v206, v247, v206
	v_add_f32_e32 v207, v249, v207
	v_add_f32_e32 v204, v205, v204
	v_add_f32_e32 v204, v204, v206
	v_add_f32_e32 v204, v204, v207
	ds_swizzle_b32 v205, v204 offset:swizzle(SWAP,1)
	s_waitcnt lgkmcnt(0)
	v_add_f32_e32 v204, v204, v205
	ds_swizzle_b32 v205, v204 offset:swizzle(SWAP,2)
	s_waitcnt lgkmcnt(0)
	v_add_f32_e32 v204, v204, v205
	ds_swizzle_b32 v205, v204 offset:swizzle(SWAP,4)
	s_waitcnt lgkmcnt(0)
	v_add_f32_e32 v204, v204, v205
	ds_swizzle_b32 v205, v204 offset:swizzle(SWAP,8)
	s_waitcnt lgkmcnt(0)
	v_add_f32_e32 v204, v204, v205
	ds_swizzle_b32 v205, v204 offset:swizzle(SWAP,16)
	s_waitcnt lgkmcnt(0)
; __device__ __forceinline__ unsigned pk2(float lo, float hi) { const g_f32x2 f = {lo, hi}; return __builtin_bit_cast(unsigned, __builtin_convertvector(f, g_bf16x2)); }
; #define PN_LOAD(dst, rw) do { const float* s_ = (rw) < NLAT ? hlat + (size_t)(rw) * 1024 : hctx + (size_t)((rw) - NLAT) * 1024; \
;         _Pragma("unroll") for (int i = 0; i < 4; ++i) dst[i] = *(const float4*)(s_ + i * 256 + lane * 4); } while (0)
; __device__ __forceinline__ void p_norm(const float* hlat, const float* hctx, const float* g, const float* modl, int sh_off, int sc_off, bf16_t* A, int M,
;                                        const float* part, const float* cgate, float* hcout) {
;     ...
;     if (row < M) PN_LOAD(v, row);
;     ...
;         for (int i = 0; i < 4; ++i) {
;             const int k = i * 256 + lane * 4;
;             const float4 gg = *(const float4*)(g + k), scv = *(const float4*)(mr + sc_off + k), shv = *(const float4*)(mr + sh_off + k);
;             const float o0 = v[i].x * rstd * gg.x * (1.0f + scv.x) + shv.x, o1 = v[i].y * rstd * gg.y * (1.0f + scv.y) + shv.y;
;             const float o2 = v[i].z * rstd * gg.z * (1.0f + scv.z) + shv.z, o3 = v[i].w * rstd * gg.w * (1.0f + scv.w) + shv.w;
;             uint2 w; w.x = pk2(o0, o1); w.y = pk2(o2, o3);
;             *(uint2*)(A + (size_t)row * 1024 + k) = w;
;         }
	v_add_f32_e32 v204, v204, v205
	v_mov_b32_e32 v205, v204
	s_nop 1
	v_permlane32_swap_b32_e32 v204, v205
	v_add_f32_e32 v204, v204, v205
	v_mov_b32_e32 v205, 0x358637bd
	v_fmamk_f32 v204, v204, 0x3a800000, v205
	v_rsq_f32_e32 v204, v204
	s_nop 0
	v_pk_mul_f32 v[172:173], v[172:173], v[204:205] op_sel_hi:[1,0]
	v_pk_mul_f32 v[174:175], v[174:175], v[204:205] op_sel_hi:[1,0]
	v_pk_mul_f32 v[172:173], v[188:189], v[172:173]
	v_pk_mul_f32 v[174:175], v[190:191], v[174:175]
	v_pk_fma_f32 v[172:173], v[34:35], v[172:173], v[224:225]
	v_pk_fma_f32 v[174:175], v[36:37], v[174:175], v[226:227]
	v_cvt_pk_bf16_f32 v172, v172, v173
	v_cvt_pk_bf16_f32 v173, v174, v175
	global_store_dwordx2 v146, v[172:173], s[66:67]
	v_pk_mul_f32 v[176:177], v[176:177], v[204:205] op_sel_hi:[1,0]
	v_pk_mul_f32 v[178:179], v[178:179], v[204:205] op_sel_hi:[1,0]
	v_pk_mul_f32 v[176:177], v[192:193], v[176:177]
	v_pk_mul_f32 v[178:179], v[194:195], v[178:179]
	v_pk_fma_f32 v[176:177], v[38:39], v[176:177], v[228:229]
	v_pk_fma_f32 v[178:179], v[40:41], v[178:179], v[230:231]
	v_cvt_pk_bf16_f32 v176, v176, v177
	v_cvt_pk_bf16_f32 v177, v178, v179
	global_store_dwordx2 v146, v[176:177], s[66:67] offset:512
	v_pk_mul_f32 v[180:181], v[180:181], v[204:205] op_sel_hi:[1,0]
	v_pk_mul_f32 v[182:183], v[182:183], v[204:205] op_sel_hi:[1,0]
	v_pk_mul_f32 v[180:181], v[196:197], v[180:181]
	v_pk_mul_f32 v[182:183], v[198:199], v[182:183]
	v_pk_fma_f32 v[180:181], v[42:43], v[180:181], v[232:233]
	v_pk_fma_f32 v[182:183], v[44:45], v[182:183], v[234:235]
	v_cvt_pk_bf16_f32 v180, v180, v181
	v_cvt_pk_bf16_f32 v181, v182, v183
	global_store_dwordx2 v146, v[180:181], s[66:67] offset:1024
	v_pk_mul_f32 v[184:185], v[184:185], v[204:205] op_sel_hi:[1,0]
	v_pk_mul_f32 v[186:187], v[186:187], v[204:205] op_sel_hi:[1,0]
	v_pk_mul_f32 v[184:185], v[200:201], v[184:185]
	v_pk_mul_f32 v[186:187], v[202:203], v[186:187]
	v_pk_fma_f32 v[184:185], v[46:47], v[184:185], v[236:237]
	v_pk_fma_f32 v[186:187], v[48:49], v[186:187], v[238:239]
	v_cvt_pk_bf16_f32 v184, v184, v185
	v_cvt_pk_bf16_f32 v185, v186, v187
	global_store_dwordx2 v146, v[184:185], s[66:67] offset:1536
	v_add_u32_e32 v146, 0x800, v146
	s_branch .Lnorm_P6_end
.Lnorm_P6_alt:
	global_load_dwordx4 v[80:83], v144, s[46:47]
	global_load_dwordx4 v[84:87], v144, s[46:47] offset:1024
	global_load_dwordx4 v[88:91], v144, s[46:47] offset:2048
	global_load_dwordx4 v[92:95], v144, s[46:47] offset:3072
	v_add_u32_e32 v144, 0x1000, v144
	global_load_dwordx4 v[34:37], v148, s[98:99]
	global_load_dwordx4 v[38:41], v148, s[98:99] offset:1024
	global_load_dwordx4 v[42:45], v148, s[98:99] offset:2048
	global_load_dwordx4 v[46:49], v148, s[98:99] offset:3072
	global_load_dwordx4 v[224:227], v148, s[50:51]
	global_load_dwordx4 v[228:231], v148, s[50:51] offset:1024
	global_load_dwordx4 v[232:235], v148, s[50:51] offset:2048
	global_load_dwordx4 v[236:239], v148, s[50:51] offset:3072
	global_load_dwordx4 v[188:191], v241, s[48:49]
	global_load_dwordx4 v[192:195], v241, s[48:49] offset:1024
	global_load_dwordx4 v[196:199], v241, s[48:49] offset:2048
	global_load_dwordx4 v[200:203], v241, s[48:49] offset:3072
	global_load_dwordx4 v[96:99], v144, s[46:47]
	global_load_dwordx4 v[100:103], v144, s[46:47] offset:1024
	global_load_dwordx4 v[104:107], v144, s[46:47] offset:2048
	global_load_dwordx4 v[108:111], v144, s[46:47] offset:3072
	v_add_u32_e32 v144, 0x1000, v144
	global_load_dwordx4 v[112:115], v144, s[46:47]
	global_load_dwordx4 v[116:119], v144, s[46:47] offset:1024
	global_load_dwordx4 v[120:123], v144, s[46:47] offset:2048
	global_load_dwordx4 v[124:127], v144, s[46:47] offset:3072
	v_add_u32_e32 v144, 0x1000, v144
	global_load_dwordx4 v[128:131], v144, s[46:47]
	global_load_dwordx4 v[132:135], v144, s[46:47] offset:1024
	global_load_dwordx4 v[136:139], v144, s[46:47] offset:2048
	global_load_dwordx4 v[140:143], v144, s[46:47] offset:3072
	v_add_u32_e32 v144, 0x1000, v144
	global_load_dwordx4 v[156:159], v144, s[46:47]
	global_load_dwordx4 v[160:163], v144, s[46:47] offset:1024
	global_load_dwordx4 v[164:167], v144, s[46:47] offset:2048
	global_load_dwordx4 v[168:171], v144, s[46:47] offset:3072
	v_add_u32_e32 v144, 0x1000, v144
	global_load_dwordx4 v[172:175], v144, s[46:47]
	global_load_dwordx4 v[176:179], v144, s[46:47] offset:1024
	global_load_dwordx4 v[180:183], v144, s[46:47] offset:2048
	global_load_dwordx4 v[184:187], v144, s[46:47] offset:3072
	v_add_u32_e32 v144, 0x1000, v144
	s_waitcnt vmcnt(32)
	v_pk_mul_f32 v[242:243], v[80:81], v[80:81]
	v_pk_mul_f32 v[244:245], v[84:85], v[84:85]
	v_pk_mul_f32 v[246:247], v[82:83], v[82:83]
	v_pk_mul_f32 v[248:249], v[86:87], v[86:87]
	v_add_f32_e32 v204, v245, v244
	v_add_f32_e32 v205, v243, v242
	v_add_f32_e32 v204, v248, v204
	v_add_f32_e32 v205, v246, v205
	v_add_f32_e32 v204, v249, v204
	v_add_f32_e32 v205, v247, v205
	v_pk_mul_f32 v[242:243], v[88:89], v[88:89]
	v_pk_mul_f32 v[244:245], v[92:93], v[92:93]
	v_pk_mul_f32 v[246:247], v[90:91], v[90:91]
	v_pk_mul_f32 v[248:249], v[94:95], v[94:95]
	v_add_f32_e32 v206, v243, v242
	v_add_f32_e32 v207, v245, v244
	v_add_f32_e32 v206, v246, v206
	v_add_f32_e32 v207, v248, v207
	v_add_f32_e32 v206, v247, v206
	v_add_f32_e32 v207, v249, v207
	v_add_f32_e32 v204, v205, v204
	v_add_f32_e32 v204, v204, v206
	v_add_f32_e32 v204, v204, v207
	ds_swizzle_b32 v205, v204 offset:swizzle(SWAP,1)
	s_waitcnt lgkmcnt(0)
	v_add_f32_e32 v204, v204, v205
	ds_swizzle_b32 v205, v204 offset:swizzle(SWAP,2)
	s_waitcnt lgkmcnt(0)
	v_add_f32_e32 v204, v204, v205
	ds_swizzle_b32 v205, v204 offset:swizzle(SWAP,4)
	s_waitcnt lgkmcnt(0)
; __device__ __forceinline__ unsigned pk2(float lo, float hi) { const g_f32x2 f = {lo, hi}; return __builtin_bit_cast(unsigned, __builtin_convertvector(f, g_bf16x2)); }
; __device__ __forceinline__ void p_norm(const float* hlat, const float* hctx, const float* g, const float* modl, int sh_off, int sc_off, bf16_t* A, int M,
;                                        const float* part, const float* cgate, float* hcout) {
;     ...
;             ss += v[i].x * v[i].x + v[i].y * v[i].y + v[i].z * v[i].z + v[i].w * v[i].w; }
;         ss = wave_sum(ss);
;         const float rstd = rsqrtf(ss * (1.0f / 1024.0f) + EPS);
;         const float* mr = modl + (size_t)r * 6144;
; #pragma unroll
;         for (int i = 0; i < 4; ++i) {
;             const int k = i * 256 + lane * 4;
;             const float4 gg = *(const float4*)(g + k), scv = *(const float4*)(mr + sc_off + k), shv = *(const float4*)(mr + sh_off + k);
;             const float o0 = v[i].x * rstd * gg.x * (1.0f + scv.x) + shv.x, o1 = v[i].y * rstd * gg.y * (1.0f + scv.y) + shv.y;
;             const float o2 = v[i].z * rstd * gg.z * (1.0f + scv.z) + shv.z, o3 = v[i].w * rstd * gg.w * (1.0f + scv.w) + shv.w;
;             uint2 w; w.x = pk2(o0, o1); w.y = pk2(o2, o3);
;             *(uint2*)(A + (size_t)row * 1024 + k) = w;
;         }
	v_add_f32_e32 v204, v204, v205
	ds_swizzle_b32 v205, v204 offset:swizzle(SWAP,8)
	s_waitcnt lgkmcnt(0)
	v_add_f32_e32 v204, v204, v205
	ds_swizzle_b32 v205, v204 offset:swizzle(SWAP,16)
	s_waitcnt lgkmcnt(0)
	v_add_f32_e32 v204, v204, v205
	v_mov_b32_e32 v205, v204
	s_nop 1
	v_permlane32_swap_b32_e32 v204, v205
	v_add_f32_e32 v204, v204, v205
	v_mov_b32_e32 v205, 0x358637bd
	v_fmamk_f32 v204, v204, 0x3a800000, v205
	v_rsq_f32_e32 v204, v204
	s_nop 0
	s_waitcnt vmcnt(20)
	v_pk_add_f32 v[34:35], v[34:35], 1.0 op_sel_hi:[1,0]
	v_pk_add_f32 v[36:37], v[36:37], 1.0 op_sel_hi:[1,0]
	v_pk_add_f32 v[38:39], v[38:39], 1.0 op_sel_hi:[1,0]
	v_pk_add_f32 v[40:41], v[40:41], 1.0 op_sel_hi:[1,0]
	v_pk_add_f32 v[42:43], v[42:43], 1.0 op_sel_hi:[1,0]
	v_pk_add_f32 v[44:45], v[44:45], 1.0 op_sel_hi:[1,0]
	v_pk_add_f32 v[46:47], v[46:47], 1.0 op_sel_hi:[1,0]
	v_pk_add_f32 v[48:49], v[48:49], 1.0 op_sel_hi:[1,0]
	v_pk_mul_f32 v[80:81], v[80:81], v[204:205] op_sel_hi:[1,0]
	v_pk_mul_f32 v[82:83], v[82:83], v[204:205] op_sel_hi:[1,0]
	v_pk_mul_f32 v[80:81], v[188:189], v[80:81]
	v_pk_mul_f32 v[82:83], v[190:191], v[82:83]
	v_pk_fma_f32 v[80:81], v[34:35], v[80:81], v[224:225]
	v_pk_fma_f32 v[82:83], v[36:37], v[82:83], v[226:227]
	v_cvt_pk_bf16_f32 v80, v80, v81
	v_cvt_pk_bf16_f32 v81, v82, v83
	global_store_dwordx2 v146, v[80:81], s[66:67]
	v_pk_mul_f32 v[84:85], v[84:85], v[204:205] op_sel_hi:[1,0]
	v_pk_mul_f32 v[86:87], v[86:87], v[204:205] op_sel_hi:[1,0]
	v_pk_mul_f32 v[84:85], v[192:193], v[84:85]
	v_pk_mul_f32 v[86:87], v[194:195], v[86:87]
	v_pk_fma_f32 v[84:85], v[38:39], v[84:85], v[228:229]
	v_pk_fma_f32 v[86:87], v[40:41], v[86:87], v[230:231]
	v_cvt_pk_bf16_f32 v84, v84, v85
	v_cvt_pk_bf16_f32 v85, v86, v87
	global_store_dwordx2 v146, v[84:85], s[66:67] offset:512
	v_pk_mul_f32 v[88:89], v[88:89], v[204:205] op_sel_hi:[1,0]
	v_pk_mul_f32 v[90:91], v[90:91], v[204:205] op_sel_hi:[1,0]
	v_pk_mul_f32 v[88:89], v[196:197], v[88:89]
	v_pk_mul_f32 v[90:91], v[198:199], v[90:91]
	v_pk_fma_f32 v[88:89], v[42:43], v[88:89], v[232:233]
	v_pk_fma_f32 v[90:91], v[44:45], v[90:91], v[234:235]
	v_cvt_pk_bf16_f32 v88, v88, v89
	v_cvt_pk_bf16_f32 v89, v90, v91
	global_store_dwordx2 v146, v[88:89], s[66:67] offset:1024
	v_pk_mul_f32 v[92:93], v[92:93], v[204:205] op_sel_hi:[1,0]
	v_pk_mul_f32 v[94:95], v[94:95], v[204:205] op_sel_hi:[1,0]
	v_pk_mul_f32 v[92:93], v[200:201], v[92:93]
	v_pk_mul_f32 v[94:95], v[202:203], v[94:95]
	v_pk_fma_f32 v[92:93], v[46:47], v[92:93], v[236:237]
	v_pk_fma_f32 v[94:95], v[48:49], v[94:95], v[238:239]
	v_cvt_pk_bf16_f32 v92, v92, v93
	v_cvt_pk_bf16_f32 v93, v94, v95
	global_store_dwordx2 v146, v[92:93], s[66:67] offset:1536
	v_add_u32_e32 v146, 0x800, v146
	global_load_dwordx4 v[80:83], v144, s[46:47]
	global_load_dwordx4 v[84:87], v144, s[46:47] offset:1024
	global_load_dwordx4 v[88:91], v144, s[46:47] offset:2048
	global_load_dwordx4 v[92:95], v144, s[46:47] offset:3072
	v_add_u32_e32 v144, 0x1000, v144
	s_waitcnt vmcnt(24)
	v_pk_mul_f32 v[242:243], v[96:97], v[96:97]
	v_pk_mul_f32 v[244:245], v[100:101], v[100:101]
	v_pk_mul_f32 v[246:247], v[98:99], v[98:99]
	v_pk_mul_f32 v[248:249], v[102:103], v[102:103]
	v_add_f32_e32 v204, v245, v244
	v_add_f32_e32 v205, v243, v242
	v_add_f32_e32 v204, v248, v204
	v_add_f32_e32 v205, v246, v205
	v_add_f32_e32 v204, v249, v204
	v_add_f32_e32 v205, v247, v205
	v_pk_mul_f32 v[242:243], v[104:105], v[104:105]
	v_pk_mul_f32 v[244:245], v[108:109], v[108:109]
	v_pk_mul_f32 v[246:247], v[106:107], v[106:107]
	v_pk_mul_f32 v[248:249], v[110:111], v[110:111]
	v_add_f32_e32 v206, v243, v242
	v_add_f32_e32 v207, v245, v244
	v_add_f32_e32 v206, v246, v206
	v_add_f32_e32 v207, v248, v207
	v_add_f32_e32 v206, v247, v206
	v_add_f32_e32 v207, v249, v207
	v_add_f32_e32 v204, v205, v204
	v_add_f32_e32 v204, v204, v206
	v_add_f32_e32 v204, v204, v207
	ds_swizzle_b32 v205, v204 offset:swizzle(SWAP,1)
	s_waitcnt lgkmcnt(0)
	v_add_f32_e32 v204, v204, v205
	ds_swizzle_b32 v205, v204 offset:swizzle(SWAP,2)
	s_waitcnt lgkmcnt(0)
	v_add_f32_e32 v204, v204, v205
	ds_swizzle_b32 v205, v204 offset:swizzle(SWAP,4)
	s_waitcnt lgkmcnt(0)
	v_add_f32_e32 v204, v204, v205
	ds_swizzle_b32 v205, v204 offset:swizzle(SWAP,8)
	s_waitcnt lgkmcnt(0)
	v_add_f32_e32 v204, v204, v205
	ds_swizzle_b32 v205, v204 offset:swizzle(SWAP,16)
	s_waitcnt lgkmcnt(0)
	v_add_f32_e32 v204, v204, v205
	v_mov_b32_e32 v205, v204
	s_nop 1
	v_permlane32_swap_b32_e32 v204, v205
	v_add_f32_e32 v204, v204, v205
	v_mov_b32_e32 v205, 0x358637bd
	v_fmamk_f32 v204, v204, 0x3a800000, v205
	v_rsq_f32_e32 v204, v204
	s_nop 0
	v_pk_mul_f32 v[96:97], v[96:97], v[204:205] op_sel_hi:[1,0]
	v_pk_mul_f32 v[98:99], v[98:99], v[204:205] op_sel_hi:[1,0]
	v_pk_mul_f32 v[96:97], v[188:189], v[96:97]
	v_pk_mul_f32 v[98:99], v[190:191], v[98:99]
	v_pk_fma_f32 v[96:97], v[34:35], v[96:97], v[224:225]
	v_pk_fma_f32 v[98:99], v[36:37], v[98:99], v[226:227]
	v_cvt_pk_bf16_f32 v96, v96, v97
	v_cvt_pk_bf16_f32 v97, v98, v99
	global_store_dwordx2 v146, v[96:97], s[66:67]
	v_pk_mul_f32 v[100:101], v[100:101], v[204:205] op_sel_hi:[1,0]
	v_pk_mul_f32 v[102:103], v[102:103], v[204:205] op_sel_hi:[1,0]
	v_pk_mul_f32 v[100:101], v[192:193], v[100:101]
	v_pk_mul_f32 v[102:103], v[194:195], v[102:103]
	v_pk_fma_f32 v[100:101], v[38:39], v[100:101], v[228:229]
	v_pk_fma_f32 v[102:103], v[40:41], v[102:103], v[230:231]
	v_cvt_pk_bf16_f32 v100, v100, v101
	v_cvt_pk_bf16_f32 v101, v102, v103
	global_store_dwordx2 v146, v[100:101], s[66:67] offset:512
	v_pk_mul_f32 v[104:105], v[104:105], v[204:205] op_sel_hi:[1,0]
	v_pk_mul_f32 v[106:107], v[106:107], v[204:205] op_sel_hi:[1,0]
	v_pk_mul_f32 v[104:105], v[196:197], v[104:105]
	v_pk_mul_f32 v[106:107], v[198:199], v[106:107]
	v_pk_fma_f32 v[104:105], v[42:43], v[104:105], v[232:233]
	v_pk_fma_f32 v[106:107], v[44:45], v[106:107], v[234:235]
	v_cvt_pk_bf16_f32 v104, v104, v105
	v_cvt_pk_bf16_f32 v105, v106, v107
	global_store_dwordx2 v146, v[104:105], s[66:67] offset:1024
	v_pk_mul_f32 v[108:109], v[108:109], v[204:205] op_sel_hi:[1,0]
	v_pk_mul_f32 v[110:111], v[110:111], v[204:205] op_sel_hi:[1,0]
	v_pk_mul_f32 v[108:109], v[200:201], v[108:109]
	v_pk_mul_f32 v[110:111], v[202:203], v[110:111]
	v_pk_fma_f32 v[108:109], v[46:47], v[108:109], v[236:237]
	v_pk_fma_f32 v[110:111], v[48:49], v[110:111], v[238:239]
	v_cvt_pk_bf16_f32 v108, v108, v109
	v_cvt_pk_bf16_f32 v109, v110, v111
	global_store_dwordx2 v146, v[108:109], s[66:67] offset:1536
	v_add_u32_e32 v146, 0x800, v146
	global_load_dwordx4 v[96:99], v144, s[46:47]
	global_load_dwordx4 v[100:103], v144, s[46:47] offset:1024
	global_load_dwordx4 v[104:107], v144, s[46:47] offset:2048
	global_load_dwordx4 v[108:111], v144, s[46:47] offset:3072
	v_add_u32_e32 v144, 0x1000, v144
	s_waitcnt vmcnt(28)
; __device__ __forceinline__ unsigned pk2(float lo, float hi) { const g_f32x2 f = {lo, hi}; return __builtin_bit_cast(unsigned, __builtin_convertvector(f, g_bf16x2)); }
; __device__ __forceinline__ void p_norm(const float* hlat, const float* hctx, const float* g, const float* modl, int sh_off, int sc_off, bf16_t* A, int M,
;                                        const float* part, const float* cgate, float* hcout) {
;     ...
;             ss += v[i].x * v[i].x + v[i].y * v[i].y + v[i].z * v[i].z + v[i].w * v[i].w; }
;         ss = wave_sum(ss);
;         const float rstd = rsqrtf(ss * (1.0f / 1024.0f) + EPS);
;         const float* mr = modl + (size_t)r * 6144;
; #pragma unroll
;         for (int i = 0; i < 4; ++i) {
;             const int k = i * 256 + lane * 4;
;             const float4 gg = *(const float4*)(g + k), scv = *(const float4*)(mr + sc_off + k), shv = *(const float4*)(mr + sh_off + k);
;             const float o0 = v[i].x * rstd * gg.x * (1.0f + scv.x) + shv.x, o1 = v[i].y * rstd * gg.y * (1.0f + scv.y) + shv.y;
;             const float o2 = v[i].z * rstd * gg.z * (1.0f + scv.z) + shv.z, o3 = v[i].w * rstd * gg.w * (1.0f + scv.w) + shv.w;
;             uint2 w; w.x = pk2(o0, o1); w.y = pk2(o2, o3);
;             *(uint2*)(A + (size_t)row * 1024 + k) = w;
;         }
	v_pk_mul_f32 v[242:243], v[112:113], v[112:113]
	v_pk_mul_f32 v[244:245], v[116:117], v[116:117]
	v_pk_mul_f32 v[246:247], v[114:115], v[114:115]
	v_pk_mul_f32 v[248:249], v[118:119], v[118:119]
	v_add_f32_e32 v204, v245, v244
	v_add_f32_e32 v205, v243, v242
	v_add_f32_e32 v204, v248, v204
	v_add_f32_e32 v205, v246, v205
	v_add_f32_e32 v204, v249, v204
	v_add_f32_e32 v205, v247, v205
	v_pk_mul_f32 v[242:243], v[120:121], v[120:121]
	v_pk_mul_f32 v[244:245], v[124:125], v[124:125]
	v_pk_mul_f32 v[246:247], v[122:123], v[122:123]
	v_pk_mul_f32 v[248:249], v[126:127], v[126:127]
	v_add_f32_e32 v206, v243, v242
	v_add_f32_e32 v207, v245, v244
	v_add_f32_e32 v206, v246, v206
	v_add_f32_e32 v207, v248, v207
	v_add_f32_e32 v206, v247, v206
	v_add_f32_e32 v207, v249, v207
	v_add_f32_e32 v204, v205, v204
	v_add_f32_e32 v204, v204, v206
	v_add_f32_e32 v204, v204, v207
	ds_swizzle_b32 v205, v204 offset:swizzle(SWAP,1)
	s_waitcnt lgkmcnt(0)
	v_add_f32_e32 v204, v204, v205
	ds_swizzle_b32 v205, v204 offset:swizzle(SWAP,2)
	s_waitcnt lgkmcnt(0)
	v_add_f32_e32 v204, v204, v205
	ds_swizzle_b32 v205, v204 offset:swizzle(SWAP,4)
	s_waitcnt lgkmcnt(0)
	v_add_f32_e32 v204, v204, v205
	ds_swizzle_b32 v205, v204 offset:swizzle(SWAP,8)
	s_waitcnt lgkmcnt(0)
	v_add_f32_e32 v204, v204, v205
	ds_swizzle_b32 v205, v204 offset:swizzle(SWAP,16)
	s_waitcnt lgkmcnt(0)
	v_add_f32_e32 v204, v204, v205
	v_mov_b32_e32 v205, v204
	s_nop 1
	v_permlane32_swap_b32_e32 v204, v205
	v_add_f32_e32 v204, v204, v205
	v_mov_b32_e32 v205, 0x358637bd
	v_fmamk_f32 v204, v204, 0x3a800000, v205
	v_rsq_f32_e32 v204, v204
	s_nop 0
	v_pk_mul_f32 v[112:113], v[112:113], v[204:205] op_sel_hi:[1,0]
	v_pk_mul_f32 v[114:115], v[114:115], v[204:205] op_sel_hi:[1,0]
	v_pk_mul_f32 v[112:113], v[188:189], v[112:113]
	v_pk_mul_f32 v[114:115], v[190:191], v[114:115]
	v_pk_fma_f32 v[112:113], v[34:35], v[112:113], v[224:225]
	v_pk_fma_f32 v[114:115], v[36:37], v[114:115], v[226:227]
	v_cvt_pk_bf16_f32 v112, v112, v113
	v_cvt_pk_bf16_f32 v113, v114, v115
	global_store_dwordx2 v146, v[112:113], s[66:67]
	v_pk_mul_f32 v[116:117], v[116:117], v[204:205] op_sel_hi:[1,0]
	v_pk_mul_f32 v[118:119], v[118:119], v[204:205] op_sel_hi:[1,0]
	v_pk_mul_f32 v[116:117], v[192:193], v[116:117]
	v_pk_mul_f32 v[118:119], v[194:195], v[118:119]
	v_pk_fma_f32 v[116:117], v[38:39], v[116:117], v[228:229]
	v_pk_fma_f32 v[118:119], v[40:41], v[118:119], v[230:231]
	v_cvt_pk_bf16_f32 v116, v116, v117
	v_cvt_pk_bf16_f32 v117, v118, v119
	global_store_dwordx2 v146, v[116:117], s[66:67] offset:512
	v_pk_mul_f32 v[120:121], v[120:121], v[204:205] op_sel_hi:[1,0]
	v_pk_mul_f32 v[122:123], v[122:123], v[204:205] op_sel_hi:[1,0]
	v_pk_mul_f32 v[120:121], v[196:197], v[120:121]
	v_pk_mul_f32 v[122:123], v[198:199], v[122:123]
	v_pk_fma_f32 v[120:121], v[42:43], v[120:121], v[232:233]
	v_pk_fma_f32 v[122:123], v[44:45], v[122:123], v[234:235]
	v_cvt_pk_bf16_f32 v120, v120, v121
	v_cvt_pk_bf16_f32 v121, v122, v123
	global_store_dwordx2 v146, v[120:121], s[66:67] offset:1024
	v_pk_mul_f32 v[124:125], v[124:125], v[204:205] op_sel_hi:[1,0]
	v_pk_mul_f32 v[126:127], v[126:127], v[204:205] op_sel_hi:[1,0]
	v_pk_mul_f32 v[124:125], v[200:201], v[124:125]
	v_pk_mul_f32 v[126:127], v[202:203], v[126:127]
	v_pk_fma_f32 v[124:125], v[46:47], v[124:125], v[236:237]
	v_pk_fma_f32 v[126:127], v[48:49], v[126:127], v[238:239]
	v_cvt_pk_bf16_f32 v124, v124, v125
	v_cvt_pk_bf16_f32 v125, v126, v127
	global_store_dwordx2 v146, v[124:125], s[66:67] offset:1536
	v_add_u32_e32 v146, 0x800, v146
	global_load_dwordx4 v[112:115], v144, s[46:47]
	global_load_dwordx4 v[116:119], v144, s[46:47] offset:1024
	global_load_dwordx4 v[120:123], v144, s[46:47] offset:2048
	global_load_dwordx4 v[124:127], v144, s[46:47] offset:3072
	v_add_u32_e32 v144, 0x1000, v144
	s_waitcnt vmcnt(32)
	v_pk_mul_f32 v[242:243], v[128:129], v[128:129]
	v_pk_mul_f32 v[244:245], v[132:133], v[132:133]
	v_pk_mul_f32 v[246:247], v[130:131], v[130:131]
	v_pk_mul_f32 v[248:249], v[134:135], v[134:135]
	v_add_f32_e32 v204, v245, v244
	v_add_f32_e32 v205, v243, v242
	v_add_f32_e32 v204, v248, v204
	v_add_f32_e32 v205, v246, v205
	v_add_f32_e32 v204, v249, v204
	v_add_f32_e32 v205, v247, v205
	v_pk_mul_f32 v[242:243], v[136:137], v[136:137]
	v_pk_mul_f32 v[244:245], v[140:141], v[140:141]
	v_pk_mul_f32 v[246:247], v[138:139], v[138:139]
	v_pk_mul_f32 v[248:249], v[142:143], v[142:143]
	v_add_f32_e32 v206, v243, v242
	v_add_f32_e32 v207, v245, v244
	v_add_f32_e32 v206, v246, v206
	v_add_f32_e32 v207, v248, v207
	v_add_f32_e32 v206, v247, v206
	v_add_f32_e32 v207, v249, v207
	v_add_f32_e32 v204, v205, v204
	v_add_f32_e32 v204, v204, v206
	v_add_f32_e32 v204, v204, v207
	ds_swizzle_b32 v205, v204 offset:swizzle(SWAP,1)
	s_waitcnt lgkmcnt(0)
	v_add_f32_e32 v204, v204, v205
	ds_swizzle_b32 v205, v204 offset:swizzle(SWAP,2)
	s_waitcnt lgkmcnt(0)
	v_add_f32_e32 v204, v204, v205
	ds_swizzle_b32 v205, v204 offset:swizzle(SWAP,4)
	s_waitcnt lgkmcnt(0)
	v_add_f32_e32 v204, v204, v205
	ds_swizzle_b32 v205, v204 offset:swizzle(SWAP,8)
	s_waitcnt lgkmcnt(0)
	v_add_f32_e32 v204, v204, v205
	ds_swizzle_b32 v205, v204 offset:swizzle(SWAP,16)
	s_waitcnt lgkmcnt(0)
; __device__ __forceinline__ unsigned pk2(float lo, float hi) { const g_f32x2 f = {lo, hi}; return __builtin_bit_cast(unsigned, __builtin_convertvector(f, g_bf16x2)); }
; __device__ __forceinline__ void p_norm(const float* hlat, const float* hctx, const float* g, const float* modl, int sh_off, int sc_off, bf16_t* A, int M,
;                                        const float* part, const float* cgate, float* hcout) {
;     ...
;             ss += v[i].x * v[i].x + v[i].y * v[i].y + v[i].z * v[i].z + v[i].w * v[i].w; }
;         ss = wave_sum(ss);
;         const float rstd = rsqrtf(ss * (1.0f / 1024.0f) + EPS);
;         const float* mr = modl + (size_t)r * 6144;
; #pragma unroll
;         for (int i = 0; i < 4; ++i) {
;             const int k = i * 256 + lane * 4;
;             const float4 gg = *(const float4*)(g + k), scv = *(const float4*)(mr + sc_off + k), shv = *(const float4*)(mr + sh_off + k);
;             const float o0 = v[i].x * rstd * gg.x * (1.0f + scv.x) + shv.x, o1 = v[i].y * rstd * gg.y * (1.0f + scv.y) + shv.y;
;             const float o2 = v[i].z * rstd * gg.z * (1.0f + scv.z) + shv.z, o3 = v[i].w * rstd * gg.w * (1.0f + scv.w) + shv.w;
;             uint2 w; w.x = pk2(o0, o1); w.y = pk2(o2, o3);
;             *(uint2*)(A + (size_t)row * 1024 + k) = w;
;         }
	v_add_f32_e32 v204, v204, v205
	v_mov_b32_e32 v205, v204
	s_nop 1
	v_permlane32_swap_b32_e32 v204, v205
	v_add_f32_e32 v204, v204, v205
	v_mov_b32_e32 v205, 0x358637bd
	v_fmamk_f32 v204, v204, 0x3a800000, v205
	v_rsq_f32_e32 v204, v204
	s_nop 0
	v_pk_mul_f32 v[128:129], v[128:129], v[204:205] op_sel_hi:[1,0]
	v_pk_mul_f32 v[130:131], v[130:131], v[204:205] op_sel_hi:[1,0]
	v_pk_mul_f32 v[128:129], v[188:189], v[128:129]
	v_pk_mul_f32 v[130:131], v[190:191], v[130:131]
	v_pk_fma_f32 v[128:129], v[34:35], v[128:129], v[224:225]
	v_pk_fma_f32 v[130:131], v[36:37], v[130:131], v[226:227]
	v_cvt_pk_bf16_f32 v128, v128, v129
	v_cvt_pk_bf16_f32 v129, v130, v131
	global_store_dwordx2 v146, v[128:129], s[66:67]
	v_pk_mul_f32 v[132:133], v[132:133], v[204:205] op_sel_hi:[1,0]
	v_pk_mul_f32 v[134:135], v[134:135], v[204:205] op_sel_hi:[1,0]
	v_pk_mul_f32 v[132:133], v[192:193], v[132:133]
	v_pk_mul_f32 v[134:135], v[194:195], v[134:135]
	v_pk_fma_f32 v[132:133], v[38:39], v[132:133], v[228:229]
	v_pk_fma_f32 v[134:135], v[40:41], v[134:135], v[230:231]
	v_cvt_pk_bf16_f32 v132, v132, v133
	v_cvt_pk_bf16_f32 v133, v134, v135
	global_store_dwordx2 v146, v[132:133], s[66:67] offset:512
	v_pk_mul_f32 v[136:137], v[136:137], v[204:205] op_sel_hi:[1,0]
	v_pk_mul_f32 v[138:139], v[138:139], v[204:205] op_sel_hi:[1,0]
	v_pk_mul_f32 v[136:137], v[196:197], v[136:137]
	v_pk_mul_f32 v[138:139], v[198:199], v[138:139]
	v_pk_fma_f32 v[136:137], v[42:43], v[136:137], v[232:233]
	v_pk_fma_f32 v[138:139], v[44:45], v[138:139], v[234:235]
	v_cvt_pk_bf16_f32 v136, v136, v137
	v_cvt_pk_bf16_f32 v137, v138, v139
	global_store_dwordx2 v146, v[136:137], s[66:67] offset:1024
	v_pk_mul_f32 v[140:141], v[140:141], v[204:205] op_sel_hi:[1,0]
	v_pk_mul_f32 v[142:143], v[142:143], v[204:205] op_sel_hi:[1,0]
	v_pk_mul_f32 v[140:141], v[200:201], v[140:141]
	v_pk_mul_f32 v[142:143], v[202:203], v[142:143]
	v_pk_fma_f32 v[140:141], v[46:47], v[140:141], v[236:237]
	v_pk_fma_f32 v[142:143], v[48:49], v[142:143], v[238:239]
	v_cvt_pk_bf16_f32 v140, v140, v141
	v_cvt_pk_bf16_f32 v141, v142, v143
	global_store_dwordx2 v146, v[140:141], s[66:67] offset:1536
	v_add_u32_e32 v146, 0x800, v146
	global_load_dwordx4 v[128:131], v144, s[46:47]
	global_load_dwordx4 v[132:135], v144, s[46:47] offset:1024
	global_load_dwordx4 v[136:139], v144, s[46:47] offset:2048
	global_load_dwordx4 v[140:143], v144, s[46:47] offset:3072
	v_add_u32_e32 v144, 0x1000, v144
	s_waitcnt vmcnt(36)
	v_pk_mul_f32 v[242:243], v[156:157], v[156:157]
	v_pk_mul_f32 v[244:245], v[160:161], v[160:161]
	v_pk_mul_f32 v[246:247], v[158:159], v[158:159]
	v_pk_mul_f32 v[248:249], v[162:163], v[162:163]
	v_add_f32_e32 v204, v245, v244
	v_add_f32_e32 v205, v243, v242
	v_add_f32_e32 v204, v248, v204
	v_add_f32_e32 v205, v246, v205
	v_add_f32_e32 v204, v249, v204
	v_add_f32_e32 v205, v247, v205
	v_pk_mul_f32 v[242:243], v[164:165], v[164:165]
	v_pk_mul_f32 v[244:245], v[168:169], v[168:169]
	v_pk_mul_f32 v[246:247], v[166:167], v[166:167]
	v_pk_mul_f32 v[248:249], v[170:171], v[170:171]
	v_add_f32_e32 v206, v243, v242
	v_add_f32_e32 v207, v245, v244
	v_add_f32_e32 v206, v246, v206
	v_add_f32_e32 v207, v248, v207
	v_add_f32_e32 v206, v247, v206
	v_add_f32_e32 v207, v249, v207
	v_add_f32_e32 v204, v205, v204
	v_add_f32_e32 v204, v204, v206
	v_add_f32_e32 v204, v204, v207
	ds_swizzle_b32 v205, v204 offset:swizzle(SWAP,1)
	s_waitcnt lgkmcnt(0)
	v_add_f32_e32 v204, v204, v205
	ds_swizzle_b32 v205, v204 offset:swizzle(SWAP,2)
	s_waitcnt lgkmcnt(0)
	v_add_f32_e32 v204, v204, v205
	ds_swizzle_b32 v205, v204 offset:swizzle(SWAP,4)
	s_waitcnt lgkmcnt(0)
	v_add_f32_e32 v204, v204, v205
	ds_swizzle_b32 v205, v204 offset:swizzle(SWAP,8)
	s_waitcnt lgkmcnt(0)
	v_add_f32_e32 v204, v204, v205
	ds_swizzle_b32 v205, v204 offset:swizzle(SWAP,16)
	s_waitcnt lgkmcnt(0)
	v_add_f32_e32 v204, v204, v205
	v_mov_b32_e32 v205, v204
	s_nop 1
	v_permlane32_swap_b32_e32 v204, v205
	v_add_f32_e32 v204, v204, v205
	v_mov_b32_e32 v205, 0x358637bd
	v_fmamk_f32 v204, v204, 0x3a800000, v205
	v_rsq_f32_e32 v204, v204
	s_nop 0
	v_pk_mul_f32 v[156:157], v[156:157], v[204:205] op_sel_hi:[1,0]
	v_pk_mul_f32 v[158:159], v[158:159], v[204:205] op_sel_hi:[1,0]
	v_pk_mul_f32 v[156:157], v[188:189], v[156:157]
	v_pk_mul_f32 v[158:159], v[190:191], v[158:159]
	v_pk_fma_f32 v[156:157], v[34:35], v[156:157], v[224:225]
	v_pk_fma_f32 v[158:159], v[36:37], v[158:159], v[226:227]
	v_cvt_pk_bf16_f32 v156, v156, v157
	v_cvt_pk_bf16_f32 v157, v158, v159
	global_store_dwordx2 v146, v[156:157], s[66:67]
	v_pk_mul_f32 v[160:161], v[160:161], v[204:205] op_sel_hi:[1,0]
	v_pk_mul_f32 v[162:163], v[162:163], v[204:205] op_sel_hi:[1,0]
	v_pk_mul_f32 v[160:161], v[192:193], v[160:161]
	v_pk_mul_f32 v[162:163], v[194:195], v[162:163]
	v_pk_fma_f32 v[160:161], v[38:39], v[160:161], v[228:229]
	v_pk_fma_f32 v[162:163], v[40:41], v[162:163], v[230:231]
	v_cvt_pk_bf16_f32 v160, v160, v161
	v_cvt_pk_bf16_f32 v161, v162, v163
	global_store_dwordx2 v146, v[160:161], s[66:67] offset:512
	v_pk_mul_f32 v[164:165], v[164:165], v[204:205] op_sel_hi:[1,0]
	v_pk_mul_f32 v[166:167], v[166:167], v[204:205] op_sel_hi:[1,0]
	v_pk_mul_f32 v[164:165], v[196:197], v[164:165]
	v_pk_mul_f32 v[166:167], v[198:199], v[166:167]
	v_pk_fma_f32 v[164:165], v[42:43], v[164:165], v[232:233]
	v_pk_fma_f32 v[166:167], v[44:45], v[166:167], v[234:235]
	v_cvt_pk_bf16_f32 v164, v164, v165
	v_cvt_pk_bf16_f32 v165, v166, v167
	global_store_dwordx2 v146, v[164:165], s[66:67] offset:1024
	v_pk_mul_f32 v[168:169], v[168:169], v[204:205] op_sel_hi:[1,0]
	v_pk_mul_f32 v[170:171], v[170:171], v[204:205] op_sel_hi:[1,0]
	v_pk_mul_f32 v[168:169], v[200:201], v[168:169]
	v_pk_mul_f32 v[170:171], v[202:203], v[170:171]
	v_pk_fma_f32 v[168:169], v[46:47], v[168:169], v[236:237]
	v_pk_fma_f32 v[170:171], v[48:49], v[170:171], v[238:239]
	v_cvt_pk_bf16_f32 v168, v168, v169
	v_cvt_pk_bf16_f32 v169, v170, v171
	global_store_dwordx2 v146, v[168:169], s[66:67] offset:1536
	v_add_u32_e32 v146, 0x800, v146
	global_load_dwordx4 v[156:159], v144, s[46:47]
	global_load_dwordx4 v[160:163], v144, s[46:47] offset:1024
	global_load_dwordx4 v[164:167], v144, s[46:47] offset:2048
	global_load_dwordx4 v[168:171], v144, s[46:47] offset:3072
	v_add_u32_e32 v144, 0x1000, v144
	s_waitcnt vmcnt(40)
; __device__ __forceinline__ unsigned pk2(float lo, float hi) { const g_f32x2 f = {lo, hi}; return __builtin_bit_cast(unsigned, __builtin_convertvector(f, g_bf16x2)); }
; __device__ __forceinline__ void p_norm(const float* hlat, const float* hctx, const float* g, const float* modl, int sh_off, int sc_off, bf16_t* A, int M,
;                                        const float* part, const float* cgate, float* hcout) {
;     ...
;             ss += v[i].x * v[i].x + v[i].y * v[i].y + v[i].z * v[i].z + v[i].w * v[i].w; }
;         ss = wave_sum(ss);
;         const float rstd = rsqrtf(ss * (1.0f / 1024.0f) + EPS);
;         const float* mr = modl + (size_t)r * 6144;
; #pragma unroll
;         for (int i = 0; i < 4; ++i) {
;             const int k = i * 256 + lane * 4;
;             const float4 gg = *(const float4*)(g + k), scv = *(const float4*)(mr + sc_off + k), shv = *(const float4*)(mr + sh_off + k);
;             const float o0 = v[i].x * rstd * gg.x * (1.0f + scv.x) + shv.x, o1 = v[i].y * rstd * gg.y * (1.0f + scv.y) + shv.y;
;             const float o2 = v[i].z * rstd * gg.z * (1.0f + scv.z) + shv.z, o3 = v[i].w * rstd * gg.w * (1.0f + scv.w) + shv.w;
;             uint2 w; w.x = pk2(o0, o1); w.y = pk2(o2, o3);
;             *(uint2*)(A + (size_t)row * 1024 + k) = w;
;         }
	v_pk_mul_f32 v[242:243], v[172:173], v[172:173]
	v_pk_mul_f32 v[244:245], v[176:177], v[176:177]
	v_pk_mul_f32 v[246:247], v[174:175], v[174:175]
	v_pk_mul_f32 v[248:249], v[178:179], v[178:179]
	v_add_f32_e32 v204, v245, v244
	v_add_f32_e32 v205, v243, v242
	v_add_f32_e32 v204, v248, v204
	v_add_f32_e32 v205, v246, v205
	v_add_f32_e32 v204, v249, v204
	v_add_f32_e32 v205, v247, v205
	v_pk_mul_f32 v[242:243], v[180:181], v[180:181]
	v_pk_mul_f32 v[244:245], v[184:185], v[184:185]
	v_pk_mul_f32 v[246:247], v[182:183], v[182:183]
	v_pk_mul_f32 v[248:249], v[186:187], v[186:187]
	v_add_f32_e32 v206, v243, v242
	v_add_f32_e32 v207, v245, v244
	v_add_f32_e32 v206, v246, v206
	v_add_f32_e32 v207, v248, v207
	v_add_f32_e32 v206, v247, v206
	v_add_f32_e32 v207, v249, v207
	v_add_f32_e32 v204, v205, v204
	v_add_f32_e32 v204, v204, v206
	v_add_f32_e32 v204, v204, v207
	ds_swizzle_b32 v205, v204 offset:swizzle(SWAP,1)
	s_waitcnt lgkmcnt(0)
	v_add_f32_e32 v204, v204, v205
	ds_swizzle_b32 v205, v204 offset:swizzle(SWAP,2)
	s_waitcnt lgkmcnt(0)
	v_add_f32_e32 v204, v204, v205
	ds_swizzle_b32 v205, v204 offset:swizzle(SWAP,4)
	s_waitcnt lgkmcnt(0)
	v_add_f32_e32 v204, v204, v205
	ds_swizzle_b32 v205, v204 offset:swizzle(SWAP,8)
	s_waitcnt lgkmcnt(0)
	v_add_f32_e32 v204, v204, v205
	ds_swizzle_b32 v205, v204 offset:swizzle(SWAP,16)
	s_waitcnt lgkmcnt(0)
	v_add_f32_e32 v204, v204, v205
	v_mov_b32_e32 v205, v204
	s_nop 1
	v_permlane32_swap_b32_e32 v204, v205
	v_add_f32_e32 v204, v204, v205
	v_mov_b32_e32 v205, 0x358637bd
	v_fmamk_f32 v204, v204, 0x3a800000, v205
	v_rsq_f32_e32 v204, v204
	s_nop 0
	v_pk_mul_f32 v[172:173], v[172:173], v[204:205] op_sel_hi:[1,0]
	v_pk_mul_f32 v[174:175], v[174:175], v[204:205] op_sel_hi:[1,0]
	v_pk_mul_f32 v[172:173], v[188:189], v[172:173]
	v_pk_mul_f32 v[174:175], v[190:191], v[174:175]
	v_pk_fma_f32 v[172:173], v[34:35], v[172:173], v[224:225]
	v_pk_fma_f32 v[174:175], v[36:37], v[174:175], v[226:227]
	v_cvt_pk_bf16_f32 v172, v172, v173
	v_cvt_pk_bf16_f32 v173, v174, v175
	global_store_dwordx2 v146, v[172:173], s[66:67]
	v_pk_mul_f32 v[176:177], v[176:177], v[204:205] op_sel_hi:[1,0]
	v_pk_mul_f32 v[178:179], v[178:179], v[204:205] op_sel_hi:[1,0]
	v_pk_mul_f32 v[176:177], v[192:193], v[176:177]
	v_pk_mul_f32 v[178:179], v[194:195], v[178:179]
	v_pk_fma_f32 v[176:177], v[38:39], v[176:177], v[228:229]
	v_pk_fma_f32 v[178:179], v[40:41], v[178:179], v[230:231]
	v_cvt_pk_bf16_f32 v176, v176, v177
	v_cvt_pk_bf16_f32 v177, v178, v179
	global_store_dwordx2 v146, v[176:177], s[66:67] offset:512
	v_pk_mul_f32 v[180:181], v[180:181], v[204:205] op_sel_hi:[1,0]
	v_pk_mul_f32 v[182:183], v[182:183], v[204:205] op_sel_hi:[1,0]
	v_pk_mul_f32 v[180:181], v[196:197], v[180:181]
	v_pk_mul_f32 v[182:183], v[198:199], v[182:183]
	v_pk_fma_f32 v[180:181], v[42:43], v[180:181], v[232:233]
	v_pk_fma_f32 v[182:183], v[44:45], v[182:183], v[234:235]
	v_cvt_pk_bf16_f32 v180, v180, v181
	v_cvt_pk_bf16_f32 v181, v182, v183
	global_store_dwordx2 v146, v[180:181], s[66:67] offset:1024
	v_pk_mul_f32 v[184:185], v[184:185], v[204:205] op_sel_hi:[1,0]
	v_pk_mul_f32 v[186:187], v[186:187], v[204:205] op_sel_hi:[1,0]
	v_pk_mul_f32 v[184:185], v[200:201], v[184:185]
	v_pk_mul_f32 v[186:187], v[202:203], v[186:187]
	v_pk_fma_f32 v[184:185], v[46:47], v[184:185], v[236:237]
	v_pk_fma_f32 v[186:187], v[48:49], v[186:187], v[238:239]
	v_cvt_pk_bf16_f32 v184, v184, v185
	v_cvt_pk_bf16_f32 v185, v186, v187
	global_store_dwordx2 v146, v[184:185], s[66:67] offset:1536
	v_add_u32_e32 v146, 0x800, v146
	global_load_dwordx4 v[172:175], v144, s[46:47]
	global_load_dwordx4 v[176:179], v144, s[46:47] offset:1024
	global_load_dwordx4 v[180:183], v144, s[46:47] offset:2048
	global_load_dwordx4 v[184:187], v144, s[46:47] offset:3072
	v_add_u32_e32 v144, 0x1000, v144
	s_waitcnt vmcnt(40)
	v_pk_mul_f32 v[242:243], v[80:81], v[80:81]
	v_pk_mul_f32 v[244:245], v[84:85], v[84:85]
	v_pk_mul_f32 v[246:247], v[82:83], v[82:83]
	v_pk_mul_f32 v[248:249], v[86:87], v[86:87]
	v_add_f32_e32 v204, v245, v244
	v_add_f32_e32 v205, v243, v242
	v_add_f32_e32 v204, v248, v204
	v_add_f32_e32 v205, v246, v205
	v_add_f32_e32 v204, v249, v204
	v_add_f32_e32 v205, v247, v205
	v_pk_mul_f32 v[242:243], v[88:89], v[88:89]
	v_pk_mul_f32 v[244:245], v[92:93], v[92:93]
	v_pk_mul_f32 v[246:247], v[90:91], v[90:91]
	v_pk_mul_f32 v[248:249], v[94:95], v[94:95]
	v_add_f32_e32 v206, v243, v242
	v_add_f32_e32 v207, v245, v244
	v_add_f32_e32 v206, v246, v206
	v_add_f32_e32 v207, v248, v207
	v_add_f32_e32 v206, v247, v206
	v_add_f32_e32 v207, v249, v207
	v_add_f32_e32 v204, v205, v204
	v_add_f32_e32 v204, v204, v206
	v_add_f32_e32 v204, v204, v207
	ds_swizzle_b32 v205, v204 offset:swizzle(SWAP,1)
	s_waitcnt lgkmcnt(0)
	v_add_f32_e32 v204, v204, v205
	ds_swizzle_b32 v205, v204 offset:swizzle(SWAP,2)
	s_waitcnt lgkmcnt(0)
	v_add_f32_e32 v204, v204, v205
	ds_swizzle_b32 v205, v204 offset:swizzle(SWAP,4)
	s_waitcnt lgkmcnt(0)
	v_add_f32_e32 v204, v204, v205
	ds_swizzle_b32 v205, v204 offset:swizzle(SWAP,8)
	s_waitcnt lgkmcnt(0)
	v_add_f32_e32 v204, v204, v205
	ds_swizzle_b32 v205, v204 offset:swizzle(SWAP,16)
	s_waitcnt lgkmcnt(0)
; __device__ __forceinline__ unsigned pk2(float lo, float hi) { const g_f32x2 f = {lo, hi}; return __builtin_bit_cast(unsigned, __builtin_convertvector(f, g_bf16x2)); }
; __device__ __forceinline__ void p_norm(const float* hlat, const float* hctx, const float* g, const float* modl, int sh_off, int sc_off, bf16_t* A, int M,
;                                        const float* part, const float* cgate, float* hcout) {
;     ...
;             ss += v[i].x * v[i].x + v[i].y * v[i].y + v[i].z * v[i].z + v[i].w * v[i].w; }
;         ss = wave_sum(ss);
;         const float rstd = rsqrtf(ss * (1.0f / 1024.0f) + EPS);
;         const float* mr = modl + (size_t)r * 6144;
; #pragma unroll
;         for (int i = 0; i < 4; ++i) {
;             const int k = i * 256 + lane * 4;
;             const float4 gg = *(const float4*)(g + k), scv = *(const float4*)(mr + sc_off + k), shv = *(const float4*)(mr + sh_off + k);
;             const float o0 = v[i].x * rstd * gg.x * (1.0f + scv.x) + shv.x, o1 = v[i].y * rstd * gg.y * (1.0f + scv.y) + shv.y;
;             const float o2 = v[i].z * rstd * gg.z * (1.0f + scv.z) + shv.z, o3 = v[i].w * rstd * gg.w * (1.0f + scv.w) + shv.w;
;             uint2 w; w.x = pk2(o0, o1); w.y = pk2(o2, o3);
;             *(uint2*)(A + (size_t)row * 1024 + k) = w;
;         }
	v_add_f32_e32 v204, v204, v205
	v_mov_b32_e32 v205, v204
	s_nop 1
	v_permlane32_swap_b32_e32 v204, v205
	v_add_f32_e32 v204, v204, v205
	v_mov_b32_e32 v205, 0x358637bd
	v_fmamk_f32 v204, v204, 0x3a800000, v205
	v_rsq_f32_e32 v204, v204
	s_nop 0
	v_pk_mul_f32 v[80:81], v[80:81], v[204:205] op_sel_hi:[1,0]
	v_pk_mul_f32 v[82:83], v[82:83], v[204:205] op_sel_hi:[1,0]
	v_pk_mul_f32 v[80:81], v[188:189], v[80:81]
	v_pk_mul_f32 v[82:83], v[190:191], v[82:83]
	v_pk_fma_f32 v[80:81], v[34:35], v[80:81], v[224:225]
	v_pk_fma_f32 v[82:83], v[36:37], v[82:83], v[226:227]
	v_cvt_pk_bf16_f32 v80, v80, v81
	v_cvt_pk_bf16_f32 v81, v82, v83
	global_store_dwordx2 v146, v[80:81], s[66:67]
	v_pk_mul_f32 v[84:85], v[84:85], v[204:205] op_sel_hi:[1,0]
	v_pk_mul_f32 v[86:87], v[86:87], v[204:205] op_sel_hi:[1,0]
	v_pk_mul_f32 v[84:85], v[192:193], v[84:85]
	v_pk_mul_f32 v[86:87], v[194:195], v[86:87]
	v_pk_fma_f32 v[84:85], v[38:39], v[84:85], v[228:229]
	v_pk_fma_f32 v[86:87], v[40:41], v[86:87], v[230:231]
	v_cvt_pk_bf16_f32 v84, v84, v85
	v_cvt_pk_bf16_f32 v85, v86, v87
	global_store_dwordx2 v146, v[84:85], s[66:67] offset:512
	v_pk_mul_f32 v[88:89], v[88:89], v[204:205] op_sel_hi:[1,0]
	v_pk_mul_f32 v[90:91], v[90:91], v[204:205] op_sel_hi:[1,0]
	v_pk_mul_f32 v[88:89], v[196:197], v[88:89]
	v_pk_mul_f32 v[90:91], v[198:199], v[90:91]
	v_pk_fma_f32 v[88:89], v[42:43], v[88:89], v[232:233]
	v_pk_fma_f32 v[90:91], v[44:45], v[90:91], v[234:235]
	v_cvt_pk_bf16_f32 v88, v88, v89
	v_cvt_pk_bf16_f32 v89, v90, v91
	global_store_dwordx2 v146, v[88:89], s[66:67] offset:1024
	v_pk_mul_f32 v[92:93], v[92:93], v[204:205] op_sel_hi:[1,0]
	v_pk_mul_f32 v[94:95], v[94:95], v[204:205] op_sel_hi:[1,0]
	v_pk_mul_f32 v[92:93], v[200:201], v[92:93]
	v_pk_mul_f32 v[94:95], v[202:203], v[94:95]
	v_pk_fma_f32 v[92:93], v[46:47], v[92:93], v[236:237]
	v_pk_fma_f32 v[94:95], v[48:49], v[94:95], v[238:239]
	v_cvt_pk_bf16_f32 v92, v92, v93
	v_cvt_pk_bf16_f32 v93, v94, v95
	global_store_dwordx2 v146, v[92:93], s[66:67] offset:1536
	v_add_u32_e32 v146, 0x800, v146
	global_load_dwordx4 v[80:83], v144, s[46:47]
	global_load_dwordx4 v[84:87], v144, s[46:47] offset:1024
	global_load_dwordx4 v[88:91], v144, s[46:47] offset:2048
	global_load_dwordx4 v[92:95], v144, s[46:47] offset:3072
	v_add_u32_e32 v144, 0x1000, v144
	s_waitcnt vmcnt(40)
	v_pk_mul_f32 v[242:243], v[96:97], v[96:97]
	v_pk_mul_f32 v[244:245], v[100:101], v[100:101]
	v_pk_mul_f32 v[246:247], v[98:99], v[98:99]
	v_pk_mul_f32 v[248:249], v[102:103], v[102:103]
	v_add_f32_e32 v204, v245, v244
	v_add_f32_e32 v205, v243, v242
	v_add_f32_e32 v204, v248, v204
	v_add_f32_e32 v205, v246, v205
	v_add_f32_e32 v204, v249, v204
	v_add_f32_e32 v205, v247, v205
	v_pk_mul_f32 v[242:243], v[104:105], v[104:105]
	v_pk_mul_f32 v[244:245], v[108:109], v[108:109]
	v_pk_mul_f32 v[246:247], v[106:107], v[106:107]
	v_pk_mul_f32 v[248:249], v[110:111], v[110:111]
	v_add_f32_e32 v206, v243, v242
	v_add_f32_e32 v207, v245, v244
	v_add_f32_e32 v206, v246, v206
	v_add_f32_e32 v207, v248, v207
	v_add_f32_e32 v206, v247, v206
	v_add_f32_e32 v207, v249, v207
	v_add_f32_e32 v204, v205, v204
	v_add_f32_e32 v204, v204, v206
	v_add_f32_e32 v204, v204, v207
	ds_swizzle_b32 v205, v204 offset:swizzle(SWAP,1)
	s_waitcnt lgkmcnt(0)
	v_add_f32_e32 v204, v204, v205
	ds_swizzle_b32 v205, v204 offset:swizzle(SWAP,2)
	s_waitcnt lgkmcnt(0)
	v_add_f32_e32 v204, v204, v205
	ds_swizzle_b32 v205, v204 offset:swizzle(SWAP,4)
	s_waitcnt lgkmcnt(0)
	v_add_f32_e32 v204, v204, v205
	ds_swizzle_b32 v205, v204 offset:swizzle(SWAP,8)
	s_waitcnt lgkmcnt(0)
	v_add_f32_e32 v204, v204, v205
	ds_swizzle_b32 v205, v204 offset:swizzle(SWAP,16)
	s_waitcnt lgkmcnt(0)
	v_add_f32_e32 v204, v204, v205
	v_mov_b32_e32 v205, v204
	s_nop 1
	v_permlane32_swap_b32_e32 v204, v205
	v_add_f32_e32 v204, v204, v205
	v_mov_b32_e32 v205, 0x358637bd
	v_fmamk_f32 v204, v204, 0x3a800000, v205
	v_rsq_f32_e32 v204, v204
	s_nop 0
	v_pk_mul_f32 v[96:97], v[96:97], v[204:205] op_sel_hi:[1,0]
	v_pk_mul_f32 v[98:99], v[98:99], v[204:205] op_sel_hi:[1,0]
	v_pk_mul_f32 v[96:97], v[188:189], v[96:97]
	v_pk_mul_f32 v[98:99], v[190:191], v[98:99]
	v_pk_fma_f32 v[96:97], v[34:35], v[96:97], v[224:225]
	v_pk_fma_f32 v[98:99], v[36:37], v[98:99], v[226:227]
	v_cvt_pk_bf16_f32 v96, v96, v97
	v_cvt_pk_bf16_f32 v97, v98, v99
	global_store_dwordx2 v146, v[96:97], s[66:67]
	v_pk_mul_f32 v[100:101], v[100:101], v[204:205] op_sel_hi:[1,0]
	v_pk_mul_f32 v[102:103], v[102:103], v[204:205] op_sel_hi:[1,0]
	v_pk_mul_f32 v[100:101], v[192:193], v[100:101]
	v_pk_mul_f32 v[102:103], v[194:195], v[102:103]
	v_pk_fma_f32 v[100:101], v[38:39], v[100:101], v[228:229]
	v_pk_fma_f32 v[102:103], v[40:41], v[102:103], v[230:231]
	v_cvt_pk_bf16_f32 v100, v100, v101
	v_cvt_pk_bf16_f32 v101, v102, v103
	global_store_dwordx2 v146, v[100:101], s[66:67] offset:512
	v_pk_mul_f32 v[104:105], v[104:105], v[204:205] op_sel_hi:[1,0]
	v_pk_mul_f32 v[106:107], v[106:107], v[204:205] op_sel_hi:[1,0]
	v_pk_mul_f32 v[104:105], v[196:197], v[104:105]
	v_pk_mul_f32 v[106:107], v[198:199], v[106:107]
	v_pk_fma_f32 v[104:105], v[42:43], v[104:105], v[232:233]
	v_pk_fma_f32 v[106:107], v[44:45], v[106:107], v[234:235]
	v_cvt_pk_bf16_f32 v104, v104, v105
	v_cvt_pk_bf16_f32 v105, v106, v107
	global_store_dwordx2 v146, v[104:105], s[66:67] offset:1024
	v_pk_mul_f32 v[108:109], v[108:109], v[204:205] op_sel_hi:[1,0]
	v_pk_mul_f32 v[110:111], v[110:111], v[204:205] op_sel_hi:[1,0]
	v_pk_mul_f32 v[108:109], v[200:201], v[108:109]
	v_pk_mul_f32 v[110:111], v[202:203], v[110:111]
	v_pk_fma_f32 v[108:109], v[46:47], v[108:109], v[236:237]
	v_pk_fma_f32 v[110:111], v[48:49], v[110:111], v[238:239]
	v_cvt_pk_bf16_f32 v108, v108, v109
	v_cvt_pk_bf16_f32 v109, v110, v111
	global_store_dwordx2 v146, v[108:109], s[66:67] offset:1536
	v_add_u32_e32 v146, 0x800, v146
	global_load_dwordx4 v[96:99], v144, s[46:47]
	global_load_dwordx4 v[100:103], v144, s[46:47] offset:1024
	global_load_dwordx4 v[104:107], v144, s[46:47] offset:2048
	global_load_dwordx4 v[108:111], v144, s[46:47] offset:3072
	v_add_u32_e32 v144, 0x1000, v144
	s_waitcnt vmcnt(40)
; __device__ __forceinline__ unsigned pk2(float lo, float hi) { const g_f32x2 f = {lo, hi}; return __builtin_bit_cast(unsigned, __builtin_convertvector(f, g_bf16x2)); }
; __device__ __forceinline__ void p_norm(const float* hlat, const float* hctx, const float* g, const float* modl, int sh_off, int sc_off, bf16_t* A, int M,
;                                        const float* part, const float* cgate, float* hcout) {
;     ...
;             ss += v[i].x * v[i].x + v[i].y * v[i].y + v[i].z * v[i].z + v[i].w * v[i].w; }
;         ss = wave_sum(ss);
;         const float rstd = rsqrtf(ss * (1.0f / 1024.0f) + EPS);
;         const float* mr = modl + (size_t)r * 6144;
; #pragma unroll
;         for (int i = 0; i < 4; ++i) {
;             const int k = i * 256 + lane * 4;
;             const float4 gg = *(const float4*)(g + k), scv = *(const float4*)(mr + sc_off + k), shv = *(const float4*)(mr + sh_off + k);
;             const float o0 = v[i].x * rstd * gg.x * (1.0f + scv.x) + shv.x, o1 = v[i].y * rstd * gg.y * (1.0f + scv.y) + shv.y;
;             const float o2 = v[i].z * rstd * gg.z * (1.0f + scv.z) + shv.z, o3 = v[i].w * rstd * gg.w * (1.0f + scv.w) + shv.w;
;             uint2 w; w.x = pk2(o0, o1); w.y = pk2(o2, o3);
;             *(uint2*)(A + (size_t)row * 1024 + k) = w;
;         }
	v_pk_mul_f32 v[242:243], v[112:113], v[112:113]
	v_pk_mul_f32 v[244:245], v[116:117], v[116:117]
	v_pk_mul_f32 v[246:247], v[114:115], v[114:115]
	v_pk_mul_f32 v[248:249], v[118:119], v[118:119]
	v_add_f32_e32 v204, v245, v244
	v_add_f32_e32 v205, v243, v242
	v_add_f32_e32 v204, v248, v204
	v_add_f32_e32 v205, v246, v205
	v_add_f32_e32 v204, v249, v204
	v_add_f32_e32 v205, v247, v205
	v_pk_mul_f32 v[242:243], v[120:121], v[120:121]
	v_pk_mul_f32 v[244:245], v[124:125], v[124:125]
	v_pk_mul_f32 v[246:247], v[122:123], v[122:123]
	v_pk_mul_f32 v[248:249], v[126:127], v[126:127]
	v_add_f32_e32 v206, v243, v242
	v_add_f32_e32 v207, v245, v244
	v_add_f32_e32 v206, v246, v206
	v_add_f32_e32 v207, v248, v207
	v_add_f32_e32 v206, v247, v206
	v_add_f32_e32 v207, v249, v207
	v_add_f32_e32 v204, v205, v204
	v_add_f32_e32 v204, v204, v206
	v_add_f32_e32 v204, v204, v207
	ds_swizzle_b32 v205, v204 offset:swizzle(SWAP,1)
	s_waitcnt lgkmcnt(0)
	v_add_f32_e32 v204, v204, v205
	ds_swizzle_b32 v205, v204 offset:swizzle(SWAP,2)
	s_waitcnt lgkmcnt(0)
	v_add_f32_e32 v204, v204, v205
	ds_swizzle_b32 v205, v204 offset:swizzle(SWAP,4)
	s_waitcnt lgkmcnt(0)
	v_add_f32_e32 v204, v204, v205
	ds_swizzle_b32 v205, v204 offset:swizzle(SWAP,8)
	s_waitcnt lgkmcnt(0)
	v_add_f32_e32 v204, v204, v205
	ds_swizzle_b32 v205, v204 offset:swizzle(SWAP,16)
	s_waitcnt lgkmcnt(0)
	v_add_f32_e32 v204, v204, v205
	v_mov_b32_e32 v205, v204
	s_nop 1
	v_permlane32_swap_b32_e32 v204, v205
	v_add_f32_e32 v204, v204, v205
	v_mov_b32_e32 v205, 0x358637bd
	v_fmamk_f32 v204, v204, 0x3a800000, v205
	v_rsq_f32_e32 v204, v204
	s_nop 0
	v_pk_mul_f32 v[112:113], v[112:113], v[204:205] op_sel_hi:[1,0]
	v_pk_mul_f32 v[114:115], v[114:115], v[204:205] op_sel_hi:[1,0]
	v_pk_mul_f32 v[112:113], v[188:189], v[112:113]
	v_pk_mul_f32 v[114:115], v[190:191], v[114:115]
	v_pk_fma_f32 v[112:113], v[34:35], v[112:113], v[224:225]
	v_pk_fma_f32 v[114:115], v[36:37], v[114:115], v[226:227]
	v_cvt_pk_bf16_f32 v112, v112, v113
	v_cvt_pk_bf16_f32 v113, v114, v115
	global_store_dwordx2 v146, v[112:113], s[66:67]
	v_pk_mul_f32 v[116:117], v[116:117], v[204:205] op_sel_hi:[1,0]
	v_pk_mul_f32 v[118:119], v[118:119], v[204:205] op_sel_hi:[1,0]
	v_pk_mul_f32 v[116:117], v[192:193], v[116:117]
	v_pk_mul_f32 v[118:119], v[194:195], v[118:119]
	v_pk_fma_f32 v[116:117], v[38:39], v[116:117], v[228:229]
	v_pk_fma_f32 v[118:119], v[40:41], v[118:119], v[230:231]
	v_cvt_pk_bf16_f32 v116, v116, v117
	v_cvt_pk_bf16_f32 v117, v118, v119
	global_store_dwordx2 v146, v[116:117], s[66:67] offset:512
	v_pk_mul_f32 v[120:121], v[120:121], v[204:205] op_sel_hi:[1,0]
	v_pk_mul_f32 v[122:123], v[122:123], v[204:205] op_sel_hi:[1,0]
	v_pk_mul_f32 v[120:121], v[196:197], v[120:121]
	v_pk_mul_f32 v[122:123], v[198:199], v[122:123]
	v_pk_fma_f32 v[120:121], v[42:43], v[120:121], v[232:233]
	v_pk_fma_f32 v[122:123], v[44:45], v[122:123], v[234:235]
	v_cvt_pk_bf16_f32 v120, v120, v121
	v_cvt_pk_bf16_f32 v121, v122, v123
	global_store_dwordx2 v146, v[120:121], s[66:67] offset:1024
	v_pk_mul_f32 v[124:125], v[124:125], v[204:205] op_sel_hi:[1,0]
	v_pk_mul_f32 v[126:127], v[126:127], v[204:205] op_sel_hi:[1,0]
	v_pk_mul_f32 v[124:125], v[200:201], v[124:125]
	v_pk_mul_f32 v[126:127], v[202:203], v[126:127]
	v_pk_fma_f32 v[124:125], v[46:47], v[124:125], v[236:237]
	v_pk_fma_f32 v[126:127], v[48:49], v[126:127], v[238:239]
	v_cvt_pk_bf16_f32 v124, v124, v125
	v_cvt_pk_bf16_f32 v125, v126, v127
	global_store_dwordx2 v146, v[124:125], s[66:67] offset:1536
	v_add_u32_e32 v146, 0x800, v146
	global_load_dwordx4 v[112:115], v144, s[46:47]
	global_load_dwordx4 v[116:119], v144, s[46:47] offset:1024
	global_load_dwordx4 v[120:123], v144, s[46:47] offset:2048
	global_load_dwordx4 v[124:127], v144, s[46:47] offset:3072
	v_add_u32_e32 v144, 0x1000, v144
	s_waitcnt vmcnt(40)
	v_pk_mul_f32 v[242:243], v[128:129], v[128:129]
	v_pk_mul_f32 v[244:245], v[132:133], v[132:133]
	v_pk_mul_f32 v[246:247], v[130:131], v[130:131]
	v_pk_mul_f32 v[248:249], v[134:135], v[134:135]
	v_add_f32_e32 v204, v245, v244
	v_add_f32_e32 v205, v243, v242
	v_add_f32_e32 v204, v248, v204
	v_add_f32_e32 v205, v246, v205
	v_add_f32_e32 v204, v249, v204
	v_add_f32_e32 v205, v247, v205
	v_pk_mul_f32 v[242:243], v[136:137], v[136:137]
	v_pk_mul_f32 v[244:245], v[140:141], v[140:141]
	v_pk_mul_f32 v[246:247], v[138:139], v[138:139]
	v_pk_mul_f32 v[248:249], v[142:143], v[142:143]
	v_add_f32_e32 v206, v243, v242
	v_add_f32_e32 v207, v245, v244
	v_add_f32_e32 v206, v246, v206
	v_add_f32_e32 v207, v248, v207
	v_add_f32_e32 v206, v247, v206
	v_add_f32_e32 v207, v249, v207
	v_add_f32_e32 v204, v205, v204
	v_add_f32_e32 v204, v204, v206
	v_add_f32_e32 v204, v204, v207
	ds_swizzle_b32 v205, v204 offset:swizzle(SWAP,1)
	s_waitcnt lgkmcnt(0)
	v_add_f32_e32 v204, v204, v205
	ds_swizzle_b32 v205, v204 offset:swizzle(SWAP,2)
	s_waitcnt lgkmcnt(0)
	v_add_f32_e32 v204, v204, v205
	ds_swizzle_b32 v205, v204 offset:swizzle(SWAP,4)
	s_waitcnt lgkmcnt(0)
	v_add_f32_e32 v204, v204, v205
	ds_swizzle_b32 v205, v204 offset:swizzle(SWAP,8)
	s_waitcnt lgkmcnt(0)
	v_add_f32_e32 v204, v204, v205
	ds_swizzle_b32 v205, v204 offset:swizzle(SWAP,16)
	s_waitcnt lgkmcnt(0)
; __device__ __forceinline__ unsigned pk2(float lo, float hi) { const g_f32x2 f = {lo, hi}; return __builtin_bit_cast(unsigned, __builtin_convertvector(f, g_bf16x2)); }
; __device__ __forceinline__ void p_norm(const float* hlat, const float* hctx, const float* g, const float* modl, int sh_off, int sc_off, bf16_t* A, int M,
;                                        const float* part, const float* cgate, float* hcout) {
;     ...
;             ss += v[i].x * v[i].x + v[i].y * v[i].y + v[i].z * v[i].z + v[i].w * v[i].w; }
;         ss = wave_sum(ss);
;         const float rstd = rsqrtf(ss * (1.0f / 1024.0f) + EPS);
;         const float* mr = modl + (size_t)r * 6144;
; #pragma unroll
;         for (int i = 0; i < 4; ++i) {
;             const int k = i * 256 + lane * 4;
;             const float4 gg = *(const float4*)(g + k), scv = *(const float4*)(mr + sc_off + k), shv = *(const float4*)(mr + sh_off + k);
;             const float o0 = v[i].x * rstd * gg.x * (1.0f + scv.x) + shv.x, o1 = v[i].y * rstd * gg.y * (1.0f + scv.y) + shv.y;
;             const float o2 = v[i].z * rstd * gg.z * (1.0f + scv.z) + shv.z, o3 = v[i].w * rstd * gg.w * (1.0f + scv.w) + shv.w;
;             uint2 w; w.x = pk2(o0, o1); w.y = pk2(o2, o3);
;             *(uint2*)(A + (size_t)row * 1024 + k) = w;
;         }
	v_add_f32_e32 v204, v204, v205
	v_mov_b32_e32 v205, v204
	s_nop 1
	v_permlane32_swap_b32_e32 v204, v205
	v_add_f32_e32 v204, v204, v205
	v_mov_b32_e32 v205, 0x358637bd
	v_fmamk_f32 v204, v204, 0x3a800000, v205
	v_rsq_f32_e32 v204, v204
	s_nop 0
	v_pk_mul_f32 v[128:129], v[128:129], v[204:205] op_sel_hi:[1,0]
	v_pk_mul_f32 v[130:131], v[130:131], v[204:205] op_sel_hi:[1,0]
	v_pk_mul_f32 v[128:129], v[188:189], v[128:129]
	v_pk_mul_f32 v[130:131], v[190:191], v[130:131]
	v_pk_fma_f32 v[128:129], v[34:35], v[128:129], v[224:225]
	v_pk_fma_f32 v[130:131], v[36:37], v[130:131], v[226:227]
	v_cvt_pk_bf16_f32 v128, v128, v129
	v_cvt_pk_bf16_f32 v129, v130, v131
	global_store_dwordx2 v146, v[128:129], s[66:67]
	v_pk_mul_f32 v[132:133], v[132:133], v[204:205] op_sel_hi:[1,0]
	v_pk_mul_f32 v[134:135], v[134:135], v[204:205] op_sel_hi:[1,0]
	v_pk_mul_f32 v[132:133], v[192:193], v[132:133]
	v_pk_mul_f32 v[134:135], v[194:195], v[134:135]
	v_pk_fma_f32 v[132:133], v[38:39], v[132:133], v[228:229]
	v_pk_fma_f32 v[134:135], v[40:41], v[134:135], v[230:231]
	v_cvt_pk_bf16_f32 v132, v132, v133
	v_cvt_pk_bf16_f32 v133, v134, v135
	global_store_dwordx2 v146, v[132:133], s[66:67] offset:512
	v_pk_mul_f32 v[136:137], v[136:137], v[204:205] op_sel_hi:[1,0]
	v_pk_mul_f32 v[138:139], v[138:139], v[204:205] op_sel_hi:[1,0]
	v_pk_mul_f32 v[136:137], v[196:197], v[136:137]
	v_pk_mul_f32 v[138:139], v[198:199], v[138:139]
	v_pk_fma_f32 v[136:137], v[42:43], v[136:137], v[232:233]
	v_pk_fma_f32 v[138:139], v[44:45], v[138:139], v[234:235]
	v_cvt_pk_bf16_f32 v136, v136, v137
	v_cvt_pk_bf16_f32 v137, v138, v139
	global_store_dwordx2 v146, v[136:137], s[66:67] offset:1024
	v_pk_mul_f32 v[140:141], v[140:141], v[204:205] op_sel_hi:[1,0]
	v_pk_mul_f32 v[142:143], v[142:143], v[204:205] op_sel_hi:[1,0]
	v_pk_mul_f32 v[140:141], v[200:201], v[140:141]
	v_pk_mul_f32 v[142:143], v[202:203], v[142:143]
	v_pk_fma_f32 v[140:141], v[46:47], v[140:141], v[236:237]
	v_pk_fma_f32 v[142:143], v[48:49], v[142:143], v[238:239]
	v_cvt_pk_bf16_f32 v140, v140, v141
	v_cvt_pk_bf16_f32 v141, v142, v143
	global_store_dwordx2 v146, v[140:141], s[66:67] offset:1536
	v_add_u32_e32 v146, 0x800, v146
	global_load_dwordx4 v[128:131], v144, s[46:47]
	global_load_dwordx4 v[132:135], v144, s[46:47] offset:1024
	global_load_dwordx4 v[136:139], v144, s[46:47] offset:2048
	global_load_dwordx4 v[140:143], v144, s[46:47] offset:3072
	v_add_u32_e32 v144, 0x1000, v144
	s_waitcnt vmcnt(40)
	v_pk_mul_f32 v[242:243], v[156:157], v[156:157]
	v_pk_mul_f32 v[244:245], v[160:161], v[160:161]
	v_pk_mul_f32 v[246:247], v[158:159], v[158:159]
	v_pk_mul_f32 v[248:249], v[162:163], v[162:163]
	v_add_f32_e32 v204, v245, v244
	v_add_f32_e32 v205, v243, v242
	v_add_f32_e32 v204, v248, v204
	v_add_f32_e32 v205, v246, v205
	v_add_f32_e32 v204, v249, v204
	v_add_f32_e32 v205, v247, v205
	v_pk_mul_f32 v[242:243], v[164:165], v[164:165]
	v_pk_mul_f32 v[244:245], v[168:169], v[168:169]
	v_pk_mul_f32 v[246:247], v[166:167], v[166:167]
	v_pk_mul_f32 v[248:249], v[170:171], v[170:171]
	v_add_f32_e32 v206, v243, v242
	v_add_f32_e32 v207, v245, v244
	v_add_f32_e32 v206, v246, v206
	v_add_f32_e32 v207, v248, v207
	v_add_f32_e32 v206, v247, v206
	v_add_f32_e32 v207, v249, v207
	v_add_f32_e32 v204, v205, v204
	v_add_f32_e32 v204, v204, v206
	v_add_f32_e32 v204, v204, v207
	ds_swizzle_b32 v205, v204 offset:swizzle(SWAP,1)
	s_waitcnt lgkmcnt(0)
	v_add_f32_e32 v204, v204, v205
	ds_swizzle_b32 v205, v204 offset:swizzle(SWAP,2)
	s_waitcnt lgkmcnt(0)
	v_add_f32_e32 v204, v204, v205
	ds_swizzle_b32 v205, v204 offset:swizzle(SWAP,4)
	s_waitcnt lgkmcnt(0)
	v_add_f32_e32 v204, v204, v205
	ds_swizzle_b32 v205, v204 offset:swizzle(SWAP,8)
	s_waitcnt lgkmcnt(0)
	v_add_f32_e32 v204, v204, v205
	ds_swizzle_b32 v205, v204 offset:swizzle(SWAP,16)
	s_waitcnt lgkmcnt(0)
	v_add_f32_e32 v204, v204, v205
	v_mov_b32_e32 v205, v204
	s_nop 1
	v_permlane32_swap_b32_e32 v204, v205
	v_add_f32_e32 v204, v204, v205
	v_mov_b32_e32 v205, 0x358637bd
	v_fmamk_f32 v204, v204, 0x3a800000, v205
	v_rsq_f32_e32 v204, v204
	s_nop 0
	v_pk_mul_f32 v[156:157], v[156:157], v[204:205] op_sel_hi:[1,0]
	v_pk_mul_f32 v[158:159], v[158:159], v[204:205] op_sel_hi:[1,0]
	v_pk_mul_f32 v[156:157], v[188:189], v[156:157]
	v_pk_mul_f32 v[158:159], v[190:191], v[158:159]
	v_pk_fma_f32 v[156:157], v[34:35], v[156:157], v[224:225]
	v_pk_fma_f32 v[158:159], v[36:37], v[158:159], v[226:227]
	v_cvt_pk_bf16_f32 v156, v156, v157
	v_cvt_pk_bf16_f32 v157, v158, v159
	global_store_dwordx2 v146, v[156:157], s[66:67]
	v_pk_mul_f32 v[160:161], v[160:161], v[204:205] op_sel_hi:[1,0]
	v_pk_mul_f32 v[162:163], v[162:163], v[204:205] op_sel_hi:[1,0]
	v_pk_mul_f32 v[160:161], v[192:193], v[160:161]
	v_pk_mul_f32 v[162:163], v[194:195], v[162:163]
	v_pk_fma_f32 v[160:161], v[38:39], v[160:161], v[228:229]
	v_pk_fma_f32 v[162:163], v[40:41], v[162:163], v[230:231]
	v_cvt_pk_bf16_f32 v160, v160, v161
	v_cvt_pk_bf16_f32 v161, v162, v163
	global_store_dwordx2 v146, v[160:161], s[66:67] offset:512
	v_pk_mul_f32 v[164:165], v[164:165], v[204:205] op_sel_hi:[1,0]
	v_pk_mul_f32 v[166:167], v[166:167], v[204:205] op_sel_hi:[1,0]
	v_pk_mul_f32 v[164:165], v[196:197], v[164:165]
	v_pk_mul_f32 v[166:167], v[198:199], v[166:167]
	v_pk_fma_f32 v[164:165], v[42:43], v[164:165], v[232:233]
	v_pk_fma_f32 v[166:167], v[44:45], v[166:167], v[234:235]
	v_cvt_pk_bf16_f32 v164, v164, v165
	v_cvt_pk_bf16_f32 v165, v166, v167
	global_store_dwordx2 v146, v[164:165], s[66:67] offset:1024
	v_pk_mul_f32 v[168:169], v[168:169], v[204:205] op_sel_hi:[1,0]
	v_pk_mul_f32 v[170:171], v[170:171], v[204:205] op_sel_hi:[1,0]
	v_pk_mul_f32 v[168:169], v[200:201], v[168:169]
	v_pk_mul_f32 v[170:171], v[202:203], v[170:171]
	v_pk_fma_f32 v[168:169], v[46:47], v[168:169], v[236:237]
	v_pk_fma_f32 v[170:171], v[48:49], v[170:171], v[238:239]
	v_cvt_pk_bf16_f32 v168, v168, v169
	v_cvt_pk_bf16_f32 v169, v170, v171
	global_store_dwordx2 v146, v[168:169], s[66:67] offset:1536
	v_add_u32_e32 v146, 0x800, v146
	s_waitcnt vmcnt(36)
; __device__ __forceinline__ unsigned pk2(float lo, float hi) { const g_f32x2 f = {lo, hi}; return __builtin_bit_cast(unsigned, __builtin_convertvector(f, g_bf16x2)); }
; __device__ __forceinline__ void p_norm(const float* hlat, const float* hctx, const float* g, const float* modl, int sh_off, int sc_off, bf16_t* A, int M,
;                                        const float* part, const float* cgate, float* hcout) {
;     ...
;         const int r = row < NLAT ? (row >> 11) : 16;
;         float ss = 0.f;
; #pragma unroll
;         for (int i = 0; i < 4; ++i) {
;             if (part != nullptr && row >= NLAT) {
;                 const size_t po = (size_t)(row - NLAT) * 1024 + i * 256 + lane * 4;
;                 const float4 p0 = *(const float4*)(part + po), p1 = *(const float4*)(part + (size_t)4096 * 1024 + po), cg = *(const float4*)(cgate + i * 256 + lane * 4);
;                 v[i].x += cg.x * (p0.x + p1.x); v[i].y += cg.y * (p0.y + p1.y); v[i].z += cg.z * (p0.z + p1.z); v[i].w += cg.w * (p0.w + p1.w);
;                 *(float4*)(hcout + po) = v[i];
;             }
;             ss += v[i].x * v[i].x + v[i].y * v[i].y + v[i].z * v[i].z + v[i].w * v[i].w; }
;         ss = wave_sum(ss);
;         const float rstd = rsqrtf(ss * (1.0f / 1024.0f) + EPS);
;         const float* mr = modl + (size_t)r * 6144;
; #pragma unroll
;         for (int i = 0; i < 4; ++i) {
;             const int k = i * 256 + lane * 4;
;             const float4 gg = *(const float4*)(g + k), scv = *(const float4*)(mr + sc_off + k), shv = *(const float4*)(mr + sh_off + k);
;             const float o0 = v[i].x * rstd * gg.x * (1.0f + scv.x) + shv.x, o1 = v[i].y * rstd * gg.y * (1.0f + scv.y) + shv.y;
;             const float o2 = v[i].z * rstd * gg.z * (1.0f + scv.z) + shv.z, o3 = v[i].w * rstd * gg.w * (1.0f + scv.w) + shv.w;
;             uint2 w; w.x = pk2(o0, o1); w.y = pk2(o2, o3);
;             *(uint2*)(A + (size_t)row * 1024 + k) = w;
;         }
	v_pk_mul_f32 v[242:243], v[172:173], v[172:173]
	v_pk_mul_f32 v[244:245], v[176:177], v[176:177]
	v_pk_mul_f32 v[246:247], v[174:175], v[174:175]
	v_pk_mul_f32 v[248:249], v[178:179], v[178:179]
	v_add_f32_e32 v204, v245, v244
	v_add_f32_e32 v205, v243, v242
	v_add_f32_e32 v204, v248, v204
	v_add_f32_e32 v205, v246, v205
	v_add_f32_e32 v204, v249, v204
	v_add_f32_e32 v205, v247, v205
	v_pk_mul_f32 v[242:243], v[180:181], v[180:181]
	v_pk_mul_f32 v[244:245], v[184:185], v[184:185]
	v_pk_mul_f32 v[246:247], v[182:183], v[182:183]
	v_pk_mul_f32 v[248:249], v[186:187], v[186:187]
	v_add_f32_e32 v206, v243, v242
	v_add_f32_e32 v207, v245, v244
	v_add_f32_e32 v206, v246, v206
	v_add_f32_e32 v207, v248, v207
	v_add_f32_e32 v206, v247, v206
	v_add_f32_e32 v207, v249, v207
	v_add_f32_e32 v204, v205, v204
	v_add_f32_e32 v204, v204, v206
	v_add_f32_e32 v204, v204, v207
	ds_swizzle_b32 v205, v204 offset:swizzle(SWAP,1)
	s_waitcnt lgkmcnt(0)
	v_add_f32_e32 v204, v204, v205
	ds_swizzle_b32 v205, v204 offset:swizzle(SWAP,2)
	s_waitcnt lgkmcnt(0)
	v_add_f32_e32 v204, v204, v205
	ds_swizzle_b32 v205, v204 offset:swizzle(SWAP,4)
	s_waitcnt lgkmcnt(0)
	v_add_f32_e32 v204, v204, v205
	ds_swizzle_b32 v205, v204 offset:swizzle(SWAP,8)
	s_waitcnt lgkmcnt(0)
	v_add_f32_e32 v204, v204, v205
	ds_swizzle_b32 v205, v204 offset:swizzle(SWAP,16)
	s_waitcnt lgkmcnt(0)
	v_add_f32_e32 v204, v204, v205
	v_mov_b32_e32 v205, v204
	s_nop 1
	v_permlane32_swap_b32_e32 v204, v205
	v_add_f32_e32 v204, v204, v205
	v_mov_b32_e32 v205, 0x358637bd
	v_fmamk_f32 v204, v204, 0x3a800000, v205
	v_rsq_f32_e32 v204, v204
	s_nop 0
	v_pk_mul_f32 v[172:173], v[172:173], v[204:205] op_sel_hi:[1,0]
	v_pk_mul_f32 v[174:175], v[174:175], v[204:205] op_sel_hi:[1,0]
	v_pk_mul_f32 v[172:173], v[188:189], v[172:173]
	v_pk_mul_f32 v[174:175], v[190:191], v[174:175]
	v_pk_fma_f32 v[172:173], v[34:35], v[172:173], v[224:225]
	v_pk_fma_f32 v[174:175], v[36:37], v[174:175], v[226:227]
	v_cvt_pk_bf16_f32 v172, v172, v173
	v_cvt_pk_bf16_f32 v173, v174, v175
	global_store_dwordx2 v146, v[172:173], s[66:67]
	v_pk_mul_f32 v[176:177], v[176:177], v[204:205] op_sel_hi:[1,0]
	v_pk_mul_f32 v[178:179], v[178:179], v[204:205] op_sel_hi:[1,0]
	v_pk_mul_f32 v[176:177], v[192:193], v[176:177]
	v_pk_mul_f32 v[178:179], v[194:195], v[178:179]
	v_pk_fma_f32 v[176:177], v[38:39], v[176:177], v[228:229]
	v_pk_fma_f32 v[178:179], v[40:41], v[178:179], v[230:231]
	v_cvt_pk_bf16_f32 v176, v176, v177
	v_cvt_pk_bf16_f32 v177, v178, v179
	global_store_dwordx2 v146, v[176:177], s[66:67] offset:512
	v_pk_mul_f32 v[180:181], v[180:181], v[204:205] op_sel_hi:[1,0]
	v_pk_mul_f32 v[182:183], v[182:183], v[204:205] op_sel_hi:[1,0]
	v_pk_mul_f32 v[180:181], v[196:197], v[180:181]
	v_pk_mul_f32 v[182:183], v[198:199], v[182:183]
	v_pk_fma_f32 v[180:181], v[42:43], v[180:181], v[232:233]
	v_pk_fma_f32 v[182:183], v[44:45], v[182:183], v[234:235]
	v_cvt_pk_bf16_f32 v180, v180, v181
	v_cvt_pk_bf16_f32 v181, v182, v183
	global_store_dwordx2 v146, v[180:181], s[66:67] offset:1024
	v_pk_mul_f32 v[184:185], v[184:185], v[204:205] op_sel_hi:[1,0]
	v_pk_mul_f32 v[186:187], v[186:187], v[204:205] op_sel_hi:[1,0]
	v_pk_mul_f32 v[184:185], v[200:201], v[184:185]
	v_pk_mul_f32 v[186:187], v[202:203], v[186:187]
	v_pk_fma_f32 v[184:185], v[46:47], v[184:185], v[236:237]
	v_pk_fma_f32 v[186:187], v[48:49], v[186:187], v[238:239]
	v_cvt_pk_bf16_f32 v184, v184, v185
	v_cvt_pk_bf16_f32 v185, v186, v187
	global_store_dwordx2 v146, v[184:185], s[66:67] offset:1536
	v_add_u32_e32 v146, 0x800, v146
	s_waitcnt vmcnt(32)
	v_pk_mul_f32 v[242:243], v[80:81], v[80:81]
	v_pk_mul_f32 v[244:245], v[84:85], v[84:85]
	v_pk_mul_f32 v[246:247], v[82:83], v[82:83]
	v_pk_mul_f32 v[248:249], v[86:87], v[86:87]
	v_add_f32_e32 v204, v245, v244
	v_add_f32_e32 v205, v243, v242
	v_add_f32_e32 v204, v248, v204
	v_add_f32_e32 v205, v246, v205
	v_add_f32_e32 v204, v249, v204
	v_add_f32_e32 v205, v247, v205
	v_pk_mul_f32 v[242:243], v[88:89], v[88:89]
	v_pk_mul_f32 v[244:245], v[92:93], v[92:93]
	v_pk_mul_f32 v[246:247], v[90:91], v[90:91]
	v_pk_mul_f32 v[248:249], v[94:95], v[94:95]
	v_add_f32_e32 v206, v243, v242
	v_add_f32_e32 v207, v245, v244
	v_add_f32_e32 v206, v246, v206
	v_add_f32_e32 v207, v248, v207
	v_add_f32_e32 v206, v247, v206
	v_add_f32_e32 v207, v249, v207
	v_add_f32_e32 v204, v205, v204
	v_add_f32_e32 v204, v204, v206
	v_add_f32_e32 v204, v204, v207
	ds_swizzle_b32 v205, v204 offset:swizzle(SWAP,1)
	s_waitcnt lgkmcnt(0)
	v_add_f32_e32 v204, v204, v205
	ds_swizzle_b32 v205, v204 offset:swizzle(SWAP,2)
	s_waitcnt lgkmcnt(0)
	v_add_f32_e32 v204, v204, v205
	ds_swizzle_b32 v205, v204 offset:swizzle(SWAP,4)
	s_waitcnt lgkmcnt(0)
	v_add_f32_e32 v204, v204, v205
	ds_swizzle_b32 v205, v204 offset:swizzle(SWAP,8)
	s_waitcnt lgkmcnt(0)
	v_add_f32_e32 v204, v204, v205
	ds_swizzle_b32 v205, v204 offset:swizzle(SWAP,16)
	s_waitcnt lgkmcnt(0)
; __device__ __forceinline__ unsigned pk2(float lo, float hi) { const g_f32x2 f = {lo, hi}; return __builtin_bit_cast(unsigned, __builtin_convertvector(f, g_bf16x2)); }
; __device__ __forceinline__ void p_norm(const float* hlat, const float* hctx, const float* g, const float* modl, int sh_off, int sc_off, bf16_t* A, int M,
;                                        const float* part, const float* cgate, float* hcout) {
;     ...
;         const int r = row < NLAT ? (row >> 11) : 16;
;         float ss = 0.f;
; #pragma unroll
;         for (int i = 0; i < 4; ++i) {
;             if (part != nullptr && row >= NLAT) {
;                 const size_t po = (size_t)(row - NLAT) * 1024 + i * 256 + lane * 4;
;                 const float4 p0 = *(const float4*)(part + po), p1 = *(const float4*)(part + (size_t)4096 * 1024 + po), cg = *(const float4*)(cgate + i * 256 + lane * 4);
;                 v[i].x += cg.x * (p0.x + p1.x); v[i].y += cg.y * (p0.y + p1.y); v[i].z += cg.z * (p0.z + p1.z); v[i].w += cg.w * (p0.w + p1.w);
;                 *(float4*)(hcout + po) = v[i];
;             }
;             ss += v[i].x * v[i].x + v[i].y * v[i].y + v[i].z * v[i].z + v[i].w * v[i].w; }
;         ss = wave_sum(ss);
;         const float rstd = rsqrtf(ss * (1.0f / 1024.0f) + EPS);
;         const float* mr = modl + (size_t)r * 6144;
; #pragma unroll
;         for (int i = 0; i < 4; ++i) {
;             const int k = i * 256 + lane * 4;
;             const float4 gg = *(const float4*)(g + k), scv = *(const float4*)(mr + sc_off + k), shv = *(const float4*)(mr + sh_off + k);
;             const float o0 = v[i].x * rstd * gg.x * (1.0f + scv.x) + shv.x, o1 = v[i].y * rstd * gg.y * (1.0f + scv.y) + shv.y;
;             const float o2 = v[i].z * rstd * gg.z * (1.0f + scv.z) + shv.z, o3 = v[i].w * rstd * gg.w * (1.0f + scv.w) + shv.w;
;             uint2 w; w.x = pk2(o0, o1); w.y = pk2(o2, o3);
;             *(uint2*)(A + (size_t)row * 1024 + k) = w;
;         }
	v_add_f32_e32 v204, v204, v205
	v_mov_b32_e32 v205, v204
	s_nop 1
	v_permlane32_swap_b32_e32 v204, v205
	v_add_f32_e32 v204, v204, v205
	v_mov_b32_e32 v205, 0x358637bd
	v_fmamk_f32 v204, v204, 0x3a800000, v205
	v_rsq_f32_e32 v204, v204
	s_nop 0
	v_pk_mul_f32 v[80:81], v[80:81], v[204:205] op_sel_hi:[1,0]
	v_pk_mul_f32 v[82:83], v[82:83], v[204:205] op_sel_hi:[1,0]
	v_pk_mul_f32 v[80:81], v[188:189], v[80:81]
	v_pk_mul_f32 v[82:83], v[190:191], v[82:83]
	v_pk_fma_f32 v[80:81], v[34:35], v[80:81], v[224:225]
	v_pk_fma_f32 v[82:83], v[36:37], v[82:83], v[226:227]
	v_cvt_pk_bf16_f32 v80, v80, v81
	v_cvt_pk_bf16_f32 v81, v82, v83
	global_store_dwordx2 v146, v[80:81], s[66:67]
	v_pk_mul_f32 v[84:85], v[84:85], v[204:205] op_sel_hi:[1,0]
	v_pk_mul_f32 v[86:87], v[86:87], v[204:205] op_sel_hi:[1,0]
	v_pk_mul_f32 v[84:85], v[192:193], v[84:85]
	v_pk_mul_f32 v[86:87], v[194:195], v[86:87]
	v_pk_fma_f32 v[84:85], v[38:39], v[84:85], v[228:229]
	v_pk_fma_f32 v[86:87], v[40:41], v[86:87], v[230:231]
	v_cvt_pk_bf16_f32 v84, v84, v85
	v_cvt_pk_bf16_f32 v85, v86, v87
	global_store_dwordx2 v146, v[84:85], s[66:67] offset:512
	v_pk_mul_f32 v[88:89], v[88:89], v[204:205] op_sel_hi:[1,0]
	v_pk_mul_f32 v[90:91], v[90:91], v[204:205] op_sel_hi:[1,0]
	v_pk_mul_f32 v[88:89], v[196:197], v[88:89]
	v_pk_mul_f32 v[90:91], v[198:199], v[90:91]
	v_pk_fma_f32 v[88:89], v[42:43], v[88:89], v[232:233]
	v_pk_fma_f32 v[90:91], v[44:45], v[90:91], v[234:235]
	v_cvt_pk_bf16_f32 v88, v88, v89
	v_cvt_pk_bf16_f32 v89, v90, v91
	global_store_dwordx2 v146, v[88:89], s[66:67] offset:1024
	v_pk_mul_f32 v[92:93], v[92:93], v[204:205] op_sel_hi:[1,0]
	v_pk_mul_f32 v[94:95], v[94:95], v[204:205] op_sel_hi:[1,0]
	v_pk_mul_f32 v[92:93], v[200:201], v[92:93]
	v_pk_mul_f32 v[94:95], v[202:203], v[94:95]
	v_pk_fma_f32 v[92:93], v[46:47], v[92:93], v[236:237]
	v_pk_fma_f32 v[94:95], v[48:49], v[94:95], v[238:239]
	v_cvt_pk_bf16_f32 v92, v92, v93
	v_cvt_pk_bf16_f32 v93, v94, v95
	global_store_dwordx2 v146, v[92:93], s[66:67] offset:1536
	v_add_u32_e32 v146, 0x800, v146
	s_waitcnt vmcnt(28)
	v_pk_mul_f32 v[242:243], v[96:97], v[96:97]
	v_pk_mul_f32 v[244:245], v[100:101], v[100:101]
	v_pk_mul_f32 v[246:247], v[98:99], v[98:99]
	v_pk_mul_f32 v[248:249], v[102:103], v[102:103]
	v_add_f32_e32 v204, v245, v244
	v_add_f32_e32 v205, v243, v242
	v_add_f32_e32 v204, v248, v204
	v_add_f32_e32 v205, v246, v205
	v_add_f32_e32 v204, v249, v204
	v_add_f32_e32 v205, v247, v205
	v_pk_mul_f32 v[242:243], v[104:105], v[104:105]
	v_pk_mul_f32 v[244:245], v[108:109], v[108:109]
	v_pk_mul_f32 v[246:247], v[106:107], v[106:107]
	v_pk_mul_f32 v[248:249], v[110:111], v[110:111]
	v_add_f32_e32 v206, v243, v242
	v_add_f32_e32 v207, v245, v244
	v_add_f32_e32 v206, v246, v206
	v_add_f32_e32 v207, v248, v207
	v_add_f32_e32 v206, v247, v206
	v_add_f32_e32 v207, v249, v207
	v_add_f32_e32 v204, v205, v204
	v_add_f32_e32 v204, v204, v206
	v_add_f32_e32 v204, v204, v207
	ds_swizzle_b32 v205, v204 offset:swizzle(SWAP,1)
	s_waitcnt lgkmcnt(0)
	v_add_f32_e32 v204, v204, v205
	ds_swizzle_b32 v205, v204 offset:swizzle(SWAP,2)
	s_waitcnt lgkmcnt(0)
	v_add_f32_e32 v204, v204, v205
	ds_swizzle_b32 v205, v204 offset:swizzle(SWAP,4)
	s_waitcnt lgkmcnt(0)
	v_add_f32_e32 v204, v204, v205
	ds_swizzle_b32 v205, v204 offset:swizzle(SWAP,8)
	s_waitcnt lgkmcnt(0)
	v_add_f32_e32 v204, v204, v205
	ds_swizzle_b32 v205, v204 offset:swizzle(SWAP,16)
	s_waitcnt lgkmcnt(0)
	v_add_f32_e32 v204, v204, v205
	v_mov_b32_e32 v205, v204
	s_nop 1
	v_permlane32_swap_b32_e32 v204, v205
	v_add_f32_e32 v204, v204, v205
	v_mov_b32_e32 v205, 0x358637bd
	v_fmamk_f32 v204, v204, 0x3a800000, v205
	v_rsq_f32_e32 v204, v204
	s_nop 0
	v_pk_mul_f32 v[96:97], v[96:97], v[204:205] op_sel_hi:[1,0]
	v_pk_mul_f32 v[98:99], v[98:99], v[204:205] op_sel_hi:[1,0]
	v_pk_mul_f32 v[96:97], v[188:189], v[96:97]
	v_pk_mul_f32 v[98:99], v[190:191], v[98:99]
	v_pk_fma_f32 v[96:97], v[34:35], v[96:97], v[224:225]
	v_pk_fma_f32 v[98:99], v[36:37], v[98:99], v[226:227]
	v_cvt_pk_bf16_f32 v96, v96, v97
	v_cvt_pk_bf16_f32 v97, v98, v99
	global_store_dwordx2 v146, v[96:97], s[66:67]
	v_pk_mul_f32 v[100:101], v[100:101], v[204:205] op_sel_hi:[1,0]
	v_pk_mul_f32 v[102:103], v[102:103], v[204:205] op_sel_hi:[1,0]
	v_pk_mul_f32 v[100:101], v[192:193], v[100:101]
	v_pk_mul_f32 v[102:103], v[194:195], v[102:103]
	v_pk_fma_f32 v[100:101], v[38:39], v[100:101], v[228:229]
	v_pk_fma_f32 v[102:103], v[40:41], v[102:103], v[230:231]
	v_cvt_pk_bf16_f32 v100, v100, v101
	v_cvt_pk_bf16_f32 v101, v102, v103
	global_store_dwordx2 v146, v[100:101], s[66:67] offset:512
	v_pk_mul_f32 v[104:105], v[104:105], v[204:205] op_sel_hi:[1,0]
	v_pk_mul_f32 v[106:107], v[106:107], v[204:205] op_sel_hi:[1,0]
	v_pk_mul_f32 v[104:105], v[196:197], v[104:105]
	v_pk_mul_f32 v[106:107], v[198:199], v[106:107]
	v_pk_fma_f32 v[104:105], v[42:43], v[104:105], v[232:233]
	v_pk_fma_f32 v[106:107], v[44:45], v[106:107], v[234:235]
	v_cvt_pk_bf16_f32 v104, v104, v105
	v_cvt_pk_bf16_f32 v105, v106, v107
	global_store_dwordx2 v146, v[104:105], s[66:67] offset:1024
	v_pk_mul_f32 v[108:109], v[108:109], v[204:205] op_sel_hi:[1,0]
	v_pk_mul_f32 v[110:111], v[110:111], v[204:205] op_sel_hi:[1,0]
	v_pk_mul_f32 v[108:109], v[200:201], v[108:109]
	v_pk_mul_f32 v[110:111], v[202:203], v[110:111]
	v_pk_fma_f32 v[108:109], v[46:47], v[108:109], v[236:237]
	v_pk_fma_f32 v[110:111], v[48:49], v[110:111], v[238:239]
	v_cvt_pk_bf16_f32 v108, v108, v109
	v_cvt_pk_bf16_f32 v109, v110, v111
	global_store_dwordx2 v146, v[108:109], s[66:67] offset:1536
	v_add_u32_e32 v146, 0x800, v146
	s_waitcnt vmcnt(24)
; __device__ __forceinline__ unsigned pk2(float lo, float hi) { const g_f32x2 f = {lo, hi}; return __builtin_bit_cast(unsigned, __builtin_convertvector(f, g_bf16x2)); }
; __device__ __forceinline__ void p_norm(const float* hlat, const float* hctx, const float* g, const float* modl, int sh_off, int sc_off, bf16_t* A, int M,
;                                        const float* part, const float* cgate, float* hcout) {
;     ...
;         const int r = row < NLAT ? (row >> 11) : 16;
;         float ss = 0.f;
; #pragma unroll
;         for (int i = 0; i < 4; ++i) {
;             if (part != nullptr && row >= NLAT) {
;                 const size_t po = (size_t)(row - NLAT) * 1024 + i * 256 + lane * 4;
;                 const float4 p0 = *(const float4*)(part + po), p1 = *(const float4*)(part + (size_t)4096 * 1024 + po), cg = *(const float4*)(cgate + i * 256 + lane * 4);
;                 v[i].x += cg.x * (p0.x + p1.x); v[i].y += cg.y * (p0.y + p1.y); v[i].z += cg.z * (p0.z + p1.z); v[i].w += cg.w * (p0.w + p1.w);
;                 *(float4*)(hcout + po) = v[i];
;             }
;             ss += v[i].x * v[i].x + v[i].y * v[i].y + v[i].z * v[i].z + v[i].w * v[i].w; }
;         ss = wave_sum(ss);
;         const float rstd = rsqrtf(ss * (1.0f / 1024.0f) + EPS);
;         const float* mr = modl + (size_t)r * 6144;
; #pragma unroll
;         for (int i = 0; i < 4; ++i) {
;             const int k = i * 256 + lane * 4;
;             const float4 gg = *(const float4*)(g + k), scv = *(const float4*)(mr + sc_off + k), shv = *(const float4*)(mr + sh_off + k);
;             const float o0 = v[i].x * rstd * gg.x * (1.0f + scv.x) + shv.x, o1 = v[i].y * rstd * gg.y * (1.0f + scv.y) + shv.y;
;             const float o2 = v[i].z * rstd * gg.z * (1.0f + scv.z) + shv.z, o3 = v[i].w * rstd * gg.w * (1.0f + scv.w) + shv.w;
;             uint2 w; w.x = pk2(o0, o1); w.y = pk2(o2, o3);
;             *(uint2*)(A + (size_t)row * 1024 + k) = w;
;         }
	v_pk_mul_f32 v[242:243], v[112:113], v[112:113]
	v_pk_mul_f32 v[244:245], v[116:117], v[116:117]
	v_pk_mul_f32 v[246:247], v[114:115], v[114:115]
	v_pk_mul_f32 v[248:249], v[118:119], v[118:119]
	v_add_f32_e32 v204, v245, v244
	v_add_f32_e32 v205, v243, v242
	v_add_f32_e32 v204, v248, v204
	v_add_f32_e32 v205, v246, v205
	v_add_f32_e32 v204, v249, v204
	v_add_f32_e32 v205, v247, v205
	v_pk_mul_f32 v[242:243], v[120:121], v[120:121]
	v_pk_mul_f32 v[244:245], v[124:125], v[124:125]
	v_pk_mul_f32 v[246:247], v[122:123], v[122:123]
	v_pk_mul_f32 v[248:249], v[126:127], v[126:127]
	v_add_f32_e32 v206, v243, v242
	v_add_f32_e32 v207, v245, v244
	v_add_f32_e32 v206, v246, v206
	v_add_f32_e32 v207, v248, v207
	v_add_f32_e32 v206, v247, v206
	v_add_f32_e32 v207, v249, v207
	v_add_f32_e32 v204, v205, v204
	v_add_f32_e32 v204, v204, v206
	v_add_f32_e32 v204, v204, v207
	ds_swizzle_b32 v205, v204 offset:swizzle(SWAP,1)
	s_waitcnt lgkmcnt(0)
	v_add_f32_e32 v204, v204, v205
	ds_swizzle_b32 v205, v204 offset:swizzle(SWAP,2)
	s_waitcnt lgkmcnt(0)
	v_add_f32_e32 v204, v204, v205
	ds_swizzle_b32 v205, v204 offset:swizzle(SWAP,4)
	s_waitcnt lgkmcnt(0)
	v_add_f32_e32 v204, v204, v205
	ds_swizzle_b32 v205, v204 offset:swizzle(SWAP,8)
	s_waitcnt lgkmcnt(0)
	v_add_f32_e32 v204, v204, v205
	ds_swizzle_b32 v205, v204 offset:swizzle(SWAP,16)
	s_waitcnt lgkmcnt(0)
	v_add_f32_e32 v204, v204, v205
	v_mov_b32_e32 v205, v204
	s_nop 1
	v_permlane32_swap_b32_e32 v204, v205
	v_add_f32_e32 v204, v204, v205
	v_mov_b32_e32 v205, 0x358637bd
	v_fmamk_f32 v204, v204, 0x3a800000, v205
	v_rsq_f32_e32 v204, v204
	s_nop 0
	v_pk_mul_f32 v[112:113], v[112:113], v[204:205] op_sel_hi:[1,0]
	v_pk_mul_f32 v[114:115], v[114:115], v[204:205] op_sel_hi:[1,0]
	v_pk_mul_f32 v[112:113], v[188:189], v[112:113]
	v_pk_mul_f32 v[114:115], v[190:191], v[114:115]
	v_pk_fma_f32 v[112:113], v[34:35], v[112:113], v[224:225]
	v_pk_fma_f32 v[114:115], v[36:37], v[114:115], v[226:227]
	v_cvt_pk_bf16_f32 v112, v112, v113
	v_cvt_pk_bf16_f32 v113, v114, v115
	global_store_dwordx2 v146, v[112:113], s[66:67]
	v_pk_mul_f32 v[116:117], v[116:117], v[204:205] op_sel_hi:[1,0]
	v_pk_mul_f32 v[118:119], v[118:119], v[204:205] op_sel_hi:[1,0]
	v_pk_mul_f32 v[116:117], v[192:193], v[116:117]
	v_pk_mul_f32 v[118:119], v[194:195], v[118:119]
	v_pk_fma_f32 v[116:117], v[38:39], v[116:117], v[228:229]
	v_pk_fma_f32 v[118:119], v[40:41], v[118:119], v[230:231]
	v_cvt_pk_bf16_f32 v116, v116, v117
	v_cvt_pk_bf16_f32 v117, v118, v119
	global_store_dwordx2 v146, v[116:117], s[66:67] offset:512
	v_pk_mul_f32 v[120:121], v[120:121], v[204:205] op_sel_hi:[1,0]
	v_pk_mul_f32 v[122:123], v[122:123], v[204:205] op_sel_hi:[1,0]
	v_pk_mul_f32 v[120:121], v[196:197], v[120:121]
	v_pk_mul_f32 v[122:123], v[198:199], v[122:123]
	v_pk_fma_f32 v[120:121], v[42:43], v[120:121], v[232:233]
	v_pk_fma_f32 v[122:123], v[44:45], v[122:123], v[234:235]
	v_cvt_pk_bf16_f32 v120, v120, v121
	v_cvt_pk_bf16_f32 v121, v122, v123
	global_store_dwordx2 v146, v[120:121], s[66:67] offset:1024
	v_pk_mul_f32 v[124:125], v[124:125], v[204:205] op_sel_hi:[1,0]
	v_pk_mul_f32 v[126:127], v[126:127], v[204:205] op_sel_hi:[1,0]
	v_pk_mul_f32 v[124:125], v[200:201], v[124:125]
	v_pk_mul_f32 v[126:127], v[202:203], v[126:127]
	v_pk_fma_f32 v[124:125], v[46:47], v[124:125], v[236:237]
	v_pk_fma_f32 v[126:127], v[48:49], v[126:127], v[238:239]
	v_cvt_pk_bf16_f32 v124, v124, v125
	v_cvt_pk_bf16_f32 v125, v126, v127
	global_store_dwordx2 v146, v[124:125], s[66:67] offset:1536
	v_add_u32_e32 v146, 0x800, v146
	s_waitcnt vmcnt(20)
	v_pk_mul_f32 v[242:243], v[128:129], v[128:129]
	v_pk_mul_f32 v[244:245], v[132:133], v[132:133]
	v_pk_mul_f32 v[246:247], v[130:131], v[130:131]
	v_pk_mul_f32 v[248:249], v[134:135], v[134:135]
	v_add_f32_e32 v204, v245, v244
	v_add_f32_e32 v205, v243, v242
	v_add_f32_e32 v204, v248, v204
	v_add_f32_e32 v205, v246, v205
	v_add_f32_e32 v204, v249, v204
	v_add_f32_e32 v205, v247, v205
	v_pk_mul_f32 v[242:243], v[136:137], v[136:137]
	v_pk_mul_f32 v[244:245], v[140:141], v[140:141]
	v_pk_mul_f32 v[246:247], v[138:139], v[138:139]
	v_pk_mul_f32 v[248:249], v[142:143], v[142:143]
	v_add_f32_e32 v206, v243, v242
	v_add_f32_e32 v207, v245, v244
	v_add_f32_e32 v206, v246, v206
	v_add_f32_e32 v207, v248, v207
	v_add_f32_e32 v206, v247, v206
	v_add_f32_e32 v207, v249, v207
	v_add_f32_e32 v204, v205, v204
	v_add_f32_e32 v204, v204, v206
	v_add_f32_e32 v204, v204, v207
	ds_swizzle_b32 v205, v204 offset:swizzle(SWAP,1)
	s_waitcnt lgkmcnt(0)
	v_add_f32_e32 v204, v204, v205
	ds_swizzle_b32 v205, v204 offset:swizzle(SWAP,2)
	s_waitcnt lgkmcnt(0)
; __device__ __forceinline__ unsigned pk2(float lo, float hi) { const g_f32x2 f = {lo, hi}; return __builtin_bit_cast(unsigned, __builtin_convertvector(f, g_bf16x2)); }
; #define PN_LOAD(dst, rw) do { const float* s_ = (rw) < NLAT ? hlat + (size_t)(rw) * 1024 : hctx + (size_t)((rw) - NLAT) * 1024; \
;         _Pragma("unroll") for (int i = 0; i < 4; ++i) dst[i] = *(const float4*)(s_ + i * 256 + lane * 4); } while (0)
; __device__ __forceinline__ void p_norm(const float* hlat, const float* hctx, const float* g, const float* modl, int sh_off, int sc_off, bf16_t* A, int M,
;                                        const float* part, const float* cgate, float* hcout) {
;     ...
;     if (row < M) PN_LOAD(v, row);
;     while (row < M) {
;         const int nrow = row + stride;
;         if (nrow < M) PN_LOAD(nv, nrow);
;         const int r = row < NLAT ? (row >> 11) : 16;
;         float ss = 0.f;
; #pragma unroll
;         for (int i = 0; i < 4; ++i) {
;             if (part != nullptr && row >= NLAT) {
;                 const size_t po = (size_t)(row - NLAT) * 1024 + i * 256 + lane * 4;
;                 const float4 p0 = *(const float4*)(part + po), p1 = *(const float4*)(part + (size_t)4096 * 1024 + po), cg = *(const float4*)(cgate + i * 256 + lane * 4);
;     ...
;         for (int i = 0; i < 4; ++i) {
;             const int k = i * 256 + lane * 4;
;             const float4 gg = *(const float4*)(g + k), scv = *(const float4*)(mr + sc_off + k), shv = *(const float4*)(mr + sh_off + k);
;             const float o0 = v[i].x * rstd * gg.x * (1.0f + scv.x) + shv.x, o1 = v[i].y * rstd * gg.y * (1.0f + scv.y) + shv.y;
;             const float o2 = v[i].z * rstd * gg.z * (1.0f + scv.z) + shv.z, o3 = v[i].w * rstd * gg.w * (1.0f + scv.w) + shv.w;
;             uint2 w; w.x = pk2(o0, o1); w.y = pk2(o2, o3);
;             *(uint2*)(A + (size_t)row * 1024 + k) = w;
;         }
	v_add_f32_e32 v204, v204, v205
	ds_swizzle_b32 v205, v204 offset:swizzle(SWAP,4)
	s_waitcnt lgkmcnt(0)
	v_add_f32_e32 v204, v204, v205
	ds_swizzle_b32 v205, v204 offset:swizzle(SWAP,8)
	s_waitcnt lgkmcnt(0)
	v_add_f32_e32 v204, v204, v205
	ds_swizzle_b32 v205, v204 offset:swizzle(SWAP,16)
	s_waitcnt lgkmcnt(0)
	v_add_f32_e32 v204, v204, v205
	v_mov_b32_e32 v205, v204
	s_nop 1
	v_permlane32_swap_b32_e32 v204, v205
	v_add_f32_e32 v204, v204, v205
	v_mov_b32_e32 v205, 0x358637bd
	v_fmamk_f32 v204, v204, 0x3a800000, v205
	v_rsq_f32_e32 v204, v204
	s_nop 0
	v_pk_mul_f32 v[128:129], v[128:129], v[204:205] op_sel_hi:[1,0]
	v_pk_mul_f32 v[130:131], v[130:131], v[204:205] op_sel_hi:[1,0]
	v_pk_mul_f32 v[128:129], v[188:189], v[128:129]
	v_pk_mul_f32 v[130:131], v[190:191], v[130:131]
	v_pk_fma_f32 v[128:129], v[34:35], v[128:129], v[224:225]
	v_pk_fma_f32 v[130:131], v[36:37], v[130:131], v[226:227]
	v_cvt_pk_bf16_f32 v128, v128, v129
	v_cvt_pk_bf16_f32 v129, v130, v131
	global_store_dwordx2 v146, v[128:129], s[66:67]
	v_pk_mul_f32 v[132:133], v[132:133], v[204:205] op_sel_hi:[1,0]
	v_pk_mul_f32 v[134:135], v[134:135], v[204:205] op_sel_hi:[1,0]
	v_pk_mul_f32 v[132:133], v[192:193], v[132:133]
	v_pk_mul_f32 v[134:135], v[194:195], v[134:135]
	v_pk_fma_f32 v[132:133], v[38:39], v[132:133], v[228:229]
	v_pk_fma_f32 v[134:135], v[40:41], v[134:135], v[230:231]
	v_cvt_pk_bf16_f32 v132, v132, v133
	v_cvt_pk_bf16_f32 v133, v134, v135
	global_store_dwordx2 v146, v[132:133], s[66:67] offset:512
	v_pk_mul_f32 v[136:137], v[136:137], v[204:205] op_sel_hi:[1,0]
	v_pk_mul_f32 v[138:139], v[138:139], v[204:205] op_sel_hi:[1,0]
	v_pk_mul_f32 v[136:137], v[196:197], v[136:137]
	v_pk_mul_f32 v[138:139], v[198:199], v[138:139]
	v_pk_fma_f32 v[136:137], v[42:43], v[136:137], v[232:233]
	v_pk_fma_f32 v[138:139], v[44:45], v[138:139], v[234:235]
	v_cvt_pk_bf16_f32 v136, v136, v137
	v_cvt_pk_bf16_f32 v137, v138, v139
	global_store_dwordx2 v146, v[136:137], s[66:67] offset:1024
	v_pk_mul_f32 v[140:141], v[140:141], v[204:205] op_sel_hi:[1,0]
	v_pk_mul_f32 v[142:143], v[142:143], v[204:205] op_sel_hi:[1,0]
	v_pk_mul_f32 v[140:141], v[200:201], v[140:141]
	v_pk_mul_f32 v[142:143], v[202:203], v[142:143]
	v_pk_fma_f32 v[140:141], v[46:47], v[140:141], v[236:237]
	v_pk_fma_f32 v[142:143], v[48:49], v[142:143], v[238:239]
	v_cvt_pk_bf16_f32 v140, v140, v141
	v_cvt_pk_bf16_f32 v141, v142, v143
	global_store_dwordx2 v146, v[140:141], s[66:67] offset:1536
	v_add_u32_e32 v146, 0x800, v146
.Lnorm_P6_end:
	v_add_u32_e32 v50, 0x10000, v50
	v_cmp_gt_i32_e32 vcc, s7, v50
	s_and_saveexec_b64 s[2:3], vcc
	s_cbranch_execz .LBB0_1050
	v_readlane_b32 s8, v255, 39
	s_mov_b32 s6, 0x8000
	v_readlane_b32 s9, v255, 40
	v_add_u32_e32 v2, 0xffff8000, v50
	v_ashrrev_i32_e32 v51, 31, v50
	v_cmp_gt_i32_e32 vcc, s6, v50
	v_mov_b32_e32 v4, s9
	v_mov_b32_e32 v5, s43
	v_cndmask_b32_e32 v3, 0, v51, vcc
	v_cndmask_b32_e32 v2, v2, v50, vcc
	v_cndmask_b32_e32 v5, v4, v5, vcc
	v_mov_b32_e32 v4, s8
	v_mov_b32_e32 v7, s42
	v_cndmask_b32_e32 v4, v4, v7, vcc
	v_lshlrev_b64 v[2:3], 12, v[2:3]
	v_lshl_add_u64 v[2:3], v[4:5], 0, v[2:3]
	v_lshlrev_b32_e32 v4, 2, v6
	v_and_b32_e32 v34, 0xfc, v4
	v_lshlrev_b32_e32 v8, 2, v34
	v_mov_b32_e32 v9, v0
	v_lshl_add_u64 v[2:3], v[2:3], 0, v[8:9]
	global_load_dwordx4 v[30:33], v[2:3], off
	global_load_dwordx4 v[26:29], v[2:3], off offset:1024
	global_load_dwordx4 v[22:25], v[2:3], off offset:2048
	s_nop 0
	global_load_dwordx4 v[2:5], v[2:3], off offset:3072
	s_load_dwordx2 s[8:9], s[0:1], 0x38
	s_and_b64 s[10:11], s[18:19], exec
	v_readlane_b32 s10, v255, 47
	v_readlane_b32 s11, v255, 48
	s_cselect_b32 s17, 0, s71
	s_cselect_b32 s16, 0, s70
	s_lshl_b64 s[10:11], s[10:11], 2
	s_waitcnt lgkmcnt(0)
	s_add_u32 s8, s8, s10
	s_addc_u32 s9, s9, s11
	s_cmp_lg_u64 s[16:17], 0
	v_readlane_b32 s10, v255, 43
	s_cselect_b64 s[24:25], -1, 0
	s_add_u32 s26, s16, 0x1000000
	v_readlane_b32 s11, v255, 44
	s_addc_u32 s27, s17, 0
	v_lshlrev_b64 v[14:15], 11, v[50:51]
	v_lshl_add_u64 v[10:11], s[10:11], 0, v[8:9]
	s_mov_b64 s[10:11], 0x62000
	v_and_b32_e32 v6, 63, v6
	s_add_i32 s5, s5, s72
	v_lshl_add_u64 v[36:37], v[10:11], 0, s[10:11]
	v_lshl_add_u64 v[38:39], s[8:9], 0, v[8:9]
	v_or_b32_e32 v8, 0x100, v34
	v_or_b32_e32 v10, 0x200, v34
	v_or_b32_e32 v12, 0x300, v34
	v_lshl_or_b32 v14, v6, 3, v14
	v_add_u32_e32 v42, s5, v1
	s_mov_b64 s[20:21], 0
	v_lshl_add_u64 v[40:41], s[66:67], 0, v[14:15]
	v_ashrrev_i32_e32 v43, 31, v42
	v_lshlrev_b32_e32 v44, 2, v8
	v_lshlrev_b32_e32 v46, 2, v10
	v_lshlrev_b32_e32 v48, 2, v12
	s_branch .LBB0_1040
